# first K-iteration peeled (C=0, relaxed waits) + write-through epilogue stores on 6 GEMMs, in0 scale loads hoisted, mixer0 rewrite
# baseline (speedup 1.0000x reference)
; #define PG8_STAGE(bufoff, gbase, voff) do { _Pragma("unroll") for (int _i = 0; _i < 2; ++_i) \
;         __builtin_amdgcn_global_load_lds((const unsigned*)((const char*)(gbase) + (voff)[_i]), (PG8_LAS unsigned*)(lds + (bufoff) + ldsw + _i * 8192), 16, 0, 0); } while (0)
; #define PG8_WAIT_V(n) asm volatile("s_waitcnt vmcnt(" #n ")" ::: "memory")
; #define PG8_BAR __builtin_amdgcn_s_barrier()
; template <class Epi, class Sched, bool ALIGN_EPI = false, bool SP2 = false>
; __device__ __forceinline__ void gemm_phase(PG8_LAS unsigned char* lds, const Gemm g, const Sched& S, const Epi& E) {
;     ...
;     for (int i = 0; i < 2; ++i) { int R, C; stage_rc(tid * 16 + i * 8192, R, C); const int Rb = Epi::PERM ? ((R & ~31) + perm32(R & 31)) : R;
;         voffA[i] = g.asub ? (unsigned)((C >> 5) * 16384 + (R * 32 + (C & 31)) * 2) : (unsigned)(R * g.lda + C) * 2u; voffB[i] = (unsigned)(Rb * K + C) * 2u; }
;     const size_t kstep = (size_t)(BK * 2);
;     const size_t hstepB = (size_t)HALF * K * 2, hstepA = (size_t)HALF * g.lda * 2;
;     const size_t tstepB = 2 * hstepB, tstepA = g.tstepA; const size_t kstepA = g.kstepA;
;     const unsigned ldsw = (unsigned)wid * 1024u;
;     const int aoff = lds_byte(wr * 64 + fr, fq * 8), boff = lds_byte(wc * 32 + fr, fq * 8);
;     ...
;         PG8_STAGE(PG8_SB(0, 0), cB, voffB); PG8_STAGE(PG8_SB(0, 1), cB + hstepB, voffB); PG8_STAGE(PG8_SA(0, 0), cA, voffA); PG8_STAGE(PG8_SA(0, 1), cA + hstepA, voffA);
;         if (wr == 1) PG8_BAR;
;         PG8_WAIT_V(2); PG8_BAR;
;         PG8_STAGE(PG8_SB(1, 0), cB + kstep, voffB); PG8_STAGE(PG8_SA(1, 0), cA + kstepA, voffA); PG8_STAGE(PG8_SB(1, 1), cB + hstepB + kstep, voffB);
;         PG8_WAIT_V(6); PG8_BAR;
.LBB0_99:
	s_lshl_b32 s3, s3, 5
	s_mov_b64 s[80:81], 0x80
	s_and_b32 s3, s3, 0x60
	s_add_i32 m0, s51, 0x18000
	v_lshl_add_u64 v[6:7], v[6:7], 0, s[80:81]
	s_lshl_b32 s1, s2, 13
	s_lshl_b32 s7, s3, 7
	s_waitcnt vmcnt(2)
	s_barrier
	global_load_lds_dwordx4 v[6:7], off
	v_lshl_add_u64 v[4:5], v[4:5], 0, s[80:81]
	s_add_i32 m0, s51, 0x1a000
	s_add_i32 s57, s51, 0x8000
	s_add_i32 s58, s51, 0xa000
	global_load_lds_dwordx4 v[4:5], off
	v_lshl_add_u64 v[0:1], v[0:1], 0, s[80:81]
	s_mov_b32 m0, s57
	s_add_u32 s12, s94, 0x40080
	global_load_lds_dwordx4 v[0:1], off
	v_lshl_add_u64 v[0:1], v[2:3], 0, s[80:81]
	s_mov_b32 m0, s58
	s_addc_u32 s13, s95, 0
	global_load_lds_dwordx4 v[0:1], off
	s_add_i32 m0, s51, 0x1c000
	v_lshl_add_u64 v[0:1], s[12:13], 0, v[130:131]
	global_load_lds_dwordx4 v[0:1], off
	v_lshl_add_u64 v[0:1], s[12:13], 0, v[134:135]
	s_add_i32 m0, s51, 0x1e000
	s_cmpk_lt_u32 s6, 0x100
	global_load_lds_dwordx4 v[0:1], off
	v_lshrrev_b32_e32 v1, 1, v8
	v_and_b32_e32 v1, 24, v1
	v_and_b32_e32 v0, 15, v8
	v_lshlrev_b32_e32 v2, 1, v1
	v_lshl_or_b32 v139, s2, 6, v0
	v_lshl_or_b32 v0, v0, 6, v2
	v_lshlrev_b32_e32 v2, 2, v8
	v_and_b32_e32 v2, 32, v2
	v_bitop3_b32 v3, v0, s1, v2 bitop3:0xde
	v_bitop3_b32 v160, v0, s7, v2 bitop3:0xde
	v_lshlrev_b32_e32 v0, 14, v9
	v_and_b32_e32 v0, 0xffff8000, v0
	v_or_b32_e32 v138, s3, v1
	v_lshl_add_u32 v0, v10, 11, v0
	v_and_b32_e32 v1, 1, v9
	v_lshl_or_b32 v0, v1, 6, v0
	v_lshl_add_u32 v140, v11, 1, v0
	v_lshlrev_b32_e32 v0, 14, v12
	v_and_b32_e32 v0, 0xffff8000, v0
	s_waitcnt vmcnt(0)
	v_lshl_add_u32 v0, v13, 11, v0
	v_and_b32_e32 v1, 1, v12
	s_cselect_b64 s[82:83], -1, 0
	v_lshl_or_b32 v0, v1, 6, v0
	s_add_i32 s62, 0, 0x10000
	s_add_i32 s63, 0, 0x14000
	s_ashr_i32 s59, s10, 31
	s_mov_b32 s60, s10
	s_ashr_i32 s61, s33, 31
	v_mov_b32_e32 v141, v137
	v_lshl_add_u32 v142, v14, 1, v0
	v_mov_b32_e32 v143, v137
	v_mov_b64_e32 v[144:145], 0x2a8
	v_mov_b64_e32 v[146:147], 0x2a7
	s_mov_b64 s[84:85], 0x100
	v_add_u32_e32 v161, s62, v160
	v_add_u32_e32 v162, s63, v160
	v_add_u32_e32 v163, 0, v3
	v_mov_b32_e32 v164, 0x358637bd
	s_movk_i32 s64, 0xc00
	s_mov_b64 s[86:87], 0x200
	s_mov_b32 s65, 0
	s_barrier
	s_branch .LBB0_102

;     __host__ __device__ __forceinline__ bool next(int i, Unit& u) const { const long L = (long)i * G + c; if (L >= nwg) return false; map((int)L, u); return true; }
; #define PG8_STAGE(bufoff, gbase, voff) do { _Pragma("unroll") for (int _i = 0; _i < 2; ++_i) \
;         __builtin_amdgcn_global_load_lds((const unsigned*)((const char*)(gbase) + (voff)[_i]), (PG8_LAS unsigned*)(lds + (bufoff) + ldsw + _i * 8192), 16, 0, 0); } while (0)
; #define PG8_WAIT_V(n) asm volatile("s_waitcnt vmcnt(" #n ")" ::: "memory")
; #define PG8_BAR __builtin_amdgcn_s_barrier()
;     __device__ __forceinline__ void operator()(const f32x4 (&acc)[2][2][4][2], const Unit& u, int wr, int wc, int fr, int fq) const {
;     ...
;             for (int m = 0; m < 4; ++m) rsv[ai][m] = ss[row0 + ai * HALF + m * 16];
; template <class Epi, class Sched, bool ALIGN_EPI = false, bool SP2 = false>
; __device__ __forceinline__ void gemm_phase(PG8_LAS unsigned char* lds, const Gemm g, const Sched& S, const Epi& E) {
;     ...
;         const bool has_next = S.next(ui + 1, nxt);
;         const char* nA = has_next ? (const char*)g.A + (size_t)nxt.pm * tstepA + (size_t)(nxt.k0 >> 6) * kstepA + (nxt.qa > 0 ? hstepA : (size_t)0) : cA; const char* nB = has_next ? (const char*)g.Bt + (size_t)nxt.pn * tstepB + (size_t)nxt.k0 * 2 + (nxt.qb > 0 ? hstepB : (size_t)0) : cB;
;         const bool whole = cur.qa < 0;
;         const int nt = cur.nt;
;         for (int t = 0; t < nt; t += 2) {
;             const bool last = (t == nt - 2);
;             const char* a1 = cA + (size_t)(t + 1) * kstepA;
;             const char* a2 = last ? nA : cA + (size_t)(t + 2) * kstepA; const char* b2 = last ? nB : cB + (size_t)(t + 2) * kstep;
;             const char* a3 = a2 + kstepA; const char* b3 = b2 + kstep;
;             if (last && has_next) S.a_ready(nxt);
;             if constexpr (SP2) {
;             PG8_LDB(B0, 0, 0); PG8_LDB(B1, 0, 1); PG8_SCHED; PG8_LDA(At, 0, 0); PG8_STAGE(PG8_SA(1, 1), a1 + hstepA, voffA);
;             PG8_WAIT_V(8); PG8_WAIT_L(0); PG8_BAR; PG8_MMA(0, 0, At, B0); if (whole) PG8_MMA(0, 1, At, B1); PG8_BAR; PG8_SCHED;
;             PG8_LDA(At, 0, 1); PG8_STAGE(PG8_SB(0, 0), b2, voffB); PG8_STAGE(PG8_SB(0, 1), b2 + hstepB, voffB); PG8_STAGE(PG8_SA(0, 0), a2, voffA);
;             PG8_WAIT_V(8); PG8_WAIT_L(0); PG8_BAR; if (whole) { PG8_MMA(1, 0, At, B0); PG8_MMA(1, 1, At, B1); } PG8_BAR; PG8_SCHED;
.LBB0_104:
	s_ashr_i32 s91, s90, 31
	s_lshl_b64 s[6:7], s[90:91], 19
	s_add_u32 s92, s30, s6
	s_addc_u32 s93, s31, s7
	s_and_b64 s[6:7], s[2:3], exec
	s_cselect_b32 s1, s93, s97
	s_cselect_b32 s9, s92, s96
	s_ashr_i32 s89, s88, 31
	s_lshl_b64 s[6:7], s[88:89], 19
	s_add_u32 s6, s8, s6
	s_addc_u32 s7, s52, s7
	s_and_b64 s[12:13], s[2:3], exec
	s_cselect_b32 s12, s7, s95
	s_cselect_b32 s13, s6, s94
	s_add_u32 s96, s96, 0x40080
	s_addc_u32 s97, s97, 0
	s_add_u32 s14, s94, 0x100
	s_addc_u32 s15, s95, 0
	s_mov_b32 s16, -2
	v_lshl_add_u32 v236, s0, 8, v139
	v_ashrrev_i32_e32 v237, 31, v236
	v_lshl_add_u64 v[236:237], v[236:237], 2, s[72:73]
	global_load_dword v228, v[236:237], off
	global_load_dword v229, v[236:237], off offset:64
	global_load_dword v230, v[236:237], off offset:128
	global_load_dword v231, v[236:237], off offset:192
	global_load_dword v232, v[236:237], off offset:512
	global_load_dword v233, v[236:237], off offset:576
	global_load_dword v234, v[236:237], off offset:640
	global_load_dword v235, v[236:237], off offset:704
	ds_read_b128 v[148:151], v161
	ds_read_b128 v[152:155], v161 offset:1024
	ds_read_b128 v[156:159], v161 offset:2048
	ds_read_b128 v[166:169], v161 offset:3072
	ds_read_b128 v[170:173], v162
	ds_read_b128 v[174:177], v162 offset:1024
	ds_read_b128 v[178:181], v162 offset:2048
	ds_read_b128 v[182:185], v162 offset:3072
	s_add_u32 s17, s96, 0xfffc0080
	s_addc_u32 s18, s97, -1
	s_cmp_eq_u32 s16, 12
	s_cselect_b32 vcc_hi, s1, s18
	s_cselect_b32 vcc_lo, s9, s17
	s_cselect_b32 s95, s12, s15
	s_cselect_b32 s94, s13, s14
	v_lshl_add_u64 v[218:219], s[96:97], 0, v[140:141]
	s_add_i32 m0, s51, 0xc000
	ds_read_b128 v[186:189], v163
	ds_read_b128 v[190:193], v163 offset:1024
	ds_read_b128 v[194:197], v163 offset:2048
	ds_read_b128 v[198:201], v163 offset:3072
	ds_read_b128 v[202:205], v163 offset:4096
	ds_read_b128 v[206:209], v163 offset:5120
	ds_read_b128 v[210:213], v163 offset:6144
	ds_read_b128 v[214:217], v163 offset:7168
	global_load_lds_dwordx4 v[218:219], off
	v_lshl_add_u64 v[218:219], s[96:97], 0, v[142:143]
	s_add_i32 m0, s51, 0xe000
	s_nop 0
	global_load_lds_dwordx4 v[218:219], off
	s_waitcnt vmcnt(16)
	s_waitcnt lgkmcnt(0)
	s_barrier
	s_setprio 1
	s_waitcnt lgkmcnt(0)
	v_mfma_f32_16x16x32_bf16 v[124:127], v[148:151], v[186:189], 0
	v_mfma_f32_16x16x32_bf16 v[120:123], v[156:159], v[186:189], 0
	v_mfma_f32_16x16x32_bf16 v[108:111], v[148:151], v[194:197], 0
	v_mfma_f32_16x16x32_bf16 v[104:107], v[156:159], v[194:197], 0
	v_mfma_f32_16x16x32_bf16 v[92:95], v[148:151], v[202:205], 0
	v_mfma_f32_16x16x32_bf16 v[88:91], v[156:159], v[202:205], 0
	v_mfma_f32_16x16x32_bf16 v[76:79], v[148:151], v[210:213], 0
	v_mfma_f32_16x16x32_bf16 v[72:75], v[156:159], v[210:213], 0
	v_mfma_f32_16x16x32_bf16 v[124:127], v[152:155], v[190:193], v[124:127]
	v_mfma_f32_16x16x32_bf16 v[120:123], v[166:169], v[190:193], v[120:123]
	v_mfma_f32_16x16x32_bf16 v[108:111], v[152:155], v[198:201], v[108:111]
	v_mfma_f32_16x16x32_bf16 v[104:107], v[166:169], v[198:201], v[104:107]
	v_mfma_f32_16x16x32_bf16 v[92:95], v[152:155], v[206:209], v[92:95]
	v_mfma_f32_16x16x32_bf16 v[88:91], v[166:169], v[206:209], v[88:91]
	v_mfma_f32_16x16x32_bf16 v[76:79], v[152:155], v[214:217], v[76:79]
	v_mfma_f32_16x16x32_bf16 v[72:75], v[166:169], v[214:217], v[72:75]
	s_setprio 0
	s_setprio 1
	v_mfma_f32_16x16x32_bf16 v[116:119], v[170:173], v[186:189], 0
	v_mfma_f32_16x16x32_bf16 v[112:115], v[178:181], v[186:189], 0
	v_mfma_f32_16x16x32_bf16 v[100:103], v[170:173], v[194:197], 0
	v_mfma_f32_16x16x32_bf16 v[96:99], v[178:181], v[194:197], 0
	v_mfma_f32_16x16x32_bf16 v[84:87], v[170:173], v[202:205], 0
	v_mfma_f32_16x16x32_bf16 v[80:83], v[178:181], v[202:205], 0
	v_mfma_f32_16x16x32_bf16 v[68:71], v[170:173], v[210:213], 0
	v_mfma_f32_16x16x32_bf16 v[64:67], v[178:181], v[210:213], 0
	v_mfma_f32_16x16x32_bf16 v[116:119], v[174:177], v[190:193], v[116:119]
	v_mfma_f32_16x16x32_bf16 v[112:115], v[182:185], v[190:193], v[112:115]
	v_mfma_f32_16x16x32_bf16 v[100:103], v[174:177], v[198:201], v[100:103]
	v_mfma_f32_16x16x32_bf16 v[96:99], v[182:185], v[198:201], v[96:99]
	v_mfma_f32_16x16x32_bf16 v[84:87], v[174:177], v[206:209], v[84:87]
	v_mfma_f32_16x16x32_bf16 v[80:83], v[182:185], v[206:209], v[80:83]
	v_mfma_f32_16x16x32_bf16 v[68:71], v[174:177], v[214:217], v[68:71]
	v_mfma_f32_16x16x32_bf16 v[64:67], v[182:185], v[214:217], v[64:67]
	s_setprio 0
	s_barrier
	s_add_i32 s17, s62, s53
	v_lshl_add_u64 v[218:219], s[94:95], 0, v[130:131]
	s_mov_b32 m0, s17
	ds_read_b128 v[186:189], v163 offset:16384
	ds_read_b128 v[190:193], v163 offset:17408
	ds_read_b128 v[194:197], v163 offset:18432
	ds_read_b128 v[198:201], v163 offset:19456
	ds_read_b128 v[202:205], v163 offset:20480
	ds_read_b128 v[206:209], v163 offset:21504
	ds_read_b128 v[210:213], v163 offset:22528
	ds_read_b128 v[214:217], v163 offset:23552
	global_load_lds_dwordx4 v[218:219], off
	s_add_i32 m0, s17, 0x2000
	s_add_u32 s18, s94, 0x40000
	v_lshl_add_u64 v[220:221], s[94:95], 0, v[134:135]
	s_addc_u32 s19, s95, 0
	s_add_i32 s17, s63, s53
	global_load_lds_dwordx4 v[220:221], off
	v_lshl_add_u64 v[222:223], s[18:19], 0, v[130:131]
	s_mov_b32 m0, s17
	v_lshl_add_u64 v[224:225], vcc, 0, v[132:133]
	global_load_lds_dwordx4 v[222:223], off
	v_lshl_add_u64 v[222:223], s[18:19], 0, v[134:135]
	s_add_i32 m0, s17, 0x2000
	s_nop 0
	global_load_lds_dwordx4 v[222:223], off
	v_lshl_add_u64 v[222:223], vcc, 0, v[128:129]
	s_mov_b32 m0, s51
	s_nop 0
	global_load_lds_dwordx4 v[222:223], off
	s_mov_b32 m0, s54
	s_nop 0
	global_load_lds_dwordx4 v[224:225], off
	s_waitcnt vmcnt(16)
	s_waitcnt lgkmcnt(0)
	s_barrier
; #define PG8_STAGE(bufoff, gbase, voff) do { _Pragma("unroll") for (int _i = 0; _i < 2; ++_i) \
;         __builtin_amdgcn_global_load_lds((const unsigned*)((const char*)(gbase) + (voff)[_i]), (PG8_LAS unsigned*)(lds + (bufoff) + ldsw + _i * 8192), 16, 0, 0); } while (0)
; #define PG8_LDA(dst, b, h) do { _Pragma("unroll") for (int m = 0; m < 4; ++m) _Pragma("unroll") for (int k = 0; k < 2; ++k) dst[m][k] = *(const PG8_LAS bf16x8*)(lds + PG8_SA(b, h) + aoff + m * 2048 + k * 1024); } while (0)
; #define PG8_LDB(dst, b, h) do { _Pragma("unroll") for (int n = 0; n < 2; ++n) _Pragma("unroll") for (int k = 0; k < 2; ++k) dst[n][k] = *(const PG8_LAS bf16x8*)(lds + PG8_SB(b, h) + boff + n * 2048 + k * 1024); } while (0)
; #define PG8_MMA(ai, bj, At, Bt) do { __builtin_amdgcn_s_setprio(1); _Pragma("unroll") for (int m = 0; m < 4; ++m) _Pragma("unroll") for (int n = 0; n < 2; ++n) _Pragma("unroll") for (int k = 0; k < 2; ++k) \
;         acc[ai][bj][m][n] = __builtin_amdgcn_mfma_f32_16x16x32_bf16(Bt[n][k], At[m][k], acc[ai][bj][m][n], 0, 0, 0); __builtin_amdgcn_s_setprio(0); } while (0)
; #define PG8_WAIT_V(n) asm volatile("s_waitcnt vmcnt(" #n ")" ::: "memory")
; #define PG8_WAIT_L(n) asm volatile("s_waitcnt lgkmcnt(" #n ")" ::: "memory")
; #define PG8_BAR __builtin_amdgcn_s_barrier()
; #define PG8_SCHED __builtin_amdgcn_sched_barrier(0)
; template <class Epi, class Sched, bool ALIGN_EPI = false, bool SP2 = false>
; __device__ __forceinline__ void gemm_phase(PG8_LAS unsigned char* lds, const Gemm g, const Sched& S, const Epi& E) {
;     ...
;             PG8_WAIT_V(8); PG8_WAIT_L(0); PG8_BAR; if (whole) { PG8_MMA(1, 0, At, B0); PG8_MMA(1, 1, At, B1); } PG8_BAR; PG8_SCHED;
;             PG8_LDB(B0, 1, 0); PG8_LDB(B1, 1, 1); PG8_SCHED; PG8_LDA(At, 1, 0); PG8_STAGE(PG8_SA(0, 1), a2 + hstepA, voffA);
;             PG8_WAIT_V(8); PG8_WAIT_L(0); PG8_BAR; PG8_MMA(0, 0, At, B0); if (whole) PG8_MMA(0, 1, At, B1); PG8_BAR; PG8_SCHED;
	s_setprio 1
	s_waitcnt lgkmcnt(0)
	v_mfma_f32_16x16x32_bf16 v[60:63], v[148:151], v[186:189], 0
	v_mfma_f32_16x16x32_bf16 v[56:59], v[156:159], v[186:189], 0
	v_mfma_f32_16x16x32_bf16 v[44:47], v[148:151], v[194:197], 0
	v_mfma_f32_16x16x32_bf16 v[40:43], v[156:159], v[194:197], 0
	v_mfma_f32_16x16x32_bf16 v[28:31], v[148:151], v[202:205], 0
	v_mfma_f32_16x16x32_bf16 v[24:27], v[156:159], v[202:205], 0
	v_mfma_f32_16x16x32_bf16 v[12:15], v[148:151], v[210:213], 0
	v_mfma_f32_16x16x32_bf16 v[8:11], v[156:159], v[210:213], 0
	v_mfma_f32_16x16x32_bf16 v[60:63], v[152:155], v[190:193], v[60:63]
	v_mfma_f32_16x16x32_bf16 v[56:59], v[166:169], v[190:193], v[56:59]
	v_mfma_f32_16x16x32_bf16 v[44:47], v[152:155], v[198:201], v[44:47]
	v_mfma_f32_16x16x32_bf16 v[40:43], v[166:169], v[198:201], v[40:43]
	v_mfma_f32_16x16x32_bf16 v[28:31], v[152:155], v[206:209], v[28:31]
	v_mfma_f32_16x16x32_bf16 v[24:27], v[166:169], v[206:209], v[24:27]
	v_mfma_f32_16x16x32_bf16 v[12:15], v[152:155], v[214:217], v[12:15]
	v_mfma_f32_16x16x32_bf16 v[8:11], v[166:169], v[214:217], v[8:11]
	s_setprio 0
	s_setprio 1
	v_mfma_f32_16x16x32_bf16 v[52:55], v[170:173], v[186:189], 0
	v_mfma_f32_16x16x32_bf16 v[48:51], v[178:181], v[186:189], 0
	v_mfma_f32_16x16x32_bf16 v[36:39], v[170:173], v[194:197], 0
	v_mfma_f32_16x16x32_bf16 v[32:35], v[178:181], v[194:197], 0
	v_mfma_f32_16x16x32_bf16 v[20:23], v[170:173], v[202:205], 0
	v_mfma_f32_16x16x32_bf16 v[16:19], v[178:181], v[202:205], 0
	v_mfma_f32_16x16x32_bf16 v[4:7], v[170:173], v[210:213], 0
	v_mfma_f32_16x16x32_bf16 v[0:3], v[178:181], v[210:213], 0
	v_mfma_f32_16x16x32_bf16 v[52:55], v[174:177], v[190:193], v[52:55]
	v_mfma_f32_16x16x32_bf16 v[48:51], v[182:185], v[190:193], v[48:51]
	v_mfma_f32_16x16x32_bf16 v[36:39], v[174:177], v[198:201], v[36:39]
	v_mfma_f32_16x16x32_bf16 v[32:35], v[182:185], v[198:201], v[32:35]
	v_mfma_f32_16x16x32_bf16 v[20:23], v[174:177], v[206:209], v[20:23]
	v_mfma_f32_16x16x32_bf16 v[16:19], v[182:185], v[206:209], v[16:19]
	v_mfma_f32_16x16x32_bf16 v[4:7], v[174:177], v[214:217], v[4:7]
	v_mfma_f32_16x16x32_bf16 v[0:3], v[182:185], v[214:217], v[0:3]
	s_setprio 0
	s_barrier
	s_add_i32 s17, 0, 0x18000
	v_add_u32_e32 v136, s17, v160
	s_add_i32 s20, 0, 0x1c000
	ds_read_b128 v[148:151], v136
	ds_read_b128 v[152:155], v136 offset:1024
	ds_read_b128 v[156:159], v136 offset:2048
	ds_read_b128 v[166:169], v136 offset:3072
	v_add_u32_e32 v136, s20, v160
	ds_read_b128 v[170:173], v136
	ds_read_b128 v[174:177], v136 offset:1024
	ds_read_b128 v[178:181], v136 offset:2048
	ds_read_b128 v[182:185], v136 offset:3072
	s_add_u32 s18, vcc_lo, 0x40000
	s_addc_u32 s19, vcc_hi, 0
	s_mov_b32 m0, s55
	v_lshl_add_u64 v[226:227], s[18:19], 0, v[128:129]
	ds_read_b128 v[186:189], v163 offset:32768
	ds_read_b128 v[190:193], v163 offset:33792
	ds_read_b128 v[194:197], v163 offset:34816
	ds_read_b128 v[198:201], v163 offset:35840
	ds_read_b128 v[202:205], v163 offset:36864
	ds_read_b128 v[206:209], v163 offset:37888
	ds_read_b128 v[210:213], v163 offset:38912
	ds_read_b128 v[214:217], v163 offset:39936
	global_load_lds_dwordx4 v[226:227], off
	v_lshl_add_u64 v[226:227], s[18:19], 0, v[132:133]
	s_mov_b32 m0, s56
	s_nop 0
	global_load_lds_dwordx4 v[226:227], off
	s_waitcnt vmcnt(8)
	s_waitcnt lgkmcnt(0)
	s_barrier
	s_setprio 1
	s_waitcnt lgkmcnt(0)
	v_mfma_f32_16x16x32_bf16 v[124:127], v[148:151], v[186:189], v[124:127]
	v_mfma_f32_16x16x32_bf16 v[120:123], v[156:159], v[186:189], v[120:123]
	v_mfma_f32_16x16x32_bf16 v[108:111], v[148:151], v[194:197], v[108:111]
	v_mfma_f32_16x16x32_bf16 v[104:107], v[156:159], v[194:197], v[104:107]
	v_mfma_f32_16x16x32_bf16 v[92:95], v[148:151], v[202:205], v[92:95]
	v_mfma_f32_16x16x32_bf16 v[88:91], v[156:159], v[202:205], v[88:91]
	v_mfma_f32_16x16x32_bf16 v[76:79], v[148:151], v[210:213], v[76:79]
	v_mfma_f32_16x16x32_bf16 v[72:75], v[156:159], v[210:213], v[72:75]
	v_mfma_f32_16x16x32_bf16 v[124:127], v[152:155], v[190:193], v[124:127]
	v_mfma_f32_16x16x32_bf16 v[120:123], v[166:169], v[190:193], v[120:123]
	v_mfma_f32_16x16x32_bf16 v[108:111], v[152:155], v[198:201], v[108:111]
	v_mfma_f32_16x16x32_bf16 v[104:107], v[166:169], v[198:201], v[104:107]
	v_mfma_f32_16x16x32_bf16 v[92:95], v[152:155], v[206:209], v[92:95]
	v_mfma_f32_16x16x32_bf16 v[88:91], v[166:169], v[206:209], v[88:91]
	v_mfma_f32_16x16x32_bf16 v[76:79], v[152:155], v[214:217], v[76:79]
	v_mfma_f32_16x16x32_bf16 v[72:75], v[166:169], v[214:217], v[72:75]
	s_setprio 0
	s_setprio 1
	v_mfma_f32_16x16x32_bf16 v[116:119], v[170:173], v[186:189], v[116:119]
	v_mfma_f32_16x16x32_bf16 v[112:115], v[178:181], v[186:189], v[112:115]
	v_mfma_f32_16x16x32_bf16 v[100:103], v[170:173], v[194:197], v[100:103]
	v_mfma_f32_16x16x32_bf16 v[96:99], v[178:181], v[194:197], v[96:99]
	v_mfma_f32_16x16x32_bf16 v[84:87], v[170:173], v[202:205], v[84:87]
	v_mfma_f32_16x16x32_bf16 v[80:83], v[178:181], v[202:205], v[80:83]
	v_mfma_f32_16x16x32_bf16 v[68:71], v[170:173], v[210:213], v[68:71]
	v_mfma_f32_16x16x32_bf16 v[64:67], v[178:181], v[210:213], v[64:67]
	v_mfma_f32_16x16x32_bf16 v[116:119], v[174:177], v[190:193], v[116:119]
	v_mfma_f32_16x16x32_bf16 v[112:115], v[182:185], v[190:193], v[112:115]
	v_mfma_f32_16x16x32_bf16 v[100:103], v[174:177], v[198:201], v[100:103]
	v_mfma_f32_16x16x32_bf16 v[96:99], v[182:185], v[198:201], v[96:99]
	v_mfma_f32_16x16x32_bf16 v[84:87], v[174:177], v[206:209], v[84:87]
	v_mfma_f32_16x16x32_bf16 v[80:83], v[182:185], v[206:209], v[80:83]
	v_mfma_f32_16x16x32_bf16 v[68:71], v[174:177], v[214:217], v[68:71]
	v_mfma_f32_16x16x32_bf16 v[64:67], v[182:185], v[214:217], v[64:67]
	s_setprio 0
	s_barrier
; #define PG8_STAGE(bufoff, gbase, voff) do { _Pragma("unroll") for (int _i = 0; _i < 2; ++_i) \
;         __builtin_amdgcn_global_load_lds((const unsigned*)((const char*)(gbase) + (voff)[_i]), (PG8_LAS unsigned*)(lds + (bufoff) + ldsw + _i * 8192), 16, 0, 0); } while (0)
; #define PG8_LDA(dst, b, h) do { _Pragma("unroll") for (int m = 0; m < 4; ++m) _Pragma("unroll") for (int k = 0; k < 2; ++k) dst[m][k] = *(const PG8_LAS bf16x8*)(lds + PG8_SA(b, h) + aoff + m * 2048 + k * 1024); } while (0)
; #define PG8_MMA(ai, bj, At, Bt) do { __builtin_amdgcn_s_setprio(1); _Pragma("unroll") for (int m = 0; m < 4; ++m) _Pragma("unroll") for (int n = 0; n < 2; ++n) _Pragma("unroll") for (int k = 0; k < 2; ++k) \
;         acc[ai][bj][m][n] = __builtin_amdgcn_mfma_f32_16x16x32_bf16(Bt[n][k], At[m][k], acc[ai][bj][m][n], 0, 0, 0); __builtin_amdgcn_s_setprio(0); } while (0)
; #define PG8_WAIT_V(n) asm volatile("s_waitcnt vmcnt(" #n ")" ::: "memory")
; #define PG8_WAIT_L(n) asm volatile("s_waitcnt lgkmcnt(" #n ")" ::: "memory")
; #define PG8_BAR __builtin_amdgcn_s_barrier()
; #define PG8_SCHED __builtin_amdgcn_sched_barrier(0)
; template <class Epi, class Sched, bool ALIGN_EPI = false, bool SP2 = false>
; __device__ __forceinline__ void gemm_phase(PG8_LAS unsigned char* lds, const Gemm g, const Sched& S, const Epi& E) {
;     ...
;         for (int t = 0; t < nt; t += 2) {
;     ...
;             PG8_LDA(At, 1, 1); PG8_STAGE(PG8_SB(1, 0), b3, voffB); PG8_STAGE(PG8_SB(1, 1), b3 + hstepB, voffB); PG8_STAGE(PG8_SA(1, 0), a3, voffA);
;             PG8_WAIT_V(8); PG8_WAIT_L(0); PG8_BAR; if (whole) { PG8_MMA(1, 0, At, B0); PG8_MMA(1, 1, At, B1); } PG8_BAR; PG8_SCHED;
	s_add_i32 s17, s17, s53
	v_lshl_add_u64 v[218:219], v[218:219], 0, s[80:81]
	s_mov_b32 m0, s17
	ds_read_b128 v[186:189], v163 offset:49152
	ds_read_b128 v[190:193], v163 offset:50176
	ds_read_b128 v[194:197], v163 offset:51200
	ds_read_b128 v[198:201], v163 offset:52224
	ds_read_b128 v[202:205], v163 offset:53248
	ds_read_b128 v[206:209], v163 offset:54272
	ds_read_b128 v[210:213], v163 offset:55296
	ds_read_b128 v[214:217], v163 offset:56320
	global_load_lds_dwordx4 v[218:219], off
	s_add_i32 m0, s17, 0x2000
	s_add_u32 s18, s94, 0x40080
	v_lshl_add_u64 v[218:219], v[220:221], 0, s[80:81]
	s_addc_u32 s19, s95, 0
	s_add_i32 s17, s20, s53
	global_load_lds_dwordx4 v[218:219], off
	v_lshl_add_u64 v[218:219], s[18:19], 0, v[130:131]
	s_mov_b32 m0, s17
	s_nop 0
	global_load_lds_dwordx4 v[218:219], off
	v_lshl_add_u64 v[218:219], s[18:19], 0, v[134:135]
	s_add_i32 m0, s17, 0x2000
	s_nop 0
	global_load_lds_dwordx4 v[218:219], off
	v_lshl_add_u64 v[218:219], v[222:223], 0, s[80:81]
	s_mov_b32 m0, s57
	s_nop 0
	global_load_lds_dwordx4 v[218:219], off
	v_lshl_add_u64 v[218:219], v[224:225], 0, s[80:81]
	s_mov_b32 m0, s58
	s_nop 0
	global_load_lds_dwordx4 v[218:219], off
	s_waitcnt vmcnt(8)
	s_waitcnt lgkmcnt(0)
	s_barrier
	s_setprio 1
	s_waitcnt lgkmcnt(0)
	v_mfma_f32_16x16x32_bf16 v[60:63], v[148:151], v[186:189], v[60:63]
	v_mfma_f32_16x16x32_bf16 v[56:59], v[156:159], v[186:189], v[56:59]
	v_mfma_f32_16x16x32_bf16 v[44:47], v[148:151], v[194:197], v[44:47]
	v_mfma_f32_16x16x32_bf16 v[40:43], v[156:159], v[194:197], v[40:43]
	v_mfma_f32_16x16x32_bf16 v[28:31], v[148:151], v[202:205], v[28:31]
	v_mfma_f32_16x16x32_bf16 v[24:27], v[156:159], v[202:205], v[24:27]
	v_mfma_f32_16x16x32_bf16 v[12:15], v[148:151], v[210:213], v[12:15]
	v_mfma_f32_16x16x32_bf16 v[8:11], v[156:159], v[210:213], v[8:11]
	v_mfma_f32_16x16x32_bf16 v[60:63], v[152:155], v[190:193], v[60:63]
	v_mfma_f32_16x16x32_bf16 v[56:59], v[166:169], v[190:193], v[56:59]
	v_mfma_f32_16x16x32_bf16 v[44:47], v[152:155], v[198:201], v[44:47]
	v_mfma_f32_16x16x32_bf16 v[40:43], v[166:169], v[198:201], v[40:43]
	v_mfma_f32_16x16x32_bf16 v[28:31], v[152:155], v[206:209], v[28:31]
	v_mfma_f32_16x16x32_bf16 v[24:27], v[166:169], v[206:209], v[24:27]
	v_mfma_f32_16x16x32_bf16 v[12:15], v[152:155], v[214:217], v[12:15]
	v_mfma_f32_16x16x32_bf16 v[8:11], v[166:169], v[214:217], v[8:11]
	s_setprio 0
	s_setprio 1
	v_mfma_f32_16x16x32_bf16 v[52:55], v[170:173], v[186:189], v[52:55]
	v_mfma_f32_16x16x32_bf16 v[48:51], v[178:181], v[186:189], v[48:51]
	v_mfma_f32_16x16x32_bf16 v[36:39], v[170:173], v[194:197], v[36:39]
	v_mfma_f32_16x16x32_bf16 v[32:35], v[178:181], v[194:197], v[32:35]
	v_mfma_f32_16x16x32_bf16 v[20:23], v[170:173], v[202:205], v[20:23]
	v_mfma_f32_16x16x32_bf16 v[16:19], v[178:181], v[202:205], v[16:19]
	v_mfma_f32_16x16x32_bf16 v[4:7], v[170:173], v[210:213], v[4:7]
	v_mfma_f32_16x16x32_bf16 v[0:3], v[178:181], v[210:213], v[0:3]
	v_mfma_f32_16x16x32_bf16 v[52:55], v[174:177], v[190:193], v[52:55]
	v_mfma_f32_16x16x32_bf16 v[48:51], v[182:185], v[190:193], v[48:51]
	v_mfma_f32_16x16x32_bf16 v[36:39], v[174:177], v[198:201], v[36:39]
	v_mfma_f32_16x16x32_bf16 v[32:35], v[182:185], v[198:201], v[32:35]
	v_mfma_f32_16x16x32_bf16 v[20:23], v[174:177], v[206:209], v[20:23]
	v_mfma_f32_16x16x32_bf16 v[16:19], v[182:185], v[206:209], v[16:19]
	v_mfma_f32_16x16x32_bf16 v[4:7], v[174:177], v[214:217], v[4:7]
	v_mfma_f32_16x16x32_bf16 v[0:3], v[182:185], v[214:217], v[0:3]
	s_setprio 0
	s_barrier
	s_add_i32 s16, s16, 2
	s_add_u32 s96, s96, 0x100
	s_addc_u32 s97, s97, 0
	s_add_u32 s14, s14, 0x100
	s_addc_u32 s15, s15, 0
	s_cmp_gt_u32 s16, 13
	s_cbranch_scc0 .LBB0_105
	s_branch .Lpeel_exit_in0

; #define PG8_BAR __builtin_amdgcn_s_barrier()
; template <class Epi, class Sched, bool ALIGN_EPI = false, bool SP2 = false>
; __device__ __forceinline__ void gemm_phase(PG8_LAS unsigned char* lds, const Gemm g, const Sched& S, const Epi& E) {
;     ...
;         if constexpr (ALIGN_EPI) { if (wr == 0) PG8_BAR; }
;         if constexpr (!Epi::AFTER_DRAIN) { E(acc, cur, wr, wc, fr, fq); S.done(cur); }
.Lpeel_exit_in0:
	s_and_b64 vcc, exec, s[82:83]
	s_cbranch_vccz .LBB0_108
	s_barrier

; __device__ __forceinline__ unsigned cvt_pk_bf16(float lo, float hi) { unsigned r; asm volatile("v_cvt_pk_bf16_f32 %0, %1, %2" : "=v"(r) : "v"(lo), "v"(hi)); return r; }
;     __device__ __forceinline__ void operator()(const f32x4 (&acc)[2][2][4][2], const Unit& u, int wr, int wc, int fr, int fq) const {
;     ...
;             for (int m = 0; m < 4; ++m) rsv[ai][m] = __builtin_amdgcn_rsqf(rsv[ai][m] * (1.0f / 1024.0f) + RMS_EPS);
; #pragma unroll
;         for (int ai = 0; ai < 2; ++ai)
; #pragma unroll
;             for (int m = 0; m < 4; ++m) {
;                 const int row = row0 + ai * HALF + m * 16;
;                 const float rs = rsv[ai][m];
;                 bf16_t* rowp = O + (size_t)row * 1536;
;                 const f32x4 a0 = acc[ai][0][m][0] * rs, a1 = acc[ai][0][m][1] * rs, b0 = acc[ai][1][m][0] * rs, b1 = acc[ai][1][m][1] * rs;
;                 if (u.pn < 2) {
;                     u32x4 w; w.x = cvt_pk_bf16(a0[0], a0[1]); w.y = cvt_pk_bf16(a0[2], a0[3]); w.z = cvt_pk_bf16(a1[0], a1[1]); w.w = cvt_pk_bf16(a1[2], a1[3]);
;                     *(u32x4*)(rowp + u.pn * 256 + wcol) = w;
;                     w.x = cvt_pk_bf16(b0[0], b0[1]); w.y = cvt_pk_bf16(b0[2], b0[3]); w.z = cvt_pk_bf16(b1[0], b1[1]); w.w = cvt_pk_bf16(b1[2], b1[3]);
;                     *(u32x4*)(rowp + u.pn * 256 + 128 + wcol) = w;
;     ...
;                     if (u.pn < 6) { r0 = a0 * b0; r1 = a1 * b1; }
;                     else {
; #pragma unroll
;                         for (int j = 0; j < 4; ++j) { r0[j] = a0[j] * __builtin_amdgcn_rcpf(1.0f + __expf(-b0[j])); r1[j] = a1[j] * __builtin_amdgcn_rcpf(1.0f + __expf(-b1[j])); }
;                     }
;                     u32x4 w; w.x = cvt_pk_bf16(r0[0], r0[1]); w.y = cvt_pk_bf16(r0[2], r0[3]); w.z = cvt_pk_bf16(r1[0], r1[1]); w.w = cvt_pk_bf16(r1[2], r1[3]);
;                     *(u32x4*)(rowp + (u.pn < 6 ? 512 + (u.pn - 2) * 128 : 1024 + (u.pn - 6) * 128) + wcol) = w;
.LBB0_112:
	s_and_b64 vcc, exec, s[0:1]
	v_lshlrev_b32_e32 v136, 1, v138
	s_cbranch_vccz .LBB0_114
	s_lshl_b32 s0, s50, 8
	s_ashr_i32 s1, s0, 31
	v_cvt_pk_bf16_f32 v112, v154, v155
	v_cvt_pk_bf16_f32 v113, v126, v127
	v_cvt_pk_bf16_f32 v114, v152, v153
	v_cvt_pk_bf16_f32 v115, v124, v125
	v_lshl_add_u64 v[124:125], s[0:1], 1, v[150:151]
	v_lshl_add_u64 v[126:127], v[124:125], 0, v[136:137]
	v_lshl_add_u64 v[156:157], v[124:125], 0, s[84:85]
	global_store_dwordx4 v[126:127], v[112:115], off sc1
	s_nop 1
	v_cvt_pk_bf16_f32 v112, v122, v123
	v_cvt_pk_bf16_f32 v113, v118, v119
	v_cvt_pk_bf16_f32 v114, v120, v121
	v_cvt_pk_bf16_f32 v115, v116, v117
.LBB0_114:
	v_fmamk_f32 v116, v229, 0x3a800000, v164
	v_rsq_f32_e32 v118, v116
	v_lshl_add_u64 v[116:117], v[156:157], 0, v[136:137]
	v_or_b32_e32 v119, 16, v148
	global_store_dwordx4 v[116:117], v[112:115], off sc1
	v_pk_mul_f32 v[110:111], v[110:111], v[118:119] op_sel_hi:[1,0]
	v_pk_mul_f32 v[116:117], v[108:109], v[118:119] op_sel_hi:[1,0]
	v_mov_b64_e32 v[112:113], s[34:35]
	v_mad_i64_i32 v[112:113], s[0:1], v119, s64, v[112:113]
	v_pk_mul_f32 v[114:115], v[104:105], v[118:119] op_sel_hi:[1,0]
	v_pk_mul_f32 v[104:105], v[96:97], v[118:119] op_sel_hi:[1,0]
	v_cndmask_b32_e64 v96, 0, 1, s[94:95]
	v_pk_mul_f32 v[108:109], v[106:107], v[118:119] op_sel_hi:[1,0]
	v_pk_mul_f32 v[102:103], v[102:103], v[118:119] op_sel_hi:[1,0]
	v_pk_mul_f32 v[106:107], v[100:101], v[118:119] op_sel_hi:[1,0]
	v_pk_mul_f32 v[100:101], v[98:99], v[118:119] op_sel_hi:[1,0]
	v_cmp_ne_u32_e64 s[0:1], 1, v96
	s_andn2_b64 vcc, exec, s[94:95]
	s_mov_b64 s[28:29], -1
	s_cbranch_vccnz .LBB0_118
	s_cmp_lt_u32 s50, 6
	v_mov_b32_e32 v96, v106
	v_mov_b32_e32 v97, v107
	v_mov_b32_e32 v118, v102
	v_mov_b32_e32 v119, v103
	v_mov_b32_e32 v98, v104
	v_mov_b32_e32 v99, v105
	v_mov_b32_e32 v120, v100
	v_mov_b32_e32 v121, v101
	s_cbranch_scc1 .LBB0_117
	v_mul_f32_e32 v97, 0xbfb8aa3b, v104
	v_mul_f32_e32 v98, 0xbfb8aa3b, v107
	v_exp_f32_e32 v97, v97
	v_exp_f32_e32 v99, v98
	v_mul_f32_e32 v98, 0xbfb8aa3b, v105
	v_exp_f32_e32 v118, v98
	v_add_f32_e32 v97, 1.0, v97
	v_mul_f32_e32 v119, 0xbfb8aa3b, v100
	v_mul_f32_e32 v120, 0xbfb8aa3b, v103
	v_mul_f32_e32 v96, 0xbfb8aa3b, v106
	v_rcp_f32_e32 v98, v97
	v_add_f32_e32 v97, 1.0, v99
	v_add_f32_e32 v99, 1.0, v118
	v_mul_f32_e32 v118, 0xbfb8aa3b, v102
	v_exp_f32_e32 v119, v119
	v_exp_f32_e32 v121, v120
	v_mul_f32_e32 v120, 0xbfb8aa3b, v101
	v_exp_f32_e32 v96, v96
	v_exp_f32_e32 v118, v118
	v_exp_f32_e32 v122, v120
	v_add_f32_e32 v119, 1.0, v119
	v_add_f32_e32 v96, 1.0, v96
	v_add_f32_e32 v118, 1.0, v118
	v_rcp_f32_e32 v120, v119
	v_add_f32_e32 v119, 1.0, v121
	v_add_f32_e32 v121, 1.0, v122
	v_rcp_f32_e32 v96, v96
	v_rcp_f32_e32 v97, v97
	v_rcp_f32_e32 v99, v99
	v_rcp_f32_e32 v118, v118
	v_rcp_f32_e32 v119, v119
	v_rcp_f32_e32 v121, v121

; __device__ __forceinline__ unsigned cvt_pk_bf16(float lo, float hi) { unsigned r; asm volatile("v_cvt_pk_bf16_f32 %0, %1, %2" : "=v"(r) : "v"(lo), "v"(hi)); return r; }
;     __device__ __forceinline__ void operator()(const f32x4 (&acc)[2][2][4][2], const Unit& u, int wr, int wc, int fr, int fq) const {
;     ...
;             for (int m = 0; m < 4; ++m) rsv[ai][m] = __builtin_amdgcn_rsqf(rsv[ai][m] * (1.0f / 1024.0f) + RMS_EPS);
; #pragma unroll
;         for (int ai = 0; ai < 2; ++ai)
; #pragma unroll
;             for (int m = 0; m < 4; ++m) {
;                 const int row = row0 + ai * HALF + m * 16;
;                 const float rs = rsv[ai][m];
;                 bf16_t* rowp = O + (size_t)row * 1536;
;                 const f32x4 a0 = acc[ai][0][m][0] * rs, a1 = acc[ai][0][m][1] * rs, b0 = acc[ai][1][m][0] * rs, b1 = acc[ai][1][m][1] * rs;
;                 if (u.pn < 2) {
;                     u32x4 w; w.x = cvt_pk_bf16(a0[0], a0[1]); w.y = cvt_pk_bf16(a0[2], a0[3]); w.z = cvt_pk_bf16(a1[0], a1[1]); w.w = cvt_pk_bf16(a1[2], a1[3]);
;                     *(u32x4*)(rowp + u.pn * 256 + wcol) = w;
;                     w.x = cvt_pk_bf16(b0[0], b0[1]); w.y = cvt_pk_bf16(b0[2], b0[3]); w.z = cvt_pk_bf16(b1[0], b1[1]); w.w = cvt_pk_bf16(b1[2], b1[3]);
;                     *(u32x4*)(rowp + u.pn * 256 + 128 + wcol) = w;
;                 } else {
;                     f32x4 r0, r1;
;                     if (u.pn < 6) { r0 = a0 * b0; r1 = a1 * b1; }
;                     else {
; #pragma unroll
;                         for (int j = 0; j < 4; ++j) { r0[j] = a0[j] * __builtin_amdgcn_rcpf(1.0f + __expf(-b0[j])); r1[j] = a1[j] * __builtin_amdgcn_rcpf(1.0f + __expf(-b1[j])); }
;                     }
;                     u32x4 w; w.x = cvt_pk_bf16(r0[0], r0[1]); w.y = cvt_pk_bf16(r0[2], r0[3]); w.z = cvt_pk_bf16(r1[0], r1[1]); w.w = cvt_pk_bf16(r1[2], r1[3]);
;                     *(u32x4*)(rowp + (u.pn < 6 ? 512 + (u.pn - 2) * 128 : 1024 + (u.pn - 6) * 128) + wcol) = w;
.LBB0_118:
	s_and_b64 vcc, exec, s[28:29]
	s_cbranch_vccz .LBB0_120
	s_lshl_b32 s12, s50, 8
	s_ashr_i32 s13, s12, 31
	v_cvt_pk_bf16_f32 v96, v116, v117
	v_cvt_pk_bf16_f32 v97, v110, v111
	v_cvt_pk_bf16_f32 v98, v114, v115
	v_cvt_pk_bf16_f32 v99, v108, v109
	v_lshl_add_u64 v[108:109], s[12:13], 1, v[112:113]
	v_lshl_add_u64 v[110:111], v[108:109], 0, v[136:137]
	v_lshl_add_u64 v[118:119], v[108:109], 0, s[84:85]
	global_store_dwordx4 v[110:111], v[96:99], off sc1
	s_nop 1
	v_cvt_pk_bf16_f32 v96, v106, v107
	v_cvt_pk_bf16_f32 v97, v102, v103
	v_cvt_pk_bf16_f32 v98, v104, v105
	v_cvt_pk_bf16_f32 v99, v100, v101
.LBB0_120:
	v_fmamk_f32 v100, v230, 0x3a800000, v164
	v_rsq_f32_e32 v102, v100
	v_lshl_add_u64 v[100:101], v[118:119], 0, v[136:137]
	v_or_b32_e32 v103, 32, v148
	global_store_dwordx4 v[100:101], v[96:99], off sc1
	v_pk_mul_f32 v[94:95], v[94:95], v[102:103] op_sel_hi:[1,0]
	v_pk_mul_f32 v[100:101], v[92:93], v[102:103] op_sel_hi:[1,0]
	v_mov_b64_e32 v[96:97], s[34:35]
	v_mad_i64_i32 v[96:97], s[12:13], v103, s64, v[96:97]
	v_pk_mul_f32 v[92:93], v[90:91], v[102:103] op_sel_hi:[1,0]
	v_pk_mul_f32 v[98:99], v[88:89], v[102:103] op_sel_hi:[1,0]
	v_pk_mul_f32 v[86:87], v[86:87], v[102:103] op_sel_hi:[1,0]
	v_pk_mul_f32 v[90:91], v[84:85], v[102:103] op_sel_hi:[1,0]
	v_pk_mul_f32 v[84:85], v[82:83], v[102:103] op_sel_hi:[1,0]
	v_pk_mul_f32 v[88:89], v[80:81], v[102:103] op_sel_hi:[1,0]
	s_and_b64 vcc, exec, s[0:1]
	s_mov_b64 s[28:29], -1
	s_cbranch_vccnz .LBB0_124
	s_cmp_lt_u32 s50, 6
	v_mov_b32_e32 v80, v90
	v_mov_b32_e32 v81, v91
	v_mov_b32_e32 v102, v86
	v_mov_b32_e32 v103, v87
	v_mov_b32_e32 v82, v88
	v_mov_b32_e32 v83, v89
	v_mov_b32_e32 v104, v84
	v_mov_b32_e32 v105, v85
	s_cbranch_scc1 .LBB0_123
	v_mul_f32_e32 v81, 0xbfb8aa3b, v88
	v_mul_f32_e32 v82, 0xbfb8aa3b, v91
	v_exp_f32_e32 v81, v81
	v_exp_f32_e32 v83, v82
	v_mul_f32_e32 v82, 0xbfb8aa3b, v89
	v_exp_f32_e32 v102, v82
	v_add_f32_e32 v81, 1.0, v81
	v_mul_f32_e32 v103, 0xbfb8aa3b, v84
	v_mul_f32_e32 v104, 0xbfb8aa3b, v87
	v_mul_f32_e32 v80, 0xbfb8aa3b, v90
	v_rcp_f32_e32 v82, v81
	v_add_f32_e32 v81, 1.0, v83
	v_add_f32_e32 v83, 1.0, v102
	v_mul_f32_e32 v102, 0xbfb8aa3b, v86
	v_exp_f32_e32 v103, v103
	v_exp_f32_e32 v105, v104
	v_mul_f32_e32 v104, 0xbfb8aa3b, v85
	v_exp_f32_e32 v80, v80
	v_exp_f32_e32 v102, v102
	v_exp_f32_e32 v106, v104
	v_add_f32_e32 v103, 1.0, v103
	v_add_f32_e32 v80, 1.0, v80
	v_add_f32_e32 v102, 1.0, v102
	v_rcp_f32_e32 v104, v103
	v_add_f32_e32 v103, 1.0, v105
	v_add_f32_e32 v105, 1.0, v106
	v_rcp_f32_e32 v80, v80
	v_rcp_f32_e32 v81, v81
	v_rcp_f32_e32 v83, v83
	v_rcp_f32_e32 v102, v102
	v_rcp_f32_e32 v103, v103
	v_rcp_f32_e32 v105, v105

; __device__ __forceinline__ unsigned cvt_pk_bf16(float lo, float hi) { unsigned r; asm volatile("v_cvt_pk_bf16_f32 %0, %1, %2" : "=v"(r) : "v"(lo), "v"(hi)); return r; }
;     __device__ __forceinline__ void operator()(const f32x4 (&acc)[2][2][4][2], const Unit& u, int wr, int wc, int fr, int fq) const {
;     ...
;             for (int m = 0; m < 4; ++m) rsv[ai][m] = __builtin_amdgcn_rsqf(rsv[ai][m] * (1.0f / 1024.0f) + RMS_EPS);
; #pragma unroll
;         for (int ai = 0; ai < 2; ++ai)
; #pragma unroll
;             for (int m = 0; m < 4; ++m) {
;                 const int row = row0 + ai * HALF + m * 16;
;                 const float rs = rsv[ai][m];
;                 bf16_t* rowp = O + (size_t)row * 1536;
;                 const f32x4 a0 = acc[ai][0][m][0] * rs, a1 = acc[ai][0][m][1] * rs, b0 = acc[ai][1][m][0] * rs, b1 = acc[ai][1][m][1] * rs;
;                 if (u.pn < 2) {
;                     u32x4 w; w.x = cvt_pk_bf16(a0[0], a0[1]); w.y = cvt_pk_bf16(a0[2], a0[3]); w.z = cvt_pk_bf16(a1[0], a1[1]); w.w = cvt_pk_bf16(a1[2], a1[3]);
;                     *(u32x4*)(rowp + u.pn * 256 + wcol) = w;
;                     w.x = cvt_pk_bf16(b0[0], b0[1]); w.y = cvt_pk_bf16(b0[2], b0[3]); w.z = cvt_pk_bf16(b1[0], b1[1]); w.w = cvt_pk_bf16(b1[2], b1[3]);
;                     *(u32x4*)(rowp + u.pn * 256 + 128 + wcol) = w;
;                 } else {
;                     f32x4 r0, r1;
;                     if (u.pn < 6) { r0 = a0 * b0; r1 = a1 * b1; }
;                     else {
; #pragma unroll
;                         for (int j = 0; j < 4; ++j) { r0[j] = a0[j] * __builtin_amdgcn_rcpf(1.0f + __expf(-b0[j])); r1[j] = a1[j] * __builtin_amdgcn_rcpf(1.0f + __expf(-b1[j])); }
;                     }
;                     u32x4 w; w.x = cvt_pk_bf16(r0[0], r0[1]); w.y = cvt_pk_bf16(r0[2], r0[3]); w.z = cvt_pk_bf16(r1[0], r1[1]); w.w = cvt_pk_bf16(r1[2], r1[3]);
;                     *(u32x4*)(rowp + (u.pn < 6 ? 512 + (u.pn - 2) * 128 : 1024 + (u.pn - 6) * 128) + wcol) = w;
.LBB0_124:
	s_and_b64 vcc, exec, s[28:29]
	s_cbranch_vccz .LBB0_126
	s_lshl_b32 s12, s50, 8
	s_ashr_i32 s13, s12, 31
	v_cvt_pk_bf16_f32 v80, v100, v101
	v_cvt_pk_bf16_f32 v81, v94, v95
	v_cvt_pk_bf16_f32 v82, v98, v99
	v_cvt_pk_bf16_f32 v83, v92, v93
	v_lshl_add_u64 v[92:93], s[12:13], 1, v[96:97]
	v_lshl_add_u64 v[94:95], v[92:93], 0, v[136:137]
	v_lshl_add_u64 v[102:103], v[92:93], 0, s[84:85]
	global_store_dwordx4 v[94:95], v[80:83], off sc1
	s_nop 1
	v_cvt_pk_bf16_f32 v80, v90, v91
	v_cvt_pk_bf16_f32 v81, v86, v87
	v_cvt_pk_bf16_f32 v82, v88, v89
	v_cvt_pk_bf16_f32 v83, v84, v85
.LBB0_126:
	v_fmamk_f32 v84, v231, 0x3a800000, v164
	v_rsq_f32_e32 v86, v84
	v_lshl_add_u64 v[84:85], v[102:103], 0, v[136:137]
	v_or_b32_e32 v87, 48, v148
	global_store_dwordx4 v[84:85], v[80:83], off sc1
	v_pk_mul_f32 v[78:79], v[78:79], v[86:87] op_sel_hi:[1,0]
	v_pk_mul_f32 v[84:85], v[76:77], v[86:87] op_sel_hi:[1,0]
	v_mov_b64_e32 v[80:81], s[34:35]
	v_mad_i64_i32 v[80:81], s[12:13], v87, s64, v[80:81]
	v_pk_mul_f32 v[76:77], v[74:75], v[86:87] op_sel_hi:[1,0]
	v_pk_mul_f32 v[82:83], v[72:73], v[86:87] op_sel_hi:[1,0]
	v_pk_mul_f32 v[70:71], v[70:71], v[86:87] op_sel_hi:[1,0]
	v_pk_mul_f32 v[74:75], v[68:69], v[86:87] op_sel_hi:[1,0]
	v_pk_mul_f32 v[68:69], v[66:67], v[86:87] op_sel_hi:[1,0]
	v_pk_mul_f32 v[72:73], v[64:65], v[86:87] op_sel_hi:[1,0]
	s_and_b64 vcc, exec, s[0:1]
	s_mov_b64 s[28:29], -1
	s_cbranch_vccnz .LBB0_130
	s_cmp_lt_u32 s50, 6
	v_mov_b32_e32 v64, v74
	v_mov_b32_e32 v65, v75
	v_mov_b32_e32 v86, v70
	v_mov_b32_e32 v87, v71
	v_mov_b32_e32 v66, v72
	v_mov_b32_e32 v67, v73
	v_mov_b32_e32 v88, v68
	v_mov_b32_e32 v89, v69
	s_cbranch_scc1 .LBB0_129
	v_mul_f32_e32 v65, 0xbfb8aa3b, v72
	v_mul_f32_e32 v66, 0xbfb8aa3b, v75
	v_exp_f32_e32 v65, v65
	v_exp_f32_e32 v67, v66
	v_mul_f32_e32 v66, 0xbfb8aa3b, v73
	v_exp_f32_e32 v86, v66
	v_add_f32_e32 v65, 1.0, v65
	v_mul_f32_e32 v87, 0xbfb8aa3b, v68
	v_mul_f32_e32 v88, 0xbfb8aa3b, v71
	v_mul_f32_e32 v64, 0xbfb8aa3b, v74
	v_rcp_f32_e32 v66, v65
	v_add_f32_e32 v65, 1.0, v67
	v_add_f32_e32 v67, 1.0, v86
	v_mul_f32_e32 v86, 0xbfb8aa3b, v70
	v_exp_f32_e32 v87, v87
	v_exp_f32_e32 v89, v88
	v_mul_f32_e32 v88, 0xbfb8aa3b, v69
	v_exp_f32_e32 v64, v64
	v_exp_f32_e32 v86, v86
	v_exp_f32_e32 v90, v88
	v_add_f32_e32 v87, 1.0, v87
	v_add_f32_e32 v64, 1.0, v64
	v_add_f32_e32 v86, 1.0, v86
	v_rcp_f32_e32 v88, v87
	v_add_f32_e32 v87, 1.0, v89
	v_add_f32_e32 v89, 1.0, v90
	v_rcp_f32_e32 v64, v64
	v_rcp_f32_e32 v65, v65
	v_rcp_f32_e32 v67, v67
	v_rcp_f32_e32 v86, v86
	v_rcp_f32_e32 v87, v87
	v_rcp_f32_e32 v89, v89

; __device__ __forceinline__ unsigned cvt_pk_bf16(float lo, float hi) { unsigned r; asm volatile("v_cvt_pk_bf16_f32 %0, %1, %2" : "=v"(r) : "v"(lo), "v"(hi)); return r; }
;     __device__ __forceinline__ void operator()(const f32x4 (&acc)[2][2][4][2], const Unit& u, int wr, int wc, int fr, int fq) const {
;     ...
;             for (int m = 0; m < 4; ++m) rsv[ai][m] = __builtin_amdgcn_rsqf(rsv[ai][m] * (1.0f / 1024.0f) + RMS_EPS);
; #pragma unroll
;         for (int ai = 0; ai < 2; ++ai)
; #pragma unroll
;             for (int m = 0; m < 4; ++m) {
;                 const int row = row0 + ai * HALF + m * 16;
;                 const float rs = rsv[ai][m];
;                 bf16_t* rowp = O + (size_t)row * 1536;
;                 const f32x4 a0 = acc[ai][0][m][0] * rs, a1 = acc[ai][0][m][1] * rs, b0 = acc[ai][1][m][0] * rs, b1 = acc[ai][1][m][1] * rs;
;                 if (u.pn < 2) {
;                     u32x4 w; w.x = cvt_pk_bf16(a0[0], a0[1]); w.y = cvt_pk_bf16(a0[2], a0[3]); w.z = cvt_pk_bf16(a1[0], a1[1]); w.w = cvt_pk_bf16(a1[2], a1[3]);
;                     *(u32x4*)(rowp + u.pn * 256 + wcol) = w;
;                     w.x = cvt_pk_bf16(b0[0], b0[1]); w.y = cvt_pk_bf16(b0[2], b0[3]); w.z = cvt_pk_bf16(b1[0], b1[1]); w.w = cvt_pk_bf16(b1[2], b1[3]);
;                     *(u32x4*)(rowp + u.pn * 256 + 128 + wcol) = w;
;                 } else {
;                     f32x4 r0, r1;
;                     if (u.pn < 6) { r0 = a0 * b0; r1 = a1 * b1; }
;                     else {
; #pragma unroll
;                         for (int j = 0; j < 4; ++j) { r0[j] = a0[j] * __builtin_amdgcn_rcpf(1.0f + __expf(-b0[j])); r1[j] = a1[j] * __builtin_amdgcn_rcpf(1.0f + __expf(-b1[j])); }
;                     }
;                     u32x4 w; w.x = cvt_pk_bf16(r0[0], r0[1]); w.y = cvt_pk_bf16(r0[2], r0[3]); w.z = cvt_pk_bf16(r1[0], r1[1]); w.w = cvt_pk_bf16(r1[2], r1[3]);
;                     *(u32x4*)(rowp + (u.pn < 6 ? 512 + (u.pn - 2) * 128 : 1024 + (u.pn - 6) * 128) + wcol) = w;
.LBB0_130:
	s_and_b64 vcc, exec, s[28:29]
	s_cbranch_vccz .LBB0_132
	s_lshl_b32 s12, s50, 8
	s_ashr_i32 s13, s12, 31
	v_cvt_pk_bf16_f32 v64, v84, v85
	v_cvt_pk_bf16_f32 v65, v78, v79
	v_cvt_pk_bf16_f32 v66, v82, v83
	v_cvt_pk_bf16_f32 v67, v76, v77
	v_lshl_add_u64 v[76:77], s[12:13], 1, v[80:81]
	v_lshl_add_u64 v[78:79], v[76:77], 0, v[136:137]
	v_lshl_add_u64 v[86:87], v[76:77], 0, s[84:85]
	global_store_dwordx4 v[78:79], v[64:67], off sc1
	s_nop 1
	v_cvt_pk_bf16_f32 v64, v74, v75
	v_cvt_pk_bf16_f32 v65, v70, v71
	v_cvt_pk_bf16_f32 v66, v72, v73
	v_cvt_pk_bf16_f32 v67, v68, v69
.LBB0_132:
	v_fmamk_f32 v68, v232, 0x3a800000, v164
	v_rsq_f32_e32 v70, v68
	v_lshl_add_u64 v[68:69], v[86:87], 0, v[136:137]
	v_add_u32_e32 v71, 0x80, v148
	global_store_dwordx4 v[68:69], v[64:67], off sc1
	v_pk_mul_f32 v[62:63], v[62:63], v[70:71] op_sel_hi:[1,0]
	v_pk_mul_f32 v[68:69], v[60:61], v[70:71] op_sel_hi:[1,0]
	v_mov_b64_e32 v[64:65], s[34:35]
	v_mad_i64_i32 v[64:65], s[12:13], v71, s64, v[64:65]
	v_pk_mul_f32 v[60:61], v[58:59], v[70:71] op_sel_hi:[1,0]
	v_pk_mul_f32 v[66:67], v[56:57], v[70:71] op_sel_hi:[1,0]
	v_pk_mul_f32 v[54:55], v[54:55], v[70:71] op_sel_hi:[1,0]
	v_pk_mul_f32 v[58:59], v[52:53], v[70:71] op_sel_hi:[1,0]
	v_pk_mul_f32 v[52:53], v[50:51], v[70:71] op_sel_hi:[1,0]
	v_pk_mul_f32 v[56:57], v[48:49], v[70:71] op_sel_hi:[1,0]
	s_and_b64 vcc, exec, s[0:1]
	s_mov_b64 s[28:29], -1
	s_cbranch_vccnz .LBB0_136
	s_cmp_lt_u32 s50, 6
	v_mov_b32_e32 v48, v58
	v_mov_b32_e32 v49, v59
	v_mov_b32_e32 v70, v54
	v_mov_b32_e32 v71, v55
	v_mov_b32_e32 v50, v56
	v_mov_b32_e32 v51, v57
	v_mov_b32_e32 v72, v52
	v_mov_b32_e32 v73, v53
	s_cbranch_scc1 .LBB0_135
	v_mul_f32_e32 v49, 0xbfb8aa3b, v56
	v_mul_f32_e32 v50, 0xbfb8aa3b, v59
	v_exp_f32_e32 v49, v49
	v_exp_f32_e32 v51, v50
	v_mul_f32_e32 v50, 0xbfb8aa3b, v57
	v_exp_f32_e32 v70, v50
	v_add_f32_e32 v49, 1.0, v49
	v_mul_f32_e32 v71, 0xbfb8aa3b, v52
	v_mul_f32_e32 v72, 0xbfb8aa3b, v55
	v_mul_f32_e32 v48, 0xbfb8aa3b, v58
	v_rcp_f32_e32 v50, v49
	v_add_f32_e32 v49, 1.0, v51
	v_add_f32_e32 v51, 1.0, v70
	v_mul_f32_e32 v70, 0xbfb8aa3b, v54
	v_exp_f32_e32 v71, v71
	v_exp_f32_e32 v73, v72
	v_mul_f32_e32 v72, 0xbfb8aa3b, v53
	v_exp_f32_e32 v48, v48
	v_exp_f32_e32 v70, v70
	v_exp_f32_e32 v74, v72
	v_add_f32_e32 v71, 1.0, v71
	v_add_f32_e32 v48, 1.0, v48
	v_add_f32_e32 v70, 1.0, v70
	v_rcp_f32_e32 v72, v71
	v_add_f32_e32 v71, 1.0, v73
	v_add_f32_e32 v73, 1.0, v74
	v_rcp_f32_e32 v48, v48
	v_rcp_f32_e32 v49, v49
	v_rcp_f32_e32 v51, v51
	v_rcp_f32_e32 v70, v70
	v_rcp_f32_e32 v71, v71
	v_rcp_f32_e32 v73, v73

; __device__ __forceinline__ unsigned cvt_pk_bf16(float lo, float hi) { unsigned r; asm volatile("v_cvt_pk_bf16_f32 %0, %1, %2" : "=v"(r) : "v"(lo), "v"(hi)); return r; }
;     __device__ __forceinline__ void operator()(const f32x4 (&acc)[2][2][4][2], const Unit& u, int wr, int wc, int fr, int fq) const {
;     ...
;             for (int m = 0; m < 4; ++m) rsv[ai][m] = __builtin_amdgcn_rsqf(rsv[ai][m] * (1.0f / 1024.0f) + RMS_EPS);
; #pragma unroll
;         for (int ai = 0; ai < 2; ++ai)
; #pragma unroll
;             for (int m = 0; m < 4; ++m) {
;                 const int row = row0 + ai * HALF + m * 16;
;                 const float rs = rsv[ai][m];
;                 bf16_t* rowp = O + (size_t)row * 1536;
;                 const f32x4 a0 = acc[ai][0][m][0] * rs, a1 = acc[ai][0][m][1] * rs, b0 = acc[ai][1][m][0] * rs, b1 = acc[ai][1][m][1] * rs;
;                 if (u.pn < 2) {
;                     u32x4 w; w.x = cvt_pk_bf16(a0[0], a0[1]); w.y = cvt_pk_bf16(a0[2], a0[3]); w.z = cvt_pk_bf16(a1[0], a1[1]); w.w = cvt_pk_bf16(a1[2], a1[3]);
;                     *(u32x4*)(rowp + u.pn * 256 + wcol) = w;
;                     w.x = cvt_pk_bf16(b0[0], b0[1]); w.y = cvt_pk_bf16(b0[2], b0[3]); w.z = cvt_pk_bf16(b1[0], b1[1]); w.w = cvt_pk_bf16(b1[2], b1[3]);
;                     *(u32x4*)(rowp + u.pn * 256 + 128 + wcol) = w;
;                 } else {
;                     f32x4 r0, r1;
;                     if (u.pn < 6) { r0 = a0 * b0; r1 = a1 * b1; }
;                     else {
; #pragma unroll
;                         for (int j = 0; j < 4; ++j) { r0[j] = a0[j] * __builtin_amdgcn_rcpf(1.0f + __expf(-b0[j])); r1[j] = a1[j] * __builtin_amdgcn_rcpf(1.0f + __expf(-b1[j])); }
;                     }
;                     u32x4 w; w.x = cvt_pk_bf16(r0[0], r0[1]); w.y = cvt_pk_bf16(r0[2], r0[3]); w.z = cvt_pk_bf16(r1[0], r1[1]); w.w = cvt_pk_bf16(r1[2], r1[3]);
;                     *(u32x4*)(rowp + (u.pn < 6 ? 512 + (u.pn - 2) * 128 : 1024 + (u.pn - 6) * 128) + wcol) = w;
.LBB0_136:
	s_and_b64 vcc, exec, s[28:29]
	s_cbranch_vccz .LBB0_138
	s_lshl_b32 s12, s50, 8
	s_ashr_i32 s13, s12, 31
	v_cvt_pk_bf16_f32 v48, v68, v69
	v_cvt_pk_bf16_f32 v49, v62, v63
	v_cvt_pk_bf16_f32 v50, v66, v67
	v_cvt_pk_bf16_f32 v51, v60, v61
	v_lshl_add_u64 v[60:61], s[12:13], 1, v[64:65]
	v_lshl_add_u64 v[62:63], v[60:61], 0, v[136:137]
	v_lshl_add_u64 v[70:71], v[60:61], 0, s[84:85]
	global_store_dwordx4 v[62:63], v[48:51], off sc1
	s_nop 1
	v_cvt_pk_bf16_f32 v48, v58, v59
	v_cvt_pk_bf16_f32 v49, v54, v55
	v_cvt_pk_bf16_f32 v50, v56, v57
	v_cvt_pk_bf16_f32 v51, v52, v53
.LBB0_138:
	v_fmamk_f32 v52, v233, 0x3a800000, v164
	v_rsq_f32_e32 v54, v52
	v_lshl_add_u64 v[52:53], v[70:71], 0, v[136:137]
	v_add_u32_e32 v55, 0x90, v148
	global_store_dwordx4 v[52:53], v[48:51], off sc1
	v_pk_mul_f32 v[46:47], v[46:47], v[54:55] op_sel_hi:[1,0]
	v_pk_mul_f32 v[52:53], v[44:45], v[54:55] op_sel_hi:[1,0]
	v_mov_b64_e32 v[48:49], s[34:35]
	v_mad_i64_i32 v[48:49], s[12:13], v55, s64, v[48:49]
	v_pk_mul_f32 v[44:45], v[42:43], v[54:55] op_sel_hi:[1,0]
	v_pk_mul_f32 v[50:51], v[40:41], v[54:55] op_sel_hi:[1,0]
	v_pk_mul_f32 v[38:39], v[38:39], v[54:55] op_sel_hi:[1,0]
	v_pk_mul_f32 v[42:43], v[36:37], v[54:55] op_sel_hi:[1,0]
	v_pk_mul_f32 v[36:37], v[34:35], v[54:55] op_sel_hi:[1,0]
	v_pk_mul_f32 v[40:41], v[32:33], v[54:55] op_sel_hi:[1,0]
	s_and_b64 vcc, exec, s[0:1]
	s_mov_b64 s[28:29], -1
	s_cbranch_vccnz .LBB0_142
	s_cmp_lt_u32 s50, 6
	v_mov_b32_e32 v32, v42
	v_mov_b32_e32 v33, v43
	v_mov_b32_e32 v54, v38
	v_mov_b32_e32 v55, v39
	v_mov_b32_e32 v34, v40
	v_mov_b32_e32 v35, v41
	v_mov_b32_e32 v56, v36
	v_mov_b32_e32 v57, v37
	s_cbranch_scc1 .LBB0_141
	v_mul_f32_e32 v33, 0xbfb8aa3b, v40
	v_mul_f32_e32 v34, 0xbfb8aa3b, v43
	v_exp_f32_e32 v33, v33
	v_exp_f32_e32 v35, v34
	v_mul_f32_e32 v34, 0xbfb8aa3b, v41
	v_exp_f32_e32 v54, v34
	v_add_f32_e32 v33, 1.0, v33
	v_mul_f32_e32 v55, 0xbfb8aa3b, v36
	v_mul_f32_e32 v56, 0xbfb8aa3b, v39
	v_mul_f32_e32 v32, 0xbfb8aa3b, v42
	v_rcp_f32_e32 v34, v33
	v_add_f32_e32 v33, 1.0, v35
	v_add_f32_e32 v35, 1.0, v54
	v_mul_f32_e32 v54, 0xbfb8aa3b, v38
	v_exp_f32_e32 v55, v55
	v_exp_f32_e32 v57, v56
	v_mul_f32_e32 v56, 0xbfb8aa3b, v37
	v_exp_f32_e32 v32, v32
	v_exp_f32_e32 v54, v54
	v_exp_f32_e32 v58, v56
	v_add_f32_e32 v55, 1.0, v55
	v_add_f32_e32 v32, 1.0, v32
	v_add_f32_e32 v54, 1.0, v54
	v_rcp_f32_e32 v56, v55
	v_add_f32_e32 v55, 1.0, v57
	v_add_f32_e32 v57, 1.0, v58
	v_rcp_f32_e32 v32, v32
	v_rcp_f32_e32 v33, v33
	v_rcp_f32_e32 v35, v35
	v_rcp_f32_e32 v54, v54
	v_rcp_f32_e32 v55, v55
	v_rcp_f32_e32 v57, v57

; __device__ __forceinline__ unsigned cvt_pk_bf16(float lo, float hi) { unsigned r; asm volatile("v_cvt_pk_bf16_f32 %0, %1, %2" : "=v"(r) : "v"(lo), "v"(hi)); return r; }
;     __device__ __forceinline__ void operator()(const f32x4 (&acc)[2][2][4][2], const Unit& u, int wr, int wc, int fr, int fq) const {
;     ...
;             for (int m = 0; m < 4; ++m) rsv[ai][m] = __builtin_amdgcn_rsqf(rsv[ai][m] * (1.0f / 1024.0f) + RMS_EPS);
; #pragma unroll
;         for (int ai = 0; ai < 2; ++ai)
; #pragma unroll
;             for (int m = 0; m < 4; ++m) {
;                 const int row = row0 + ai * HALF + m * 16;
;                 const float rs = rsv[ai][m];
;                 bf16_t* rowp = O + (size_t)row * 1536;
;                 const f32x4 a0 = acc[ai][0][m][0] * rs, a1 = acc[ai][0][m][1] * rs, b0 = acc[ai][1][m][0] * rs, b1 = acc[ai][1][m][1] * rs;
;                 if (u.pn < 2) {
;                     u32x4 w; w.x = cvt_pk_bf16(a0[0], a0[1]); w.y = cvt_pk_bf16(a0[2], a0[3]); w.z = cvt_pk_bf16(a1[0], a1[1]); w.w = cvt_pk_bf16(a1[2], a1[3]);
;                     *(u32x4*)(rowp + u.pn * 256 + wcol) = w;
;                     w.x = cvt_pk_bf16(b0[0], b0[1]); w.y = cvt_pk_bf16(b0[2], b0[3]); w.z = cvt_pk_bf16(b1[0], b1[1]); w.w = cvt_pk_bf16(b1[2], b1[3]);
;                     *(u32x4*)(rowp + u.pn * 256 + 128 + wcol) = w;
;                 } else {
;                     f32x4 r0, r1;
;                     if (u.pn < 6) { r0 = a0 * b0; r1 = a1 * b1; }
;                     else {
; #pragma unroll
;                         for (int j = 0; j < 4; ++j) { r0[j] = a0[j] * __builtin_amdgcn_rcpf(1.0f + __expf(-b0[j])); r1[j] = a1[j] * __builtin_amdgcn_rcpf(1.0f + __expf(-b1[j])); }
;                     }
;                     u32x4 w; w.x = cvt_pk_bf16(r0[0], r0[1]); w.y = cvt_pk_bf16(r0[2], r0[3]); w.z = cvt_pk_bf16(r1[0], r1[1]); w.w = cvt_pk_bf16(r1[2], r1[3]);
;                     *(u32x4*)(rowp + (u.pn < 6 ? 512 + (u.pn - 2) * 128 : 1024 + (u.pn - 6) * 128) + wcol) = w;
.LBB0_142:
	s_and_b64 vcc, exec, s[28:29]
	s_cbranch_vccz .LBB0_144
	s_lshl_b32 s12, s50, 8
	s_ashr_i32 s13, s12, 31
	v_cvt_pk_bf16_f32 v32, v52, v53
	v_cvt_pk_bf16_f32 v33, v46, v47
	v_cvt_pk_bf16_f32 v34, v50, v51
	v_cvt_pk_bf16_f32 v35, v44, v45
	v_lshl_add_u64 v[44:45], s[12:13], 1, v[48:49]
	v_lshl_add_u64 v[46:47], v[44:45], 0, v[136:137]
	v_lshl_add_u64 v[54:55], v[44:45], 0, s[84:85]
	global_store_dwordx4 v[46:47], v[32:35], off sc1
	s_nop 1
	v_cvt_pk_bf16_f32 v32, v42, v43
	v_cvt_pk_bf16_f32 v33, v38, v39
	v_cvt_pk_bf16_f32 v34, v40, v41
	v_cvt_pk_bf16_f32 v35, v36, v37
.LBB0_144:
	v_fmamk_f32 v36, v234, 0x3a800000, v164
	v_rsq_f32_e32 v38, v36
	v_lshl_add_u64 v[36:37], v[54:55], 0, v[136:137]
	v_add_u32_e32 v39, 0xa0, v148
	global_store_dwordx4 v[36:37], v[32:35], off sc1
	v_pk_mul_f32 v[30:31], v[30:31], v[38:39] op_sel_hi:[1,0]
	v_pk_mul_f32 v[36:37], v[28:29], v[38:39] op_sel_hi:[1,0]
	v_mov_b64_e32 v[32:33], s[34:35]
	v_mad_i64_i32 v[32:33], s[12:13], v39, s64, v[32:33]
	v_pk_mul_f32 v[28:29], v[26:27], v[38:39] op_sel_hi:[1,0]
	v_pk_mul_f32 v[34:35], v[24:25], v[38:39] op_sel_hi:[1,0]
	v_pk_mul_f32 v[22:23], v[22:23], v[38:39] op_sel_hi:[1,0]
	v_pk_mul_f32 v[26:27], v[20:21], v[38:39] op_sel_hi:[1,0]
	v_pk_mul_f32 v[20:21], v[18:19], v[38:39] op_sel_hi:[1,0]
	v_pk_mul_f32 v[24:25], v[16:17], v[38:39] op_sel_hi:[1,0]
	s_and_b64 vcc, exec, s[0:1]
	s_mov_b64 s[28:29], -1
	s_cbranch_vccnz .LBB0_148
	s_cmp_lt_u32 s50, 6
	v_mov_b32_e32 v16, v26
	v_mov_b32_e32 v17, v27
	v_mov_b32_e32 v38, v22
	v_mov_b32_e32 v39, v23
	v_mov_b32_e32 v18, v24
	v_mov_b32_e32 v19, v25
	v_mov_b32_e32 v40, v20
	v_mov_b32_e32 v41, v21
	s_cbranch_scc1 .LBB0_147
	v_mul_f32_e32 v17, 0xbfb8aa3b, v24
	v_mul_f32_e32 v18, 0xbfb8aa3b, v27
	v_exp_f32_e32 v17, v17
	v_exp_f32_e32 v19, v18
	v_mul_f32_e32 v18, 0xbfb8aa3b, v25
	v_exp_f32_e32 v38, v18
	v_add_f32_e32 v17, 1.0, v17
	v_mul_f32_e32 v39, 0xbfb8aa3b, v20
	v_mul_f32_e32 v40, 0xbfb8aa3b, v23
	v_mul_f32_e32 v16, 0xbfb8aa3b, v26
	v_rcp_f32_e32 v18, v17
	v_add_f32_e32 v17, 1.0, v19
	v_add_f32_e32 v19, 1.0, v38
	v_mul_f32_e32 v38, 0xbfb8aa3b, v22
	v_exp_f32_e32 v39, v39
	v_exp_f32_e32 v41, v40
	v_mul_f32_e32 v40, 0xbfb8aa3b, v21
	v_exp_f32_e32 v16, v16
	v_exp_f32_e32 v38, v38
	v_exp_f32_e32 v42, v40
	v_add_f32_e32 v39, 1.0, v39
	v_add_f32_e32 v16, 1.0, v16
	v_add_f32_e32 v38, 1.0, v38
	v_rcp_f32_e32 v40, v39
	v_add_f32_e32 v39, 1.0, v41
	v_add_f32_e32 v41, 1.0, v42
	v_rcp_f32_e32 v16, v16
	v_rcp_f32_e32 v17, v17
	v_rcp_f32_e32 v19, v19
	v_rcp_f32_e32 v38, v38
	v_rcp_f32_e32 v39, v39
	v_rcp_f32_e32 v41, v41

; __device__ __forceinline__ unsigned cvt_pk_bf16(float lo, float hi) { unsigned r; asm volatile("v_cvt_pk_bf16_f32 %0, %1, %2" : "=v"(r) : "v"(lo), "v"(hi)); return r; }
;     __device__ __forceinline__ void operator()(const f32x4 (&acc)[2][2][4][2], const Unit& u, int wr, int wc, int fr, int fq) const {
;     ...
;             for (int m = 0; m < 4; ++m) rsv[ai][m] = __builtin_amdgcn_rsqf(rsv[ai][m] * (1.0f / 1024.0f) + RMS_EPS);
; #pragma unroll
;         for (int ai = 0; ai < 2; ++ai)
; #pragma unroll
;             for (int m = 0; m < 4; ++m) {
;                 const int row = row0 + ai * HALF + m * 16;
;                 const float rs = rsv[ai][m];
;                 bf16_t* rowp = O + (size_t)row * 1536;
;                 const f32x4 a0 = acc[ai][0][m][0] * rs, a1 = acc[ai][0][m][1] * rs, b0 = acc[ai][1][m][0] * rs, b1 = acc[ai][1][m][1] * rs;
;                 if (u.pn < 2) {
;                     u32x4 w; w.x = cvt_pk_bf16(a0[0], a0[1]); w.y = cvt_pk_bf16(a0[2], a0[3]); w.z = cvt_pk_bf16(a1[0], a1[1]); w.w = cvt_pk_bf16(a1[2], a1[3]);
;                     *(u32x4*)(rowp + u.pn * 256 + wcol) = w;
;                     w.x = cvt_pk_bf16(b0[0], b0[1]); w.y = cvt_pk_bf16(b0[2], b0[3]); w.z = cvt_pk_bf16(b1[0], b1[1]); w.w = cvt_pk_bf16(b1[2], b1[3]);
;                     *(u32x4*)(rowp + u.pn * 256 + 128 + wcol) = w;
;                 } else {
;                     f32x4 r0, r1;
;                     if (u.pn < 6) { r0 = a0 * b0; r1 = a1 * b1; }
;                     else {
; #pragma unroll
;                         for (int j = 0; j < 4; ++j) { r0[j] = a0[j] * __builtin_amdgcn_rcpf(1.0f + __expf(-b0[j])); r1[j] = a1[j] * __builtin_amdgcn_rcpf(1.0f + __expf(-b1[j])); }
;                     }
;                     u32x4 w; w.x = cvt_pk_bf16(r0[0], r0[1]); w.y = cvt_pk_bf16(r0[2], r0[3]); w.z = cvt_pk_bf16(r1[0], r1[1]); w.w = cvt_pk_bf16(r1[2], r1[3]);
;                     *(u32x4*)(rowp + (u.pn < 6 ? 512 + (u.pn - 2) * 128 : 1024 + (u.pn - 6) * 128) + wcol) = w;
.LBB0_148:
	s_and_b64 vcc, exec, s[28:29]
	s_cbranch_vccz .LBB0_150
	s_lshl_b32 s12, s50, 8
	s_ashr_i32 s13, s12, 31
	v_cvt_pk_bf16_f32 v16, v36, v37
	v_cvt_pk_bf16_f32 v17, v30, v31
	v_cvt_pk_bf16_f32 v18, v34, v35
	v_cvt_pk_bf16_f32 v19, v28, v29
	v_lshl_add_u64 v[28:29], s[12:13], 1, v[32:33]
	v_lshl_add_u64 v[30:31], v[28:29], 0, v[136:137]
	v_lshl_add_u64 v[38:39], v[28:29], 0, s[84:85]
	global_store_dwordx4 v[30:31], v[16:19], off sc1
	s_nop 1
	v_cvt_pk_bf16_f32 v16, v26, v27
	v_cvt_pk_bf16_f32 v17, v22, v23
	v_cvt_pk_bf16_f32 v18, v24, v25
	v_cvt_pk_bf16_f32 v19, v20, v21
.LBB0_150:
	v_fmamk_f32 v20, v235, 0x3a800000, v164
	v_rsq_f32_e32 v22, v20
	v_lshl_add_u64 v[20:21], v[38:39], 0, v[136:137]
	v_add_u32_e32 v23, 0xb0, v148
	global_store_dwordx4 v[20:21], v[16:19], off sc1
	v_pk_mul_f32 v[14:15], v[14:15], v[22:23] op_sel_hi:[1,0]
	v_pk_mul_f32 v[20:21], v[12:13], v[22:23] op_sel_hi:[1,0]
	v_mov_b64_e32 v[16:17], s[34:35]
	v_mad_i64_i32 v[16:17], s[12:13], v23, s64, v[16:17]
	v_pk_mul_f32 v[12:13], v[10:11], v[22:23] op_sel_hi:[1,0]
	v_pk_mul_f32 v[18:19], v[8:9], v[22:23] op_sel_hi:[1,0]
	v_pk_mul_f32 v[6:7], v[6:7], v[22:23] op_sel_hi:[1,0]
	v_pk_mul_f32 v[10:11], v[4:5], v[22:23] op_sel_hi:[1,0]
	v_pk_mul_f32 v[4:5], v[2:3], v[22:23] op_sel_hi:[1,0]
	v_pk_mul_f32 v[8:9], v[0:1], v[22:23] op_sel_hi:[1,0]
	s_and_b64 vcc, exec, s[0:1]
	s_mov_b64 s[0:1], -1
	s_cbranch_vccnz .LBB0_154
	s_cmp_lt_u32 s50, 6
	v_mov_b32_e32 v0, v10
	v_mov_b32_e32 v1, v11
	v_mov_b32_e32 v22, v6
	v_mov_b32_e32 v23, v7
	v_mov_b32_e32 v2, v8
	v_mov_b32_e32 v3, v9
	v_mov_b32_e32 v24, v4
	v_mov_b32_e32 v25, v5
	s_cbranch_scc1 .LBB0_153
	v_mul_f32_e32 v1, 0xbfb8aa3b, v8
	v_mul_f32_e32 v2, 0xbfb8aa3b, v11
	v_exp_f32_e32 v1, v1
	v_exp_f32_e32 v3, v2
	v_mul_f32_e32 v2, 0xbfb8aa3b, v9
	v_exp_f32_e32 v22, v2
	v_add_f32_e32 v1, 1.0, v1
	v_mul_f32_e32 v23, 0xbfb8aa3b, v4
	v_mul_f32_e32 v24, 0xbfb8aa3b, v7
	v_mul_f32_e32 v0, 0xbfb8aa3b, v10
	v_rcp_f32_e32 v2, v1
	v_add_f32_e32 v1, 1.0, v3
	v_add_f32_e32 v3, 1.0, v22
	v_mul_f32_e32 v22, 0xbfb8aa3b, v6
	v_exp_f32_e32 v23, v23
	v_exp_f32_e32 v25, v24
	v_mul_f32_e32 v24, 0xbfb8aa3b, v5
	v_exp_f32_e32 v0, v0
	v_exp_f32_e32 v22, v22
	v_exp_f32_e32 v26, v24
	v_add_f32_e32 v23, 1.0, v23
	v_add_f32_e32 v0, 1.0, v0
	v_add_f32_e32 v22, 1.0, v22
	v_rcp_f32_e32 v24, v23
	v_add_f32_e32 v23, 1.0, v25
	v_add_f32_e32 v25, 1.0, v26
	v_rcp_f32_e32 v0, v0
	v_rcp_f32_e32 v1, v1
	v_rcp_f32_e32 v3, v3
	v_rcp_f32_e32 v22, v22
	v_rcp_f32_e32 v23, v23
	v_rcp_f32_e32 v25, v25

; __device__ __forceinline__ unsigned cvt_pk_bf16(float lo, float hi) { unsigned r; asm volatile("v_cvt_pk_bf16_f32 %0, %1, %2" : "=v"(r) : "v"(lo), "v"(hi)); return r; }
; #define PG8_BAR __builtin_amdgcn_s_barrier()
;     __device__ __forceinline__ void operator()(const f32x4 (&acc)[2][2][4][2], const Unit& u, int wr, int wc, int fr, int fq) const {
;     ...
;                     u32x4 w; w.x = cvt_pk_bf16(a0[0], a0[1]); w.y = cvt_pk_bf16(a0[2], a0[3]); w.z = cvt_pk_bf16(a1[0], a1[1]); w.w = cvt_pk_bf16(a1[2], a1[3]);
;                     *(u32x4*)(rowp + u.pn * 256 + wcol) = w;
;                     w.x = cvt_pk_bf16(b0[0], b0[1]); w.y = cvt_pk_bf16(b0[2], b0[3]); w.z = cvt_pk_bf16(b1[0], b1[1]); w.w = cvt_pk_bf16(b1[2], b1[3]);
;                     *(u32x4*)(rowp + u.pn * 256 + 128 + wcol) = w;
; template <class Epi, class Sched, bool ALIGN_EPI = false, bool SP2 = false>
; __device__ __forceinline__ void gemm_phase(PG8_LAS unsigned char* lds, const Gemm g, const Sched& S, const Epi& E) {
;     ...
;         if (!has_next) break;
; #pragma unroll
;         for (int a = 0; a < 2; ++a)
; #pragma unroll
;             for (int b = 0; b < 2; ++b)
; #pragma unroll
;                 for (int m = 0; m < 4; ++m)
; #pragma unroll
;                     for (int n = 0; n < 2; ++n) acc[a][b][m][n] = (f32x4){0.f, 0.f, 0.f, 0.f};
;         cur = nxt; cA = nA; cB = nB; ++ui;
;         if constexpr (ALIGN_EPI) { if (wr == 1) PG8_BAR; }
.LBB0_154:
	s_and_b64 vcc, exec, s[0:1]
	s_cbranch_vccz .LBB0_156
	s_lshl_b32 s0, s50, 8
	s_ashr_i32 s1, s0, 31
	v_cvt_pk_bf16_f32 v0, v20, v21
	v_cvt_pk_bf16_f32 v1, v14, v15
	v_cvt_pk_bf16_f32 v2, v18, v19
	v_cvt_pk_bf16_f32 v3, v12, v13
	v_lshl_add_u64 v[12:13], s[0:1], 1, v[16:17]
	v_lshl_add_u64 v[14:15], v[12:13], 0, v[136:137]
	v_lshl_add_u64 v[22:23], v[12:13], 0, s[84:85]
	global_store_dwordx4 v[14:15], v[0:3], off sc1
	s_nop 1
	v_cvt_pk_bf16_f32 v0, v10, v11
	v_cvt_pk_bf16_f32 v1, v6, v7
	v_cvt_pk_bf16_f32 v2, v8, v9
	v_cvt_pk_bf16_f32 v3, v4, v5
.LBB0_156:
	v_lshl_add_u64 v[4:5], v[22:23], 0, v[136:137]
	s_andn2_b64 vcc, exec, s[2:3]
	s_mov_b64 s[0:1], -1
	global_store_dwordx4 v[4:5], v[0:3], off sc1
	s_cbranch_vccnz .LBB0_101
	s_andn2_b64 vcc, exec, s[78:79]
	s_cbranch_vccnz .LBB0_100
	s_barrier
	s_branch .LBB0_100

; #define PG8_STAGE(bufoff, gbase, voff) do { _Pragma("unroll") for (int _i = 0; _i < 2; ++_i) \
;         __builtin_amdgcn_global_load_lds((const unsigned*)((const char*)(gbase) + (voff)[_i]), (PG8_LAS unsigned*)(lds + (bufoff) + ldsw + _i * 8192), 16, 0, 0); } while (0)
; #define PG8_WAIT_V(n) asm volatile("s_waitcnt vmcnt(" #n ")" ::: "memory")
; template <class Epi, class Sched, bool ALIGN_EPI = false, bool SP2 = false>
; __device__ __forceinline__ void gemm_phase(PG8_LAS unsigned char* lds, const Gemm g, const Sched& S, const Epi& E) {
;     ...
;     for (int i = 0; i < 2; ++i) { int R, C; stage_rc(tid * 16 + i * 8192, R, C); const int Rb = Epi::PERM ? ((R & ~31) + perm32(R & 31)) : R;
;         voffA[i] = g.asub ? (unsigned)((C >> 5) * 16384 + (R * 32 + (C & 31)) * 2) : (unsigned)(R * g.lda + C) * 2u; voffB[i] = (unsigned)(Rb * K + C) * 2u; }
;     const size_t kstep = (size_t)(BK * 2);
;     const size_t hstepB = (size_t)HALF * K * 2, hstepA = (size_t)HALF * g.lda * 2;
;     const size_t tstepB = 2 * hstepB, tstepA = g.tstepA; const size_t kstepA = g.kstepA;
;     const unsigned ldsw = (unsigned)wid * 1024u;
;     const int aoff = lds_byte(wr * 64 + fr, fq * 8), boff = lds_byte(wc * 32 + fr, fq * 8);
;     ...
;     const char* cA = (const char*)g.A + (size_t)cur.pm * tstepA + (size_t)(cur.k0 >> 6) * kstepA + (cur.qa > 0 ? hstepA : (size_t)0); const char* cB = (const char*)g.Bt + (size_t)cur.pn * tstepB + (size_t)cur.k0 * 2 + (cur.qb > 0 ? hstepB : (size_t)0);
;     S.a_ready(cur);
;     if constexpr (SP2) {
;         PG8_STAGE(PG8_SB(0, 0), cB, voffB); PG8_STAGE(PG8_SB(0, 1), cB + hstepB, voffB); PG8_STAGE(PG8_SA(0, 0), cA, voffA); PG8_STAGE(PG8_SA(0, 1), cA + hstepA, voffA);
;         if (wr == 1) PG8_BAR;
;         PG8_WAIT_V(2); PG8_BAR;
;         PG8_STAGE(PG8_SB(1, 0), cB + kstep, voffB); PG8_STAGE(PG8_SA(1, 0), cA + kstepA, voffA); PG8_STAGE(PG8_SB(1, 1), cB + hstepB + kstep, voffB);
;         PG8_WAIT_V(6); PG8_BAR;
;     } else {
;         PG8_STAGE(PG8_SB(0, 0), cB, voffB); PG8_STAGE(PG8_SA(0, 0), cA, voffA); PG8_STAGE(PG8_SB(0, 1), cB + hstepB, voffB); PG8_STAGE(PG8_SA(0, 1), cA + hstepA, voffA);
;         if (wr == 1) PG8_BAR;
;         PG8_WAIT_V(4); PG8_BAR;
;         PG8_STAGE(PG8_SB(1, 0), cB + kstep, voffB); PG8_STAGE(PG8_SA(1, 0), cA + kstepA, voffA); PG8_STAGE(PG8_SB(1, 1), cB + hstepB + kstep, voffB);
;         PG8_WAIT_V(6); PG8_BAR;
.LBB0_375:
	s_and_b64 s[2:3], s[2:3], exec
	s_cselect_b32 s50, -1, s7
	s_cselect_b32 s9, 16, 4
	s_lshl_b32 s2, s13, 5
	s_mov_b64 s[52:53], 0x80
	s_and_b32 s13, s2, 0x60
	s_add_i32 m0, s28, 0x18000
	v_lshl_add_u64 v[6:7], v[6:7], 0, s[52:53]
	s_lshl_b32 s7, s6, 13
	s_lshl_b32 s14, s13, 7
	s_waitcnt vmcnt(2)
	s_barrier
	global_load_lds_dwordx4 v[6:7], off
	v_lshl_add_u64 v[4:5], v[4:5], 0, s[52:53]
	s_add_i32 m0, s28, 0x1a000
	s_add_i32 s79, s28, 0x8000
	s_add_i32 s81, s28, 0xa000
	global_load_lds_dwordx4 v[4:5], off
	v_lshl_add_u64 v[0:1], v[0:1], 0, s[52:53]
	s_mov_b32 m0, s79
	s_add_u32 s2, s84, 0x40080
	global_load_lds_dwordx4 v[0:1], off
	v_lshl_add_u64 v[0:1], v[2:3], 0, s[52:53]
	s_mov_b32 m0, s81
	s_addc_u32 s3, s85, 0
	global_load_lds_dwordx4 v[0:1], off
	s_add_i32 m0, s28, 0x1c000
	v_lshl_add_u64 v[0:1], s[2:3], 0, v[194:195]
	global_load_lds_dwordx4 v[0:1], off
	v_lshl_add_u64 v[0:1], s[2:3], 0, v[198:199]
	s_add_i32 m0, s28, 0x1e000
	s_cmpk_lt_u32 s12, 0x100
	global_load_lds_dwordx4 v[0:1], off
	v_bfe_u32 v1, v8, 4, 2
	v_and_b32_e32 v0, 15, v8
	v_lshlrev_b32_e32 v2, 4, v1
	v_lshl_or_b32 v239, s6, 6, v0
	v_lshl_or_b32 v0, v0, 6, v2
	v_lshlrev_b32_e32 v2, 2, v8
	v_and_b32_e32 v2, 32, v2
	v_bitop3_b32 v3, v0, s7, v2 bitop3:0xde
	v_bitop3_b32 v240, v0, s14, v2 bitop3:0xde
	v_lshlrev_b32_e32 v0, 14, v9
	v_and_b32_e32 v0, 0xffff8000, v0
	v_cmp_eq_u32_e64 s[2:3], 0, v1
	v_lshl_or_b32 v241, v1, 3, s13
	v_lshl_add_u32 v0, v10, 11, v0
	v_and_b32_e32 v1, 1, v9
	v_lshl_or_b32 v0, v1, 6, v0
	v_lshl_add_u32 v200, v11, 1, v0
	v_lshlrev_b32_e32 v0, 14, v12
	v_and_b32_e32 v0, 0xffff8000, v0
	v_lshl_add_u32 v0, v13, 11, v0
	v_and_b32_e32 v1, 1, v12
	s_waitcnt vmcnt(0)
	v_lshl_or_b32 v0, v1, 6, v0
	s_mov_b32 s51, 0
	s_cselect_b64 s[54:55], -1, 0
	v_lshl_add_u32 v202, v14, 1, v0
	s_add_i32 s86, 0, 0x10000
	s_add_i32 s87, 0, 0x14000
	v_mbcnt_lo_u32_b32 v0, -1, 0
	v_mov_b32_e32 v201, v195
	v_mov_b32_e32 v203, v195
	v_add_u32_e32 v242, s86, v240
	v_add_u32_e32 v243, s87, v240
	v_add_u32_e32 v244, 0, v3
	v_mbcnt_hi_u32_b32 v245, -1, v0
	s_mov_b32 s90, s51
	s_barrier
	s_branch .LBB0_378

;     __host__ __device__ __forceinline__ bool next(int i, Unit& u) const { const long L = (long)i * G + c; if (L >= nwg) return false; map((int)L, u); return true; }
; #define PG8_STAGE(bufoff, gbase, voff) do { _Pragma("unroll") for (int _i = 0; _i < 2; ++_i) \
;         __builtin_amdgcn_global_load_lds((const unsigned*)((const char*)(gbase) + (voff)[_i]), (PG8_LAS unsigned*)(lds + (bufoff) + ldsw + _i * 8192), 16, 0, 0); } while (0)
; #define PG8_BAR __builtin_amdgcn_s_barrier()
;     __host__ __device__ __forceinline__ bool next(int i, Unit& u) const {
;         const int ii = (so.c < 16 * S && so.G >= so.nwg && i < 2) ? 1 - i : i;
;         const int L = ii * so.G + so.c; const bool isp = L < so.nwg; const int j = isp ? 0 : L - so.nwg;
;         Unit a; so.map(isp ? L : 0, a);
;         const int q = j / S, sp = j - q * S;
;         u.pm = isp ? a.pm : 64 + (q >> 2); u.pn = isp ? a.pn : (q & 3); u.sp = isp ? -1 : sp; u.nt = isp ? a.nt : ntS; u.k0 = isp ? 0 : sp * ntS * BK; u.qa = -1; u.qb = -1;
;         return isp || j < 16 * S;
;     }
; template <class Epi, class Sched, bool ALIGN_EPI = false, bool SP2 = false>
; __device__ __forceinline__ void gemm_phase(PG8_LAS unsigned char* lds, const Gemm g, const Sched& S, const Epi& E) {
;     ...
;         const bool has_next = S.next(ui + 1, nxt);
;         const char* nA = has_next ? (const char*)g.A + (size_t)nxt.pm * tstepA + (size_t)(nxt.k0 >> 6) * kstepA + (nxt.qa > 0 ? hstepA : (size_t)0) : cA; const char* nB = has_next ? (const char*)g.Bt + (size_t)nxt.pn * tstepB + (size_t)nxt.k0 * 2 + (nxt.qb > 0 ? hstepB : (size_t)0) : cB;
;         const bool whole = cur.qa < 0;
;         const int nt = cur.nt;
;         for (int t = 0; t < nt; t += 2) {
;             const bool last = (t == nt - 2);
;             const char* a1 = cA + (size_t)(t + 1) * kstepA;
;             const char* a2 = last ? nA : cA + (size_t)(t + 2) * kstepA; const char* b2 = last ? nB : cB + (size_t)(t + 2) * kstep;
;             const char* a3 = a2 + kstepA; const char* b3 = b2 + kstep;
;             if (last && has_next) S.a_ready(nxt);
;             if constexpr (SP2) {
;             PG8_LDB(B0, 0, 0); PG8_LDB(B1, 0, 1); PG8_SCHED; PG8_LDA(At, 0, 0); PG8_STAGE(PG8_SA(1, 1), a1 + hstepA, voffA);
;             PG8_WAIT_V(8); PG8_WAIT_L(0); PG8_BAR; PG8_MMA(0, 0, At, B0); if (whole) PG8_MMA(0, 1, At, B1); PG8_BAR; PG8_SCHED;
.LBB0_382:
	s_add_i32 s7, s13, s6
	s_ashr_i32 s6, s7, 31
	s_lshr_b32 s6, s6, 28
	s_add_i32 s13, s7, s6
	s_ashr_i32 s6, s13, 4
	s_lshl_b32 s14, s6, 2
	s_sub_i32 s6, 64, s14
	s_min_i32 s15, s6, 4
	s_abs_i32 s16, s15
	v_cvt_f32_u32_e32 v0, s16
	s_sub_i32 s20, 0, s16
	s_and_b32 s13, s13, -16
	s_sub_i32 s7, s7, s13
	v_rcp_iflag_f32_e32 v0, v0
	s_abs_i32 s13, s7
	s_max_i32 s17, s12, 0x100
	s_xor_b32 s19, s7, s15
	v_mul_f32_e32 v0, 0x4f7ffffe, v0
	v_cvt_u32_f32_e32 v0, v0
	s_add_i32 s18, s17, 0xffffff00
	s_ashr_i32 s19, s19, 31
	s_mov_b32 s6, 0
	v_readfirstlane_b32 s21, v0
	s_mul_i32 s20, s20, s21
	s_mul_hi_u32 s20, s21, s20
	s_add_i32 s21, s21, s20
	s_mul_hi_u32 s20, s13, s21
	s_mul_i32 s21, s20, s16
	s_sub_i32 s13, s13, s21
	s_add_i32 s21, s20, 1
	s_sub_i32 s22, s13, s16
	s_cmp_ge_u32 s13, s16
	s_cselect_b32 s20, s21, s20
	s_cselect_b32 s13, s22, s13
	s_add_i32 s21, s20, 1
	s_cmp_ge_u32 s13, s16
	s_cselect_b32 s13, s21, s20
	s_xor_b32 s13, s13, s19
	s_sub_i32 s13, s13, s19
	s_mul_i32 s15, s13, s15
	s_sub_i32 s7, s7, s15
	s_add_i32 s7, s14, s7
	s_lshr_b32 s14, s18, 4
	s_and_b32 s91, s17, 3
	s_add_i32 s16, s14, 64
	s_and_b64 s[14:15], s[56:57], exec
	s_cselect_b32 s58, s7, s16
	s_bfe_u32 s7, s17, 0x20002
	s_and_b64 s[14:15], s[56:57], exec
	s_cselect_b32 s60, s13, s7
	s_lshl_b32 s7, s91, 9
	s_and_b64 s[14:15], s[56:57], exec
	s_cselect_b32 s7, 0, s7
	s_ashr_i32 s59, s58, 31
	s_lshl_b64 s[14:15], s[58:59], 19
	s_add_u32 s13, s36, s14
	s_addc_u32 s14, s37, s15
	s_add_u32 s62, s13, s7
	s_addc_u32 s63, s14, 0
	s_ashr_i32 s61, s60, 31
	s_lshl_b64 s[14:15], s[60:61], 19
	s_add_u32 s13, s4, s14
	s_addc_u32 s14, s5, s15
	s_add_u32 s64, s13, s7
	s_addc_u32 s65, s14, 0
	s_cmpk_lt_i32 s12, 0x140
	s_cselect_b64 s[76:77], -1, 0
	s_and_b64 s[12:13], s[76:77], exec
	s_cselect_b32 s12, s63, s83
	s_cselect_b32 s13, s62, s82
	s_cselect_b32 s14, s65, s85
	s_cselect_b32 s15, s64, s84
	s_add_i32 s16, s9, -2
	s_add_u32 s82, s82, 0x40080
	s_addc_u32 s83, s83, 0
	s_add_u32 s17, s84, 0x100
	s_addc_u32 s18, s85, 0
	s_waitcnt lgkmcnt(0)
	ds_read_b128 v[128:131], v242
	ds_read_b128 v[132:135], v242 offset:1024
	ds_read_b128 v[136:139], v242 offset:2048
	ds_read_b128 v[140:143], v242 offset:3072
	ds_read_b128 v[144:147], v243
	ds_read_b128 v[148:151], v243 offset:1024
	ds_read_b128 v[152:155], v243 offset:2048
	ds_read_b128 v[156:159], v243 offset:3072
	s_add_i32 s19, s6, 2
	s_add_u32 s7, s82, 0xfffc0080
	s_addc_u32 s20, s83, -1
	s_cmp_eq_u32 s16, s6
	s_cselect_b32 s6, s15, s17
	s_cselect_b32 s85, s12, s20
	s_cselect_b32 s84, s13, s7
	s_cselect_b32 s7, s14, s18
	v_lshl_add_u64 v[204:205], s[82:83], 0, v[200:201]
	s_add_i32 m0, s28, 0xc000
	ds_read_b128 v[160:163], v244
	ds_read_b128 v[164:167], v244 offset:1024
	ds_read_b128 v[168:171], v244 offset:2048
	ds_read_b128 v[172:175], v244 offset:3072
	ds_read_b128 v[176:179], v244 offset:4096
	ds_read_b128 v[180:183], v244 offset:5120
	ds_read_b128 v[184:187], v244 offset:6144
	ds_read_b128 v[188:191], v244 offset:7168
	global_load_lds_dwordx4 v[204:205], off
	v_lshl_add_u64 v[204:205], s[82:83], 0, v[202:203]
	s_add_i32 m0, s28, 0xe000
	s_nop 0
	global_load_lds_dwordx4 v[204:205], off
	s_waitcnt vmcnt(16)
	s_waitcnt lgkmcnt(0)
	s_barrier
	s_setprio 1
	s_waitcnt lgkmcnt(0)
	v_mfma_f32_16x16x32_bf16 v[124:127], v[128:131], v[160:163], 0
	v_mfma_f32_16x16x32_bf16 v[120:123], v[136:139], v[160:163], 0
	v_mfma_f32_16x16x32_bf16 v[116:119], v[128:131], v[168:171], 0
	v_mfma_f32_16x16x32_bf16 v[108:111], v[136:139], v[168:171], 0
	v_mfma_f32_16x16x32_bf16 v[100:103], v[128:131], v[176:179], 0
	v_mfma_f32_16x16x32_bf16 v[92:95], v[136:139], v[176:179], 0
	v_mfma_f32_16x16x32_bf16 v[84:87], v[128:131], v[184:187], 0
	v_mfma_f32_16x16x32_bf16 v[76:79], v[136:139], v[184:187], 0
	v_mfma_f32_16x16x32_bf16 v[124:127], v[132:135], v[164:167], v[124:127]
	v_mfma_f32_16x16x32_bf16 v[120:123], v[140:143], v[164:167], v[120:123]
	v_mfma_f32_16x16x32_bf16 v[116:119], v[132:135], v[172:175], v[116:119]
	v_mfma_f32_16x16x32_bf16 v[108:111], v[140:143], v[172:175], v[108:111]
	v_mfma_f32_16x16x32_bf16 v[100:103], v[132:135], v[180:183], v[100:103]
	v_mfma_f32_16x16x32_bf16 v[92:95], v[140:143], v[180:183], v[92:95]
	v_mfma_f32_16x16x32_bf16 v[84:87], v[132:135], v[188:191], v[84:87]
	v_mfma_f32_16x16x32_bf16 v[76:79], v[140:143], v[188:191], v[76:79]
	s_setprio 0
	s_setprio 1
	v_mfma_f32_16x16x32_bf16 v[112:115], v[144:147], v[160:163], 0
	v_mfma_f32_16x16x32_bf16 v[104:107], v[152:155], v[160:163], 0
	v_mfma_f32_16x16x32_bf16 v[96:99], v[144:147], v[168:171], 0
	v_mfma_f32_16x16x32_bf16 v[88:91], v[152:155], v[168:171], 0
	v_mfma_f32_16x16x32_bf16 v[80:83], v[144:147], v[176:179], 0
	v_mfma_f32_16x16x32_bf16 v[72:75], v[152:155], v[176:179], 0
	v_mfma_f32_16x16x32_bf16 v[68:71], v[144:147], v[184:187], 0
	v_mfma_f32_16x16x32_bf16 v[64:67], v[152:155], v[184:187], 0
	v_mfma_f32_16x16x32_bf16 v[112:115], v[148:151], v[164:167], v[112:115]
	v_mfma_f32_16x16x32_bf16 v[104:107], v[156:159], v[164:167], v[104:107]
	v_mfma_f32_16x16x32_bf16 v[96:99], v[148:151], v[172:175], v[96:99]
	v_mfma_f32_16x16x32_bf16 v[88:91], v[156:159], v[172:175], v[88:91]
	v_mfma_f32_16x16x32_bf16 v[80:83], v[148:151], v[180:183], v[80:83]
	v_mfma_f32_16x16x32_bf16 v[72:75], v[156:159], v[180:183], v[72:75]
	v_mfma_f32_16x16x32_bf16 v[68:71], v[148:151], v[188:191], v[68:71]
	v_mfma_f32_16x16x32_bf16 v[64:67], v[156:159], v[188:191], v[64:67]
	s_setprio 0
	s_barrier
; #define PG8_STAGE(bufoff, gbase, voff) do { _Pragma("unroll") for (int _i = 0; _i < 2; ++_i) \
;         __builtin_amdgcn_global_load_lds((const unsigned*)((const char*)(gbase) + (voff)[_i]), (PG8_LAS unsigned*)(lds + (bufoff) + ldsw + _i * 8192), 16, 0, 0); } while (0)
; #define PG8_LDA(dst, b, h) do { _Pragma("unroll") for (int m = 0; m < 4; ++m) _Pragma("unroll") for (int k = 0; k < 2; ++k) dst[m][k] = *(const PG8_LAS bf16x8*)(lds + PG8_SA(b, h) + aoff + m * 2048 + k * 1024); } while (0)
; #define PG8_LDB(dst, b, h) do { _Pragma("unroll") for (int n = 0; n < 2; ++n) _Pragma("unroll") for (int k = 0; k < 2; ++k) dst[n][k] = *(const PG8_LAS bf16x8*)(lds + PG8_SB(b, h) + boff + n * 2048 + k * 1024); } while (0)
; #define PG8_MMA(ai, bj, At, Bt) do { __builtin_amdgcn_s_setprio(1); _Pragma("unroll") for (int m = 0; m < 4; ++m) _Pragma("unroll") for (int n = 0; n < 2; ++n) _Pragma("unroll") for (int k = 0; k < 2; ++k) \
;         acc[ai][bj][m][n] = __builtin_amdgcn_mfma_f32_16x16x32_bf16(Bt[n][k], At[m][k], acc[ai][bj][m][n], 0, 0, 0); __builtin_amdgcn_s_setprio(0); } while (0)
; #define PG8_WAIT_V(n) asm volatile("s_waitcnt vmcnt(" #n ")" ::: "memory")
; #define PG8_WAIT_L(n) asm volatile("s_waitcnt lgkmcnt(" #n ")" ::: "memory")
; #define PG8_BAR __builtin_amdgcn_s_barrier()
; #define PG8_SCHED __builtin_amdgcn_sched_barrier(0)
; template <class Epi, class Sched, bool ALIGN_EPI = false, bool SP2 = false>
; __device__ __forceinline__ void gemm_phase(PG8_LAS unsigned char* lds, const Gemm g, const Sched& S, const Epi& E) {
;     ...
;             PG8_WAIT_V(8); PG8_WAIT_L(0); PG8_BAR; PG8_MMA(0, 0, At, B0); if (whole) PG8_MMA(0, 1, At, B1); PG8_BAR; PG8_SCHED;
;             PG8_LDA(At, 0, 1); PG8_STAGE(PG8_SB(0, 0), b2, voffB); PG8_STAGE(PG8_SB(0, 1), b2 + hstepB, voffB); PG8_STAGE(PG8_SA(0, 0), a2, voffA);
;             PG8_WAIT_V(8); PG8_WAIT_L(0); PG8_BAR; if (whole) { PG8_MMA(1, 0, At, B0); PG8_MMA(1, 1, At, B1); } PG8_BAR; PG8_SCHED;
;             PG8_LDB(B0, 1, 0); PG8_LDB(B1, 1, 1); PG8_SCHED; PG8_LDA(At, 1, 0); PG8_STAGE(PG8_SA(0, 1), a2 + hstepA, voffA);
;             PG8_WAIT_V(8); PG8_WAIT_L(0); PG8_BAR; PG8_MMA(0, 0, At, B0); if (whole) PG8_MMA(0, 1, At, B1); PG8_BAR; PG8_SCHED;
	s_add_i32 s20, s86, s8
	v_lshl_add_u64 v[204:205], s[6:7], 0, v[194:195]
	s_mov_b32 m0, s20
	ds_read_b128 v[160:163], v244 offset:16384
	ds_read_b128 v[164:167], v244 offset:17408
	ds_read_b128 v[168:171], v244 offset:18432
	ds_read_b128 v[172:175], v244 offset:19456
	ds_read_b128 v[176:179], v244 offset:20480
	ds_read_b128 v[180:183], v244 offset:21504
	ds_read_b128 v[184:187], v244 offset:22528
	ds_read_b128 v[188:191], v244 offset:23552
	global_load_lds_dwordx4 v[204:205], off
	s_add_i32 m0, s20, 0x2000
	s_add_u32 s20, s6, 0x40000
	v_lshl_add_u64 v[206:207], s[6:7], 0, v[198:199]
	s_addc_u32 s21, s7, 0
	s_add_i32 s22, s87, s8
	global_load_lds_dwordx4 v[206:207], off
	v_lshl_add_u64 v[208:209], s[20:21], 0, v[194:195]
	s_mov_b32 m0, s22
	v_lshl_add_u64 v[210:211], s[84:85], 0, v[196:197]
	global_load_lds_dwordx4 v[208:209], off
	v_lshl_add_u64 v[208:209], s[20:21], 0, v[198:199]
	s_add_i32 m0, s22, 0x2000
	s_nop 0
	global_load_lds_dwordx4 v[208:209], off
	v_lshl_add_u64 v[208:209], s[84:85], 0, v[192:193]
	s_mov_b32 m0, s28
	s_nop 0
	global_load_lds_dwordx4 v[208:209], off
	s_mov_b32 m0, s29
	s_nop 0
	global_load_lds_dwordx4 v[210:211], off
	s_waitcnt vmcnt(16)
	s_waitcnt lgkmcnt(0)
	s_barrier
	s_setprio 1
	s_waitcnt lgkmcnt(0)
	v_mfma_f32_16x16x32_bf16 v[60:63], v[128:131], v[160:163], 0
	v_mfma_f32_16x16x32_bf16 v[56:59], v[136:139], v[160:163], 0
	v_mfma_f32_16x16x32_bf16 v[52:55], v[128:131], v[168:171], 0
	v_mfma_f32_16x16x32_bf16 v[44:47], v[136:139], v[168:171], 0
	v_mfma_f32_16x16x32_bf16 v[36:39], v[128:131], v[176:179], 0
	v_mfma_f32_16x16x32_bf16 v[28:31], v[136:139], v[176:179], 0
	v_mfma_f32_16x16x32_bf16 v[20:23], v[128:131], v[184:187], 0
	v_mfma_f32_16x16x32_bf16 v[12:15], v[136:139], v[184:187], 0
	v_mfma_f32_16x16x32_bf16 v[60:63], v[132:135], v[164:167], v[60:63]
	v_mfma_f32_16x16x32_bf16 v[56:59], v[140:143], v[164:167], v[56:59]
	v_mfma_f32_16x16x32_bf16 v[52:55], v[132:135], v[172:175], v[52:55]
	v_mfma_f32_16x16x32_bf16 v[44:47], v[140:143], v[172:175], v[44:47]
	v_mfma_f32_16x16x32_bf16 v[36:39], v[132:135], v[180:183], v[36:39]
	v_mfma_f32_16x16x32_bf16 v[28:31], v[140:143], v[180:183], v[28:31]
	v_mfma_f32_16x16x32_bf16 v[20:23], v[132:135], v[188:191], v[20:23]
	v_mfma_f32_16x16x32_bf16 v[12:15], v[140:143], v[188:191], v[12:15]
	s_setprio 0
	s_setprio 1
	v_mfma_f32_16x16x32_bf16 v[48:51], v[144:147], v[160:163], 0
	v_mfma_f32_16x16x32_bf16 v[40:43], v[152:155], v[160:163], 0
	v_mfma_f32_16x16x32_bf16 v[32:35], v[144:147], v[168:171], 0
	v_mfma_f32_16x16x32_bf16 v[24:27], v[152:155], v[168:171], 0
	v_mfma_f32_16x16x32_bf16 v[16:19], v[144:147], v[176:179], 0
	v_mfma_f32_16x16x32_bf16 v[8:11], v[152:155], v[176:179], 0
	v_mfma_f32_16x16x32_bf16 v[4:7], v[144:147], v[184:187], 0
	v_mfma_f32_16x16x32_bf16 v[0:3], v[152:155], v[184:187], 0
	v_mfma_f32_16x16x32_bf16 v[48:51], v[148:151], v[164:167], v[48:51]
	v_mfma_f32_16x16x32_bf16 v[40:43], v[156:159], v[164:167], v[40:43]
	v_mfma_f32_16x16x32_bf16 v[32:35], v[148:151], v[172:175], v[32:35]
	v_mfma_f32_16x16x32_bf16 v[24:27], v[156:159], v[172:175], v[24:27]
	v_mfma_f32_16x16x32_bf16 v[16:19], v[148:151], v[180:183], v[16:19]
	v_mfma_f32_16x16x32_bf16 v[8:11], v[156:159], v[180:183], v[8:11]
	v_mfma_f32_16x16x32_bf16 v[4:7], v[148:151], v[188:191], v[4:7]
	v_mfma_f32_16x16x32_bf16 v[0:3], v[156:159], v[188:191], v[0:3]
	s_setprio 0
	s_barrier
	s_add_i32 s22, 0, 0x18000
	s_add_i32 s23, 0, 0x1c000
	v_add_u32_e32 v140, s22, v240
	v_add_u32_e32 v156, s23, v240
	ds_read_b128 v[128:131], v140
	ds_read_b128 v[132:135], v140 offset:1024
	ds_read_b128 v[136:139], v140 offset:2048
	ds_read_b128 v[140:143], v140 offset:3072
	ds_read_b128 v[144:147], v156
	ds_read_b128 v[148:151], v156 offset:1024
	ds_read_b128 v[152:155], v156 offset:2048
	ds_read_b128 v[156:159], v156 offset:3072
	s_add_u32 s20, s84, 0x40000
	s_addc_u32 s21, s85, 0
	s_mov_b32 m0, s66
	v_lshl_add_u64 v[212:213], s[20:21], 0, v[192:193]
	ds_read_b128 v[160:163], v244 offset:32768
	ds_read_b128 v[164:167], v244 offset:33792
	ds_read_b128 v[168:171], v244 offset:34816
	ds_read_b128 v[172:175], v244 offset:35840
	ds_read_b128 v[176:179], v244 offset:36864
	ds_read_b128 v[180:183], v244 offset:37888
	ds_read_b128 v[184:187], v244 offset:38912
	ds_read_b128 v[188:191], v244 offset:39936
	global_load_lds_dwordx4 v[212:213], off
	v_lshl_add_u64 v[212:213], s[20:21], 0, v[196:197]
	s_mov_b32 m0, s67
	s_nop 0
	global_load_lds_dwordx4 v[212:213], off
	s_waitcnt vmcnt(8)
	s_waitcnt lgkmcnt(0)
	s_barrier
; #define PG8_STAGE(bufoff, gbase, voff) do { _Pragma("unroll") for (int _i = 0; _i < 2; ++_i) \
;         __builtin_amdgcn_global_load_lds((const unsigned*)((const char*)(gbase) + (voff)[_i]), (PG8_LAS unsigned*)(lds + (bufoff) + ldsw + _i * 8192), 16, 0, 0); } while (0)
; #define PG8_LDA(dst, b, h) do { _Pragma("unroll") for (int m = 0; m < 4; ++m) _Pragma("unroll") for (int k = 0; k < 2; ++k) dst[m][k] = *(const PG8_LAS bf16x8*)(lds + PG8_SA(b, h) + aoff + m * 2048 + k * 1024); } while (0)
; #define PG8_LDB(dst, b, h) do { _Pragma("unroll") for (int n = 0; n < 2; ++n) _Pragma("unroll") for (int k = 0; k < 2; ++k) dst[n][k] = *(const PG8_LAS bf16x8*)(lds + PG8_SB(b, h) + boff + n * 2048 + k * 1024); } while (0)
; #define PG8_MMA(ai, bj, At, Bt) do { __builtin_amdgcn_s_setprio(1); _Pragma("unroll") for (int m = 0; m < 4; ++m) _Pragma("unroll") for (int n = 0; n < 2; ++n) _Pragma("unroll") for (int k = 0; k < 2; ++k) \
;         acc[ai][bj][m][n] = __builtin_amdgcn_mfma_f32_16x16x32_bf16(Bt[n][k], At[m][k], acc[ai][bj][m][n], 0, 0, 0); __builtin_amdgcn_s_setprio(0); } while (0)
; #define PG8_WAIT_V(n) asm volatile("s_waitcnt vmcnt(" #n ")" ::: "memory")
; #define PG8_WAIT_L(n) asm volatile("s_waitcnt lgkmcnt(" #n ")" ::: "memory")
; #define PG8_BAR __builtin_amdgcn_s_barrier()
; #define PG8_SCHED __builtin_amdgcn_sched_barrier(0)
; template <class Epi, class Sched, bool ALIGN_EPI = false, bool SP2 = false>
; __device__ __forceinline__ void gemm_phase(PG8_LAS unsigned char* lds, const Gemm g, const Sched& S, const Epi& E) {
;     ...
;         for (int t = 0; t < nt; t += 2) {
;     ...
;             PG8_LDB(B0, 1, 0); PG8_LDB(B1, 1, 1); PG8_SCHED; PG8_LDA(At, 1, 0); PG8_STAGE(PG8_SA(0, 1), a2 + hstepA, voffA);
;             PG8_WAIT_V(8); PG8_WAIT_L(0); PG8_BAR; PG8_MMA(0, 0, At, B0); if (whole) PG8_MMA(0, 1, At, B1); PG8_BAR; PG8_SCHED;
;             PG8_LDA(At, 1, 1); PG8_STAGE(PG8_SB(1, 0), b3, voffB); PG8_STAGE(PG8_SB(1, 1), b3 + hstepB, voffB); PG8_STAGE(PG8_SA(1, 0), a3, voffA);
;             PG8_WAIT_V(8); PG8_WAIT_L(0); PG8_BAR; if (whole) { PG8_MMA(1, 0, At, B0); PG8_MMA(1, 1, At, B1); } PG8_BAR; PG8_SCHED;
	s_setprio 1
	s_waitcnt lgkmcnt(0)
	v_mfma_f32_16x16x32_bf16 v[124:127], v[128:131], v[160:163], v[124:127]
	v_mfma_f32_16x16x32_bf16 v[120:123], v[136:139], v[160:163], v[120:123]
	v_mfma_f32_16x16x32_bf16 v[116:119], v[128:131], v[168:171], v[116:119]
	v_mfma_f32_16x16x32_bf16 v[108:111], v[136:139], v[168:171], v[108:111]
	v_mfma_f32_16x16x32_bf16 v[100:103], v[128:131], v[176:179], v[100:103]
	v_mfma_f32_16x16x32_bf16 v[92:95], v[136:139], v[176:179], v[92:95]
	v_mfma_f32_16x16x32_bf16 v[84:87], v[128:131], v[184:187], v[84:87]
	v_mfma_f32_16x16x32_bf16 v[76:79], v[136:139], v[184:187], v[76:79]
	v_mfma_f32_16x16x32_bf16 v[124:127], v[132:135], v[164:167], v[124:127]
	v_mfma_f32_16x16x32_bf16 v[120:123], v[140:143], v[164:167], v[120:123]
	v_mfma_f32_16x16x32_bf16 v[116:119], v[132:135], v[172:175], v[116:119]
	v_mfma_f32_16x16x32_bf16 v[108:111], v[140:143], v[172:175], v[108:111]
	v_mfma_f32_16x16x32_bf16 v[100:103], v[132:135], v[180:183], v[100:103]
	v_mfma_f32_16x16x32_bf16 v[92:95], v[140:143], v[180:183], v[92:95]
	v_mfma_f32_16x16x32_bf16 v[84:87], v[132:135], v[188:191], v[84:87]
	v_mfma_f32_16x16x32_bf16 v[76:79], v[140:143], v[188:191], v[76:79]
	s_setprio 0
	s_setprio 1
	v_mfma_f32_16x16x32_bf16 v[112:115], v[144:147], v[160:163], v[112:115]
	v_mfma_f32_16x16x32_bf16 v[104:107], v[152:155], v[160:163], v[104:107]
	v_mfma_f32_16x16x32_bf16 v[96:99], v[144:147], v[168:171], v[96:99]
	v_mfma_f32_16x16x32_bf16 v[88:91], v[152:155], v[168:171], v[88:91]
	v_mfma_f32_16x16x32_bf16 v[80:83], v[144:147], v[176:179], v[80:83]
	v_mfma_f32_16x16x32_bf16 v[72:75], v[152:155], v[176:179], v[72:75]
	v_mfma_f32_16x16x32_bf16 v[68:71], v[144:147], v[184:187], v[68:71]
	v_mfma_f32_16x16x32_bf16 v[64:67], v[152:155], v[184:187], v[64:67]
	v_mfma_f32_16x16x32_bf16 v[112:115], v[148:151], v[164:167], v[112:115]
	v_mfma_f32_16x16x32_bf16 v[104:107], v[156:159], v[164:167], v[104:107]
	v_mfma_f32_16x16x32_bf16 v[96:99], v[148:151], v[172:175], v[96:99]
	v_mfma_f32_16x16x32_bf16 v[88:91], v[156:159], v[172:175], v[88:91]
	v_mfma_f32_16x16x32_bf16 v[80:83], v[148:151], v[180:183], v[80:83]
	v_mfma_f32_16x16x32_bf16 v[72:75], v[156:159], v[180:183], v[72:75]
	v_mfma_f32_16x16x32_bf16 v[68:71], v[148:151], v[188:191], v[68:71]
	v_mfma_f32_16x16x32_bf16 v[64:67], v[156:159], v[188:191], v[64:67]
	s_setprio 0
	s_barrier
	s_add_i32 s20, s22, s8
	v_lshl_add_u64 v[204:205], v[204:205], 0, s[52:53]
	s_mov_b32 m0, s20
	ds_read_b128 v[160:163], v244 offset:49152
	ds_read_b128 v[164:167], v244 offset:50176
	ds_read_b128 v[168:171], v244 offset:51200
	ds_read_b128 v[172:175], v244 offset:52224
	ds_read_b128 v[176:179], v244 offset:53248
	ds_read_b128 v[180:183], v244 offset:54272
	ds_read_b128 v[184:187], v244 offset:55296
	ds_read_b128 v[188:191], v244 offset:56320
	global_load_lds_dwordx4 v[204:205], off
	s_add_i32 m0, s20, 0x2000
	s_add_u32 s6, s6, 0x40080
	v_lshl_add_u64 v[204:205], v[206:207], 0, s[52:53]
	s_addc_u32 s7, s7, 0
	s_add_i32 s20, s23, s8
	global_load_lds_dwordx4 v[204:205], off
	v_lshl_add_u64 v[204:205], s[6:7], 0, v[194:195]
	s_mov_b32 m0, s20
	s_nop 0
	global_load_lds_dwordx4 v[204:205], off
	v_lshl_add_u64 v[204:205], s[6:7], 0, v[198:199]
	s_add_i32 m0, s20, 0x2000
	s_nop 0
	global_load_lds_dwordx4 v[204:205], off
	v_lshl_add_u64 v[204:205], v[208:209], 0, s[52:53]
	s_mov_b32 m0, s79
	s_nop 0
	global_load_lds_dwordx4 v[204:205], off
	v_lshl_add_u64 v[204:205], v[210:211], 0, s[52:53]
	s_mov_b32 m0, s81
	s_nop 0
	global_load_lds_dwordx4 v[204:205], off
	s_waitcnt vmcnt(8)
	s_waitcnt lgkmcnt(0)
	s_barrier
	s_setprio 1
	s_waitcnt lgkmcnt(0)
	v_mfma_f32_16x16x32_bf16 v[60:63], v[128:131], v[160:163], v[60:63]
	v_mfma_f32_16x16x32_bf16 v[56:59], v[136:139], v[160:163], v[56:59]
	v_mfma_f32_16x16x32_bf16 v[52:55], v[128:131], v[168:171], v[52:55]
	v_mfma_f32_16x16x32_bf16 v[44:47], v[136:139], v[168:171], v[44:47]
	v_mfma_f32_16x16x32_bf16 v[36:39], v[128:131], v[176:179], v[36:39]
	v_mfma_f32_16x16x32_bf16 v[28:31], v[136:139], v[176:179], v[28:31]
	v_mfma_f32_16x16x32_bf16 v[20:23], v[128:131], v[184:187], v[20:23]
	v_mfma_f32_16x16x32_bf16 v[12:15], v[136:139], v[184:187], v[12:15]
	v_mfma_f32_16x16x32_bf16 v[60:63], v[132:135], v[164:167], v[60:63]
	v_mfma_f32_16x16x32_bf16 v[56:59], v[140:143], v[164:167], v[56:59]
	v_mfma_f32_16x16x32_bf16 v[52:55], v[132:135], v[172:175], v[52:55]
	v_mfma_f32_16x16x32_bf16 v[44:47], v[140:143], v[172:175], v[44:47]
	v_mfma_f32_16x16x32_bf16 v[36:39], v[132:135], v[180:183], v[36:39]
	v_mfma_f32_16x16x32_bf16 v[28:31], v[140:143], v[180:183], v[28:31]
	v_mfma_f32_16x16x32_bf16 v[20:23], v[132:135], v[188:191], v[20:23]
	v_mfma_f32_16x16x32_bf16 v[12:15], v[140:143], v[188:191], v[12:15]
	s_setprio 0
	s_setprio 1
	v_mfma_f32_16x16x32_bf16 v[48:51], v[144:147], v[160:163], v[48:51]
	v_mfma_f32_16x16x32_bf16 v[40:43], v[152:155], v[160:163], v[40:43]
	v_mfma_f32_16x16x32_bf16 v[32:35], v[144:147], v[168:171], v[32:35]
	v_mfma_f32_16x16x32_bf16 v[24:27], v[152:155], v[168:171], v[24:27]
	v_mfma_f32_16x16x32_bf16 v[16:19], v[144:147], v[176:179], v[16:19]
	v_mfma_f32_16x16x32_bf16 v[8:11], v[152:155], v[176:179], v[8:11]
	v_mfma_f32_16x16x32_bf16 v[4:7], v[144:147], v[184:187], v[4:7]
	v_mfma_f32_16x16x32_bf16 v[0:3], v[152:155], v[184:187], v[0:3]
	v_mfma_f32_16x16x32_bf16 v[48:51], v[148:151], v[164:167], v[48:51]
	v_mfma_f32_16x16x32_bf16 v[40:43], v[156:159], v[164:167], v[40:43]
	v_mfma_f32_16x16x32_bf16 v[32:35], v[148:151], v[172:175], v[32:35]
	v_mfma_f32_16x16x32_bf16 v[24:27], v[156:159], v[172:175], v[24:27]
	v_mfma_f32_16x16x32_bf16 v[16:19], v[148:151], v[180:183], v[16:19]
	v_mfma_f32_16x16x32_bf16 v[8:11], v[156:159], v[180:183], v[8:11]
	v_mfma_f32_16x16x32_bf16 v[4:7], v[148:151], v[188:191], v[4:7]
	v_mfma_f32_16x16x32_bf16 v[0:3], v[156:159], v[188:191], v[0:3]
	s_setprio 0
	s_barrier
	s_add_u32 s82, s82, 0x100
	s_addc_u32 s83, s83, 0
	s_add_u32 s17, s17, 0x100
	s_addc_u32 s18, s18, 0
	s_cmp_ge_u32 s19, s9
	s_mov_b32 s6, s19
	s_cbranch_scc0 .LBB0_383
	s_branch .Lpeel_exit_out0

; #define PG8_BAR __builtin_amdgcn_s_barrier()
;     __device__ __forceinline__ void operator()(const f32x4 (&acc)[2][2][4][2], const Unit& u, int wr, int wc, int fr, int fq) const {
;     ...
;         u32x4 xo[2][4][2];
; #pragma unroll
;         for (int ai = 0; ai < 2; ++ai)
; #pragma unroll
;             for (int m = 0; m < 4; ++m)
; #pragma unroll
;                 for (int bj = 0; bj < 2; ++bj) xo[ai][m][bj] = *(const u32x4*)(xb + (size_t)(row0 + ai * HALF + m * 16) * 1024 + col0 + bj * HALF);
; #pragma unroll
;         for (int ai = 0; ai < 2; ++ai)
; #pragma unroll
;             for (int m = 0; m < 4; ++m) {
;                 const int row = row0 + ai * HALF + m * 16;
;                 bf16_t* xr = xb + (size_t)row * 1024 + col0;
;                 float part_ss = 0.f;
; #pragma unroll
;                 for (int bj = 0; bj < 2; ++bj) {
;                     const u32x4 o = xo[ai][m][bj];
;                     f32x4 v0 = acc[ai][bj][m][0], v1 = acc[ai][bj][m][1];
;                     v0[0] += __uint_as_float(o.x << 16); v0[1] += __uint_as_float(o.x & 0xffff0000u); v0[2] += __uint_as_float(o.y << 16); v0[3] += __uint_as_float(o.y & 0xffff0000u);
;                     v1[0] += __uint_as_float(o.z << 16); v1[1] += __uint_as_float(o.z & 0xffff0000u); v1[2] += __uint_as_float(o.w << 16); v1[3] += __uint_as_float(o.w & 0xffff0000u);
;                     if (xout) { float* xo = xout + (size_t)row * 1024 + col0 + bj * HALF; *(f32x4*)xo = v0; *(f32x4*)(xo + 4) = v1; }
;                     else { u32x4 w; w.x = cvt_pk_bf16(v0[0], v0[1]); w.y = cvt_pk_bf16(v0[2], v0[3]); w.z = cvt_pk_bf16(v1[0], v1[1]); w.w = cvt_pk_bf16(v1[2], v1[3]); *(u32x4*)(xr + bj * HALF) = w; }
;                     part_ss += (v0[0] * v0[0] + v0[1] * v0[1]) + (v0[2] * v0[2] + v0[3] * v0[3]) + (v1[0] * v1[0] + v1[1] * v1[1]) + (v1[2] * v1[2] + v1[3] * v1[3]);
;                 }
;                 part_ss += __shfl_xor(part_ss, 16); part_ss += __shfl_xor(part_ss, 32);
;                 if (fq == 0) atomicAdd(ss + row, part_ss);
; template <class Epi, class Sched, bool ALIGN_EPI = false, bool SP2 = false>
; __device__ __forceinline__ void gemm_phase(PG8_LAS unsigned char* lds, const Gemm g, const Sched& S, const Epi& E) {
;     ...
;         if constexpr (ALIGN_EPI) { if (wr == 0) PG8_BAR; }
.Lpeel_exit_out0:
	s_and_b64 vcc, exec, s[54:55]
	s_cbranch_vccz .LBB0_386
	s_barrier
.LBB0_386:
	v_lshl_add_u32 v206, s78, 8, v239
	v_lshl_or_b32 v204, s80, 8, v241
	s_mov_b64 s[6:7], -1
	s_cmp_lt_i32 s50, 0
	v_ashrrev_i32_e32 v205, 31, v204
	v_ashrrev_i32_e32 v207, 31, v206
	s_cbranch_scc0 .LBB0_405
	v_lshlrev_b64 v[236:237], 1, v[204:205]
	v_lshl_add_u64 v[128:129], s[30:31], 0, v[236:237]
	v_lshlrev_b64 v[246:247], 11, v[206:207]
	v_lshl_add_u64 v[130:131], v[128:129], 0, v[246:247]
	global_load_dwordx4 v[188:191], v[130:131], off
	global_load_dwordx4 v[184:187], v[130:131], off offset:256
	v_or_b32_e32 v230, 16, v206
	v_ashrrev_i32_e32 v231, 31, v230
	v_or_b32_e32 v226, 32, v206
	v_lshlrev_b64 v[234:235], 11, v[230:231]
	v_ashrrev_i32_e32 v227, 31, v226
	v_or_b32_e32 v222, 48, v206
	v_lshl_add_u64 v[130:131], v[128:129], 0, v[234:235]
	v_lshlrev_b64 v[232:233], 11, v[226:227]
	v_ashrrev_i32_e32 v223, 31, v222
	v_add_u32_e32 v218, 0x80, v206
	global_load_dwordx4 v[180:183], v[130:131], off
	global_load_dwordx4 v[176:179], v[130:131], off offset:256
	v_lshl_add_u64 v[130:131], v[128:129], 0, v[232:233]
	v_lshlrev_b64 v[228:229], 11, v[222:223]
	v_ashrrev_i32_e32 v219, 31, v218
	v_add_u32_e32 v214, 0x90, v206
	global_load_dwordx4 v[172:175], v[130:131], off
	global_load_dwordx4 v[168:171], v[130:131], off offset:256
	v_lshl_add_u64 v[130:131], v[128:129], 0, v[228:229]
	v_lshlrev_b64 v[224:225], 11, v[218:219]
	v_ashrrev_i32_e32 v215, 31, v214
	v_add_u32_e32 v210, 0xa0, v206
	v_add_u32_e32 v208, 0xb0, v206
	global_load_dwordx4 v[164:167], v[130:131], off
	global_load_dwordx4 v[160:163], v[130:131], off offset:256
	v_lshl_add_u64 v[130:131], v[128:129], 0, v[224:225]
	v_lshlrev_b64 v[220:221], 11, v[214:215]
	v_ashrrev_i32_e32 v211, 31, v210
	v_ashrrev_i32_e32 v209, 31, v208
	global_load_dwordx4 v[156:159], v[130:131], off
	global_load_dwordx4 v[152:155], v[130:131], off offset:256
	v_lshl_add_u64 v[130:131], v[128:129], 0, v[220:221]
	v_lshlrev_b64 v[216:217], 11, v[210:211]
	v_lshlrev_b64 v[212:213], 11, v[208:209]
	global_load_dwordx4 v[148:151], v[130:131], off
	global_load_dwordx4 v[144:147], v[130:131], off offset:256
	v_lshl_add_u64 v[130:131], v[128:129], 0, v[216:217]
	v_lshl_add_u64 v[128:129], v[128:129], 0, v[212:213]
	global_load_dwordx4 v[140:143], v[130:131], off
	global_load_dwordx4 v[136:139], v[130:131], off offset:256
	global_load_dwordx4 v[132:135], v[128:129], off
	s_nop 0
	global_load_dwordx4 v[128:131], v[128:129], off offset:256
	v_lshl_add_u64 v[246:247], s[30:31], 0, v[246:247]
	v_lshl_add_u64 v[236:237], v[246:247], 0, v[236:237]
	s_waitcnt vmcnt(0)
	v_lshlrev_b32_e32 v246, 16, v188
	v_and_b32_e32 v188, 0xffff0000, v188
	v_add_f32_e32 v247, v125, v188
	v_lshlrev_b32_e32 v188, 16, v189
	v_add_f32_e32 v248, v126, v188
	v_and_b32_e32 v188, 0xffff0000, v189
	v_add_f32_e32 v249, v127, v188
	v_lshlrev_b32_e32 v188, 16, v190
	v_add_f32_e32 v250, v120, v188
	v_and_b32_e32 v188, 0xffff0000, v190
	v_add_f32_e32 v251, v121, v188
	v_lshlrev_b32_e32 v188, 16, v191
	v_add_f32_e32 v252, v122, v188
	v_and_b32_e32 v188, 0xffff0000, v191
	v_add_f32_e32 v246, v124, v246
	v_add_f32_e32 v253, v123, v188
	v_cvt_pk_bf16_f32 v188, v246, v247
	v_cvt_pk_bf16_f32 v189, v248, v249
	v_cvt_pk_bf16_f32 v190, v250, v251
	v_cvt_pk_bf16_f32 v191, v252, v253
	global_store_dwordx4 v[236:237], v[188:191], off sc1
	s_nop 1
	v_mul_f32_e32 v188, v247, v247
	v_mul_f32_e32 v189, v249, v249
	v_fmac_f32_e32 v188, v246, v246
	v_fmac_f32_e32 v189, v248, v248
	v_add_f32_e32 v188, v188, v189
	v_mul_f32_e32 v189, v251, v251
	v_fmac_f32_e32 v189, v250, v250
	v_add_f32_e32 v188, v189, v188
	v_mul_f32_e32 v189, v253, v253
	v_fmac_f32_e32 v189, v252, v252
	v_add_f32_e32 v188, v189, v188
	v_lshlrev_b32_e32 v189, 16, v184
	v_and_b32_e32 v184, 0xffff0000, v184
	v_add_f32_e32 v190, v113, v184
	v_lshlrev_b32_e32 v184, 16, v185
	v_add_f32_e32 v191, v114, v184
	v_and_b32_e32 v184, 0xffff0000, v185
	v_add_f32_e32 v246, v115, v184
	v_lshlrev_b32_e32 v184, 16, v186
	v_add_f32_e32 v247, v104, v184
	v_and_b32_e32 v184, 0xffff0000, v186
	v_add_f32_e32 v248, v105, v184
	v_lshlrev_b32_e32 v184, 16, v187
	v_add_f32_e32 v249, v106, v184
	v_and_b32_e32 v184, 0xffff0000, v187
	v_add_f32_e32 v189, v112, v189
	v_add_f32_e32 v250, v107, v184
	v_cvt_pk_bf16_f32 v184, v189, v190
	v_cvt_pk_bf16_f32 v185, v191, v246
	v_cvt_pk_bf16_f32 v186, v247, v248
	v_cvt_pk_bf16_f32 v187, v249, v250
	global_store_dwordx4 v[236:237], v[184:187], off offset:256 sc1
	s_nop 1
	v_mul_f32_e32 v184, v190, v190
	v_mul_f32_e32 v185, v246, v246
	v_fmac_f32_e32 v184, v189, v189
	v_fmac_f32_e32 v185, v191, v191
	v_add_f32_e32 v184, v184, v185
	v_mul_f32_e32 v185, v248, v248
	v_fmac_f32_e32 v185, v247, v247
	v_add_f32_e32 v184, v185, v184
	v_mul_f32_e32 v185, v250, v250
	v_fmac_f32_e32 v185, v249, v249
	v_add_f32_e32 v184, v185, v184
	v_and_b32_e32 v186, 64, v245
	v_add_f32_e32 v185, v188, v184
	v_xor_b32_e32 v184, 16, v245
	v_add_u32_e32 v187, 64, v186
	v_cmp_lt_i32_e32 vcc, v184, v187
	s_nop 1
	v_cndmask_b32_e32 v184, v245, v184, vcc
	v_lshlrev_b32_e32 v184, 2, v184
	ds_bpermute_b32 v186, v184, v185
	s_waitcnt lgkmcnt(0)
	v_add_f32_e32 v186, v185, v186
	v_xor_b32_e32 v185, 32, v245
	v_cmp_lt_i32_e32 vcc, v185, v187
	s_nop 1
	v_cndmask_b32_e32 v185, v245, v185, vcc
	v_lshlrev_b32_e32 v185, 2, v185
	ds_bpermute_b32 v187, v185, v186
	s_and_saveexec_b64 s[6:7], s[2:3]
	s_cbranch_execz .LBB0_389
	s_waitcnt lgkmcnt(0)
	v_add_f32_e32 v188, v186, v187
	v_lshl_add_u64 v[186:187], v[206:207], 2, s[42:43]
	global_atomic_add_f32 v[186:187], v188, off
; __device__ __forceinline__ unsigned cvt_pk_bf16(float lo, float hi) { unsigned r; asm volatile("v_cvt_pk_bf16_f32 %0, %1, %2" : "=v"(r) : "v"(lo), "v"(hi)); return r; }
;     __device__ __forceinline__ void operator()(const f32x4 (&acc)[2][2][4][2], const Unit& u, int wr, int wc, int fr, int fq) const {
;     ...
;         for (int ai = 0; ai < 2; ++ai)
; #pragma unroll
;             for (int m = 0; m < 4; ++m) {
;                 const int row = row0 + ai * HALF + m * 16;
;                 bf16_t* xr = xb + (size_t)row * 1024 + col0;
;                 float part_ss = 0.f;
; #pragma unroll
;                 for (int bj = 0; bj < 2; ++bj) {
;                     const u32x4 o = xo[ai][m][bj];
;                     f32x4 v0 = acc[ai][bj][m][0], v1 = acc[ai][bj][m][1];
;                     v0[0] += __uint_as_float(o.x << 16); v0[1] += __uint_as_float(o.x & 0xffff0000u); v0[2] += __uint_as_float(o.y << 16); v0[3] += __uint_as_float(o.y & 0xffff0000u);
;                     v1[0] += __uint_as_float(o.z << 16); v1[1] += __uint_as_float(o.z & 0xffff0000u); v1[2] += __uint_as_float(o.w << 16); v1[3] += __uint_as_float(o.w & 0xffff0000u);
;                     if (xout) { float* xo = xout + (size_t)row * 1024 + col0 + bj * HALF; *(f32x4*)xo = v0; *(f32x4*)(xo + 4) = v1; }
;                     else { u32x4 w; w.x = cvt_pk_bf16(v0[0], v0[1]); w.y = cvt_pk_bf16(v0[2], v0[3]); w.z = cvt_pk_bf16(v1[0], v1[1]); w.w = cvt_pk_bf16(v1[2], v1[3]); *(u32x4*)(xr + bj * HALF) = w; }
;                     part_ss += (v0[0] * v0[0] + v0[1] * v0[1]) + (v0[2] * v0[2] + v0[3] * v0[3]) + (v1[0] * v1[0] + v1[1] * v1[1]) + (v1[2] * v1[2] + v1[3] * v1[3]);
;                 }
;                 part_ss += __shfl_xor(part_ss, 16); part_ss += __shfl_xor(part_ss, 32);
;                 if (fq == 0) atomicAdd(ss + row, part_ss);
.LBB0_389:
	s_or_b64 exec, exec, s[6:7]
	v_lshlrev_b32_e32 v188, 16, v180
	v_and_b32_e32 v180, 0xffff0000, v180
	v_add_f32_e32 v189, v117, v180
	v_lshlrev_b32_e32 v180, 16, v181
	v_add_f32_e32 v190, v118, v180
	v_and_b32_e32 v180, 0xffff0000, v181
	v_add_f32_e32 v191, v119, v180
	v_lshlrev_b32_e32 v180, 16, v182
	s_waitcnt lgkmcnt(0)
	v_lshl_add_u64 v[186:187], s[30:31], 0, v[234:235]
	v_add_f32_e32 v234, v108, v180
	v_and_b32_e32 v180, 0xffff0000, v182
	v_add_f32_e32 v182, v109, v180
	v_lshlrev_b32_e32 v180, 16, v183
	v_add_f32_e32 v235, v110, v180
	v_and_b32_e32 v180, 0xffff0000, v183
	v_add_f32_e32 v188, v116, v188
	v_add_f32_e32 v183, v111, v180
	v_cvt_pk_bf16_f32 v180, v188, v189
	v_mul_f32_e32 v189, v189, v189
	v_fmac_f32_e32 v189, v188, v188
	v_mul_f32_e32 v188, v191, v191
	v_fmac_f32_e32 v188, v190, v190
	v_add_f32_e32 v188, v189, v188
	v_mul_f32_e32 v189, v182, v182
	v_cvt_pk_bf16_f32 v181, v190, v191
	v_fmac_f32_e32 v189, v234, v234
	v_lshlrev_b32_e32 v190, 16, v177
	v_and_b32_e32 v177, 0xffff0000, v177
	v_add_f32_e32 v188, v189, v188
	v_mul_f32_e32 v189, v183, v183
	v_add_f32_e32 v191, v99, v177
	v_lshlrev_b32_e32 v177, 16, v178
	v_fmac_f32_e32 v189, v235, v235
	v_add_f32_e32 v236, v88, v177
	v_and_b32_e32 v177, 0xffff0000, v178
	v_add_f32_e32 v188, v189, v188
	v_lshlrev_b32_e32 v189, 16, v176
	v_and_b32_e32 v176, 0xffff0000, v176
	v_add_f32_e32 v237, v89, v177
	v_lshlrev_b32_e32 v177, 16, v179
	v_add_f32_e32 v176, v97, v176
	v_add_f32_e32 v246, v90, v177
	v_and_b32_e32 v177, 0xffff0000, v179
	v_add_f32_e32 v189, v96, v189
	v_add_f32_e32 v190, v98, v190
	v_add_f32_e32 v247, v91, v177
	v_mul_f32_e32 v177, v176, v176
	v_mul_f32_e32 v178, v191, v191
	v_fmac_f32_e32 v177, v189, v189
	v_fmac_f32_e32 v178, v190, v190
	v_add_f32_e32 v177, v177, v178
	v_mul_f32_e32 v178, v237, v237
	v_fmac_f32_e32 v178, v236, v236
	v_add_f32_e32 v177, v178, v177
	v_mul_f32_e32 v178, v247, v247
	v_fmac_f32_e32 v178, v246, v246
	v_add_f32_e32 v177, v178, v177
	v_add_f32_e32 v177, v188, v177
	ds_bpermute_b32 v179, v184, v177
	v_lshl_add_u64 v[186:187], v[204:205], 1, v[186:187]
	v_cvt_pk_bf16_f32 v182, v234, v182
	v_cvt_pk_bf16_f32 v183, v235, v183
	global_store_dwordx4 v[186:187], v[180:183], off sc1
	v_cvt_pk_bf16_f32 v178, v189, v176
	s_waitcnt lgkmcnt(0)
	v_add_f32_e32 v176, v177, v179
	ds_bpermute_b32 v177, v185, v176
	v_cvt_pk_bf16_f32 v179, v190, v191
	v_cvt_pk_bf16_f32 v180, v236, v237
	v_cvt_pk_bf16_f32 v181, v246, v247
	global_store_dwordx4 v[186:187], v[178:181], off offset:256 sc1
	s_and_saveexec_b64 s[6:7], s[2:3]
	s_cbranch_execz .LBB0_391
	s_waitcnt lgkmcnt(0)
	v_add_f32_e32 v178, v176, v177
	v_lshl_add_u64 v[176:177], v[230:231], 2, s[42:43]
	global_atomic_add_f32 v[176:177], v178, off
.LBB0_391:
	s_or_b64 exec, exec, s[6:7]
	v_lshlrev_b32_e32 v178, 16, v172
	v_and_b32_e32 v172, 0xffff0000, v172
	v_add_f32_e32 v179, v101, v172
	v_lshlrev_b32_e32 v172, 16, v173
	v_add_f32_e32 v180, v102, v172
	v_and_b32_e32 v172, 0xffff0000, v173
	v_add_f32_e32 v181, v103, v172
	v_lshlrev_b32_e32 v172, 16, v174
	v_add_f32_e32 v182, v92, v172
	v_and_b32_e32 v172, 0xffff0000, v174
	v_add_f32_e32 v174, v93, v172
	v_lshlrev_b32_e32 v172, 16, v175
	v_add_f32_e32 v183, v94, v172
	v_and_b32_e32 v172, 0xffff0000, v175
	v_add_f32_e32 v178, v100, v178
	v_add_f32_e32 v175, v95, v172
	v_cvt_pk_bf16_f32 v172, v178, v179
	v_mul_f32_e32 v179, v179, v179
	v_fmac_f32_e32 v179, v178, v178
	v_mul_f32_e32 v178, v181, v181
	v_fmac_f32_e32 v178, v180, v180
	v_add_f32_e32 v178, v179, v178
	v_mul_f32_e32 v179, v174, v174
	v_cvt_pk_bf16_f32 v173, v180, v181
	v_fmac_f32_e32 v179, v182, v182
	v_lshlrev_b32_e32 v180, 16, v169
	v_and_b32_e32 v169, 0xffff0000, v169
	v_add_f32_e32 v178, v179, v178
	v_mul_f32_e32 v179, v175, v175
	v_add_f32_e32 v181, v83, v169
	v_lshlrev_b32_e32 v169, 16, v170
	v_fmac_f32_e32 v179, v183, v183
	v_add_f32_e32 v186, v72, v169
	v_and_b32_e32 v169, 0xffff0000, v170
	v_add_f32_e32 v178, v179, v178
	v_lshlrev_b32_e32 v179, 16, v168
	v_and_b32_e32 v168, 0xffff0000, v168
	v_add_f32_e32 v187, v73, v169
	v_lshlrev_b32_e32 v169, 16, v171
	v_add_f32_e32 v168, v81, v168
	v_add_f32_e32 v188, v74, v169
	v_and_b32_e32 v169, 0xffff0000, v171
	v_add_f32_e32 v179, v80, v179
	v_add_f32_e32 v180, v82, v180
	v_add_f32_e32 v189, v75, v169
	v_mul_f32_e32 v169, v168, v168
	v_mul_f32_e32 v170, v181, v181
	v_fmac_f32_e32 v169, v179, v179
	v_fmac_f32_e32 v170, v180, v180
	v_add_f32_e32 v169, v169, v170
	v_mul_f32_e32 v170, v187, v187
	v_fmac_f32_e32 v170, v186, v186
	v_add_f32_e32 v169, v170, v169
	v_mul_f32_e32 v170, v189, v189
	v_fmac_f32_e32 v170, v188, v188
	v_add_f32_e32 v169, v170, v169
	v_add_f32_e32 v169, v178, v169
	ds_bpermute_b32 v171, v184, v169
	s_waitcnt lgkmcnt(1)
	v_lshl_add_u64 v[176:177], s[30:31], 0, v[232:233]
	v_lshl_add_u64 v[176:177], v[204:205], 1, v[176:177]
	v_cvt_pk_bf16_f32 v174, v182, v174
	v_cvt_pk_bf16_f32 v175, v183, v175
	global_store_dwordx4 v[176:177], v[172:175], off sc1
	v_cvt_pk_bf16_f32 v170, v179, v168
	s_waitcnt lgkmcnt(0)
	v_add_f32_e32 v168, v169, v171
	ds_bpermute_b32 v169, v185, v168
	v_cvt_pk_bf16_f32 v171, v180, v181
	v_cvt_pk_bf16_f32 v172, v186, v187
	v_cvt_pk_bf16_f32 v173, v188, v189
	global_store_dwordx4 v[176:177], v[170:173], off offset:256 sc1
	s_and_saveexec_b64 s[6:7], s[2:3]
	s_cbranch_execz .LBB0_393
	s_waitcnt lgkmcnt(0)
	v_add_f32_e32 v170, v168, v169
	v_lshl_add_u64 v[168:169], v[226:227], 2, s[42:43]
	global_atomic_add_f32 v[168:169], v170, off
; __device__ __forceinline__ unsigned cvt_pk_bf16(float lo, float hi) { unsigned r; asm volatile("v_cvt_pk_bf16_f32 %0, %1, %2" : "=v"(r) : "v"(lo), "v"(hi)); return r; }
;     __device__ __forceinline__ void operator()(const f32x4 (&acc)[2][2][4][2], const Unit& u, int wr, int wc, int fr, int fq) const {
;     ...
;         for (int ai = 0; ai < 2; ++ai)
; #pragma unroll
;             for (int m = 0; m < 4; ++m) {
;                 const int row = row0 + ai * HALF + m * 16;
;                 bf16_t* xr = xb + (size_t)row * 1024 + col0;
;                 float part_ss = 0.f;
; #pragma unroll
;                 for (int bj = 0; bj < 2; ++bj) {
;                     const u32x4 o = xo[ai][m][bj];
;                     f32x4 v0 = acc[ai][bj][m][0], v1 = acc[ai][bj][m][1];
;                     v0[0] += __uint_as_float(o.x << 16); v0[1] += __uint_as_float(o.x & 0xffff0000u); v0[2] += __uint_as_float(o.y << 16); v0[3] += __uint_as_float(o.y & 0xffff0000u);
;                     v1[0] += __uint_as_float(o.z << 16); v1[1] += __uint_as_float(o.z & 0xffff0000u); v1[2] += __uint_as_float(o.w << 16); v1[3] += __uint_as_float(o.w & 0xffff0000u);
;                     if (xout) { float* xo = xout + (size_t)row * 1024 + col0 + bj * HALF; *(f32x4*)xo = v0; *(f32x4*)(xo + 4) = v1; }
;                     else { u32x4 w; w.x = cvt_pk_bf16(v0[0], v0[1]); w.y = cvt_pk_bf16(v0[2], v0[3]); w.z = cvt_pk_bf16(v1[0], v1[1]); w.w = cvt_pk_bf16(v1[2], v1[3]); *(u32x4*)(xr + bj * HALF) = w; }
;                     part_ss += (v0[0] * v0[0] + v0[1] * v0[1]) + (v0[2] * v0[2] + v0[3] * v0[3]) + (v1[0] * v1[0] + v1[1] * v1[1]) + (v1[2] * v1[2] + v1[3] * v1[3]);
;                 }
;                 part_ss += __shfl_xor(part_ss, 16); part_ss += __shfl_xor(part_ss, 32);
;                 if (fq == 0) atomicAdd(ss + row, part_ss);
.LBB0_393:
	s_or_b64 exec, exec, s[6:7]
	v_lshlrev_b32_e32 v170, 16, v164
	v_and_b32_e32 v164, 0xffff0000, v164
	v_add_f32_e32 v171, v85, v164
	v_lshlrev_b32_e32 v164, 16, v165
	v_add_f32_e32 v172, v86, v164
	v_and_b32_e32 v164, 0xffff0000, v165
	v_add_f32_e32 v173, v87, v164
	v_lshlrev_b32_e32 v164, 16, v166
	v_add_f32_e32 v174, v76, v164
	v_and_b32_e32 v164, 0xffff0000, v166
	v_add_f32_e32 v166, v77, v164
	v_lshlrev_b32_e32 v164, 16, v167
	v_add_f32_e32 v175, v78, v164
	v_and_b32_e32 v164, 0xffff0000, v167
	v_add_f32_e32 v170, v84, v170
	v_add_f32_e32 v167, v79, v164
	v_cvt_pk_bf16_f32 v164, v170, v171
	v_mul_f32_e32 v171, v171, v171
	v_fmac_f32_e32 v171, v170, v170
	v_mul_f32_e32 v170, v173, v173
	v_fmac_f32_e32 v170, v172, v172
	v_add_f32_e32 v170, v171, v170
	v_mul_f32_e32 v171, v166, v166
	v_cvt_pk_bf16_f32 v165, v172, v173
	v_fmac_f32_e32 v171, v174, v174
	v_lshlrev_b32_e32 v172, 16, v161
	v_and_b32_e32 v161, 0xffff0000, v161
	v_add_f32_e32 v170, v171, v170
	v_mul_f32_e32 v171, v167, v167
	v_add_f32_e32 v173, v71, v161
	v_lshlrev_b32_e32 v161, 16, v162
	v_fmac_f32_e32 v171, v175, v175
	v_add_f32_e32 v176, v64, v161
	v_and_b32_e32 v161, 0xffff0000, v162
	v_add_f32_e32 v170, v171, v170
	v_lshlrev_b32_e32 v171, 16, v160
	v_and_b32_e32 v160, 0xffff0000, v160
	v_add_f32_e32 v177, v65, v161
	v_lshlrev_b32_e32 v161, 16, v163
	v_add_f32_e32 v160, v69, v160
	v_add_f32_e32 v178, v66, v161
	v_and_b32_e32 v161, 0xffff0000, v163
	v_add_f32_e32 v171, v68, v171
	v_add_f32_e32 v172, v70, v172
	v_add_f32_e32 v179, v67, v161
	v_mul_f32_e32 v161, v160, v160
	v_mul_f32_e32 v162, v173, v173
	v_fmac_f32_e32 v161, v171, v171
	v_fmac_f32_e32 v162, v172, v172
	v_add_f32_e32 v161, v161, v162
	v_mul_f32_e32 v162, v177, v177
	v_fmac_f32_e32 v162, v176, v176
	v_add_f32_e32 v161, v162, v161
	v_mul_f32_e32 v162, v179, v179
	v_fmac_f32_e32 v162, v178, v178
	v_add_f32_e32 v161, v162, v161
	v_add_f32_e32 v161, v170, v161
	ds_bpermute_b32 v163, v184, v161
	s_waitcnt lgkmcnt(1)
	v_lshl_add_u64 v[168:169], s[30:31], 0, v[228:229]
	v_lshl_add_u64 v[168:169], v[204:205], 1, v[168:169]
	v_cvt_pk_bf16_f32 v166, v174, v166
	v_cvt_pk_bf16_f32 v167, v175, v167
	global_store_dwordx4 v[168:169], v[164:167], off sc1
	v_cvt_pk_bf16_f32 v162, v171, v160
	s_waitcnt lgkmcnt(0)
	v_add_f32_e32 v160, v161, v163
	ds_bpermute_b32 v161, v185, v160
	v_cvt_pk_bf16_f32 v163, v172, v173
	v_cvt_pk_bf16_f32 v164, v176, v177
	v_cvt_pk_bf16_f32 v165, v178, v179
	global_store_dwordx4 v[168:169], v[162:165], off offset:256 sc1
	s_and_saveexec_b64 s[6:7], s[2:3]
	s_cbranch_execz .LBB0_395
	s_waitcnt lgkmcnt(0)
	v_add_f32_e32 v162, v160, v161
	v_lshl_add_u64 v[160:161], v[222:223], 2, s[42:43]
	global_atomic_add_f32 v[160:161], v162, off
.LBB0_395:
	s_or_b64 exec, exec, s[6:7]
	v_lshlrev_b32_e32 v162, 16, v156
	v_and_b32_e32 v156, 0xffff0000, v156
	v_add_f32_e32 v163, v61, v156
	v_lshlrev_b32_e32 v156, 16, v157
	v_add_f32_e32 v164, v62, v156
	v_and_b32_e32 v156, 0xffff0000, v157
	v_add_f32_e32 v165, v63, v156
	v_lshlrev_b32_e32 v156, 16, v158
	v_add_f32_e32 v166, v56, v156
	v_and_b32_e32 v156, 0xffff0000, v158
	v_add_f32_e32 v158, v57, v156
	v_lshlrev_b32_e32 v156, 16, v159
	v_add_f32_e32 v167, v58, v156
	v_and_b32_e32 v156, 0xffff0000, v159
	v_add_f32_e32 v162, v60, v162
	v_add_f32_e32 v159, v59, v156
	v_cvt_pk_bf16_f32 v156, v162, v163
	v_mul_f32_e32 v163, v163, v163
	v_fmac_f32_e32 v163, v162, v162
	v_mul_f32_e32 v162, v165, v165
	v_fmac_f32_e32 v162, v164, v164
	v_add_f32_e32 v162, v163, v162
	v_mul_f32_e32 v163, v158, v158
	v_cvt_pk_bf16_f32 v157, v164, v165
	v_fmac_f32_e32 v163, v166, v166
	v_lshlrev_b32_e32 v164, 16, v153
	v_and_b32_e32 v153, 0xffff0000, v153
	v_add_f32_e32 v162, v163, v162
	v_mul_f32_e32 v163, v159, v159
	v_add_f32_e32 v165, v51, v153
	v_lshlrev_b32_e32 v153, 16, v154
	v_fmac_f32_e32 v163, v167, v167
	v_add_f32_e32 v168, v40, v153
	v_and_b32_e32 v153, 0xffff0000, v154
	v_add_f32_e32 v162, v163, v162
	v_lshlrev_b32_e32 v163, 16, v152
	v_and_b32_e32 v152, 0xffff0000, v152
	v_add_f32_e32 v169, v41, v153
	v_lshlrev_b32_e32 v153, 16, v155
	v_add_f32_e32 v152, v49, v152
	v_add_f32_e32 v170, v42, v153
	v_and_b32_e32 v153, 0xffff0000, v155
	v_add_f32_e32 v163, v48, v163
	v_add_f32_e32 v164, v50, v164
	v_add_f32_e32 v171, v43, v153
	v_mul_f32_e32 v153, v152, v152
	v_mul_f32_e32 v154, v165, v165
	v_fmac_f32_e32 v153, v163, v163
	v_fmac_f32_e32 v154, v164, v164
	v_add_f32_e32 v153, v153, v154
	v_mul_f32_e32 v154, v169, v169
	v_fmac_f32_e32 v154, v168, v168
	v_add_f32_e32 v153, v154, v153
	v_mul_f32_e32 v154, v171, v171
	v_fmac_f32_e32 v154, v170, v170
	v_add_f32_e32 v153, v154, v153
	v_add_f32_e32 v153, v162, v153
	ds_bpermute_b32 v155, v184, v153
	s_waitcnt lgkmcnt(1)
	v_lshl_add_u64 v[160:161], s[30:31], 0, v[224:225]
	v_lshl_add_u64 v[160:161], v[204:205], 1, v[160:161]
	v_cvt_pk_bf16_f32 v158, v166, v158
	v_cvt_pk_bf16_f32 v159, v167, v159
	global_store_dwordx4 v[160:161], v[156:159], off sc1
	v_cvt_pk_bf16_f32 v154, v163, v152
	s_waitcnt lgkmcnt(0)
	v_add_f32_e32 v152, v153, v155
	ds_bpermute_b32 v153, v185, v152
	v_cvt_pk_bf16_f32 v155, v164, v165
	v_cvt_pk_bf16_f32 v156, v168, v169
	v_cvt_pk_bf16_f32 v157, v170, v171
	global_store_dwordx4 v[160:161], v[154:157], off offset:256 sc1
	s_and_saveexec_b64 s[6:7], s[2:3]
	s_cbranch_execz .LBB0_397
	s_waitcnt lgkmcnt(0)
	v_add_f32_e32 v154, v152, v153
	v_lshl_add_u64 v[152:153], v[218:219], 2, s[42:43]
	global_atomic_add_f32 v[152:153], v154, off
; __device__ __forceinline__ unsigned cvt_pk_bf16(float lo, float hi) { unsigned r; asm volatile("v_cvt_pk_bf16_f32 %0, %1, %2" : "=v"(r) : "v"(lo), "v"(hi)); return r; }
;     __device__ __forceinline__ void operator()(const f32x4 (&acc)[2][2][4][2], const Unit& u, int wr, int wc, int fr, int fq) const {
;     ...
;         for (int ai = 0; ai < 2; ++ai)
; #pragma unroll
;             for (int m = 0; m < 4; ++m) {
;                 const int row = row0 + ai * HALF + m * 16;
;                 bf16_t* xr = xb + (size_t)row * 1024 + col0;
;                 float part_ss = 0.f;
; #pragma unroll
;                 for (int bj = 0; bj < 2; ++bj) {
;                     const u32x4 o = xo[ai][m][bj];
;                     f32x4 v0 = acc[ai][bj][m][0], v1 = acc[ai][bj][m][1];
;                     v0[0] += __uint_as_float(o.x << 16); v0[1] += __uint_as_float(o.x & 0xffff0000u); v0[2] += __uint_as_float(o.y << 16); v0[3] += __uint_as_float(o.y & 0xffff0000u);
;                     v1[0] += __uint_as_float(o.z << 16); v1[1] += __uint_as_float(o.z & 0xffff0000u); v1[2] += __uint_as_float(o.w << 16); v1[3] += __uint_as_float(o.w & 0xffff0000u);
;                     if (xout) { float* xo = xout + (size_t)row * 1024 + col0 + bj * HALF; *(f32x4*)xo = v0; *(f32x4*)(xo + 4) = v1; }
;                     else { u32x4 w; w.x = cvt_pk_bf16(v0[0], v0[1]); w.y = cvt_pk_bf16(v0[2], v0[3]); w.z = cvt_pk_bf16(v1[0], v1[1]); w.w = cvt_pk_bf16(v1[2], v1[3]); *(u32x4*)(xr + bj * HALF) = w; }
;                     part_ss += (v0[0] * v0[0] + v0[1] * v0[1]) + (v0[2] * v0[2] + v0[3] * v0[3]) + (v1[0] * v1[0] + v1[1] * v1[1]) + (v1[2] * v1[2] + v1[3] * v1[3]);
;                 }
;                 part_ss += __shfl_xor(part_ss, 16); part_ss += __shfl_xor(part_ss, 32);
;                 if (fq == 0) atomicAdd(ss + row, part_ss);
.LBB0_397:
	s_or_b64 exec, exec, s[6:7]
	v_lshlrev_b32_e32 v154, 16, v148
	v_and_b32_e32 v148, 0xffff0000, v148
	v_add_f32_e32 v155, v53, v148
	v_lshlrev_b32_e32 v148, 16, v149
	v_add_f32_e32 v156, v54, v148
	v_and_b32_e32 v148, 0xffff0000, v149
	v_add_f32_e32 v157, v55, v148
	v_lshlrev_b32_e32 v148, 16, v150
	v_add_f32_e32 v158, v44, v148
	v_and_b32_e32 v148, 0xffff0000, v150
	v_add_f32_e32 v150, v45, v148
	v_lshlrev_b32_e32 v148, 16, v151
	v_add_f32_e32 v159, v46, v148
	v_and_b32_e32 v148, 0xffff0000, v151
	v_add_f32_e32 v154, v52, v154
	v_add_f32_e32 v151, v47, v148
	v_cvt_pk_bf16_f32 v148, v154, v155
	v_mul_f32_e32 v155, v155, v155
	v_fmac_f32_e32 v155, v154, v154
	v_mul_f32_e32 v154, v157, v157
	v_fmac_f32_e32 v154, v156, v156
	v_add_f32_e32 v154, v155, v154
	v_mul_f32_e32 v155, v150, v150
	v_cvt_pk_bf16_f32 v149, v156, v157
	v_fmac_f32_e32 v155, v158, v158
	v_lshlrev_b32_e32 v156, 16, v145
	v_and_b32_e32 v145, 0xffff0000, v145
	v_add_f32_e32 v154, v155, v154
	v_mul_f32_e32 v155, v151, v151
	v_add_f32_e32 v157, v35, v145
	v_lshlrev_b32_e32 v145, 16, v146
	v_fmac_f32_e32 v155, v159, v159
	v_add_f32_e32 v160, v24, v145
	v_and_b32_e32 v145, 0xffff0000, v146
	v_add_f32_e32 v154, v155, v154
	v_lshlrev_b32_e32 v155, 16, v144
	v_and_b32_e32 v144, 0xffff0000, v144
	v_add_f32_e32 v161, v25, v145
	v_lshlrev_b32_e32 v145, 16, v147
	v_add_f32_e32 v144, v33, v144
	v_add_f32_e32 v162, v26, v145
	v_and_b32_e32 v145, 0xffff0000, v147
	v_add_f32_e32 v155, v32, v155
	v_add_f32_e32 v156, v34, v156
	v_add_f32_e32 v163, v27, v145
	v_mul_f32_e32 v145, v144, v144
	v_mul_f32_e32 v146, v157, v157
	v_fmac_f32_e32 v145, v155, v155
	v_fmac_f32_e32 v146, v156, v156
	v_add_f32_e32 v145, v145, v146
	v_mul_f32_e32 v146, v161, v161
	v_fmac_f32_e32 v146, v160, v160
	v_add_f32_e32 v145, v146, v145
	v_mul_f32_e32 v146, v163, v163
	v_fmac_f32_e32 v146, v162, v162
	v_add_f32_e32 v145, v146, v145
	v_add_f32_e32 v145, v154, v145
	ds_bpermute_b32 v147, v184, v145
	s_waitcnt lgkmcnt(1)
	v_lshl_add_u64 v[152:153], s[30:31], 0, v[220:221]
	v_lshl_add_u64 v[152:153], v[204:205], 1, v[152:153]
	v_cvt_pk_bf16_f32 v150, v158, v150
	v_cvt_pk_bf16_f32 v151, v159, v151
	global_store_dwordx4 v[152:153], v[148:151], off sc1
	v_cvt_pk_bf16_f32 v146, v155, v144
	s_waitcnt lgkmcnt(0)
	v_add_f32_e32 v144, v145, v147
	ds_bpermute_b32 v145, v185, v144
	v_cvt_pk_bf16_f32 v147, v156, v157
	v_cvt_pk_bf16_f32 v148, v160, v161
	v_cvt_pk_bf16_f32 v149, v162, v163
	global_store_dwordx4 v[152:153], v[146:149], off offset:256 sc1
	s_and_saveexec_b64 s[6:7], s[2:3]
	s_cbranch_execz .LBB0_399
	s_waitcnt lgkmcnt(0)
	v_add_f32_e32 v146, v144, v145
	v_lshl_add_u64 v[144:145], v[214:215], 2, s[42:43]
	global_atomic_add_f32 v[144:145], v146, off
; __device__ __forceinline__ unsigned cvt_pk_bf16(float lo, float hi) { unsigned r; asm volatile("v_cvt_pk_bf16_f32 %0, %1, %2" : "=v"(r) : "v"(lo), "v"(hi)); return r; }
;     __device__ __forceinline__ void operator()(const f32x4 (&acc)[2][2][4][2], const Unit& u, int wr, int wc, int fr, int fq) const {
;     ...
;         for (int ai = 0; ai < 2; ++ai)
; #pragma unroll
;             for (int m = 0; m < 4; ++m) {
;                 const int row = row0 + ai * HALF + m * 16;
;                 bf16_t* xr = xb + (size_t)row * 1024 + col0;
;                 float part_ss = 0.f;
; #pragma unroll
;                 for (int bj = 0; bj < 2; ++bj) {
;                     const u32x4 o = xo[ai][m][bj];
;                     f32x4 v0 = acc[ai][bj][m][0], v1 = acc[ai][bj][m][1];
;                     v0[0] += __uint_as_float(o.x << 16); v0[1] += __uint_as_float(o.x & 0xffff0000u); v0[2] += __uint_as_float(o.y << 16); v0[3] += __uint_as_float(o.y & 0xffff0000u);
;                     v1[0] += __uint_as_float(o.z << 16); v1[1] += __uint_as_float(o.z & 0xffff0000u); v1[2] += __uint_as_float(o.w << 16); v1[3] += __uint_as_float(o.w & 0xffff0000u);
;                     if (xout) { float* xo = xout + (size_t)row * 1024 + col0 + bj * HALF; *(f32x4*)xo = v0; *(f32x4*)(xo + 4) = v1; }
;                     else { u32x4 w; w.x = cvt_pk_bf16(v0[0], v0[1]); w.y = cvt_pk_bf16(v0[2], v0[3]); w.z = cvt_pk_bf16(v1[0], v1[1]); w.w = cvt_pk_bf16(v1[2], v1[3]); *(u32x4*)(xr + bj * HALF) = w; }
;                     part_ss += (v0[0] * v0[0] + v0[1] * v0[1]) + (v0[2] * v0[2] + v0[3] * v0[3]) + (v1[0] * v1[0] + v1[1] * v1[1]) + (v1[2] * v1[2] + v1[3] * v1[3]);
;                 }
;                 part_ss += __shfl_xor(part_ss, 16); part_ss += __shfl_xor(part_ss, 32);
;                 if (fq == 0) atomicAdd(ss + row, part_ss);
.LBB0_399:
	s_or_b64 exec, exec, s[6:7]
	v_lshlrev_b32_e32 v146, 16, v140
	v_and_b32_e32 v140, 0xffff0000, v140
	v_add_f32_e32 v147, v37, v140
	v_lshlrev_b32_e32 v140, 16, v141
	v_add_f32_e32 v148, v38, v140
	v_and_b32_e32 v140, 0xffff0000, v141
	v_add_f32_e32 v149, v39, v140
	v_lshlrev_b32_e32 v140, 16, v142
	v_add_f32_e32 v150, v28, v140
	v_and_b32_e32 v140, 0xffff0000, v142
	v_add_f32_e32 v142, v29, v140
	v_lshlrev_b32_e32 v140, 16, v143
	v_add_f32_e32 v151, v30, v140
	v_and_b32_e32 v140, 0xffff0000, v143
	v_add_f32_e32 v146, v36, v146
	v_add_f32_e32 v143, v31, v140
	v_cvt_pk_bf16_f32 v140, v146, v147
	v_mul_f32_e32 v147, v147, v147
	v_fmac_f32_e32 v147, v146, v146
	v_mul_f32_e32 v146, v149, v149
	v_fmac_f32_e32 v146, v148, v148
	v_add_f32_e32 v146, v147, v146
	v_mul_f32_e32 v147, v142, v142
	v_cvt_pk_bf16_f32 v141, v148, v149
	v_fmac_f32_e32 v147, v150, v150
	v_lshlrev_b32_e32 v148, 16, v137
	v_and_b32_e32 v137, 0xffff0000, v137
	v_add_f32_e32 v146, v147, v146
	v_mul_f32_e32 v147, v143, v143
	v_add_f32_e32 v149, v19, v137
	v_lshlrev_b32_e32 v137, 16, v138
	v_fmac_f32_e32 v147, v151, v151
	v_add_f32_e32 v152, v8, v137
	v_and_b32_e32 v137, 0xffff0000, v138
	v_add_f32_e32 v146, v147, v146
	v_lshlrev_b32_e32 v147, 16, v136
	v_and_b32_e32 v136, 0xffff0000, v136
	v_add_f32_e32 v153, v9, v137
	v_lshlrev_b32_e32 v137, 16, v139
	v_add_f32_e32 v136, v17, v136
	v_add_f32_e32 v154, v10, v137
	v_and_b32_e32 v137, 0xffff0000, v139
	v_add_f32_e32 v147, v16, v147
	v_add_f32_e32 v148, v18, v148
	v_add_f32_e32 v155, v11, v137
	v_mul_f32_e32 v137, v136, v136
	v_mul_f32_e32 v138, v149, v149
	v_fmac_f32_e32 v137, v147, v147
	v_fmac_f32_e32 v138, v148, v148
	v_add_f32_e32 v137, v137, v138
	v_mul_f32_e32 v138, v153, v153
	v_fmac_f32_e32 v138, v152, v152
	v_add_f32_e32 v137, v138, v137
	v_mul_f32_e32 v138, v155, v155
	v_fmac_f32_e32 v138, v154, v154
	v_add_f32_e32 v137, v138, v137
	v_add_f32_e32 v137, v146, v137
	ds_bpermute_b32 v139, v184, v137
	s_waitcnt lgkmcnt(1)
	v_lshl_add_u64 v[144:145], s[30:31], 0, v[216:217]
	v_lshl_add_u64 v[144:145], v[204:205], 1, v[144:145]
	v_cvt_pk_bf16_f32 v142, v150, v142
	v_cvt_pk_bf16_f32 v143, v151, v143
	global_store_dwordx4 v[144:145], v[140:143], off sc1
	v_cvt_pk_bf16_f32 v138, v147, v136
	s_waitcnt lgkmcnt(0)
	v_add_f32_e32 v136, v137, v139
	ds_bpermute_b32 v137, v185, v136
	v_cvt_pk_bf16_f32 v139, v148, v149
	v_cvt_pk_bf16_f32 v140, v152, v153
	v_cvt_pk_bf16_f32 v141, v154, v155
	global_store_dwordx4 v[144:145], v[138:141], off offset:256 sc1
	s_and_saveexec_b64 s[6:7], s[2:3]
	s_cbranch_execz .LBB0_401
	s_waitcnt lgkmcnt(0)
	v_add_f32_e32 v138, v136, v137
	v_lshl_add_u64 v[136:137], v[210:211], 2, s[42:43]
	global_atomic_add_f32 v[136:137], v138, off
.LBB0_401:
	s_or_b64 exec, exec, s[6:7]
	v_lshlrev_b32_e32 v138, 16, v132
	v_and_b32_e32 v132, 0xffff0000, v132
	v_add_f32_e32 v139, v21, v132
	v_lshlrev_b32_e32 v132, 16, v133
	v_add_f32_e32 v140, v22, v132
	v_and_b32_e32 v132, 0xffff0000, v133
	v_add_f32_e32 v141, v23, v132
	v_lshlrev_b32_e32 v132, 16, v134
	v_add_f32_e32 v142, v12, v132
	v_and_b32_e32 v132, 0xffff0000, v134
	v_add_f32_e32 v134, v13, v132
	v_lshlrev_b32_e32 v132, 16, v135
	v_add_f32_e32 v143, v14, v132
	v_and_b32_e32 v132, 0xffff0000, v135
	v_add_f32_e32 v138, v20, v138
	v_add_f32_e32 v135, v15, v132
	v_cvt_pk_bf16_f32 v132, v138, v139
	v_mul_f32_e32 v139, v139, v139
	v_fmac_f32_e32 v139, v138, v138
	v_mul_f32_e32 v138, v141, v141
	v_fmac_f32_e32 v138, v140, v140
	v_add_f32_e32 v138, v139, v138
	v_mul_f32_e32 v139, v134, v134
	v_cvt_pk_bf16_f32 v133, v140, v141
	v_fmac_f32_e32 v139, v142, v142
	v_lshlrev_b32_e32 v140, 16, v129
	v_and_b32_e32 v129, 0xffff0000, v129
	v_add_f32_e32 v138, v139, v138
	v_mul_f32_e32 v139, v135, v135
	v_add_f32_e32 v141, v7, v129
	v_lshlrev_b32_e32 v129, 16, v130
	v_fmac_f32_e32 v139, v143, v143
	v_add_f32_e32 v144, v0, v129
	v_and_b32_e32 v129, 0xffff0000, v130
	v_add_f32_e32 v138, v139, v138
	v_lshlrev_b32_e32 v139, 16, v128
	v_and_b32_e32 v128, 0xffff0000, v128
	v_add_f32_e32 v145, v1, v129
	v_lshlrev_b32_e32 v129, 16, v131
	v_add_f32_e32 v128, v5, v128
	v_add_f32_e32 v146, v2, v129
	v_and_b32_e32 v129, 0xffff0000, v131
	v_add_f32_e32 v139, v4, v139
	v_add_f32_e32 v140, v6, v140
	v_add_f32_e32 v147, v3, v129
	v_mul_f32_e32 v129, v128, v128
	v_mul_f32_e32 v130, v141, v141
	v_fmac_f32_e32 v129, v139, v139
	v_fmac_f32_e32 v130, v140, v140
	v_add_f32_e32 v129, v129, v130
	v_mul_f32_e32 v130, v145, v145
	v_fmac_f32_e32 v130, v144, v144
	v_add_f32_e32 v129, v130, v129
	v_mul_f32_e32 v130, v147, v147
	v_fmac_f32_e32 v130, v146, v146
	v_add_f32_e32 v129, v130, v129
	v_add_f32_e32 v129, v138, v129
	ds_bpermute_b32 v131, v184, v129
	s_waitcnt lgkmcnt(1)
	v_lshl_add_u64 v[136:137], s[30:31], 0, v[212:213]
	v_lshl_add_u64 v[136:137], v[204:205], 1, v[136:137]
	v_cvt_pk_bf16_f32 v134, v142, v134
	v_cvt_pk_bf16_f32 v135, v143, v135
	global_store_dwordx4 v[136:137], v[132:135], off sc1
	v_cvt_pk_bf16_f32 v130, v139, v128
	s_waitcnt lgkmcnt(0)
	v_add_f32_e32 v128, v129, v131
	ds_bpermute_b32 v129, v185, v128
	v_cvt_pk_bf16_f32 v131, v140, v141
	v_cvt_pk_bf16_f32 v132, v144, v145
	v_cvt_pk_bf16_f32 v133, v146, v147
	global_store_dwordx4 v[136:137], v[130:133], off offset:256 sc1
	s_and_saveexec_b64 s[6:7], s[2:3]
	s_cbranch_execz .LBB0_403
	s_waitcnt lgkmcnt(0)
	v_add_f32_e32 v130, v128, v129
	v_lshl_add_u64 v[128:129], v[208:209], 2, s[42:43]
	global_atomic_add_f32 v[128:129], v130, off

; __device__ __forceinline__ unsigned cvt_pk_bf16(float lo, float hi) { unsigned r; asm volatile("v_cvt_pk_bf16_f32 %0, %1, %2" : "=v"(r) : "v"(lo), "v"(hi)); return r; }
;     __device__ __forceinline__ void operator()(const f32x4 (&acc)[2][2][4][2], const Unit& u, int wr, int wc, int fr, int fq) const {
;     ...
;         if (u.sp >= 0) {
;             bf16_t* pb = (bf16_t*)part + ((size_t)u.sp * 1024 + (row0 - 16384)) * 1024 + col0;
; #pragma unroll
;             for (int ai = 0; ai < 2; ++ai)
; #pragma unroll
;                 for (int m = 0; m < 4; ++m)
; #pragma unroll
;                     for (int bj = 0; bj < 2; ++bj) { const f32x4 v0 = acc[ai][bj][m][0], v1 = acc[ai][bj][m][1];
;                         u32x4 w; w.x = cvt_pk_bf16(v0[0], v0[1]); w.y = cvt_pk_bf16(v0[2], v0[3]); w.z = cvt_pk_bf16(v1[0], v1[1]); w.w = cvt_pk_bf16(v1[2], v1[3]);
;                         *(u32x4*)(pb + (size_t)(ai * HALF + m * 16) * 1024 + bj * HALF) = w; }
;             return;
.LBB0_405:
	s_and_b64 vcc, exec, s[6:7]
	s_cbranch_vccz .LBB0_404
	s_lshl_b64 s[6:7], s[50:51], 21
	s_add_u32 s6, s88, s6
	s_waitcnt lgkmcnt(0)
	v_lshlrev_b64 v[128:129], 11, v[206:207]
	s_addc_u32 s7, s89, s7
	v_lshl_add_u64 v[128:129], s[6:7], 0, v[128:129]
	s_mov_b32 s6, 0xfe000000
	v_lshl_add_u64 v[128:129], v[204:205], 1, v[128:129]
	s_mov_b32 s7, -1
	v_lshl_add_u64 v[130:131], v[128:129], 0, s[6:7]
	s_mov_b32 s6, 0xfe000000
	v_cvt_pk_bf16_f32 v124, v124, v125
	v_cvt_pk_bf16_f32 v125, v126, v127
	v_cvt_pk_bf16_f32 v126, v120, v121
	v_add_co_u32_e32 v120, vcc, s6, v128
	s_mov_b32 s6, 0xfe008000
	s_nop 0
	v_addc_co_u32_e32 v121, vcc, -1, v129, vcc
	v_cvt_pk_bf16_f32 v127, v122, v123
	global_store_dwordx4 v[120:121], v[124:127], off sc1
	v_cvt_pk_bf16_f32 v112, v112, v113
	v_cvt_pk_bf16_f32 v113, v114, v115
	v_cvt_pk_bf16_f32 v114, v104, v105
	v_cvt_pk_bf16_f32 v115, v106, v107
	global_store_dwordx4 v[130:131], v[112:115], off offset:256 sc1
	v_cvt_pk_bf16_f32 v104, v116, v117
	v_cvt_pk_bf16_f32 v105, v118, v119
	v_cvt_pk_bf16_f32 v106, v108, v109
	v_add_co_u32_e32 v108, vcc, s6, v128
	s_mov_b32 s6, 0xfe009000
	s_nop 0
	v_addc_co_u32_e32 v109, vcc, -1, v129, vcc
	v_cvt_pk_bf16_f32 v107, v110, v111
	global_store_dwordx4 v[108:109], v[104:107], off sc1
	v_cvt_pk_bf16_f32 v96, v96, v97
	v_cvt_pk_bf16_f32 v97, v98, v99
	v_cvt_pk_bf16_f32 v98, v88, v89
	v_add_co_u32_e32 v88, vcc, s6, v128
	s_mov_b32 s6, 0xfe010000
	s_nop 0
	v_addc_co_u32_e32 v89, vcc, -1, v129, vcc
	v_cvt_pk_bf16_f32 v99, v90, v91
	global_store_dwordx4 v[88:89], v[96:99], off offset:-3840 sc1
	v_cvt_pk_bf16_f32 v88, v100, v101
	v_cvt_pk_bf16_f32 v89, v102, v103
	v_cvt_pk_bf16_f32 v90, v92, v93
	v_add_co_u32_e32 v92, vcc, s6, v128
	s_mov_b32 s6, 0xfe011000
	s_nop 0
	v_addc_co_u32_e32 v93, vcc, -1, v129, vcc
	v_cvt_pk_bf16_f32 v91, v94, v95
	global_store_dwordx4 v[92:93], v[88:91], off sc1
	v_cvt_pk_bf16_f32 v80, v80, v81
	v_cvt_pk_bf16_f32 v81, v82, v83
	v_cvt_pk_bf16_f32 v82, v72, v73
	v_add_co_u32_e32 v72, vcc, s6, v128
	s_mov_b32 s6, 0xfe018000
	s_nop 0
	v_addc_co_u32_e32 v73, vcc, -1, v129, vcc
	v_cvt_pk_bf16_f32 v83, v74, v75
	global_store_dwordx4 v[72:73], v[80:83], off offset:-3840 sc1
	v_cvt_pk_bf16_f32 v72, v84, v85
	v_cvt_pk_bf16_f32 v73, v86, v87
	v_cvt_pk_bf16_f32 v74, v76, v77
	v_add_co_u32_e32 v76, vcc, s6, v128
	s_mov_b32 s6, 0xfe019000
	s_nop 0
	v_addc_co_u32_e32 v77, vcc, -1, v129, vcc
	v_cvt_pk_bf16_f32 v75, v78, v79
	global_store_dwordx4 v[76:77], v[72:75], off sc1
	v_cvt_pk_bf16_f32 v68, v68, v69
	v_cvt_pk_bf16_f32 v69, v70, v71
	v_cvt_pk_bf16_f32 v70, v64, v65
	v_add_co_u32_e32 v64, vcc, s6, v128
	s_mov_b32 s6, 0xfe040000
	s_nop 0
	v_addc_co_u32_e32 v65, vcc, -1, v129, vcc
	v_cvt_pk_bf16_f32 v71, v66, v67
	global_store_dwordx4 v[64:65], v[68:71], off offset:-3840 sc1
	v_cvt_pk_bf16_f32 v60, v60, v61
	v_cvt_pk_bf16_f32 v61, v62, v63
	v_cvt_pk_bf16_f32 v62, v56, v57
	v_add_co_u32_e32 v56, vcc, s6, v128
	s_mov_b32 s6, 0xfe041000
	s_nop 0
	v_addc_co_u32_e32 v57, vcc, -1, v129, vcc
	v_cvt_pk_bf16_f32 v63, v58, v59
	global_store_dwordx4 v[56:57], v[60:63], off sc1
	v_cvt_pk_bf16_f32 v48, v48, v49
	v_cvt_pk_bf16_f32 v49, v50, v51
	v_cvt_pk_bf16_f32 v50, v40, v41
	v_add_co_u32_e32 v40, vcc, s6, v128
	s_mov_b32 s6, 0xfe048000
	s_nop 0
	v_addc_co_u32_e32 v41, vcc, -1, v129, vcc
	v_cvt_pk_bf16_f32 v51, v42, v43
	global_store_dwordx4 v[40:41], v[48:51], off offset:-3840 sc1
	v_cvt_pk_bf16_f32 v40, v52, v53
	v_cvt_pk_bf16_f32 v41, v54, v55
	v_cvt_pk_bf16_f32 v42, v44, v45
	v_add_co_u32_e32 v44, vcc, s6, v128
	s_mov_b32 s6, 0xfe049000
	s_nop 0
	v_addc_co_u32_e32 v45, vcc, -1, v129, vcc
	v_cvt_pk_bf16_f32 v43, v46, v47
	global_store_dwordx4 v[44:45], v[40:43], off sc1
	v_cvt_pk_bf16_f32 v32, v32, v33
	v_cvt_pk_bf16_f32 v33, v34, v35
	v_cvt_pk_bf16_f32 v34, v24, v25
	v_add_co_u32_e32 v24, vcc, s6, v128
	s_mov_b32 s6, 0xfe050000
	s_nop 0
	v_addc_co_u32_e32 v25, vcc, -1, v129, vcc
	v_cvt_pk_bf16_f32 v35, v26, v27
	global_store_dwordx4 v[24:25], v[32:35], off offset:-3840 sc1
	v_cvt_pk_bf16_f32 v24, v36, v37
	v_cvt_pk_bf16_f32 v25, v38, v39
	v_cvt_pk_bf16_f32 v26, v28, v29
	v_add_co_u32_e32 v28, vcc, s6, v128
	s_mov_b32 s6, 0xfe051000
	s_nop 0
	v_addc_co_u32_e32 v29, vcc, -1, v129, vcc
	v_cvt_pk_bf16_f32 v27, v30, v31
	global_store_dwordx4 v[28:29], v[24:27], off sc1
	v_cvt_pk_bf16_f32 v16, v16, v17
	v_cvt_pk_bf16_f32 v17, v18, v19
	v_cvt_pk_bf16_f32 v18, v8, v9
	v_add_co_u32_e32 v8, vcc, s6, v128
	s_mov_b32 s6, 0xfe058000
	s_nop 0
	v_addc_co_u32_e32 v9, vcc, -1, v129, vcc
	v_cvt_pk_bf16_f32 v19, v10, v11
	global_store_dwordx4 v[8:9], v[16:19], off offset:-3840 sc1
	v_cvt_pk_bf16_f32 v8, v20, v21
	v_cvt_pk_bf16_f32 v9, v22, v23
	v_cvt_pk_bf16_f32 v10, v12, v13
	v_add_co_u32_e32 v12, vcc, s6, v128
	v_cvt_pk_bf16_f32 v11, v14, v15
	s_nop 1
	v_addc_co_u32_e32 v13, vcc, -1, v129, vcc
	global_store_dwordx4 v[12:13], v[8:11], off sc1
	v_cvt_pk_bf16_f32 v4, v4, v5
	v_cvt_pk_bf16_f32 v5, v6, v7
	v_cvt_pk_bf16_f32 v6, v0, v1
	v_add_co_u32_e32 v0, vcc, 0xfe059000, v128
	v_cvt_pk_bf16_f32 v7, v2, v3
	s_nop 1
	v_addc_co_u32_e32 v1, vcc, -1, v129, vcc
	global_store_dwordx4 v[0:1], v[4:7], off offset:-3840 sc1
	s_andn2_b64 vcc, exec, s[76:77]
	s_mov_b64 s[6:7], -1
	s_cbranch_vccnz .LBB0_377

; #define PG8_STAGE(bufoff, gbase, voff) do { _Pragma("unroll") for (int _i = 0; _i < 2; ++_i) \
;         __builtin_amdgcn_global_load_lds((const unsigned*)((const char*)(gbase) + (voff)[_i]), (PG8_LAS unsigned*)(lds + (bufoff) + ldsw + _i * 8192), 16, 0, 0); } while (0)
; #define PG8_WAIT_V(n) asm volatile("s_waitcnt vmcnt(" #n ")" ::: "memory")
; template <class Epi, class Sched, bool ALIGN_EPI = false, bool SP2 = false>
; __device__ __forceinline__ void gemm_phase(PG8_LAS unsigned char* lds, const Gemm g, const Sched& S, const Epi& E) {
;     ...
;     for (int i = 0; i < 2; ++i) { int R, C; stage_rc(tid * 16 + i * 8192, R, C); const int Rb = Epi::PERM ? ((R & ~31) + perm32(R & 31)) : R;
;         voffA[i] = g.asub ? (unsigned)((C >> 5) * 16384 + (R * 32 + (C & 31)) * 2) : (unsigned)(R * g.lda + C) * 2u; voffB[i] = (unsigned)(Rb * K + C) * 2u; }
;     const size_t kstep = (size_t)(BK * 2);
;     const size_t hstepB = (size_t)HALF * K * 2, hstepA = (size_t)HALF * g.lda * 2;
;     const size_t tstepB = 2 * hstepB, tstepA = g.tstepA; const size_t kstepA = g.kstepA;
;     const unsigned ldsw = (unsigned)wid * 1024u;
;     const int aoff = lds_byte(wr * 64 + fr, fq * 8), boff = lds_byte(wc * 32 + fr, fq * 8);
;     ...
;     const char* cA = (const char*)g.A + (size_t)cur.pm * tstepA + (size_t)(cur.k0 >> 6) * kstepA + (cur.qa > 0 ? hstepA : (size_t)0); const char* cB = (const char*)g.Bt + (size_t)cur.pn * tstepB + (size_t)cur.k0 * 2 + (cur.qb > 0 ? hstepB : (size_t)0);
;     S.a_ready(cur);
;     if constexpr (SP2) {
;         PG8_STAGE(PG8_SB(0, 0), cB, voffB); PG8_STAGE(PG8_SB(0, 1), cB + hstepB, voffB); PG8_STAGE(PG8_SA(0, 0), cA, voffA); PG8_STAGE(PG8_SA(0, 1), cA + hstepA, voffA);
;         if (wr == 1) PG8_BAR;
;         PG8_WAIT_V(2); PG8_BAR;
;         PG8_STAGE(PG8_SB(1, 0), cB + kstep, voffB); PG8_STAGE(PG8_SA(1, 0), cA + kstepA, voffA); PG8_STAGE(PG8_SB(1, 1), cB + hstepB + kstep, voffB);
;         PG8_WAIT_V(6); PG8_BAR;
;     } else {
;         PG8_STAGE(PG8_SB(0, 0), cB, voffB); PG8_STAGE(PG8_SA(0, 0), cA, voffA); PG8_STAGE(PG8_SB(0, 1), cB + hstepB, voffB); PG8_STAGE(PG8_SA(0, 1), cA + hstepA, voffA);
;         if (wr == 1) PG8_BAR;
;         PG8_WAIT_V(4); PG8_BAR;
;         PG8_STAGE(PG8_SB(1, 0), cB + kstep, voffB); PG8_STAGE(PG8_SA(1, 0), cA + kstepA, voffA); PG8_STAGE(PG8_SB(1, 1), cB + hstepB + kstep, voffB);
;         PG8_WAIT_V(6); PG8_BAR;
.LBB0_583:
	s_and_b64 s[2:3], s[2:3], exec
	s_cselect_b32 s22, -1, s7
	s_cselect_b32 s9, 64, 8
	s_lshl_b32 s2, s15, 5
	s_mov_b64 s[42:43], 0x80
	s_and_b32 s15, s2, 0x60
	s_add_i32 m0, s28, 0x18000
	v_lshl_add_u64 v[2:3], v[2:3], 0, s[42:43]
	s_lshl_b32 s7, s6, 13
	s_lshl_b32 s16, s15, 7
	s_waitcnt vmcnt(2)
	s_barrier
	global_load_lds_dwordx4 v[2:3], off
	s_add_i32 m0, s28, 0x1a000
	s_add_u32 s2, s66, 0x8000
	v_lshl_add_u64 v[0:1], v[0:1], 0, s[42:43]
	s_addc_u32 s3, s67, 0
	s_add_i32 s82, s28, 0x8000
	global_load_lds_dwordx4 v[0:1], off
	v_lshl_add_u64 v[0:1], s[2:3], 0, v[192:193]
	s_mov_b32 m0, s82
	s_add_i32 s83, s28, 0xa000
	global_load_lds_dwordx4 v[0:1], off
	v_lshl_add_u64 v[0:1], s[2:3], 0, v[196:197]
	s_add_u32 s2, s76, 0x100080
	s_mov_b32 m0, s83
	s_addc_u32 s3, s77, 0
	global_load_lds_dwordx4 v[0:1], off
	s_add_i32 m0, s28, 0x1c000
	v_lshl_add_u64 v[0:1], s[2:3], 0, v[194:195]
	global_load_lds_dwordx4 v[0:1], off
	v_lshl_add_u64 v[0:1], s[2:3], 0, v[198:199]
	s_add_i32 m0, s28, 0x1e000
	s_cmpk_lt_u32 s14, 0x100
	global_load_lds_dwordx4 v[0:1], off
	v_bfe_u32 v1, v4, 4, 2
	v_and_b32_e32 v0, 15, v4
	v_lshlrev_b32_e32 v2, 4, v1
	v_lshl_or_b32 v239, s6, 6, v0
	v_lshl_or_b32 v0, v0, 6, v2
	v_lshlrev_b32_e32 v2, 2, v4
	v_and_b32_e32 v2, 32, v2
	v_bitop3_b32 v3, v0, s7, v2 bitop3:0xde
	v_bitop3_b32 v240, v0, s16, v2 bitop3:0xde
	v_lshlrev_b32_e32 v0, 9, v5
	v_and_b32_e32 v0, 0xfffffc00, v0
	v_add_u32_e32 v0, v7, v0
	v_cmp_eq_u32_e64 s[2:3], 0, v1
	v_lshl_or_b32 v241, v1, 3, s15
	v_add3_u32 v0, v0, v6, v8
	v_mov_b32_e32 v1, v195
	s_mov_b64 s[6:7], 0xa000
	v_lshl_add_u64 v[200:201], v[0:1], 0, s[6:7]
	v_lshlrev_b32_e32 v0, 9, v9
	v_and_b32_e32 v0, 0xfffffc00, v0
	v_add_u32_e32 v0, v11, v0
	s_waitcnt vmcnt(0)
	v_add3_u32 v0, v0, v10, v12
	s_mov_b32 s23, 0
	s_cselect_b64 s[46:47], -1, 0
	v_lshl_add_u64 v[202:203], v[0:1], 0, s[6:7]
	s_add_i32 s84, 0, 0x10000
	s_add_i32 s85, 0, 0x14000
	v_mbcnt_lo_u32_b32 v0, -1, 0
	v_add_u32_e32 v242, s84, v240
	v_add_u32_e32 v243, s85, v240
	v_add_u32_e32 v244, 0, v3
	v_mbcnt_hi_u32_b32 v245, -1, v0
	s_mov_b32 s86, s23
	s_barrier
	s_branch .LBB0_586

;     __host__ __device__ __forceinline__ bool next(int i, Unit& u) const { const long L = (long)i * G + c; if (L >= nwg) return false; map((int)L, u); return true; }
; #define PG8_STAGE(bufoff, gbase, voff) do { _Pragma("unroll") for (int _i = 0; _i < 2; ++_i) \
;         __builtin_amdgcn_global_load_lds((const unsigned*)((const char*)(gbase) + (voff)[_i]), (PG8_LAS unsigned*)(lds + (bufoff) + ldsw + _i * 8192), 16, 0, 0); } while (0)
; #define PG8_BAR __builtin_amdgcn_s_barrier()
;     __host__ __device__ __forceinline__ bool next(int i, Unit& u) const {
;         const int ii = (so.c < 16 * S && so.G >= so.nwg && i < 2) ? 1 - i : i;
;         const int L = ii * so.G + so.c; const bool isp = L < so.nwg; const int j = isp ? 0 : L - so.nwg;
;         Unit a; so.map(isp ? L : 0, a);
;         const int q = j / S, sp = j - q * S;
;         u.pm = isp ? a.pm : 64 + (q >> 2); u.pn = isp ? a.pn : (q & 3); u.sp = isp ? -1 : sp; u.nt = isp ? a.nt : ntS; u.k0 = isp ? 0 : sp * ntS * BK; u.qa = -1; u.qb = -1;
;         return isp || j < 16 * S;
;     }
; template <class Epi, class Sched, bool ALIGN_EPI = false, bool SP2 = false>
; __device__ __forceinline__ void gemm_phase(PG8_LAS unsigned char* lds, const Gemm g, const Sched& S, const Epi& E) {
;     ...
;         const bool has_next = S.next(ui + 1, nxt);
;         const char* nA = has_next ? (const char*)g.A + (size_t)nxt.pm * tstepA + (size_t)(nxt.k0 >> 6) * kstepA + (nxt.qa > 0 ? hstepA : (size_t)0) : cA; const char* nB = has_next ? (const char*)g.Bt + (size_t)nxt.pn * tstepB + (size_t)nxt.k0 * 2 + (nxt.qb > 0 ? hstepB : (size_t)0) : cB;
;         const bool whole = cur.qa < 0;
;         const int nt = cur.nt;
;         for (int t = 0; t < nt; t += 2) {
;             const bool last = (t == nt - 2);
;             const char* a1 = cA + (size_t)(t + 1) * kstepA;
;             const char* a2 = last ? nA : cA + (size_t)(t + 2) * kstepA; const char* b2 = last ? nB : cB + (size_t)(t + 2) * kstep;
;             const char* a3 = a2 + kstepA; const char* b3 = b2 + kstep;
;             if (last && has_next) S.a_ready(nxt);
;             if constexpr (SP2) {
;             PG8_LDB(B0, 0, 0); PG8_LDB(B1, 0, 1); PG8_SCHED; PG8_LDA(At, 0, 0); PG8_STAGE(PG8_SA(1, 1), a1 + hstepA, voffA);
;             PG8_WAIT_V(8); PG8_WAIT_L(0); PG8_BAR; PG8_MMA(0, 0, At, B0); if (whole) PG8_MMA(0, 1, At, B1); PG8_BAR; PG8_SCHED;
.LBB0_590:
	s_add_i32 s7, s15, s6
	s_ashr_i32 s6, s7, 31
	s_lshr_b32 s6, s6, 28
	s_add_i32 s15, s7, s6
	s_ashr_i32 s6, s15, 4
	s_lshl_b32 s16, s6, 2
	s_sub_i32 s6, 64, s16
	s_min_i32 s17, s6, 4
	s_abs_i32 s18, s17
	v_cvt_f32_u32_e32 v0, s18
	s_sub_i32 s24, 0, s18
	s_and_b32 s15, s15, -16
	s_sub_i32 s7, s7, s15
	v_rcp_iflag_f32_e32 v0, v0
	s_abs_i32 s15, s7
	s_max_i32 s19, s14, 0x100
	s_xor_b32 s21, s7, s17
	v_mul_f32_e32 v0, 0x4f7ffffe, v0
	v_cvt_u32_f32_e32 v0, v0
	s_add_i32 s20, s19, 0xffffff00
	s_ashr_i32 s21, s21, 31
	s_mov_b32 s6, 0
	v_readfirstlane_b32 s25, v0
	s_mul_i32 s24, s24, s25
	s_mul_hi_u32 s24, s25, s24
	s_add_i32 s25, s25, s24
	s_mul_hi_u32 s24, s15, s25
	s_mul_i32 s25, s24, s18
	s_sub_i32 s15, s15, s25
	s_add_i32 s25, s24, 1
	s_sub_i32 s26, s15, s18
	s_cmp_ge_u32 s15, s18
	s_cselect_b32 s24, s25, s24
	s_cselect_b32 s15, s26, s15
	s_add_i32 s25, s24, 1
	s_cmp_ge_u32 s15, s18
	s_cselect_b32 s15, s25, s24
	s_xor_b32 s15, s15, s21
	s_sub_i32 s15, s15, s21
	s_mul_i32 s17, s15, s17
	s_sub_i32 s7, s7, s17
	s_add_i32 s7, s16, s7
	s_lshr_b32 s16, s20, 5
	s_and_b32 s87, s19, 7
	s_add_i32 s18, s16, 64
	s_and_b64 s[16:17], s[50:51], exec
	s_cselect_b32 s52, s7, s18
	s_bfe_u32 s7, s19, 0x20003
	s_and_b64 s[16:17], s[50:51], exec
	s_cselect_b32 s54, s15, s7
	s_lshl_b32 s7, s87, 9
	s_and_b64 s[16:17], s[50:51], exec
	s_cselect_b32 s7, 0, s7
	s_ashr_i32 s53, s52, 31
	s_lshl_b64 s[16:17], s[52:53], 21
	s_add_u32 s15, s34, s16
	s_addc_u32 s16, s35, s17
	s_lshl_b32 s17, s7, 9
	s_add_u32 s56, s15, s17
	s_addc_u32 s57, s16, 0
	s_ashr_i32 s55, s54, 31
	s_lshl_b64 s[16:17], s[54:55], 21
	s_add_u32 s15, s40, s16
	s_addc_u32 s16, s41, s17
	s_lshl_b32 s7, s7, 1
	s_add_u32 s58, s15, s7
	s_addc_u32 s59, s16, 0
	s_cmpk_lt_i32 s14, 0x180
	s_cselect_b64 s[60:61], -1, 0
	s_and_b64 s[14:15], s[60:61], exec
	s_cselect_b32 s14, s57, s67
	s_cselect_b32 s15, s56, s66
	s_cselect_b32 s16, s59, s77
	s_cselect_b32 s17, s58, s76
	s_add_i32 s18, s9, -2
	s_add_u32 s19, s76, 0x100
	s_addc_u32 s20, s77, 0
	s_waitcnt lgkmcnt(0)
	ds_read_b128 v[128:131], v242
	ds_read_b128 v[132:135], v242 offset:1024
	ds_read_b128 v[136:139], v242 offset:2048
	ds_read_b128 v[140:143], v242 offset:3072
	ds_read_b128 v[144:147], v243
	ds_read_b128 v[148:151], v243 offset:1024
	ds_read_b128 v[152:155], v243 offset:2048
	ds_read_b128 v[156:159], v243 offset:3072
	s_add_i32 s21, s6, 2
	s_add_u32 s76, s66, 0x10000
	s_addc_u32 s77, s67, 0
	s_cmp_eq_u32 s18, s6
	s_cselect_b32 s80, s15, s76
	s_cselect_b32 s81, s14, s77
	s_cselect_b32 s78, s17, s19
	s_cselect_b32 s79, s16, s20
	s_add_u32 s6, s80, 0x8000
	s_addc_u32 s7, s81, 0
	v_lshl_add_u64 v[204:205], s[66:67], 0, v[200:201]
	s_add_i32 m0, s28, 0xc000
	ds_read_b128 v[160:163], v244
	ds_read_b128 v[164:167], v244 offset:1024
	ds_read_b128 v[168:171], v244 offset:2048
	ds_read_b128 v[172:175], v244 offset:3072
	ds_read_b128 v[176:179], v244 offset:4096
	ds_read_b128 v[180:183], v244 offset:5120
	ds_read_b128 v[184:187], v244 offset:6144
	ds_read_b128 v[188:191], v244 offset:7168
	global_load_lds_dwordx4 v[204:205], off
	v_lshl_add_u64 v[204:205], s[66:67], 0, v[202:203]
	s_add_i32 m0, s28, 0xe000
	s_nop 0
	global_load_lds_dwordx4 v[204:205], off
	s_waitcnt vmcnt(16)
	s_waitcnt lgkmcnt(0)
	s_barrier
	s_setprio 1
	s_waitcnt lgkmcnt(0)
	v_mfma_f32_16x16x32_bf16 v[124:127], v[128:131], v[160:163], 0
	v_mfma_f32_16x16x32_bf16 v[120:123], v[136:139], v[160:163], 0
	v_mfma_f32_16x16x32_bf16 v[116:119], v[128:131], v[168:171], 0
	v_mfma_f32_16x16x32_bf16 v[108:111], v[136:139], v[168:171], 0
	v_mfma_f32_16x16x32_bf16 v[100:103], v[128:131], v[176:179], 0
	v_mfma_f32_16x16x32_bf16 v[92:95], v[136:139], v[176:179], 0
	v_mfma_f32_16x16x32_bf16 v[84:87], v[128:131], v[184:187], 0
	v_mfma_f32_16x16x32_bf16 v[76:79], v[136:139], v[184:187], 0
	v_mfma_f32_16x16x32_bf16 v[124:127], v[132:135], v[164:167], v[124:127]
	v_mfma_f32_16x16x32_bf16 v[120:123], v[140:143], v[164:167], v[120:123]
	v_mfma_f32_16x16x32_bf16 v[116:119], v[132:135], v[172:175], v[116:119]
	v_mfma_f32_16x16x32_bf16 v[108:111], v[140:143], v[172:175], v[108:111]
	v_mfma_f32_16x16x32_bf16 v[100:103], v[132:135], v[180:183], v[100:103]
	v_mfma_f32_16x16x32_bf16 v[92:95], v[140:143], v[180:183], v[92:95]
	v_mfma_f32_16x16x32_bf16 v[84:87], v[132:135], v[188:191], v[84:87]
	v_mfma_f32_16x16x32_bf16 v[76:79], v[140:143], v[188:191], v[76:79]
	s_setprio 0
	s_setprio 1
	v_mfma_f32_16x16x32_bf16 v[112:115], v[144:147], v[160:163], 0
	v_mfma_f32_16x16x32_bf16 v[104:107], v[152:155], v[160:163], 0
	v_mfma_f32_16x16x32_bf16 v[96:99], v[144:147], v[168:171], 0
	v_mfma_f32_16x16x32_bf16 v[88:91], v[152:155], v[168:171], 0
	v_mfma_f32_16x16x32_bf16 v[80:83], v[144:147], v[176:179], 0
	v_mfma_f32_16x16x32_bf16 v[72:75], v[152:155], v[176:179], 0
	v_mfma_f32_16x16x32_bf16 v[68:71], v[144:147], v[184:187], 0
	v_mfma_f32_16x16x32_bf16 v[64:67], v[152:155], v[184:187], 0
	v_mfma_f32_16x16x32_bf16 v[112:115], v[148:151], v[164:167], v[112:115]
	v_mfma_f32_16x16x32_bf16 v[104:107], v[156:159], v[164:167], v[104:107]
	v_mfma_f32_16x16x32_bf16 v[96:99], v[148:151], v[172:175], v[96:99]
	v_mfma_f32_16x16x32_bf16 v[88:91], v[156:159], v[172:175], v[88:91]
	v_mfma_f32_16x16x32_bf16 v[80:83], v[148:151], v[180:183], v[80:83]
	v_mfma_f32_16x16x32_bf16 v[72:75], v[156:159], v[180:183], v[72:75]
	v_mfma_f32_16x16x32_bf16 v[68:71], v[148:151], v[188:191], v[68:71]
	v_mfma_f32_16x16x32_bf16 v[64:67], v[156:159], v[188:191], v[64:67]
	s_setprio 0
	s_barrier
; #define PG8_STAGE(bufoff, gbase, voff) do { _Pragma("unroll") for (int _i = 0; _i < 2; ++_i) \
;         __builtin_amdgcn_global_load_lds((const unsigned*)((const char*)(gbase) + (voff)[_i]), (PG8_LAS unsigned*)(lds + (bufoff) + ldsw + _i * 8192), 16, 0, 0); } while (0)
; #define PG8_LDA(dst, b, h) do { _Pragma("unroll") for (int m = 0; m < 4; ++m) _Pragma("unroll") for (int k = 0; k < 2; ++k) dst[m][k] = *(const PG8_LAS bf16x8*)(lds + PG8_SA(b, h) + aoff + m * 2048 + k * 1024); } while (0)
; #define PG8_LDB(dst, b, h) do { _Pragma("unroll") for (int n = 0; n < 2; ++n) _Pragma("unroll") for (int k = 0; k < 2; ++k) dst[n][k] = *(const PG8_LAS bf16x8*)(lds + PG8_SB(b, h) + boff + n * 2048 + k * 1024); } while (0)
; #define PG8_MMA(ai, bj, At, Bt) do { __builtin_amdgcn_s_setprio(1); _Pragma("unroll") for (int m = 0; m < 4; ++m) _Pragma("unroll") for (int n = 0; n < 2; ++n) _Pragma("unroll") for (int k = 0; k < 2; ++k) \
;         acc[ai][bj][m][n] = __builtin_amdgcn_mfma_f32_16x16x32_bf16(Bt[n][k], At[m][k], acc[ai][bj][m][n], 0, 0, 0); __builtin_amdgcn_s_setprio(0); } while (0)
; #define PG8_WAIT_V(n) asm volatile("s_waitcnt vmcnt(" #n ")" ::: "memory")
; #define PG8_WAIT_L(n) asm volatile("s_waitcnt lgkmcnt(" #n ")" ::: "memory")
; #define PG8_BAR __builtin_amdgcn_s_barrier()
; #define PG8_SCHED __builtin_amdgcn_sched_barrier(0)
; template <class Epi, class Sched, bool ALIGN_EPI = false, bool SP2 = false>
; __device__ __forceinline__ void gemm_phase(PG8_LAS unsigned char* lds, const Gemm g, const Sched& S, const Epi& E) {
;     ...
;             PG8_WAIT_V(8); PG8_WAIT_L(0); PG8_BAR; PG8_MMA(0, 0, At, B0); if (whole) PG8_MMA(0, 1, At, B1); PG8_BAR; PG8_SCHED;
;             PG8_LDA(At, 0, 1); PG8_STAGE(PG8_SB(0, 0), b2, voffB); PG8_STAGE(PG8_SB(0, 1), b2 + hstepB, voffB); PG8_STAGE(PG8_SA(0, 0), a2, voffA);
;             PG8_WAIT_V(8); PG8_WAIT_L(0); PG8_BAR; if (whole) { PG8_MMA(1, 0, At, B0); PG8_MMA(1, 1, At, B1); } PG8_BAR; PG8_SCHED;
;             PG8_LDB(B0, 1, 0); PG8_LDB(B1, 1, 1); PG8_SCHED; PG8_LDA(At, 1, 0); PG8_STAGE(PG8_SA(0, 1), a2 + hstepA, voffA);
;             PG8_WAIT_V(8); PG8_WAIT_L(0); PG8_BAR; PG8_MMA(0, 0, At, B0); if (whole) PG8_MMA(0, 1, At, B1); PG8_BAR; PG8_SCHED;
	s_add_i32 s24, s84, s8
	v_lshl_add_u64 v[204:205], s[78:79], 0, v[194:195]
	s_mov_b32 m0, s24
	ds_read_b128 v[160:163], v244 offset:16384
	ds_read_b128 v[164:167], v244 offset:17408
	ds_read_b128 v[168:171], v244 offset:18432
	ds_read_b128 v[172:175], v244 offset:19456
	ds_read_b128 v[176:179], v244 offset:20480
	ds_read_b128 v[180:183], v244 offset:21504
	ds_read_b128 v[184:187], v244 offset:22528
	ds_read_b128 v[188:191], v244 offset:23552
	global_load_lds_dwordx4 v[204:205], off
	s_add_i32 m0, s24, 0x2000
	s_add_u32 s24, s78, 0x100000
	v_lshl_add_u64 v[206:207], s[78:79], 0, v[198:199]
	s_addc_u32 s25, s79, 0
	s_add_i32 s26, s85, s8
	global_load_lds_dwordx4 v[206:207], off
	v_lshl_add_u64 v[208:209], s[24:25], 0, v[194:195]
	s_mov_b32 m0, s26
	s_nop 0
	global_load_lds_dwordx4 v[208:209], off
	v_lshl_add_u64 v[208:209], s[24:25], 0, v[198:199]
	s_add_i32 m0, s26, 0x2000
	s_nop 0
	global_load_lds_dwordx4 v[208:209], off
	v_lshl_add_u64 v[208:209], s[80:81], 0, v[192:193]
	s_mov_b32 m0, s28
	s_nop 0
	global_load_lds_dwordx4 v[208:209], off
	v_lshl_add_u64 v[208:209], s[80:81], 0, v[196:197]
	s_mov_b32 m0, s29
	s_nop 0
	global_load_lds_dwordx4 v[208:209], off
	s_waitcnt vmcnt(16)
	s_waitcnt lgkmcnt(0)
	s_barrier
	s_setprio 1
	s_waitcnt lgkmcnt(0)
	v_mfma_f32_16x16x32_bf16 v[60:63], v[128:131], v[160:163], 0
	v_mfma_f32_16x16x32_bf16 v[56:59], v[136:139], v[160:163], 0
	v_mfma_f32_16x16x32_bf16 v[52:55], v[128:131], v[168:171], 0
	v_mfma_f32_16x16x32_bf16 v[44:47], v[136:139], v[168:171], 0
	v_mfma_f32_16x16x32_bf16 v[36:39], v[128:131], v[176:179], 0
	v_mfma_f32_16x16x32_bf16 v[28:31], v[136:139], v[176:179], 0
	v_mfma_f32_16x16x32_bf16 v[20:23], v[128:131], v[184:187], 0
	v_mfma_f32_16x16x32_bf16 v[12:15], v[136:139], v[184:187], 0
	v_mfma_f32_16x16x32_bf16 v[60:63], v[132:135], v[164:167], v[60:63]
	v_mfma_f32_16x16x32_bf16 v[56:59], v[140:143], v[164:167], v[56:59]
	v_mfma_f32_16x16x32_bf16 v[52:55], v[132:135], v[172:175], v[52:55]
	v_mfma_f32_16x16x32_bf16 v[44:47], v[140:143], v[172:175], v[44:47]
	v_mfma_f32_16x16x32_bf16 v[36:39], v[132:135], v[180:183], v[36:39]
	v_mfma_f32_16x16x32_bf16 v[28:31], v[140:143], v[180:183], v[28:31]
	v_mfma_f32_16x16x32_bf16 v[20:23], v[132:135], v[188:191], v[20:23]
	v_mfma_f32_16x16x32_bf16 v[12:15], v[140:143], v[188:191], v[12:15]
	s_setprio 0
	s_setprio 1
	v_mfma_f32_16x16x32_bf16 v[48:51], v[144:147], v[160:163], 0
	v_mfma_f32_16x16x32_bf16 v[40:43], v[152:155], v[160:163], 0
	v_mfma_f32_16x16x32_bf16 v[32:35], v[144:147], v[168:171], 0
	v_mfma_f32_16x16x32_bf16 v[24:27], v[152:155], v[168:171], 0
	v_mfma_f32_16x16x32_bf16 v[16:19], v[144:147], v[176:179], 0
	v_mfma_f32_16x16x32_bf16 v[8:11], v[152:155], v[176:179], 0
	v_mfma_f32_16x16x32_bf16 v[4:7], v[144:147], v[184:187], 0
	v_mfma_f32_16x16x32_bf16 v[0:3], v[152:155], v[184:187], 0
	v_mfma_f32_16x16x32_bf16 v[48:51], v[148:151], v[164:167], v[48:51]
	v_mfma_f32_16x16x32_bf16 v[40:43], v[156:159], v[164:167], v[40:43]
	v_mfma_f32_16x16x32_bf16 v[32:35], v[148:151], v[172:175], v[32:35]
	v_mfma_f32_16x16x32_bf16 v[24:27], v[156:159], v[172:175], v[24:27]
	v_mfma_f32_16x16x32_bf16 v[16:19], v[148:151], v[180:183], v[16:19]
	v_mfma_f32_16x16x32_bf16 v[8:11], v[156:159], v[180:183], v[8:11]
	v_mfma_f32_16x16x32_bf16 v[4:7], v[148:151], v[188:191], v[4:7]
	v_mfma_f32_16x16x32_bf16 v[0:3], v[156:159], v[188:191], v[0:3]
	s_setprio 0
	s_barrier
	s_add_i32 s26, 0, 0x18000
	s_add_i32 s27, 0, 0x1c000
	v_add_u32_e32 v140, s26, v240
	v_add_u32_e32 v156, s27, v240
	ds_read_b128 v[128:131], v140
	ds_read_b128 v[132:135], v140 offset:1024
	ds_read_b128 v[136:139], v140 offset:2048
	ds_read_b128 v[140:143], v140 offset:3072
	ds_read_b128 v[144:147], v156
	ds_read_b128 v[148:151], v156 offset:1024
	ds_read_b128 v[152:155], v156 offset:2048
	ds_read_b128 v[156:159], v156 offset:3072
	s_add_u32 s24, s80, 0x2000
	s_addc_u32 s25, s81, 0
	s_mov_b32 m0, s63
	v_lshl_add_u64 v[208:209], s[24:25], 0, v[192:193]
	ds_read_b128 v[160:163], v244 offset:32768
	ds_read_b128 v[164:167], v244 offset:33792
	ds_read_b128 v[168:171], v244 offset:34816
	ds_read_b128 v[172:175], v244 offset:35840
	ds_read_b128 v[176:179], v244 offset:36864
	ds_read_b128 v[180:183], v244 offset:37888
	ds_read_b128 v[184:187], v244 offset:38912
	ds_read_b128 v[188:191], v244 offset:39936
	global_load_lds_dwordx4 v[208:209], off
	v_lshl_add_u64 v[208:209], s[24:25], 0, v[196:197]
	s_mov_b32 m0, s65
	s_nop 0
	global_load_lds_dwordx4 v[208:209], off
	s_waitcnt vmcnt(8)
	s_waitcnt lgkmcnt(0)
	s_barrier
; #define PG8_STAGE(bufoff, gbase, voff) do { _Pragma("unroll") for (int _i = 0; _i < 2; ++_i) \
;         __builtin_amdgcn_global_load_lds((const unsigned*)((const char*)(gbase) + (voff)[_i]), (PG8_LAS unsigned*)(lds + (bufoff) + ldsw + _i * 8192), 16, 0, 0); } while (0)
; #define PG8_LDA(dst, b, h) do { _Pragma("unroll") for (int m = 0; m < 4; ++m) _Pragma("unroll") for (int k = 0; k < 2; ++k) dst[m][k] = *(const PG8_LAS bf16x8*)(lds + PG8_SA(b, h) + aoff + m * 2048 + k * 1024); } while (0)
; #define PG8_LDB(dst, b, h) do { _Pragma("unroll") for (int n = 0; n < 2; ++n) _Pragma("unroll") for (int k = 0; k < 2; ++k) dst[n][k] = *(const PG8_LAS bf16x8*)(lds + PG8_SB(b, h) + boff + n * 2048 + k * 1024); } while (0)
; #define PG8_MMA(ai, bj, At, Bt) do { __builtin_amdgcn_s_setprio(1); _Pragma("unroll") for (int m = 0; m < 4; ++m) _Pragma("unroll") for (int n = 0; n < 2; ++n) _Pragma("unroll") for (int k = 0; k < 2; ++k) \
;         acc[ai][bj][m][n] = __builtin_amdgcn_mfma_f32_16x16x32_bf16(Bt[n][k], At[m][k], acc[ai][bj][m][n], 0, 0, 0); __builtin_amdgcn_s_setprio(0); } while (0)
; #define PG8_WAIT_V(n) asm volatile("s_waitcnt vmcnt(" #n ")" ::: "memory")
; #define PG8_WAIT_L(n) asm volatile("s_waitcnt lgkmcnt(" #n ")" ::: "memory")
; #define PG8_BAR __builtin_amdgcn_s_barrier()
; #define PG8_SCHED __builtin_amdgcn_sched_barrier(0)
; template <class Epi, class Sched, bool ALIGN_EPI = false, bool SP2 = false>
; __device__ __forceinline__ void gemm_phase(PG8_LAS unsigned char* lds, const Gemm g, const Sched& S, const Epi& E) {
;     ...
;         for (int t = 0; t < nt; t += 2) {
;     ...
;             PG8_LDB(B0, 1, 0); PG8_LDB(B1, 1, 1); PG8_SCHED; PG8_LDA(At, 1, 0); PG8_STAGE(PG8_SA(0, 1), a2 + hstepA, voffA);
;             PG8_WAIT_V(8); PG8_WAIT_L(0); PG8_BAR; PG8_MMA(0, 0, At, B0); if (whole) PG8_MMA(0, 1, At, B1); PG8_BAR; PG8_SCHED;
;             PG8_LDA(At, 1, 1); PG8_STAGE(PG8_SB(1, 0), b3, voffB); PG8_STAGE(PG8_SB(1, 1), b3 + hstepB, voffB); PG8_STAGE(PG8_SA(1, 0), a3, voffA);
;             PG8_WAIT_V(8); PG8_WAIT_L(0); PG8_BAR; if (whole) { PG8_MMA(1, 0, At, B0); PG8_MMA(1, 1, At, B1); } PG8_BAR; PG8_SCHED;
	s_setprio 1
	s_waitcnt lgkmcnt(0)
	v_mfma_f32_16x16x32_bf16 v[124:127], v[128:131], v[160:163], v[124:127]
	v_mfma_f32_16x16x32_bf16 v[120:123], v[136:139], v[160:163], v[120:123]
	v_mfma_f32_16x16x32_bf16 v[116:119], v[128:131], v[168:171], v[116:119]
	v_mfma_f32_16x16x32_bf16 v[108:111], v[136:139], v[168:171], v[108:111]
	v_mfma_f32_16x16x32_bf16 v[100:103], v[128:131], v[176:179], v[100:103]
	v_mfma_f32_16x16x32_bf16 v[92:95], v[136:139], v[176:179], v[92:95]
	v_mfma_f32_16x16x32_bf16 v[84:87], v[128:131], v[184:187], v[84:87]
	v_mfma_f32_16x16x32_bf16 v[76:79], v[136:139], v[184:187], v[76:79]
	v_mfma_f32_16x16x32_bf16 v[124:127], v[132:135], v[164:167], v[124:127]
	v_mfma_f32_16x16x32_bf16 v[120:123], v[140:143], v[164:167], v[120:123]
	v_mfma_f32_16x16x32_bf16 v[116:119], v[132:135], v[172:175], v[116:119]
	v_mfma_f32_16x16x32_bf16 v[108:111], v[140:143], v[172:175], v[108:111]
	v_mfma_f32_16x16x32_bf16 v[100:103], v[132:135], v[180:183], v[100:103]
	v_mfma_f32_16x16x32_bf16 v[92:95], v[140:143], v[180:183], v[92:95]
	v_mfma_f32_16x16x32_bf16 v[84:87], v[132:135], v[188:191], v[84:87]
	v_mfma_f32_16x16x32_bf16 v[76:79], v[140:143], v[188:191], v[76:79]
	s_setprio 0
	s_setprio 1
	v_mfma_f32_16x16x32_bf16 v[112:115], v[144:147], v[160:163], v[112:115]
	v_mfma_f32_16x16x32_bf16 v[104:107], v[152:155], v[160:163], v[104:107]
	v_mfma_f32_16x16x32_bf16 v[96:99], v[144:147], v[168:171], v[96:99]
	v_mfma_f32_16x16x32_bf16 v[88:91], v[152:155], v[168:171], v[88:91]
	v_mfma_f32_16x16x32_bf16 v[80:83], v[144:147], v[176:179], v[80:83]
	v_mfma_f32_16x16x32_bf16 v[72:75], v[152:155], v[176:179], v[72:75]
	v_mfma_f32_16x16x32_bf16 v[68:71], v[144:147], v[184:187], v[68:71]
	v_mfma_f32_16x16x32_bf16 v[64:67], v[152:155], v[184:187], v[64:67]
	v_mfma_f32_16x16x32_bf16 v[112:115], v[148:151], v[164:167], v[112:115]
	v_mfma_f32_16x16x32_bf16 v[104:107], v[156:159], v[164:167], v[104:107]
	v_mfma_f32_16x16x32_bf16 v[96:99], v[148:151], v[172:175], v[96:99]
	v_mfma_f32_16x16x32_bf16 v[88:91], v[156:159], v[172:175], v[88:91]
	v_mfma_f32_16x16x32_bf16 v[80:83], v[148:151], v[180:183], v[80:83]
	v_mfma_f32_16x16x32_bf16 v[72:75], v[156:159], v[180:183], v[72:75]
	v_mfma_f32_16x16x32_bf16 v[68:71], v[148:151], v[188:191], v[68:71]
	v_mfma_f32_16x16x32_bf16 v[64:67], v[156:159], v[188:191], v[64:67]
	s_setprio 0
	s_barrier
	s_add_i32 s24, s26, s8
	v_lshl_add_u64 v[204:205], v[204:205], 0, s[42:43]
	s_mov_b32 m0, s24
	ds_read_b128 v[160:163], v244 offset:49152
	ds_read_b128 v[164:167], v244 offset:50176
	ds_read_b128 v[168:171], v244 offset:51200
	ds_read_b128 v[172:175], v244 offset:52224
	ds_read_b128 v[176:179], v244 offset:53248
	ds_read_b128 v[180:183], v244 offset:54272
	ds_read_b128 v[184:187], v244 offset:55296
	ds_read_b128 v[188:191], v244 offset:56320
	global_load_lds_dwordx4 v[204:205], off
	s_add_i32 m0, s24, 0x2000
	s_add_u32 s24, s78, 0x100080
	v_lshl_add_u64 v[204:205], v[206:207], 0, s[42:43]
	s_addc_u32 s25, s79, 0
	s_add_i32 s26, s27, s8
	global_load_lds_dwordx4 v[204:205], off
	v_lshl_add_u64 v[204:205], s[24:25], 0, v[194:195]
	s_mov_b32 m0, s26
	s_nop 0
	global_load_lds_dwordx4 v[204:205], off
	v_lshl_add_u64 v[204:205], s[24:25], 0, v[198:199]
	s_add_i32 m0, s26, 0x2000
	s_nop 0
	global_load_lds_dwordx4 v[204:205], off
	v_lshl_add_u64 v[204:205], s[6:7], 0, v[192:193]
	s_mov_b32 m0, s82
	s_nop 0
	global_load_lds_dwordx4 v[204:205], off
	v_lshl_add_u64 v[204:205], s[6:7], 0, v[196:197]
	s_mov_b32 m0, s83
	s_nop 0
	global_load_lds_dwordx4 v[204:205], off
	s_waitcnt vmcnt(8)
	s_waitcnt lgkmcnt(0)
	s_barrier
	s_setprio 1
	s_waitcnt lgkmcnt(0)
	v_mfma_f32_16x16x32_bf16 v[60:63], v[128:131], v[160:163], v[60:63]
	v_mfma_f32_16x16x32_bf16 v[56:59], v[136:139], v[160:163], v[56:59]
	v_mfma_f32_16x16x32_bf16 v[52:55], v[128:131], v[168:171], v[52:55]
	v_mfma_f32_16x16x32_bf16 v[44:47], v[136:139], v[168:171], v[44:47]
	v_mfma_f32_16x16x32_bf16 v[36:39], v[128:131], v[176:179], v[36:39]
	v_mfma_f32_16x16x32_bf16 v[28:31], v[136:139], v[176:179], v[28:31]
	v_mfma_f32_16x16x32_bf16 v[20:23], v[128:131], v[184:187], v[20:23]
	v_mfma_f32_16x16x32_bf16 v[12:15], v[136:139], v[184:187], v[12:15]
	v_mfma_f32_16x16x32_bf16 v[60:63], v[132:135], v[164:167], v[60:63]
	v_mfma_f32_16x16x32_bf16 v[56:59], v[140:143], v[164:167], v[56:59]
	v_mfma_f32_16x16x32_bf16 v[52:55], v[132:135], v[172:175], v[52:55]
	v_mfma_f32_16x16x32_bf16 v[44:47], v[140:143], v[172:175], v[44:47]
	v_mfma_f32_16x16x32_bf16 v[36:39], v[132:135], v[180:183], v[36:39]
	v_mfma_f32_16x16x32_bf16 v[28:31], v[140:143], v[180:183], v[28:31]
	v_mfma_f32_16x16x32_bf16 v[20:23], v[132:135], v[188:191], v[20:23]
	v_mfma_f32_16x16x32_bf16 v[12:15], v[140:143], v[188:191], v[12:15]
	s_setprio 0
	s_setprio 1
	v_mfma_f32_16x16x32_bf16 v[48:51], v[144:147], v[160:163], v[48:51]
	v_mfma_f32_16x16x32_bf16 v[40:43], v[152:155], v[160:163], v[40:43]
	v_mfma_f32_16x16x32_bf16 v[32:35], v[144:147], v[168:171], v[32:35]
	v_mfma_f32_16x16x32_bf16 v[24:27], v[152:155], v[168:171], v[24:27]
	v_mfma_f32_16x16x32_bf16 v[16:19], v[144:147], v[176:179], v[16:19]
	v_mfma_f32_16x16x32_bf16 v[8:11], v[152:155], v[176:179], v[8:11]
	v_mfma_f32_16x16x32_bf16 v[4:7], v[144:147], v[184:187], v[4:7]
	v_mfma_f32_16x16x32_bf16 v[0:3], v[152:155], v[184:187], v[0:3]
	v_mfma_f32_16x16x32_bf16 v[48:51], v[148:151], v[164:167], v[48:51]
	v_mfma_f32_16x16x32_bf16 v[40:43], v[156:159], v[164:167], v[40:43]
	v_mfma_f32_16x16x32_bf16 v[32:35], v[148:151], v[172:175], v[32:35]
	v_mfma_f32_16x16x32_bf16 v[24:27], v[156:159], v[172:175], v[24:27]
	v_mfma_f32_16x16x32_bf16 v[16:19], v[148:151], v[180:183], v[16:19]
	v_mfma_f32_16x16x32_bf16 v[8:11], v[156:159], v[180:183], v[8:11]
	v_mfma_f32_16x16x32_bf16 v[4:7], v[148:151], v[188:191], v[4:7]
	v_mfma_f32_16x16x32_bf16 v[0:3], v[156:159], v[188:191], v[0:3]
	s_setprio 0
	s_barrier
	s_add_u32 s19, s19, 0x100
	s_addc_u32 s20, s20, 0
	s_cmp_ge_u32 s21, s9
	s_mov_b64 s[66:67], s[76:77]
	s_mov_b32 s6, s21
	s_cbranch_scc0 .LBB0_591
	s_branch .Lpeel_exit_down0

; #define PG8_BAR __builtin_amdgcn_s_barrier()
;     __device__ __forceinline__ void operator()(const f32x4 (&acc)[2][2][4][2], const Unit& u, int wr, int wc, int fr, int fq) const {
;     ...
;         u32x4 xo[2][4][2];
; #pragma unroll
;         for (int ai = 0; ai < 2; ++ai)
; #pragma unroll
;             for (int m = 0; m < 4; ++m)
; #pragma unroll
;                 for (int bj = 0; bj < 2; ++bj) xo[ai][m][bj] = *(const u32x4*)(xb + (size_t)(row0 + ai * HALF + m * 16) * 1024 + col0 + bj * HALF);
; #pragma unroll
;         for (int ai = 0; ai < 2; ++ai)
; #pragma unroll
;             for (int m = 0; m < 4; ++m) {
;                 const int row = row0 + ai * HALF + m * 16;
;                 bf16_t* xr = xb + (size_t)row * 1024 + col0;
;                 float part_ss = 0.f;
; #pragma unroll
;                 for (int bj = 0; bj < 2; ++bj) {
;                     const u32x4 o = xo[ai][m][bj];
;                     f32x4 v0 = acc[ai][bj][m][0], v1 = acc[ai][bj][m][1];
;                     v0[0] += __uint_as_float(o.x << 16); v0[1] += __uint_as_float(o.x & 0xffff0000u); v0[2] += __uint_as_float(o.y << 16); v0[3] += __uint_as_float(o.y & 0xffff0000u);
;                     v1[0] += __uint_as_float(o.z << 16); v1[1] += __uint_as_float(o.z & 0xffff0000u); v1[2] += __uint_as_float(o.w << 16); v1[3] += __uint_as_float(o.w & 0xffff0000u);
;                     if (xout) { float* xo = xout + (size_t)row * 1024 + col0 + bj * HALF; *(f32x4*)xo = v0; *(f32x4*)(xo + 4) = v1; }
;                     else { u32x4 w; w.x = cvt_pk_bf16(v0[0], v0[1]); w.y = cvt_pk_bf16(v0[2], v0[3]); w.z = cvt_pk_bf16(v1[0], v1[1]); w.w = cvt_pk_bf16(v1[2], v1[3]); *(u32x4*)(xr + bj * HALF) = w; }
;                     part_ss += (v0[0] * v0[0] + v0[1] * v0[1]) + (v0[2] * v0[2] + v0[3] * v0[3]) + (v1[0] * v1[0] + v1[1] * v1[1]) + (v1[2] * v1[2] + v1[3] * v1[3]);
;                 }
;                 part_ss += __shfl_xor(part_ss, 16); part_ss += __shfl_xor(part_ss, 32);
;                 if (fq == 0) atomicAdd(ss + row, part_ss);
; template <class Epi, class Sched, bool ALIGN_EPI = false, bool SP2 = false>
; __device__ __forceinline__ void gemm_phase(PG8_LAS unsigned char* lds, const Gemm g, const Sched& S, const Epi& E) {
;     ...
;         if constexpr (ALIGN_EPI) { if (wr == 0) PG8_BAR; }
.Lpeel_exit_down0:
	s_and_b64 vcc, exec, s[46:47]
	s_cbranch_vccz .LBB0_594
	s_barrier
.LBB0_594:
	v_lshl_add_u32 v206, s62, 8, v239
	v_lshl_or_b32 v204, s64, 8, v241
	s_mov_b64 s[6:7], -1
	s_cmp_lt_i32 s22, 0
	v_ashrrev_i32_e32 v205, 31, v204
	v_ashrrev_i32_e32 v207, 31, v206
	s_cbranch_scc0 .LBB0_613
	v_lshlrev_b64 v[236:237], 1, v[204:205]
	v_lshl_add_u64 v[128:129], s[30:31], 0, v[236:237]
	v_lshlrev_b64 v[246:247], 11, v[206:207]
	v_lshl_add_u64 v[130:131], v[128:129], 0, v[246:247]
	global_load_dwordx4 v[188:191], v[130:131], off
	global_load_dwordx4 v[184:187], v[130:131], off offset:256
	v_or_b32_e32 v230, 16, v206
	v_ashrrev_i32_e32 v231, 31, v230
	v_or_b32_e32 v226, 32, v206
	v_lshlrev_b64 v[234:235], 11, v[230:231]
	v_ashrrev_i32_e32 v227, 31, v226
	v_or_b32_e32 v222, 48, v206
	v_lshl_add_u64 v[130:131], v[128:129], 0, v[234:235]
	v_lshlrev_b64 v[232:233], 11, v[226:227]
	v_ashrrev_i32_e32 v223, 31, v222
	v_add_u32_e32 v218, 0x80, v206
	global_load_dwordx4 v[180:183], v[130:131], off
	global_load_dwordx4 v[176:179], v[130:131], off offset:256
	v_lshl_add_u64 v[130:131], v[128:129], 0, v[232:233]
	v_lshlrev_b64 v[228:229], 11, v[222:223]
	v_ashrrev_i32_e32 v219, 31, v218
	v_add_u32_e32 v214, 0x90, v206
	global_load_dwordx4 v[172:175], v[130:131], off
	global_load_dwordx4 v[168:171], v[130:131], off offset:256
	v_lshl_add_u64 v[130:131], v[128:129], 0, v[228:229]
	v_lshlrev_b64 v[224:225], 11, v[218:219]
	v_ashrrev_i32_e32 v215, 31, v214
	v_add_u32_e32 v210, 0xa0, v206
	v_add_u32_e32 v208, 0xb0, v206
	global_load_dwordx4 v[164:167], v[130:131], off
	global_load_dwordx4 v[160:163], v[130:131], off offset:256
	v_lshl_add_u64 v[130:131], v[128:129], 0, v[224:225]
	v_lshlrev_b64 v[220:221], 11, v[214:215]
	v_ashrrev_i32_e32 v211, 31, v210
	v_ashrrev_i32_e32 v209, 31, v208
	global_load_dwordx4 v[156:159], v[130:131], off
	global_load_dwordx4 v[152:155], v[130:131], off offset:256
	v_lshl_add_u64 v[130:131], v[128:129], 0, v[220:221]
	v_lshlrev_b64 v[216:217], 11, v[210:211]
	v_lshlrev_b64 v[212:213], 11, v[208:209]
	global_load_dwordx4 v[148:151], v[130:131], off
	global_load_dwordx4 v[144:147], v[130:131], off offset:256
	v_lshl_add_u64 v[130:131], v[128:129], 0, v[216:217]
	v_lshl_add_u64 v[128:129], v[128:129], 0, v[212:213]
	global_load_dwordx4 v[140:143], v[130:131], off
	global_load_dwordx4 v[136:139], v[130:131], off offset:256
	global_load_dwordx4 v[132:135], v[128:129], off
	s_nop 0
	global_load_dwordx4 v[128:131], v[128:129], off offset:256
	v_lshl_add_u64 v[246:247], s[30:31], 0, v[246:247]
	v_lshl_add_u64 v[236:237], v[246:247], 0, v[236:237]
	s_waitcnt vmcnt(0)
	v_lshlrev_b32_e32 v246, 16, v188
	v_and_b32_e32 v188, 0xffff0000, v188
	v_add_f32_e32 v247, v125, v188
	v_lshlrev_b32_e32 v188, 16, v189
	v_add_f32_e32 v248, v126, v188
	v_and_b32_e32 v188, 0xffff0000, v189
	v_add_f32_e32 v249, v127, v188
	v_lshlrev_b32_e32 v188, 16, v190
	v_add_f32_e32 v250, v120, v188
	v_and_b32_e32 v188, 0xffff0000, v190
	v_add_f32_e32 v251, v121, v188
	v_lshlrev_b32_e32 v188, 16, v191
	v_add_f32_e32 v252, v122, v188
	v_and_b32_e32 v188, 0xffff0000, v191
	v_add_f32_e32 v246, v124, v246
	v_add_f32_e32 v253, v123, v188
	v_cvt_pk_bf16_f32 v188, v246, v247
	v_cvt_pk_bf16_f32 v189, v248, v249
	v_cvt_pk_bf16_f32 v190, v250, v251
	v_cvt_pk_bf16_f32 v191, v252, v253
	global_store_dwordx4 v[236:237], v[188:191], off sc1
	s_nop 1
	v_mul_f32_e32 v188, v247, v247
	v_mul_f32_e32 v189, v249, v249
	v_fmac_f32_e32 v188, v246, v246
	v_fmac_f32_e32 v189, v248, v248
	v_add_f32_e32 v188, v188, v189
	v_mul_f32_e32 v189, v251, v251
	v_fmac_f32_e32 v189, v250, v250
	v_add_f32_e32 v188, v189, v188
	v_mul_f32_e32 v189, v253, v253
	v_fmac_f32_e32 v189, v252, v252
	v_add_f32_e32 v188, v189, v188
	v_lshlrev_b32_e32 v189, 16, v184
	v_and_b32_e32 v184, 0xffff0000, v184
	v_add_f32_e32 v190, v113, v184
	v_lshlrev_b32_e32 v184, 16, v185
	v_add_f32_e32 v191, v114, v184
	v_and_b32_e32 v184, 0xffff0000, v185
	v_add_f32_e32 v246, v115, v184
	v_lshlrev_b32_e32 v184, 16, v186
	v_add_f32_e32 v247, v104, v184
	v_and_b32_e32 v184, 0xffff0000, v186
	v_add_f32_e32 v248, v105, v184
	v_lshlrev_b32_e32 v184, 16, v187
	v_add_f32_e32 v249, v106, v184
	v_and_b32_e32 v184, 0xffff0000, v187
	v_add_f32_e32 v189, v112, v189
	v_add_f32_e32 v250, v107, v184
	v_cvt_pk_bf16_f32 v184, v189, v190
	v_cvt_pk_bf16_f32 v185, v191, v246
	v_cvt_pk_bf16_f32 v186, v247, v248
	v_cvt_pk_bf16_f32 v187, v249, v250
	global_store_dwordx4 v[236:237], v[184:187], off offset:256 sc1
	s_nop 1
	v_mul_f32_e32 v184, v190, v190
	v_mul_f32_e32 v185, v246, v246
	v_fmac_f32_e32 v184, v189, v189
	v_fmac_f32_e32 v185, v191, v191
	v_add_f32_e32 v184, v184, v185
	v_mul_f32_e32 v185, v248, v248
	v_fmac_f32_e32 v185, v247, v247
	v_add_f32_e32 v184, v185, v184
	v_mul_f32_e32 v185, v250, v250
	v_fmac_f32_e32 v185, v249, v249
	v_add_f32_e32 v184, v185, v184
	v_and_b32_e32 v186, 64, v245
	v_add_f32_e32 v185, v188, v184
	v_xor_b32_e32 v184, 16, v245
	v_add_u32_e32 v187, 64, v186
	v_cmp_lt_i32_e32 vcc, v184, v187
	s_nop 1
	v_cndmask_b32_e32 v184, v245, v184, vcc
	v_lshlrev_b32_e32 v184, 2, v184
	ds_bpermute_b32 v186, v184, v185
	s_waitcnt lgkmcnt(0)
	v_add_f32_e32 v186, v185, v186
	v_xor_b32_e32 v185, 32, v245
	v_cmp_lt_i32_e32 vcc, v185, v187
	s_nop 1
	v_cndmask_b32_e32 v185, v245, v185, vcc
	v_lshlrev_b32_e32 v185, 2, v185
	ds_bpermute_b32 v187, v185, v186
	s_and_saveexec_b64 s[6:7], s[2:3]
	s_cbranch_execz .LBB0_597
	s_waitcnt lgkmcnt(0)
	v_add_f32_e32 v188, v186, v187
	v_lshl_add_u64 v[186:187], v[206:207], 2, s[38:39]
	global_atomic_add_f32 v[186:187], v188, off
; __device__ __forceinline__ unsigned cvt_pk_bf16(float lo, float hi) { unsigned r; asm volatile("v_cvt_pk_bf16_f32 %0, %1, %2" : "=v"(r) : "v"(lo), "v"(hi)); return r; }
;     __device__ __forceinline__ void operator()(const f32x4 (&acc)[2][2][4][2], const Unit& u, int wr, int wc, int fr, int fq) const {
;     ...
;         for (int ai = 0; ai < 2; ++ai)
; #pragma unroll
;             for (int m = 0; m < 4; ++m) {
;                 const int row = row0 + ai * HALF + m * 16;
;                 bf16_t* xr = xb + (size_t)row * 1024 + col0;
;                 float part_ss = 0.f;
; #pragma unroll
;                 for (int bj = 0; bj < 2; ++bj) {
;                     const u32x4 o = xo[ai][m][bj];
;                     f32x4 v0 = acc[ai][bj][m][0], v1 = acc[ai][bj][m][1];
;                     v0[0] += __uint_as_float(o.x << 16); v0[1] += __uint_as_float(o.x & 0xffff0000u); v0[2] += __uint_as_float(o.y << 16); v0[3] += __uint_as_float(o.y & 0xffff0000u);
;                     v1[0] += __uint_as_float(o.z << 16); v1[1] += __uint_as_float(o.z & 0xffff0000u); v1[2] += __uint_as_float(o.w << 16); v1[3] += __uint_as_float(o.w & 0xffff0000u);
;                     if (xout) { float* xo = xout + (size_t)row * 1024 + col0 + bj * HALF; *(f32x4*)xo = v0; *(f32x4*)(xo + 4) = v1; }
;                     else { u32x4 w; w.x = cvt_pk_bf16(v0[0], v0[1]); w.y = cvt_pk_bf16(v0[2], v0[3]); w.z = cvt_pk_bf16(v1[0], v1[1]); w.w = cvt_pk_bf16(v1[2], v1[3]); *(u32x4*)(xr + bj * HALF) = w; }
;                     part_ss += (v0[0] * v0[0] + v0[1] * v0[1]) + (v0[2] * v0[2] + v0[3] * v0[3]) + (v1[0] * v1[0] + v1[1] * v1[1]) + (v1[2] * v1[2] + v1[3] * v1[3]);
;                 }
;                 part_ss += __shfl_xor(part_ss, 16); part_ss += __shfl_xor(part_ss, 32);
;                 if (fq == 0) atomicAdd(ss + row, part_ss);
;             }
.LBB0_597:
	s_or_b64 exec, exec, s[6:7]
	v_lshlrev_b32_e32 v188, 16, v180
	v_and_b32_e32 v180, 0xffff0000, v180
	v_add_f32_e32 v189, v117, v180
	v_lshlrev_b32_e32 v180, 16, v181
	v_add_f32_e32 v190, v118, v180
	v_and_b32_e32 v180, 0xffff0000, v181
	v_add_f32_e32 v191, v119, v180
	v_lshlrev_b32_e32 v180, 16, v182
	s_waitcnt lgkmcnt(0)
	v_lshl_add_u64 v[186:187], s[30:31], 0, v[234:235]
	v_add_f32_e32 v234, v108, v180
	v_and_b32_e32 v180, 0xffff0000, v182
	v_add_f32_e32 v182, v109, v180
	v_lshlrev_b32_e32 v180, 16, v183
	v_add_f32_e32 v235, v110, v180
	v_and_b32_e32 v180, 0xffff0000, v183
	v_add_f32_e32 v188, v116, v188
	v_add_f32_e32 v183, v111, v180
	v_cvt_pk_bf16_f32 v180, v188, v189
	v_mul_f32_e32 v189, v189, v189
	v_fmac_f32_e32 v189, v188, v188
	v_mul_f32_e32 v188, v191, v191
	v_fmac_f32_e32 v188, v190, v190
	v_add_f32_e32 v188, v189, v188
	v_mul_f32_e32 v189, v182, v182
	v_cvt_pk_bf16_f32 v181, v190, v191
	v_fmac_f32_e32 v189, v234, v234
	v_lshlrev_b32_e32 v190, 16, v177
	v_and_b32_e32 v177, 0xffff0000, v177
	v_add_f32_e32 v188, v189, v188
	v_mul_f32_e32 v189, v183, v183
	v_add_f32_e32 v191, v99, v177
	v_lshlrev_b32_e32 v177, 16, v178
	v_fmac_f32_e32 v189, v235, v235
	v_add_f32_e32 v236, v88, v177
	v_and_b32_e32 v177, 0xffff0000, v178
	v_add_f32_e32 v188, v189, v188
	v_lshlrev_b32_e32 v189, 16, v176
	v_and_b32_e32 v176, 0xffff0000, v176
	v_add_f32_e32 v237, v89, v177
	v_lshlrev_b32_e32 v177, 16, v179
	v_add_f32_e32 v176, v97, v176
	v_add_f32_e32 v246, v90, v177
	v_and_b32_e32 v177, 0xffff0000, v179
	v_add_f32_e32 v189, v96, v189
	v_add_f32_e32 v190, v98, v190
	v_add_f32_e32 v247, v91, v177
	v_mul_f32_e32 v177, v176, v176
	v_mul_f32_e32 v178, v191, v191
	v_fmac_f32_e32 v177, v189, v189
	v_fmac_f32_e32 v178, v190, v190
	v_add_f32_e32 v177, v177, v178
	v_mul_f32_e32 v178, v237, v237
	v_fmac_f32_e32 v178, v236, v236
	v_add_f32_e32 v177, v178, v177
	v_mul_f32_e32 v178, v247, v247
	v_fmac_f32_e32 v178, v246, v246
	v_add_f32_e32 v177, v178, v177
	v_add_f32_e32 v177, v188, v177
	ds_bpermute_b32 v179, v184, v177
	v_lshl_add_u64 v[186:187], v[204:205], 1, v[186:187]
	v_cvt_pk_bf16_f32 v182, v234, v182
	v_cvt_pk_bf16_f32 v183, v235, v183
	global_store_dwordx4 v[186:187], v[180:183], off sc1
	v_cvt_pk_bf16_f32 v178, v189, v176
	s_waitcnt lgkmcnt(0)
	v_add_f32_e32 v176, v177, v179
	ds_bpermute_b32 v177, v185, v176
	v_cvt_pk_bf16_f32 v179, v190, v191
	v_cvt_pk_bf16_f32 v180, v236, v237
	v_cvt_pk_bf16_f32 v181, v246, v247
	global_store_dwordx4 v[186:187], v[178:181], off offset:256 sc1
	s_and_saveexec_b64 s[6:7], s[2:3]
	s_cbranch_execz .LBB0_599
	s_waitcnt lgkmcnt(0)
	v_add_f32_e32 v178, v176, v177
	v_lshl_add_u64 v[176:177], v[230:231], 2, s[38:39]
	global_atomic_add_f32 v[176:177], v178, off
.LBB0_599:
	s_or_b64 exec, exec, s[6:7]
	v_lshlrev_b32_e32 v178, 16, v172
	v_and_b32_e32 v172, 0xffff0000, v172
	v_add_f32_e32 v179, v101, v172
	v_lshlrev_b32_e32 v172, 16, v173
	v_add_f32_e32 v180, v102, v172
	v_and_b32_e32 v172, 0xffff0000, v173
	v_add_f32_e32 v181, v103, v172
	v_lshlrev_b32_e32 v172, 16, v174
	v_add_f32_e32 v182, v92, v172
	v_and_b32_e32 v172, 0xffff0000, v174
	v_add_f32_e32 v174, v93, v172
	v_lshlrev_b32_e32 v172, 16, v175
	v_add_f32_e32 v183, v94, v172
	v_and_b32_e32 v172, 0xffff0000, v175
	v_add_f32_e32 v178, v100, v178
	v_add_f32_e32 v175, v95, v172
	v_cvt_pk_bf16_f32 v172, v178, v179
	v_mul_f32_e32 v179, v179, v179
	v_fmac_f32_e32 v179, v178, v178
	v_mul_f32_e32 v178, v181, v181
	v_fmac_f32_e32 v178, v180, v180
	v_add_f32_e32 v178, v179, v178
	v_mul_f32_e32 v179, v174, v174
	v_cvt_pk_bf16_f32 v173, v180, v181
	v_fmac_f32_e32 v179, v182, v182
	v_lshlrev_b32_e32 v180, 16, v169
	v_and_b32_e32 v169, 0xffff0000, v169
	v_add_f32_e32 v178, v179, v178
	v_mul_f32_e32 v179, v175, v175
	v_add_f32_e32 v181, v83, v169
	v_lshlrev_b32_e32 v169, 16, v170
	v_fmac_f32_e32 v179, v183, v183
	v_add_f32_e32 v186, v72, v169
	v_and_b32_e32 v169, 0xffff0000, v170
	v_add_f32_e32 v178, v179, v178
	v_lshlrev_b32_e32 v179, 16, v168
	v_and_b32_e32 v168, 0xffff0000, v168
	v_add_f32_e32 v187, v73, v169
	v_lshlrev_b32_e32 v169, 16, v171
	v_add_f32_e32 v168, v81, v168
	v_add_f32_e32 v188, v74, v169
	v_and_b32_e32 v169, 0xffff0000, v171
	v_add_f32_e32 v179, v80, v179
	v_add_f32_e32 v180, v82, v180
	v_add_f32_e32 v189, v75, v169
	v_mul_f32_e32 v169, v168, v168
	v_mul_f32_e32 v170, v181, v181
	v_fmac_f32_e32 v169, v179, v179
	v_fmac_f32_e32 v170, v180, v180
	v_add_f32_e32 v169, v169, v170
	v_mul_f32_e32 v170, v187, v187
	v_fmac_f32_e32 v170, v186, v186
	v_add_f32_e32 v169, v170, v169
	v_mul_f32_e32 v170, v189, v189
	v_fmac_f32_e32 v170, v188, v188
	v_add_f32_e32 v169, v170, v169
	v_add_f32_e32 v169, v178, v169
	ds_bpermute_b32 v171, v184, v169
	s_waitcnt lgkmcnt(1)
	v_lshl_add_u64 v[176:177], s[30:31], 0, v[232:233]
	v_lshl_add_u64 v[176:177], v[204:205], 1, v[176:177]
	v_cvt_pk_bf16_f32 v174, v182, v174
	v_cvt_pk_bf16_f32 v175, v183, v175
	global_store_dwordx4 v[176:177], v[172:175], off sc1
	v_cvt_pk_bf16_f32 v170, v179, v168
	s_waitcnt lgkmcnt(0)
	v_add_f32_e32 v168, v169, v171
	ds_bpermute_b32 v169, v185, v168
	v_cvt_pk_bf16_f32 v171, v180, v181
	v_cvt_pk_bf16_f32 v172, v186, v187
	v_cvt_pk_bf16_f32 v173, v188, v189
	global_store_dwordx4 v[176:177], v[170:173], off offset:256 sc1
	s_and_saveexec_b64 s[6:7], s[2:3]
	s_cbranch_execz .LBB0_601
	s_waitcnt lgkmcnt(0)
	v_add_f32_e32 v170, v168, v169
	v_lshl_add_u64 v[168:169], v[226:227], 2, s[38:39]
	global_atomic_add_f32 v[168:169], v170, off
; __device__ __forceinline__ unsigned cvt_pk_bf16(float lo, float hi) { unsigned r; asm volatile("v_cvt_pk_bf16_f32 %0, %1, %2" : "=v"(r) : "v"(lo), "v"(hi)); return r; }
;     __device__ __forceinline__ void operator()(const f32x4 (&acc)[2][2][4][2], const Unit& u, int wr, int wc, int fr, int fq) const {
;     ...
;         for (int ai = 0; ai < 2; ++ai)
; #pragma unroll
;             for (int m = 0; m < 4; ++m) {
;                 const int row = row0 + ai * HALF + m * 16;
;                 bf16_t* xr = xb + (size_t)row * 1024 + col0;
;                 float part_ss = 0.f;
; #pragma unroll
;                 for (int bj = 0; bj < 2; ++bj) {
;                     const u32x4 o = xo[ai][m][bj];
;                     f32x4 v0 = acc[ai][bj][m][0], v1 = acc[ai][bj][m][1];
;                     v0[0] += __uint_as_float(o.x << 16); v0[1] += __uint_as_float(o.x & 0xffff0000u); v0[2] += __uint_as_float(o.y << 16); v0[3] += __uint_as_float(o.y & 0xffff0000u);
;                     v1[0] += __uint_as_float(o.z << 16); v1[1] += __uint_as_float(o.z & 0xffff0000u); v1[2] += __uint_as_float(o.w << 16); v1[3] += __uint_as_float(o.w & 0xffff0000u);
;                     if (xout) { float* xo = xout + (size_t)row * 1024 + col0 + bj * HALF; *(f32x4*)xo = v0; *(f32x4*)(xo + 4) = v1; }
;                     else { u32x4 w; w.x = cvt_pk_bf16(v0[0], v0[1]); w.y = cvt_pk_bf16(v0[2], v0[3]); w.z = cvt_pk_bf16(v1[0], v1[1]); w.w = cvt_pk_bf16(v1[2], v1[3]); *(u32x4*)(xr + bj * HALF) = w; }
;                     part_ss += (v0[0] * v0[0] + v0[1] * v0[1]) + (v0[2] * v0[2] + v0[3] * v0[3]) + (v1[0] * v1[0] + v1[1] * v1[1]) + (v1[2] * v1[2] + v1[3] * v1[3]);
;                 }
;                 part_ss += __shfl_xor(part_ss, 16); part_ss += __shfl_xor(part_ss, 32);
;                 if (fq == 0) atomicAdd(ss + row, part_ss);
;             }
.LBB0_601:
	s_or_b64 exec, exec, s[6:7]
	v_lshlrev_b32_e32 v170, 16, v164
	v_and_b32_e32 v164, 0xffff0000, v164
	v_add_f32_e32 v171, v85, v164
	v_lshlrev_b32_e32 v164, 16, v165
	v_add_f32_e32 v172, v86, v164
	v_and_b32_e32 v164, 0xffff0000, v165
	v_add_f32_e32 v173, v87, v164
	v_lshlrev_b32_e32 v164, 16, v166
	v_add_f32_e32 v174, v76, v164
	v_and_b32_e32 v164, 0xffff0000, v166
	v_add_f32_e32 v166, v77, v164
	v_lshlrev_b32_e32 v164, 16, v167
	v_add_f32_e32 v175, v78, v164
	v_and_b32_e32 v164, 0xffff0000, v167
	v_add_f32_e32 v170, v84, v170
	v_add_f32_e32 v167, v79, v164
	v_cvt_pk_bf16_f32 v164, v170, v171
	v_mul_f32_e32 v171, v171, v171
	v_fmac_f32_e32 v171, v170, v170
	v_mul_f32_e32 v170, v173, v173
	v_fmac_f32_e32 v170, v172, v172
	v_add_f32_e32 v170, v171, v170
	v_mul_f32_e32 v171, v166, v166
	v_cvt_pk_bf16_f32 v165, v172, v173
	v_fmac_f32_e32 v171, v174, v174
	v_lshlrev_b32_e32 v172, 16, v161
	v_and_b32_e32 v161, 0xffff0000, v161
	v_add_f32_e32 v170, v171, v170
	v_mul_f32_e32 v171, v167, v167
	v_add_f32_e32 v173, v71, v161
	v_lshlrev_b32_e32 v161, 16, v162
	v_fmac_f32_e32 v171, v175, v175
	v_add_f32_e32 v176, v64, v161
	v_and_b32_e32 v161, 0xffff0000, v162
	v_add_f32_e32 v170, v171, v170
	v_lshlrev_b32_e32 v171, 16, v160
	v_and_b32_e32 v160, 0xffff0000, v160
	v_add_f32_e32 v177, v65, v161
	v_lshlrev_b32_e32 v161, 16, v163
	v_add_f32_e32 v160, v69, v160
	v_add_f32_e32 v178, v66, v161
	v_and_b32_e32 v161, 0xffff0000, v163
	v_add_f32_e32 v171, v68, v171
	v_add_f32_e32 v172, v70, v172
	v_add_f32_e32 v179, v67, v161
	v_mul_f32_e32 v161, v160, v160
	v_mul_f32_e32 v162, v173, v173
	v_fmac_f32_e32 v161, v171, v171
	v_fmac_f32_e32 v162, v172, v172
	v_add_f32_e32 v161, v161, v162
	v_mul_f32_e32 v162, v177, v177
	v_fmac_f32_e32 v162, v176, v176
	v_add_f32_e32 v161, v162, v161
	v_mul_f32_e32 v162, v179, v179
	v_fmac_f32_e32 v162, v178, v178
	v_add_f32_e32 v161, v162, v161
	v_add_f32_e32 v161, v170, v161
	ds_bpermute_b32 v163, v184, v161
	s_waitcnt lgkmcnt(1)
	v_lshl_add_u64 v[168:169], s[30:31], 0, v[228:229]
	v_lshl_add_u64 v[168:169], v[204:205], 1, v[168:169]
	v_cvt_pk_bf16_f32 v166, v174, v166
	v_cvt_pk_bf16_f32 v167, v175, v167
	global_store_dwordx4 v[168:169], v[164:167], off sc1
	v_cvt_pk_bf16_f32 v162, v171, v160
	s_waitcnt lgkmcnt(0)
	v_add_f32_e32 v160, v161, v163
	ds_bpermute_b32 v161, v185, v160
	v_cvt_pk_bf16_f32 v163, v172, v173
	v_cvt_pk_bf16_f32 v164, v176, v177
	v_cvt_pk_bf16_f32 v165, v178, v179
	global_store_dwordx4 v[168:169], v[162:165], off offset:256 sc1
	s_and_saveexec_b64 s[6:7], s[2:3]
	s_cbranch_execz .LBB0_603
	s_waitcnt lgkmcnt(0)
	v_add_f32_e32 v162, v160, v161
	v_lshl_add_u64 v[160:161], v[222:223], 2, s[38:39]
	global_atomic_add_f32 v[160:161], v162, off
.LBB0_603:
	s_or_b64 exec, exec, s[6:7]
	v_lshlrev_b32_e32 v162, 16, v156
	v_and_b32_e32 v156, 0xffff0000, v156
	v_add_f32_e32 v163, v61, v156
	v_lshlrev_b32_e32 v156, 16, v157
	v_add_f32_e32 v164, v62, v156
	v_and_b32_e32 v156, 0xffff0000, v157
	v_add_f32_e32 v165, v63, v156
	v_lshlrev_b32_e32 v156, 16, v158
	v_add_f32_e32 v166, v56, v156
	v_and_b32_e32 v156, 0xffff0000, v158
	v_add_f32_e32 v158, v57, v156
	v_lshlrev_b32_e32 v156, 16, v159
	v_add_f32_e32 v167, v58, v156
	v_and_b32_e32 v156, 0xffff0000, v159
	v_add_f32_e32 v162, v60, v162
	v_add_f32_e32 v159, v59, v156
	v_cvt_pk_bf16_f32 v156, v162, v163
	v_mul_f32_e32 v163, v163, v163
	v_fmac_f32_e32 v163, v162, v162
	v_mul_f32_e32 v162, v165, v165
	v_fmac_f32_e32 v162, v164, v164
	v_add_f32_e32 v162, v163, v162
	v_mul_f32_e32 v163, v158, v158
	v_cvt_pk_bf16_f32 v157, v164, v165
	v_fmac_f32_e32 v163, v166, v166
	v_lshlrev_b32_e32 v164, 16, v153
	v_and_b32_e32 v153, 0xffff0000, v153
	v_add_f32_e32 v162, v163, v162
	v_mul_f32_e32 v163, v159, v159
	v_add_f32_e32 v165, v51, v153
	v_lshlrev_b32_e32 v153, 16, v154
	v_fmac_f32_e32 v163, v167, v167
	v_add_f32_e32 v168, v40, v153
	v_and_b32_e32 v153, 0xffff0000, v154
	v_add_f32_e32 v162, v163, v162
	v_lshlrev_b32_e32 v163, 16, v152
	v_and_b32_e32 v152, 0xffff0000, v152
	v_add_f32_e32 v169, v41, v153
	v_lshlrev_b32_e32 v153, 16, v155
	v_add_f32_e32 v152, v49, v152
	v_add_f32_e32 v170, v42, v153
	v_and_b32_e32 v153, 0xffff0000, v155
	v_add_f32_e32 v163, v48, v163
	v_add_f32_e32 v164, v50, v164
	v_add_f32_e32 v171, v43, v153
	v_mul_f32_e32 v153, v152, v152
	v_mul_f32_e32 v154, v165, v165
	v_fmac_f32_e32 v153, v163, v163
	v_fmac_f32_e32 v154, v164, v164
	v_add_f32_e32 v153, v153, v154
	v_mul_f32_e32 v154, v169, v169
	v_fmac_f32_e32 v154, v168, v168
	v_add_f32_e32 v153, v154, v153
	v_mul_f32_e32 v154, v171, v171
	v_fmac_f32_e32 v154, v170, v170
	v_add_f32_e32 v153, v154, v153
	v_add_f32_e32 v153, v162, v153
	ds_bpermute_b32 v155, v184, v153
	s_waitcnt lgkmcnt(1)
	v_lshl_add_u64 v[160:161], s[30:31], 0, v[224:225]
	v_lshl_add_u64 v[160:161], v[204:205], 1, v[160:161]
	v_cvt_pk_bf16_f32 v158, v166, v158
	v_cvt_pk_bf16_f32 v159, v167, v159
	global_store_dwordx4 v[160:161], v[156:159], off sc1
	v_cvt_pk_bf16_f32 v154, v163, v152
	s_waitcnt lgkmcnt(0)
	v_add_f32_e32 v152, v153, v155
	ds_bpermute_b32 v153, v185, v152
	v_cvt_pk_bf16_f32 v155, v164, v165
	v_cvt_pk_bf16_f32 v156, v168, v169
	v_cvt_pk_bf16_f32 v157, v170, v171
	global_store_dwordx4 v[160:161], v[154:157], off offset:256 sc1
	s_and_saveexec_b64 s[6:7], s[2:3]
	s_cbranch_execz .LBB0_605
	s_waitcnt lgkmcnt(0)
	v_add_f32_e32 v154, v152, v153
	v_lshl_add_u64 v[152:153], v[218:219], 2, s[38:39]
	global_atomic_add_f32 v[152:153], v154, off
; __device__ __forceinline__ unsigned cvt_pk_bf16(float lo, float hi) { unsigned r; asm volatile("v_cvt_pk_bf16_f32 %0, %1, %2" : "=v"(r) : "v"(lo), "v"(hi)); return r; }
;     __device__ __forceinline__ void operator()(const f32x4 (&acc)[2][2][4][2], const Unit& u, int wr, int wc, int fr, int fq) const {
;     ...
;         for (int ai = 0; ai < 2; ++ai)
; #pragma unroll
;             for (int m = 0; m < 4; ++m) {
;                 const int row = row0 + ai * HALF + m * 16;
;                 bf16_t* xr = xb + (size_t)row * 1024 + col0;
;                 float part_ss = 0.f;
; #pragma unroll
;                 for (int bj = 0; bj < 2; ++bj) {
;                     const u32x4 o = xo[ai][m][bj];
;                     f32x4 v0 = acc[ai][bj][m][0], v1 = acc[ai][bj][m][1];
;                     v0[0] += __uint_as_float(o.x << 16); v0[1] += __uint_as_float(o.x & 0xffff0000u); v0[2] += __uint_as_float(o.y << 16); v0[3] += __uint_as_float(o.y & 0xffff0000u);
;                     v1[0] += __uint_as_float(o.z << 16); v1[1] += __uint_as_float(o.z & 0xffff0000u); v1[2] += __uint_as_float(o.w << 16); v1[3] += __uint_as_float(o.w & 0xffff0000u);
;                     if (xout) { float* xo = xout + (size_t)row * 1024 + col0 + bj * HALF; *(f32x4*)xo = v0; *(f32x4*)(xo + 4) = v1; }
;                     else { u32x4 w; w.x = cvt_pk_bf16(v0[0], v0[1]); w.y = cvt_pk_bf16(v0[2], v0[3]); w.z = cvt_pk_bf16(v1[0], v1[1]); w.w = cvt_pk_bf16(v1[2], v1[3]); *(u32x4*)(xr + bj * HALF) = w; }
;                     part_ss += (v0[0] * v0[0] + v0[1] * v0[1]) + (v0[2] * v0[2] + v0[3] * v0[3]) + (v1[0] * v1[0] + v1[1] * v1[1]) + (v1[2] * v1[2] + v1[3] * v1[3]);
;                 }
;                 part_ss += __shfl_xor(part_ss, 16); part_ss += __shfl_xor(part_ss, 32);
;                 if (fq == 0) atomicAdd(ss + row, part_ss);
;             }
.LBB0_605:
	s_or_b64 exec, exec, s[6:7]
	v_lshlrev_b32_e32 v154, 16, v148
	v_and_b32_e32 v148, 0xffff0000, v148
	v_add_f32_e32 v155, v53, v148
	v_lshlrev_b32_e32 v148, 16, v149
	v_add_f32_e32 v156, v54, v148
	v_and_b32_e32 v148, 0xffff0000, v149
	v_add_f32_e32 v157, v55, v148
	v_lshlrev_b32_e32 v148, 16, v150
	v_add_f32_e32 v158, v44, v148
	v_and_b32_e32 v148, 0xffff0000, v150
	v_add_f32_e32 v150, v45, v148
	v_lshlrev_b32_e32 v148, 16, v151
	v_add_f32_e32 v159, v46, v148
	v_and_b32_e32 v148, 0xffff0000, v151
	v_add_f32_e32 v154, v52, v154
	v_add_f32_e32 v151, v47, v148
	v_cvt_pk_bf16_f32 v148, v154, v155
	v_mul_f32_e32 v155, v155, v155
	v_fmac_f32_e32 v155, v154, v154
	v_mul_f32_e32 v154, v157, v157
	v_fmac_f32_e32 v154, v156, v156
	v_add_f32_e32 v154, v155, v154
	v_mul_f32_e32 v155, v150, v150
	v_cvt_pk_bf16_f32 v149, v156, v157
	v_fmac_f32_e32 v155, v158, v158
	v_lshlrev_b32_e32 v156, 16, v145
	v_and_b32_e32 v145, 0xffff0000, v145
	v_add_f32_e32 v154, v155, v154
	v_mul_f32_e32 v155, v151, v151
	v_add_f32_e32 v157, v35, v145
	v_lshlrev_b32_e32 v145, 16, v146
	v_fmac_f32_e32 v155, v159, v159
	v_add_f32_e32 v160, v24, v145
	v_and_b32_e32 v145, 0xffff0000, v146
	v_add_f32_e32 v154, v155, v154
	v_lshlrev_b32_e32 v155, 16, v144
	v_and_b32_e32 v144, 0xffff0000, v144
	v_add_f32_e32 v161, v25, v145
	v_lshlrev_b32_e32 v145, 16, v147
	v_add_f32_e32 v144, v33, v144
	v_add_f32_e32 v162, v26, v145
	v_and_b32_e32 v145, 0xffff0000, v147
	v_add_f32_e32 v155, v32, v155
	v_add_f32_e32 v156, v34, v156
	v_add_f32_e32 v163, v27, v145
	v_mul_f32_e32 v145, v144, v144
	v_mul_f32_e32 v146, v157, v157
	v_fmac_f32_e32 v145, v155, v155
	v_fmac_f32_e32 v146, v156, v156
	v_add_f32_e32 v145, v145, v146
	v_mul_f32_e32 v146, v161, v161
	v_fmac_f32_e32 v146, v160, v160
	v_add_f32_e32 v145, v146, v145
	v_mul_f32_e32 v146, v163, v163
	v_fmac_f32_e32 v146, v162, v162
	v_add_f32_e32 v145, v146, v145
	v_add_f32_e32 v145, v154, v145
	ds_bpermute_b32 v147, v184, v145
	s_waitcnt lgkmcnt(1)
	v_lshl_add_u64 v[152:153], s[30:31], 0, v[220:221]
	v_lshl_add_u64 v[152:153], v[204:205], 1, v[152:153]
	v_cvt_pk_bf16_f32 v150, v158, v150
	v_cvt_pk_bf16_f32 v151, v159, v151
	global_store_dwordx4 v[152:153], v[148:151], off sc1
	v_cvt_pk_bf16_f32 v146, v155, v144
	s_waitcnt lgkmcnt(0)
	v_add_f32_e32 v144, v145, v147
	ds_bpermute_b32 v145, v185, v144
	v_cvt_pk_bf16_f32 v147, v156, v157
	v_cvt_pk_bf16_f32 v148, v160, v161
	v_cvt_pk_bf16_f32 v149, v162, v163
	global_store_dwordx4 v[152:153], v[146:149], off offset:256 sc1
	s_and_saveexec_b64 s[6:7], s[2:3]
	s_cbranch_execz .LBB0_607
	s_waitcnt lgkmcnt(0)
	v_add_f32_e32 v146, v144, v145
	v_lshl_add_u64 v[144:145], v[214:215], 2, s[38:39]
	global_atomic_add_f32 v[144:145], v146, off
; __device__ __forceinline__ unsigned cvt_pk_bf16(float lo, float hi) { unsigned r; asm volatile("v_cvt_pk_bf16_f32 %0, %1, %2" : "=v"(r) : "v"(lo), "v"(hi)); return r; }
;     __device__ __forceinline__ void operator()(const f32x4 (&acc)[2][2][4][2], const Unit& u, int wr, int wc, int fr, int fq) const {
;     ...
;         for (int ai = 0; ai < 2; ++ai)
; #pragma unroll
;             for (int m = 0; m < 4; ++m) {
;                 const int row = row0 + ai * HALF + m * 16;
;                 bf16_t* xr = xb + (size_t)row * 1024 + col0;
;                 float part_ss = 0.f;
; #pragma unroll
;                 for (int bj = 0; bj < 2; ++bj) {
;                     const u32x4 o = xo[ai][m][bj];
;                     f32x4 v0 = acc[ai][bj][m][0], v1 = acc[ai][bj][m][1];
;                     v0[0] += __uint_as_float(o.x << 16); v0[1] += __uint_as_float(o.x & 0xffff0000u); v0[2] += __uint_as_float(o.y << 16); v0[3] += __uint_as_float(o.y & 0xffff0000u);
;                     v1[0] += __uint_as_float(o.z << 16); v1[1] += __uint_as_float(o.z & 0xffff0000u); v1[2] += __uint_as_float(o.w << 16); v1[3] += __uint_as_float(o.w & 0xffff0000u);
;                     if (xout) { float* xo = xout + (size_t)row * 1024 + col0 + bj * HALF; *(f32x4*)xo = v0; *(f32x4*)(xo + 4) = v1; }
;                     else { u32x4 w; w.x = cvt_pk_bf16(v0[0], v0[1]); w.y = cvt_pk_bf16(v0[2], v0[3]); w.z = cvt_pk_bf16(v1[0], v1[1]); w.w = cvt_pk_bf16(v1[2], v1[3]); *(u32x4*)(xr + bj * HALF) = w; }
;                     part_ss += (v0[0] * v0[0] + v0[1] * v0[1]) + (v0[2] * v0[2] + v0[3] * v0[3]) + (v1[0] * v1[0] + v1[1] * v1[1]) + (v1[2] * v1[2] + v1[3] * v1[3]);
;                 }
;                 part_ss += __shfl_xor(part_ss, 16); part_ss += __shfl_xor(part_ss, 32);
;                 if (fq == 0) atomicAdd(ss + row, part_ss);
;             }
.LBB0_607:
	s_or_b64 exec, exec, s[6:7]
	v_lshlrev_b32_e32 v146, 16, v140
	v_and_b32_e32 v140, 0xffff0000, v140
	v_add_f32_e32 v147, v37, v140
	v_lshlrev_b32_e32 v140, 16, v141
	v_add_f32_e32 v148, v38, v140
	v_and_b32_e32 v140, 0xffff0000, v141
	v_add_f32_e32 v149, v39, v140
	v_lshlrev_b32_e32 v140, 16, v142
	v_add_f32_e32 v150, v28, v140
	v_and_b32_e32 v140, 0xffff0000, v142
	v_add_f32_e32 v142, v29, v140
	v_lshlrev_b32_e32 v140, 16, v143
	v_add_f32_e32 v151, v30, v140
	v_and_b32_e32 v140, 0xffff0000, v143
	v_add_f32_e32 v146, v36, v146
	v_add_f32_e32 v143, v31, v140
	v_cvt_pk_bf16_f32 v140, v146, v147
	v_mul_f32_e32 v147, v147, v147
	v_fmac_f32_e32 v147, v146, v146
	v_mul_f32_e32 v146, v149, v149
	v_fmac_f32_e32 v146, v148, v148
	v_add_f32_e32 v146, v147, v146
	v_mul_f32_e32 v147, v142, v142
	v_cvt_pk_bf16_f32 v141, v148, v149
	v_fmac_f32_e32 v147, v150, v150
	v_lshlrev_b32_e32 v148, 16, v137
	v_and_b32_e32 v137, 0xffff0000, v137
	v_add_f32_e32 v146, v147, v146
	v_mul_f32_e32 v147, v143, v143
	v_add_f32_e32 v149, v19, v137
	v_lshlrev_b32_e32 v137, 16, v138
	v_fmac_f32_e32 v147, v151, v151
	v_add_f32_e32 v152, v8, v137
	v_and_b32_e32 v137, 0xffff0000, v138
	v_add_f32_e32 v146, v147, v146
	v_lshlrev_b32_e32 v147, 16, v136
	v_and_b32_e32 v136, 0xffff0000, v136
	v_add_f32_e32 v153, v9, v137
	v_lshlrev_b32_e32 v137, 16, v139
	v_add_f32_e32 v136, v17, v136
	v_add_f32_e32 v154, v10, v137
	v_and_b32_e32 v137, 0xffff0000, v139
	v_add_f32_e32 v147, v16, v147
	v_add_f32_e32 v148, v18, v148
	v_add_f32_e32 v155, v11, v137
	v_mul_f32_e32 v137, v136, v136
	v_mul_f32_e32 v138, v149, v149
	v_fmac_f32_e32 v137, v147, v147
	v_fmac_f32_e32 v138, v148, v148
	v_add_f32_e32 v137, v137, v138
	v_mul_f32_e32 v138, v153, v153
	v_fmac_f32_e32 v138, v152, v152
	v_add_f32_e32 v137, v138, v137
	v_mul_f32_e32 v138, v155, v155
	v_fmac_f32_e32 v138, v154, v154
	v_add_f32_e32 v137, v138, v137
	v_add_f32_e32 v137, v146, v137
	ds_bpermute_b32 v139, v184, v137
	s_waitcnt lgkmcnt(1)
	v_lshl_add_u64 v[144:145], s[30:31], 0, v[216:217]
	v_lshl_add_u64 v[144:145], v[204:205], 1, v[144:145]
	v_cvt_pk_bf16_f32 v142, v150, v142
	v_cvt_pk_bf16_f32 v143, v151, v143
	global_store_dwordx4 v[144:145], v[140:143], off sc1
	v_cvt_pk_bf16_f32 v138, v147, v136
	s_waitcnt lgkmcnt(0)
	v_add_f32_e32 v136, v137, v139
	ds_bpermute_b32 v137, v185, v136
	v_cvt_pk_bf16_f32 v139, v148, v149
	v_cvt_pk_bf16_f32 v140, v152, v153
	v_cvt_pk_bf16_f32 v141, v154, v155
	global_store_dwordx4 v[144:145], v[138:141], off offset:256 sc1
	s_and_saveexec_b64 s[6:7], s[2:3]
	s_cbranch_execz .LBB0_609
	s_waitcnt lgkmcnt(0)
	v_add_f32_e32 v138, v136, v137
	v_lshl_add_u64 v[136:137], v[210:211], 2, s[38:39]
	global_atomic_add_f32 v[136:137], v138, off
.LBB0_609:
	s_or_b64 exec, exec, s[6:7]
	v_lshlrev_b32_e32 v138, 16, v132
	v_and_b32_e32 v132, 0xffff0000, v132
	v_add_f32_e32 v139, v21, v132
	v_lshlrev_b32_e32 v132, 16, v133
	v_add_f32_e32 v140, v22, v132
	v_and_b32_e32 v132, 0xffff0000, v133
	v_add_f32_e32 v141, v23, v132
	v_lshlrev_b32_e32 v132, 16, v134
	v_add_f32_e32 v142, v12, v132
	v_and_b32_e32 v132, 0xffff0000, v134
	v_add_f32_e32 v134, v13, v132
	v_lshlrev_b32_e32 v132, 16, v135
	v_add_f32_e32 v143, v14, v132
	v_and_b32_e32 v132, 0xffff0000, v135
	v_add_f32_e32 v138, v20, v138
	v_add_f32_e32 v135, v15, v132
	v_cvt_pk_bf16_f32 v132, v138, v139
	v_mul_f32_e32 v139, v139, v139
	v_fmac_f32_e32 v139, v138, v138
	v_mul_f32_e32 v138, v141, v141
	v_fmac_f32_e32 v138, v140, v140
	v_add_f32_e32 v138, v139, v138
	v_mul_f32_e32 v139, v134, v134
	v_cvt_pk_bf16_f32 v133, v140, v141
	v_fmac_f32_e32 v139, v142, v142
	v_lshlrev_b32_e32 v140, 16, v129
	v_and_b32_e32 v129, 0xffff0000, v129
	v_add_f32_e32 v138, v139, v138
	v_mul_f32_e32 v139, v135, v135
	v_add_f32_e32 v141, v7, v129
	v_lshlrev_b32_e32 v129, 16, v130
	v_fmac_f32_e32 v139, v143, v143
	v_add_f32_e32 v144, v0, v129
	v_and_b32_e32 v129, 0xffff0000, v130
	v_add_f32_e32 v138, v139, v138
	v_lshlrev_b32_e32 v139, 16, v128
	v_and_b32_e32 v128, 0xffff0000, v128
	v_add_f32_e32 v145, v1, v129
	v_lshlrev_b32_e32 v129, 16, v131
	v_add_f32_e32 v128, v5, v128
	v_add_f32_e32 v146, v2, v129
	v_and_b32_e32 v129, 0xffff0000, v131
	v_add_f32_e32 v139, v4, v139
	v_add_f32_e32 v140, v6, v140
	v_add_f32_e32 v147, v3, v129
	v_mul_f32_e32 v129, v128, v128
	v_mul_f32_e32 v130, v141, v141
	v_fmac_f32_e32 v129, v139, v139
	v_fmac_f32_e32 v130, v140, v140
	v_add_f32_e32 v129, v129, v130
	v_mul_f32_e32 v130, v145, v145
	v_fmac_f32_e32 v130, v144, v144
	v_add_f32_e32 v129, v130, v129
	v_mul_f32_e32 v130, v147, v147
	v_fmac_f32_e32 v130, v146, v146
	v_add_f32_e32 v129, v130, v129
	v_add_f32_e32 v129, v138, v129
	ds_bpermute_b32 v131, v184, v129
	s_waitcnt lgkmcnt(1)
	v_lshl_add_u64 v[136:137], s[30:31], 0, v[212:213]
	v_lshl_add_u64 v[136:137], v[204:205], 1, v[136:137]
	v_cvt_pk_bf16_f32 v134, v142, v134
	v_cvt_pk_bf16_f32 v135, v143, v135
	global_store_dwordx4 v[136:137], v[132:135], off sc1
	v_cvt_pk_bf16_f32 v130, v139, v128
	s_waitcnt lgkmcnt(0)
	v_add_f32_e32 v128, v129, v131
	ds_bpermute_b32 v129, v185, v128
	v_cvt_pk_bf16_f32 v131, v140, v141
	v_cvt_pk_bf16_f32 v132, v144, v145
	v_cvt_pk_bf16_f32 v133, v146, v147
	global_store_dwordx4 v[136:137], v[130:133], off offset:256 sc1
	s_and_saveexec_b64 s[6:7], s[2:3]
	s_cbranch_execz .LBB0_611
	s_waitcnt lgkmcnt(0)
	v_add_f32_e32 v130, v128, v129
	v_lshl_add_u64 v[128:129], v[208:209], 2, s[38:39]
	global_atomic_add_f32 v[128:129], v130, off

; __device__ __forceinline__ unsigned cvt_pk_bf16(float lo, float hi) { unsigned r; asm volatile("v_cvt_pk_bf16_f32 %0, %1, %2" : "=v"(r) : "v"(lo), "v"(hi)); return r; }
;     __device__ __forceinline__ void operator()(const f32x4 (&acc)[2][2][4][2], const Unit& u, int wr, int wc, int fr, int fq) const {
;     ...
;         if (u.sp >= 0) {
;             bf16_t* pb = (bf16_t*)part + ((size_t)u.sp * 1024 + (row0 - 16384)) * 1024 + col0;
; #pragma unroll
;             for (int ai = 0; ai < 2; ++ai)
; #pragma unroll
;                 for (int m = 0; m < 4; ++m)
; #pragma unroll
;                     for (int bj = 0; bj < 2; ++bj) { const f32x4 v0 = acc[ai][bj][m][0], v1 = acc[ai][bj][m][1];
;                         u32x4 w; w.x = cvt_pk_bf16(v0[0], v0[1]); w.y = cvt_pk_bf16(v0[2], v0[3]); w.z = cvt_pk_bf16(v1[0], v1[1]); w.w = cvt_pk_bf16(v1[2], v1[3]);
;                         *(u32x4*)(pb + (size_t)(ai * HALF + m * 16) * 1024 + bj * HALF) = w; }
;             return;
.LBB0_613:
	s_and_b64 vcc, exec, s[6:7]
	s_cbranch_vccz .LBB0_612
	s_lshl_b64 s[6:7], s[22:23], 21
	s_add_u32 s6, s88, s6
	s_waitcnt lgkmcnt(0)
	v_lshlrev_b64 v[128:129], 11, v[206:207]
	s_addc_u32 s7, s89, s7
	v_lshl_add_u64 v[128:129], s[6:7], 0, v[128:129]
	s_mov_b32 s6, 0xfe000000
	v_lshl_add_u64 v[128:129], v[204:205], 1, v[128:129]
	s_mov_b32 s7, -1
	v_lshl_add_u64 v[130:131], v[128:129], 0, s[6:7]
	s_mov_b32 s6, 0xfe000000
	v_cvt_pk_bf16_f32 v124, v124, v125
	v_cvt_pk_bf16_f32 v125, v126, v127
	v_cvt_pk_bf16_f32 v126, v120, v121
	v_add_co_u32_e32 v120, vcc, s6, v128
	s_mov_b32 s6, 0xfe008000
	s_nop 0
	v_addc_co_u32_e32 v121, vcc, -1, v129, vcc
	v_cvt_pk_bf16_f32 v127, v122, v123
	global_store_dwordx4 v[120:121], v[124:127], off sc1
	v_cvt_pk_bf16_f32 v112, v112, v113
	v_cvt_pk_bf16_f32 v113, v114, v115
	v_cvt_pk_bf16_f32 v114, v104, v105
	v_cvt_pk_bf16_f32 v115, v106, v107
	global_store_dwordx4 v[130:131], v[112:115], off offset:256 sc1
	v_cvt_pk_bf16_f32 v104, v116, v117
	v_cvt_pk_bf16_f32 v105, v118, v119
	v_cvt_pk_bf16_f32 v106, v108, v109
	v_add_co_u32_e32 v108, vcc, s6, v128
	s_mov_b32 s6, 0xfe009000
	s_nop 0
	v_addc_co_u32_e32 v109, vcc, -1, v129, vcc
	v_cvt_pk_bf16_f32 v107, v110, v111
	global_store_dwordx4 v[108:109], v[104:107], off sc1
	v_cvt_pk_bf16_f32 v96, v96, v97
	v_cvt_pk_bf16_f32 v97, v98, v99
	v_cvt_pk_bf16_f32 v98, v88, v89
	v_add_co_u32_e32 v88, vcc, s6, v128
	s_mov_b32 s6, 0xfe010000
	s_nop 0
	v_addc_co_u32_e32 v89, vcc, -1, v129, vcc
	v_cvt_pk_bf16_f32 v99, v90, v91
	global_store_dwordx4 v[88:89], v[96:99], off offset:-3840 sc1
	v_cvt_pk_bf16_f32 v88, v100, v101
	v_cvt_pk_bf16_f32 v89, v102, v103
	v_cvt_pk_bf16_f32 v90, v92, v93
	v_add_co_u32_e32 v92, vcc, s6, v128
	s_mov_b32 s6, 0xfe011000
	s_nop 0
	v_addc_co_u32_e32 v93, vcc, -1, v129, vcc
	v_cvt_pk_bf16_f32 v91, v94, v95
	global_store_dwordx4 v[92:93], v[88:91], off sc1
	v_cvt_pk_bf16_f32 v80, v80, v81
	v_cvt_pk_bf16_f32 v81, v82, v83
	v_cvt_pk_bf16_f32 v82, v72, v73
	v_add_co_u32_e32 v72, vcc, s6, v128
	s_mov_b32 s6, 0xfe018000
	s_nop 0
	v_addc_co_u32_e32 v73, vcc, -1, v129, vcc
	v_cvt_pk_bf16_f32 v83, v74, v75
	global_store_dwordx4 v[72:73], v[80:83], off offset:-3840 sc1
	v_cvt_pk_bf16_f32 v72, v84, v85
	v_cvt_pk_bf16_f32 v73, v86, v87
	v_cvt_pk_bf16_f32 v74, v76, v77
	v_add_co_u32_e32 v76, vcc, s6, v128
	s_mov_b32 s6, 0xfe019000
	s_nop 0
	v_addc_co_u32_e32 v77, vcc, -1, v129, vcc
	v_cvt_pk_bf16_f32 v75, v78, v79
	global_store_dwordx4 v[76:77], v[72:75], off sc1
	v_cvt_pk_bf16_f32 v68, v68, v69
	v_cvt_pk_bf16_f32 v69, v70, v71
	v_cvt_pk_bf16_f32 v70, v64, v65
	v_add_co_u32_e32 v64, vcc, s6, v128
	s_mov_b32 s6, 0xfe040000
	s_nop 0
	v_addc_co_u32_e32 v65, vcc, -1, v129, vcc
	v_cvt_pk_bf16_f32 v71, v66, v67
	global_store_dwordx4 v[64:65], v[68:71], off offset:-3840 sc1
	v_cvt_pk_bf16_f32 v60, v60, v61
	v_cvt_pk_bf16_f32 v61, v62, v63
	v_cvt_pk_bf16_f32 v62, v56, v57
	v_add_co_u32_e32 v56, vcc, s6, v128
	s_mov_b32 s6, 0xfe041000
	s_nop 0
	v_addc_co_u32_e32 v57, vcc, -1, v129, vcc
	v_cvt_pk_bf16_f32 v63, v58, v59
	global_store_dwordx4 v[56:57], v[60:63], off sc1
	v_cvt_pk_bf16_f32 v48, v48, v49
	v_cvt_pk_bf16_f32 v49, v50, v51
	v_cvt_pk_bf16_f32 v50, v40, v41
	v_add_co_u32_e32 v40, vcc, s6, v128
	s_mov_b32 s6, 0xfe048000
	s_nop 0
	v_addc_co_u32_e32 v41, vcc, -1, v129, vcc
	v_cvt_pk_bf16_f32 v51, v42, v43
	global_store_dwordx4 v[40:41], v[48:51], off offset:-3840 sc1
	v_cvt_pk_bf16_f32 v40, v52, v53
	v_cvt_pk_bf16_f32 v41, v54, v55
	v_cvt_pk_bf16_f32 v42, v44, v45
	v_add_co_u32_e32 v44, vcc, s6, v128
	s_mov_b32 s6, 0xfe049000
	s_nop 0
	v_addc_co_u32_e32 v45, vcc, -1, v129, vcc
	v_cvt_pk_bf16_f32 v43, v46, v47
	global_store_dwordx4 v[44:45], v[40:43], off sc1
	v_cvt_pk_bf16_f32 v32, v32, v33
	v_cvt_pk_bf16_f32 v33, v34, v35
	v_cvt_pk_bf16_f32 v34, v24, v25
	v_add_co_u32_e32 v24, vcc, s6, v128
	s_mov_b32 s6, 0xfe050000
	s_nop 0
	v_addc_co_u32_e32 v25, vcc, -1, v129, vcc
	v_cvt_pk_bf16_f32 v35, v26, v27
	global_store_dwordx4 v[24:25], v[32:35], off offset:-3840 sc1
	v_cvt_pk_bf16_f32 v24, v36, v37
	v_cvt_pk_bf16_f32 v25, v38, v39
	v_cvt_pk_bf16_f32 v26, v28, v29
	v_add_co_u32_e32 v28, vcc, s6, v128
	s_mov_b32 s6, 0xfe051000
	s_nop 0
	v_addc_co_u32_e32 v29, vcc, -1, v129, vcc
	v_cvt_pk_bf16_f32 v27, v30, v31
	global_store_dwordx4 v[28:29], v[24:27], off sc1
	v_cvt_pk_bf16_f32 v16, v16, v17
	v_cvt_pk_bf16_f32 v17, v18, v19
	v_cvt_pk_bf16_f32 v18, v8, v9
	v_add_co_u32_e32 v8, vcc, s6, v128
	s_mov_b32 s6, 0xfe058000
	s_nop 0
	v_addc_co_u32_e32 v9, vcc, -1, v129, vcc
	v_cvt_pk_bf16_f32 v19, v10, v11
	global_store_dwordx4 v[8:9], v[16:19], off offset:-3840 sc1
	v_cvt_pk_bf16_f32 v8, v20, v21
	v_cvt_pk_bf16_f32 v9, v22, v23
	v_cvt_pk_bf16_f32 v10, v12, v13
	v_add_co_u32_e32 v12, vcc, s6, v128
	v_cvt_pk_bf16_f32 v11, v14, v15
	s_nop 1
	v_addc_co_u32_e32 v13, vcc, -1, v129, vcc
	global_store_dwordx4 v[12:13], v[8:11], off sc1
	v_cvt_pk_bf16_f32 v4, v4, v5
	v_cvt_pk_bf16_f32 v5, v6, v7
	v_cvt_pk_bf16_f32 v6, v0, v1
	v_add_co_u32_e32 v0, vcc, 0xfe059000, v128
	v_cvt_pk_bf16_f32 v7, v2, v3
	s_nop 1
	v_addc_co_u32_e32 v1, vcc, -1, v129, vcc
	global_store_dwordx4 v[0:1], v[4:7], off offset:-3840 sc1
	s_andn2_b64 vcc, exec, s[60:61]
	s_mov_b64 s[6:7], -1
	s_cbranch_vccnz .LBB0_585

; #define PG8_STAGE(bufoff, gbase, voff) do { _Pragma("unroll") for (int _i = 0; _i < 2; ++_i) \
;         __builtin_amdgcn_global_load_lds((const unsigned*)((const char*)(gbase) + (voff)[_i]), (PG8_LAS unsigned*)(lds + (bufoff) + ldsw + _i * 8192), 16, 0, 0); } while (0)
; #define PG8_WAIT_V(n) asm volatile("s_waitcnt vmcnt(" #n ")" ::: "memory")
; #define PG8_BAR __builtin_amdgcn_s_barrier()
; template <class Epi, class Sched, bool ALIGN_EPI = false, bool SP2 = false>
; __device__ __forceinline__ void gemm_phase(PG8_LAS unsigned char* lds, const Gemm g, const Sched& S, const Epi& E) {
;     ...
;     const int tid = tid_, wid = __builtin_amdgcn_readfirstlane(tid >> 6), lane = tid & 63, wr = wid >> 2, wc = wid & 3, fr = lane & 15, fq = lane >> 4;
;     const int K = g.K;
;     unsigned voffA[2], voffB[2];
; #pragma unroll
;     for (int i = 0; i < 2; ++i) { int R, C; stage_rc(tid * 16 + i * 8192, R, C); const int Rb = Epi::PERM ? ((R & ~31) + perm32(R & 31)) : R;
;         voffA[i] = g.asub ? (unsigned)((C >> 5) * 16384 + (R * 32 + (C & 31)) * 2) : (unsigned)(R * g.lda + C) * 2u; voffB[i] = (unsigned)(Rb * K + C) * 2u; }
;     const size_t kstep = (size_t)(BK * 2);
;     const size_t hstepB = (size_t)HALF * K * 2, hstepA = (size_t)HALF * g.lda * 2;
;     const size_t tstepB = 2 * hstepB, tstepA = g.tstepA; const size_t kstepA = g.kstepA;
;     const unsigned ldsw = (unsigned)wid * 1024u;
;     const int aoff = lds_byte(wr * 64 + fr, fq * 8), boff = lds_byte(wc * 32 + fr, fq * 8);
;     ...
;     if constexpr (SP2) {
;         PG8_STAGE(PG8_SB(0, 0), cB, voffB); PG8_STAGE(PG8_SB(0, 1), cB + hstepB, voffB); PG8_STAGE(PG8_SA(0, 0), cA, voffA); PG8_STAGE(PG8_SA(0, 1), cA + hstepA, voffA);
;         if (wr == 1) PG8_BAR;
;         PG8_WAIT_V(2); PG8_BAR;
;         PG8_STAGE(PG8_SB(1, 0), cB + kstep, voffB); PG8_STAGE(PG8_SA(1, 0), cA + kstepA, voffA); PG8_STAGE(PG8_SB(1, 1), cB + hstepB + kstep, voffB);
;         PG8_WAIT_V(6); PG8_BAR;
.LBB0_739:
	s_add_u32 s46, s72, 0x55000
	s_addc_u32 s47, s73, 0
	s_add_u32 s50, s72, 0x66000
	s_addc_u32 s51, s73, 0
	s_lshl_b32 s3, s3, 5
	s_mov_b64 s[52:53], 0x80
	s_and_b32 s5, s3, 0x60
	s_add_i32 m0, s65, 0x18000
	v_lshl_add_u64 v[6:7], v[6:7], 0, s[52:53]
	s_lshl_b32 s1, s2, 13
	s_lshl_b32 s3, s5, 7
	s_waitcnt vmcnt(2)
	s_barrier
	global_load_lds_dwordx4 v[6:7], off
	v_lshl_add_u64 v[4:5], v[4:5], 0, s[52:53]
	s_add_i32 m0, s65, 0x1a000
	s_add_i32 s84, s65, 0x8000
	s_add_i32 s85, s65, 0xa000
	global_load_lds_dwordx4 v[4:5], off
	v_lshl_add_u64 v[0:1], v[0:1], 0, s[52:53]
	s_mov_b32 m0, s84
	s_add_u32 s14, s76, 0x40080
	global_load_lds_dwordx4 v[0:1], off
	v_lshl_add_u64 v[0:1], v[2:3], 0, s[52:53]
	s_mov_b32 m0, s85
	s_addc_u32 s15, s77, 0
	global_load_lds_dwordx4 v[0:1], off
	s_add_i32 m0, s65, 0x1c000
	v_lshl_add_u64 v[0:1], s[14:15], 0, v[130:131]
	global_load_lds_dwordx4 v[0:1], off
	v_lshl_add_u64 v[0:1], s[14:15], 0, v[134:135]
	s_add_i32 m0, s65, 0x1e000
	s_cmpk_lt_u32 s4, 0x100
	global_load_lds_dwordx4 v[0:1], off
	v_bfe_u32 v1, v8, 4, 2
	v_and_b32_e32 v0, 15, v8
	v_lshlrev_b32_e32 v2, 4, v1
	v_lshl_or_b32 v162, s2, 6, v0
	v_lshl_or_b32 v0, v0, 6, v2
	v_lshlrev_b32_e32 v2, 2, v8
	v_and_b32_e32 v2, 32, v2
	v_bitop3_b32 v3, v0, s1, v2 bitop3:0xde
	v_bitop3_b32 v163, v0, s3, v2 bitop3:0xde
	v_lshlrev_b32_e32 v0, 14, v9
	v_and_b32_e32 v0, 0xffff8000, v0
	v_cmp_eq_u32_e64 s[2:3], 0, v1
	v_lshl_or_b32 v164, v1, 3, s5
	v_lshl_add_u32 v0, v10, 11, v0
	v_and_b32_e32 v1, 1, v9
	v_lshl_or_b32 v0, v1, 6, v0
	v_lshl_add_u32 v136, v11, 1, v0
	v_lshlrev_b32_e32 v0, 14, v12
	v_and_b32_e32 v0, 0xffff8000, v0
	v_lshl_add_u32 v0, v13, 11, v0
	v_and_b32_e32 v1, 1, v12
	s_waitcnt vmcnt(0)
	v_lshl_or_b32 v0, v1, 6, v0
	s_cselect_b64 s[54:55], -1, 0
	v_lshl_add_u32 v138, v14, 1, v0
	s_add_i32 s91, 0, 0x10000
	s_add_i32 s92, 0, 0x14000
	v_mbcnt_lo_u32_b32 v0, -1, 0
	s_ashr_i32 s86, s10, 31
	s_mov_b32 s87, s10
	s_ashr_i32 s90, s33, 31
	v_mov_b32_e32 v137, v131
	v_mov_b32_e32 v139, v131
	v_mov_b64_e32 v[140:141], 0x198
	v_mov_b64_e32 v[142:143], 0x197
	v_add_u32_e32 v165, s91, v163
	v_add_u32_e32 v166, s92, v163
	v_add_u32_e32 v167, 0, v3
	v_mov_b32_e32 v168, 0x358637bd
	s_movk_i32 s93, 0xc00
	v_mbcnt_hi_u32_b32 v169, -1, v0
	s_barrier
	s_branch .LBB0_742

;     __host__ __device__ __forceinline__ bool next(int i, Unit& u) const { const long L = (long)i * G + c; if (L >= nwg) return false; map((int)L, u); return true; }
; #define PG8_STAGE(bufoff, gbase, voff) do { _Pragma("unroll") for (int _i = 0; _i < 2; ++_i) \
;         __builtin_amdgcn_global_load_lds((const unsigned*)((const char*)(gbase) + (voff)[_i]), (PG8_LAS unsigned*)(lds + (bufoff) + ldsw + _i * 8192), 16, 0, 0); } while (0)
; #define PG8_LDA(dst, b, h) do { _Pragma("unroll") for (int m = 0; m < 4; ++m) _Pragma("unroll") for (int k = 0; k < 2; ++k) dst[m][k] = *(const PG8_LAS bf16x8*)(lds + PG8_SA(b, h) + aoff + m * 2048 + k * 1024); } while (0)
; #define PG8_WAIT_V(n) asm volatile("s_waitcnt vmcnt(" #n ")" ::: "memory")
; #define PG8_BAR __builtin_amdgcn_s_barrier()
; template <class Epi, class Sched, bool ALIGN_EPI = false, bool SP2 = false>
; __device__ __forceinline__ void gemm_phase(PG8_LAS unsigned char* lds, const Gemm g, const Sched& S, const Epi& E) {
;     ...
;         const bool has_next = S.next(ui + 1, nxt);
;         const char* nA = has_next ? (const char*)g.A + (size_t)nxt.pm * tstepA + (size_t)(nxt.k0 >> 6) * kstepA + (nxt.qa > 0 ? hstepA : (size_t)0) : cA; const char* nB = has_next ? (const char*)g.Bt + (size_t)nxt.pn * tstepB + (size_t)nxt.k0 * 2 + (nxt.qb > 0 ? hstepB : (size_t)0) : cB;
;         const bool whole = cur.qa < 0;
;         const int nt = cur.nt;
;         for (int t = 0; t < nt; t += 2) {
;             const bool last = (t == nt - 2);
;             const char* a1 = cA + (size_t)(t + 1) * kstepA;
;             const char* a2 = last ? nA : cA + (size_t)(t + 2) * kstepA; const char* b2 = last ? nB : cB + (size_t)(t + 2) * kstep;
;             const char* a3 = a2 + kstepA; const char* b3 = b2 + kstep;
;             if (last && has_next) S.a_ready(nxt);
;             if constexpr (SP2) {
;             PG8_LDB(B0, 0, 0); PG8_LDB(B1, 0, 1); PG8_SCHED; PG8_LDA(At, 0, 0); PG8_STAGE(PG8_SA(1, 1), a1 + hstepA, voffA);
;             PG8_WAIT_V(8); PG8_WAIT_L(0); PG8_BAR; PG8_MMA(0, 0, At, B0); if (whole) PG8_MMA(0, 1, At, B1); PG8_BAR; PG8_SCHED;
;             PG8_LDA(At, 0, 1); PG8_STAGE(PG8_SB(0, 0), b2, voffB); PG8_STAGE(PG8_SB(0, 1), b2 + hstepB, voffB); PG8_STAGE(PG8_SA(0, 0), a2, voffA);
;             PG8_WAIT_V(8); PG8_WAIT_L(0); PG8_BAR; if (whole) { PG8_MMA(1, 0, At, B0); PG8_MMA(1, 1, At, B1); } PG8_BAR; PG8_SCHED;
.LBB0_744:
	s_ashr_i32 s59, s58, 31
	s_lshl_b64 s[14:15], s[58:59], 19
	s_add_u32 s60, s30, s14
	s_addc_u32 s61, s31, s15
	s_and_b64 s[14:15], s[4:5], exec
	s_cselect_b32 s1, s61, s7
	s_cselect_b32 s9, s60, s6
	s_ashr_i32 s57, s56, 31
	s_lshl_b64 s[14:15], s[56:57], 19
	s_add_u32 s62, s8, s14
	s_addc_u32 s63, s78, s15
	s_and_b64 s[14:15], s[4:5], exec
	s_cselect_b32 s14, s63, s77
	s_cselect_b32 s15, s62, s76
	s_add_u32 s66, s6, 0x40080
	s_addc_u32 s67, s7, 0
	s_add_u32 s16, s76, 0x100
	s_addc_u32 s17, s77, 0
	s_mov_b32 s18, -2
	s_waitcnt lgkmcnt(0)
	ds_read_b128 v[144:147], v165
	ds_read_b128 v[148:151], v165 offset:1024
	ds_read_b128 v[152:155], v165 offset:2048
	ds_read_b128 v[156:159], v165 offset:3072
	ds_read_b128 v[170:173], v166
	ds_read_b128 v[174:177], v166 offset:1024
	ds_read_b128 v[178:181], v166 offset:2048
	ds_read_b128 v[182:185], v166 offset:3072
	s_add_u32 s6, s66, 0xfffc0080
	s_addc_u32 s7, s67, -1
	s_cmp_eq_u32 s18, 12
	s_cselect_b32 s77, s1, s7
	s_cselect_b32 s76, s9, s6
	s_cselect_b32 s7, s14, s17
	s_cselect_b32 s6, s15, s16
	v_lshl_add_u64 v[160:161], s[66:67], 0, v[136:137]
	s_add_i32 m0, s65, 0xc000
	ds_read_b128 v[186:189], v167
	ds_read_b128 v[190:193], v167 offset:1024
	ds_read_b128 v[194:197], v167 offset:2048
	ds_read_b128 v[198:201], v167 offset:3072
	ds_read_b128 v[202:205], v167 offset:4096
	ds_read_b128 v[206:209], v167 offset:5120
	ds_read_b128 v[210:213], v167 offset:6144
	ds_read_b128 v[214:217], v167 offset:7168
	global_load_lds_dwordx4 v[160:161], off
	v_lshl_add_u64 v[160:161], s[66:67], 0, v[138:139]
	s_add_i32 m0, s65, 0xe000
	s_nop 0
	global_load_lds_dwordx4 v[160:161], off
	s_waitcnt vmcnt(16)
	s_waitcnt lgkmcnt(0)
	s_barrier
	s_setprio 1
	s_waitcnt lgkmcnt(0)
	v_mfma_f32_16x16x32_bf16 v[124:127], v[144:147], v[186:189], 0
	v_mfma_f32_16x16x32_bf16 v[120:123], v[152:155], v[186:189], 0
	v_mfma_f32_16x16x32_bf16 v[108:111], v[144:147], v[194:197], 0
	v_mfma_f32_16x16x32_bf16 v[104:107], v[152:155], v[194:197], 0
	v_mfma_f32_16x16x32_bf16 v[92:95], v[144:147], v[202:205], 0
	v_mfma_f32_16x16x32_bf16 v[88:91], v[152:155], v[202:205], 0
	v_mfma_f32_16x16x32_bf16 v[76:79], v[144:147], v[210:213], 0
	v_mfma_f32_16x16x32_bf16 v[72:75], v[152:155], v[210:213], 0
	v_mfma_f32_16x16x32_bf16 v[124:127], v[148:151], v[190:193], v[124:127]
	v_mfma_f32_16x16x32_bf16 v[120:123], v[156:159], v[190:193], v[120:123]
	v_mfma_f32_16x16x32_bf16 v[108:111], v[148:151], v[198:201], v[108:111]
	v_mfma_f32_16x16x32_bf16 v[104:107], v[156:159], v[198:201], v[104:107]
	v_mfma_f32_16x16x32_bf16 v[92:95], v[148:151], v[206:209], v[92:95]
	v_mfma_f32_16x16x32_bf16 v[88:91], v[156:159], v[206:209], v[88:91]
	v_mfma_f32_16x16x32_bf16 v[76:79], v[148:151], v[214:217], v[76:79]
	v_mfma_f32_16x16x32_bf16 v[72:75], v[156:159], v[214:217], v[72:75]
	s_setprio 0
	s_setprio 1
	v_mfma_f32_16x16x32_bf16 v[116:119], v[170:173], v[186:189], 0
	v_mfma_f32_16x16x32_bf16 v[112:115], v[178:181], v[186:189], 0
	v_mfma_f32_16x16x32_bf16 v[100:103], v[170:173], v[194:197], 0
	v_mfma_f32_16x16x32_bf16 v[96:99], v[178:181], v[194:197], 0
	v_mfma_f32_16x16x32_bf16 v[84:87], v[170:173], v[202:205], 0
	v_mfma_f32_16x16x32_bf16 v[80:83], v[178:181], v[202:205], 0
	v_mfma_f32_16x16x32_bf16 v[68:71], v[170:173], v[210:213], 0
	v_mfma_f32_16x16x32_bf16 v[64:67], v[178:181], v[210:213], 0
	v_mfma_f32_16x16x32_bf16 v[116:119], v[174:177], v[190:193], v[116:119]
	v_mfma_f32_16x16x32_bf16 v[112:115], v[182:185], v[190:193], v[112:115]
	v_mfma_f32_16x16x32_bf16 v[100:103], v[174:177], v[198:201], v[100:103]
	v_mfma_f32_16x16x32_bf16 v[96:99], v[182:185], v[198:201], v[96:99]
	v_mfma_f32_16x16x32_bf16 v[84:87], v[174:177], v[206:209], v[84:87]
	v_mfma_f32_16x16x32_bf16 v[80:83], v[182:185], v[206:209], v[80:83]
	v_mfma_f32_16x16x32_bf16 v[68:71], v[174:177], v[214:217], v[68:71]
	v_mfma_f32_16x16x32_bf16 v[64:67], v[182:185], v[214:217], v[64:67]
	s_setprio 0
	s_barrier
	s_add_i32 s19, s91, s79
	v_lshl_add_u64 v[160:161], s[6:7], 0, v[130:131]
	s_mov_b32 m0, s19
	ds_read_b128 v[186:189], v167 offset:16384
	ds_read_b128 v[190:193], v167 offset:17408
	ds_read_b128 v[194:197], v167 offset:18432
	ds_read_b128 v[198:201], v167 offset:19456
	ds_read_b128 v[202:205], v167 offset:20480
	ds_read_b128 v[206:209], v167 offset:21504
	ds_read_b128 v[210:213], v167 offset:22528
	ds_read_b128 v[214:217], v167 offset:23552
	global_load_lds_dwordx4 v[160:161], off
	s_add_i32 m0, s19, 0x2000
	s_add_u32 s20, s6, 0x40000
	v_lshl_add_u64 v[218:219], s[6:7], 0, v[134:135]
	s_addc_u32 s21, s7, 0
	s_add_i32 s19, s92, s79
	global_load_lds_dwordx4 v[218:219], off
	v_lshl_add_u64 v[220:221], s[20:21], 0, v[130:131]
	s_mov_b32 m0, s19
	v_lshl_add_u64 v[222:223], s[76:77], 0, v[132:133]
	global_load_lds_dwordx4 v[220:221], off
	v_lshl_add_u64 v[220:221], s[20:21], 0, v[134:135]
	s_add_i32 m0, s19, 0x2000
	s_nop 0
	global_load_lds_dwordx4 v[220:221], off
	v_lshl_add_u64 v[220:221], s[76:77], 0, v[128:129]
	s_mov_b32 m0, s65
	s_nop 0
	global_load_lds_dwordx4 v[220:221], off
	s_mov_b32 m0, s80
	s_nop 0
	global_load_lds_dwordx4 v[222:223], off
	s_waitcnt vmcnt(16)
	s_waitcnt lgkmcnt(0)
	s_barrier
; #define PG8_STAGE(bufoff, gbase, voff) do { _Pragma("unroll") for (int _i = 0; _i < 2; ++_i) \
;         __builtin_amdgcn_global_load_lds((const unsigned*)((const char*)(gbase) + (voff)[_i]), (PG8_LAS unsigned*)(lds + (bufoff) + ldsw + _i * 8192), 16, 0, 0); } while (0)
; #define PG8_LDA(dst, b, h) do { _Pragma("unroll") for (int m = 0; m < 4; ++m) _Pragma("unroll") for (int k = 0; k < 2; ++k) dst[m][k] = *(const PG8_LAS bf16x8*)(lds + PG8_SA(b, h) + aoff + m * 2048 + k * 1024); } while (0)
; #define PG8_LDB(dst, b, h) do { _Pragma("unroll") for (int n = 0; n < 2; ++n) _Pragma("unroll") for (int k = 0; k < 2; ++k) dst[n][k] = *(const PG8_LAS bf16x8*)(lds + PG8_SB(b, h) + boff + n * 2048 + k * 1024); } while (0)
; #define PG8_MMA(ai, bj, At, Bt) do { __builtin_amdgcn_s_setprio(1); _Pragma("unroll") for (int m = 0; m < 4; ++m) _Pragma("unroll") for (int n = 0; n < 2; ++n) _Pragma("unroll") for (int k = 0; k < 2; ++k) \
;         acc[ai][bj][m][n] = __builtin_amdgcn_mfma_f32_16x16x32_bf16(Bt[n][k], At[m][k], acc[ai][bj][m][n], 0, 0, 0); __builtin_amdgcn_s_setprio(0); } while (0)
; #define PG8_WAIT_V(n) asm volatile("s_waitcnt vmcnt(" #n ")" ::: "memory")
; #define PG8_WAIT_L(n) asm volatile("s_waitcnt lgkmcnt(" #n ")" ::: "memory")
; #define PG8_BAR __builtin_amdgcn_s_barrier()
; #define PG8_SCHED __builtin_amdgcn_sched_barrier(0)
; template <class Epi, class Sched, bool ALIGN_EPI = false, bool SP2 = false>
; __device__ __forceinline__ void gemm_phase(PG8_LAS unsigned char* lds, const Gemm g, const Sched& S, const Epi& E) {
;     ...
;             PG8_WAIT_V(8); PG8_WAIT_L(0); PG8_BAR; PG8_MMA(0, 0, At, B0); if (whole) PG8_MMA(0, 1, At, B1); PG8_BAR; PG8_SCHED;
;             PG8_LDA(At, 0, 1); PG8_STAGE(PG8_SB(0, 0), b2, voffB); PG8_STAGE(PG8_SB(0, 1), b2 + hstepB, voffB); PG8_STAGE(PG8_SA(0, 0), a2, voffA);
;             PG8_WAIT_V(8); PG8_WAIT_L(0); PG8_BAR; if (whole) { PG8_MMA(1, 0, At, B0); PG8_MMA(1, 1, At, B1); } PG8_BAR; PG8_SCHED;
;             PG8_LDB(B0, 1, 0); PG8_LDB(B1, 1, 1); PG8_SCHED; PG8_LDA(At, 1, 0); PG8_STAGE(PG8_SA(0, 1), a2 + hstepA, voffA);
;             PG8_WAIT_V(8); PG8_WAIT_L(0); PG8_BAR; PG8_MMA(0, 0, At, B0); if (whole) PG8_MMA(0, 1, At, B1); PG8_BAR; PG8_SCHED;
	s_setprio 1
	s_waitcnt lgkmcnt(0)
	v_mfma_f32_16x16x32_bf16 v[60:63], v[144:147], v[186:189], 0
	v_mfma_f32_16x16x32_bf16 v[56:59], v[152:155], v[186:189], 0
	v_mfma_f32_16x16x32_bf16 v[44:47], v[144:147], v[194:197], 0
	v_mfma_f32_16x16x32_bf16 v[40:43], v[152:155], v[194:197], 0
	v_mfma_f32_16x16x32_bf16 v[28:31], v[144:147], v[202:205], 0
	v_mfma_f32_16x16x32_bf16 v[24:27], v[152:155], v[202:205], 0
	v_mfma_f32_16x16x32_bf16 v[12:15], v[144:147], v[210:213], 0
	v_mfma_f32_16x16x32_bf16 v[8:11], v[152:155], v[210:213], 0
	v_mfma_f32_16x16x32_bf16 v[60:63], v[148:151], v[190:193], v[60:63]
	v_mfma_f32_16x16x32_bf16 v[56:59], v[156:159], v[190:193], v[56:59]
	v_mfma_f32_16x16x32_bf16 v[44:47], v[148:151], v[198:201], v[44:47]
	v_mfma_f32_16x16x32_bf16 v[40:43], v[156:159], v[198:201], v[40:43]
	v_mfma_f32_16x16x32_bf16 v[28:31], v[148:151], v[206:209], v[28:31]
	v_mfma_f32_16x16x32_bf16 v[24:27], v[156:159], v[206:209], v[24:27]
	v_mfma_f32_16x16x32_bf16 v[12:15], v[148:151], v[214:217], v[12:15]
	v_mfma_f32_16x16x32_bf16 v[8:11], v[156:159], v[214:217], v[8:11]
	s_setprio 0
	s_setprio 1
	v_mfma_f32_16x16x32_bf16 v[52:55], v[170:173], v[186:189], 0
	v_mfma_f32_16x16x32_bf16 v[48:51], v[178:181], v[186:189], 0
	v_mfma_f32_16x16x32_bf16 v[36:39], v[170:173], v[194:197], 0
	v_mfma_f32_16x16x32_bf16 v[32:35], v[178:181], v[194:197], 0
	v_mfma_f32_16x16x32_bf16 v[20:23], v[170:173], v[202:205], 0
	v_mfma_f32_16x16x32_bf16 v[16:19], v[178:181], v[202:205], 0
	v_mfma_f32_16x16x32_bf16 v[4:7], v[170:173], v[210:213], 0
	v_mfma_f32_16x16x32_bf16 v[0:3], v[178:181], v[210:213], 0
	v_mfma_f32_16x16x32_bf16 v[52:55], v[174:177], v[190:193], v[52:55]
	v_mfma_f32_16x16x32_bf16 v[48:51], v[182:185], v[190:193], v[48:51]
	v_mfma_f32_16x16x32_bf16 v[36:39], v[174:177], v[198:201], v[36:39]
	v_mfma_f32_16x16x32_bf16 v[32:35], v[182:185], v[198:201], v[32:35]
	v_mfma_f32_16x16x32_bf16 v[20:23], v[174:177], v[206:209], v[20:23]
	v_mfma_f32_16x16x32_bf16 v[16:19], v[182:185], v[206:209], v[16:19]
	v_mfma_f32_16x16x32_bf16 v[4:7], v[174:177], v[214:217], v[4:7]
	v_mfma_f32_16x16x32_bf16 v[0:3], v[182:185], v[214:217], v[0:3]
	s_setprio 0
	s_barrier
	s_add_i32 s19, 0, 0x18000
	s_add_i32 s24, 0, 0x1c000
	v_add_u32_e32 v156, s19, v163
	v_add_u32_e32 v182, s24, v163
	ds_read_b128 v[144:147], v156
	ds_read_b128 v[148:151], v156 offset:1024
	ds_read_b128 v[152:155], v156 offset:2048
	ds_read_b128 v[156:159], v156 offset:3072
	ds_read_b128 v[170:173], v182
	ds_read_b128 v[174:177], v182 offset:1024
	ds_read_b128 v[178:181], v182 offset:2048
	ds_read_b128 v[182:185], v182 offset:3072
	s_add_u32 s20, s76, 0x40000
	s_addc_u32 s21, s77, 0
	s_mov_b32 m0, s81
	v_lshl_add_u64 v[224:225], s[20:21], 0, v[128:129]
	ds_read_b128 v[186:189], v167 offset:32768
	ds_read_b128 v[190:193], v167 offset:33792
	ds_read_b128 v[194:197], v167 offset:34816
	ds_read_b128 v[198:201], v167 offset:35840
	ds_read_b128 v[202:205], v167 offset:36864
	ds_read_b128 v[206:209], v167 offset:37888
	ds_read_b128 v[210:213], v167 offset:38912
	ds_read_b128 v[214:217], v167 offset:39936
	global_load_lds_dwordx4 v[224:225], off
	v_lshl_add_u64 v[224:225], s[20:21], 0, v[132:133]
	s_mov_b32 m0, s82
	s_nop 0
	global_load_lds_dwordx4 v[224:225], off
	s_waitcnt vmcnt(8)
	s_waitcnt lgkmcnt(0)
	s_barrier
	s_setprio 1
	s_waitcnt lgkmcnt(0)
	v_mfma_f32_16x16x32_bf16 v[124:127], v[144:147], v[186:189], v[124:127]
	v_mfma_f32_16x16x32_bf16 v[120:123], v[152:155], v[186:189], v[120:123]
	v_mfma_f32_16x16x32_bf16 v[108:111], v[144:147], v[194:197], v[108:111]
	v_mfma_f32_16x16x32_bf16 v[104:107], v[152:155], v[194:197], v[104:107]
	v_mfma_f32_16x16x32_bf16 v[92:95], v[144:147], v[202:205], v[92:95]
	v_mfma_f32_16x16x32_bf16 v[88:91], v[152:155], v[202:205], v[88:91]
	v_mfma_f32_16x16x32_bf16 v[76:79], v[144:147], v[210:213], v[76:79]
	v_mfma_f32_16x16x32_bf16 v[72:75], v[152:155], v[210:213], v[72:75]
	v_mfma_f32_16x16x32_bf16 v[124:127], v[148:151], v[190:193], v[124:127]
	v_mfma_f32_16x16x32_bf16 v[120:123], v[156:159], v[190:193], v[120:123]
	v_mfma_f32_16x16x32_bf16 v[108:111], v[148:151], v[198:201], v[108:111]
	v_mfma_f32_16x16x32_bf16 v[104:107], v[156:159], v[198:201], v[104:107]
	v_mfma_f32_16x16x32_bf16 v[92:95], v[148:151], v[206:209], v[92:95]
	v_mfma_f32_16x16x32_bf16 v[88:91], v[156:159], v[206:209], v[88:91]
	v_mfma_f32_16x16x32_bf16 v[76:79], v[148:151], v[214:217], v[76:79]
	v_mfma_f32_16x16x32_bf16 v[72:75], v[156:159], v[214:217], v[72:75]
	s_setprio 0
	s_setprio 1
	v_mfma_f32_16x16x32_bf16 v[116:119], v[170:173], v[186:189], v[116:119]
	v_mfma_f32_16x16x32_bf16 v[112:115], v[178:181], v[186:189], v[112:115]
	v_mfma_f32_16x16x32_bf16 v[100:103], v[170:173], v[194:197], v[100:103]
	v_mfma_f32_16x16x32_bf16 v[96:99], v[178:181], v[194:197], v[96:99]
	v_mfma_f32_16x16x32_bf16 v[84:87], v[170:173], v[202:205], v[84:87]
	v_mfma_f32_16x16x32_bf16 v[80:83], v[178:181], v[202:205], v[80:83]
	v_mfma_f32_16x16x32_bf16 v[68:71], v[170:173], v[210:213], v[68:71]
	v_mfma_f32_16x16x32_bf16 v[64:67], v[178:181], v[210:213], v[64:67]
	v_mfma_f32_16x16x32_bf16 v[116:119], v[174:177], v[190:193], v[116:119]
	v_mfma_f32_16x16x32_bf16 v[112:115], v[182:185], v[190:193], v[112:115]
	v_mfma_f32_16x16x32_bf16 v[100:103], v[174:177], v[198:201], v[100:103]
	v_mfma_f32_16x16x32_bf16 v[96:99], v[182:185], v[198:201], v[96:99]
	v_mfma_f32_16x16x32_bf16 v[84:87], v[174:177], v[206:209], v[84:87]
	v_mfma_f32_16x16x32_bf16 v[80:83], v[182:185], v[206:209], v[80:83]
	v_mfma_f32_16x16x32_bf16 v[68:71], v[174:177], v[214:217], v[68:71]
	v_mfma_f32_16x16x32_bf16 v[64:67], v[182:185], v[214:217], v[64:67]
	s_setprio 0
	s_barrier
; #define PG8_STAGE(bufoff, gbase, voff) do { _Pragma("unroll") for (int _i = 0; _i < 2; ++_i) \
;         __builtin_amdgcn_global_load_lds((const unsigned*)((const char*)(gbase) + (voff)[_i]), (PG8_LAS unsigned*)(lds + (bufoff) + ldsw + _i * 8192), 16, 0, 0); } while (0)
; #define PG8_LDA(dst, b, h) do { _Pragma("unroll") for (int m = 0; m < 4; ++m) _Pragma("unroll") for (int k = 0; k < 2; ++k) dst[m][k] = *(const PG8_LAS bf16x8*)(lds + PG8_SA(b, h) + aoff + m * 2048 + k * 1024); } while (0)
; #define PG8_LDB(dst, b, h) do { _Pragma("unroll") for (int n = 0; n < 2; ++n) _Pragma("unroll") for (int k = 0; k < 2; ++k) dst[n][k] = *(const PG8_LAS bf16x8*)(lds + PG8_SB(b, h) + boff + n * 2048 + k * 1024); } while (0)
; #define PG8_MMA(ai, bj, At, Bt) do { __builtin_amdgcn_s_setprio(1); _Pragma("unroll") for (int m = 0; m < 4; ++m) _Pragma("unroll") for (int n = 0; n < 2; ++n) _Pragma("unroll") for (int k = 0; k < 2; ++k) \
;         acc[ai][bj][m][n] = __builtin_amdgcn_mfma_f32_16x16x32_bf16(Bt[n][k], At[m][k], acc[ai][bj][m][n], 0, 0, 0); __builtin_amdgcn_s_setprio(0); } while (0)
; #define PG8_WAIT_V(n) asm volatile("s_waitcnt vmcnt(" #n ")" ::: "memory")
; #define PG8_WAIT_L(n) asm volatile("s_waitcnt lgkmcnt(" #n ")" ::: "memory")
; #define PG8_BAR __builtin_amdgcn_s_barrier()
; #define PG8_SCHED __builtin_amdgcn_sched_barrier(0)
; template <class Epi, class Sched, bool ALIGN_EPI = false, bool SP2 = false>
; __device__ __forceinline__ void gemm_phase(PG8_LAS unsigned char* lds, const Gemm g, const Sched& S, const Epi& E) {
;     ...
;             PG8_LDB(B0, 1, 0); PG8_LDB(B1, 1, 1); PG8_SCHED; PG8_LDA(At, 1, 0); PG8_STAGE(PG8_SA(0, 1), a2 + hstepA, voffA);
;             PG8_WAIT_V(8); PG8_WAIT_L(0); PG8_BAR; PG8_MMA(0, 0, At, B0); if (whole) PG8_MMA(0, 1, At, B1); PG8_BAR; PG8_SCHED;
;             PG8_LDA(At, 1, 1); PG8_STAGE(PG8_SB(1, 0), b3, voffB); PG8_STAGE(PG8_SB(1, 1), b3 + hstepB, voffB); PG8_STAGE(PG8_SA(1, 0), a3, voffA);
;             PG8_WAIT_V(8); PG8_WAIT_L(0); PG8_BAR; if (whole) { PG8_MMA(1, 0, At, B0); PG8_MMA(1, 1, At, B1); } PG8_BAR; PG8_SCHED;
	s_add_i32 s19, s19, s79
	v_lshl_add_u64 v[160:161], v[160:161], 0, s[52:53]
	s_mov_b32 m0, s19
	ds_read_b128 v[186:189], v167 offset:49152
	ds_read_b128 v[190:193], v167 offset:50176
	ds_read_b128 v[194:197], v167 offset:51200
	ds_read_b128 v[198:201], v167 offset:52224
	ds_read_b128 v[202:205], v167 offset:53248
	ds_read_b128 v[206:209], v167 offset:54272
	ds_read_b128 v[210:213], v167 offset:55296
	ds_read_b128 v[214:217], v167 offset:56320
	global_load_lds_dwordx4 v[160:161], off
	s_add_i32 m0, s19, 0x2000
	s_add_u32 s6, s6, 0x40080
	v_lshl_add_u64 v[160:161], v[218:219], 0, s[52:53]
	s_addc_u32 s7, s7, 0
	s_add_i32 s19, s24, s79
	global_load_lds_dwordx4 v[160:161], off
	v_lshl_add_u64 v[160:161], s[6:7], 0, v[130:131]
	s_mov_b32 m0, s19
	s_nop 0
	global_load_lds_dwordx4 v[160:161], off
	v_lshl_add_u64 v[160:161], s[6:7], 0, v[134:135]
	s_add_i32 m0, s19, 0x2000
	s_nop 0
	global_load_lds_dwordx4 v[160:161], off
	v_lshl_add_u64 v[160:161], v[220:221], 0, s[52:53]
	s_mov_b32 m0, s84
	s_nop 0
	global_load_lds_dwordx4 v[160:161], off
	v_lshl_add_u64 v[160:161], v[222:223], 0, s[52:53]
	s_mov_b32 m0, s85
	s_nop 0
	global_load_lds_dwordx4 v[160:161], off
	s_waitcnt vmcnt(8)
	s_waitcnt lgkmcnt(0)
	s_barrier
	s_setprio 1
	s_waitcnt lgkmcnt(0)
	v_mfma_f32_16x16x32_bf16 v[60:63], v[144:147], v[186:189], v[60:63]
	v_mfma_f32_16x16x32_bf16 v[56:59], v[152:155], v[186:189], v[56:59]
	v_mfma_f32_16x16x32_bf16 v[44:47], v[144:147], v[194:197], v[44:47]
	v_mfma_f32_16x16x32_bf16 v[40:43], v[152:155], v[194:197], v[40:43]
	v_mfma_f32_16x16x32_bf16 v[28:31], v[144:147], v[202:205], v[28:31]
	v_mfma_f32_16x16x32_bf16 v[24:27], v[152:155], v[202:205], v[24:27]
	v_mfma_f32_16x16x32_bf16 v[12:15], v[144:147], v[210:213], v[12:15]
	v_mfma_f32_16x16x32_bf16 v[8:11], v[152:155], v[210:213], v[8:11]
	v_mfma_f32_16x16x32_bf16 v[60:63], v[148:151], v[190:193], v[60:63]
	v_mfma_f32_16x16x32_bf16 v[56:59], v[156:159], v[190:193], v[56:59]
	v_mfma_f32_16x16x32_bf16 v[44:47], v[148:151], v[198:201], v[44:47]
	v_mfma_f32_16x16x32_bf16 v[40:43], v[156:159], v[198:201], v[40:43]
	v_mfma_f32_16x16x32_bf16 v[28:31], v[148:151], v[206:209], v[28:31]
	v_mfma_f32_16x16x32_bf16 v[24:27], v[156:159], v[206:209], v[24:27]
	v_mfma_f32_16x16x32_bf16 v[12:15], v[148:151], v[214:217], v[12:15]
	v_mfma_f32_16x16x32_bf16 v[8:11], v[156:159], v[214:217], v[8:11]
	s_setprio 0
	s_setprio 1
	v_mfma_f32_16x16x32_bf16 v[52:55], v[170:173], v[186:189], v[52:55]
	v_mfma_f32_16x16x32_bf16 v[48:51], v[178:181], v[186:189], v[48:51]
	v_mfma_f32_16x16x32_bf16 v[36:39], v[170:173], v[194:197], v[36:39]
	v_mfma_f32_16x16x32_bf16 v[32:35], v[178:181], v[194:197], v[32:35]
	v_mfma_f32_16x16x32_bf16 v[20:23], v[170:173], v[202:205], v[20:23]
	v_mfma_f32_16x16x32_bf16 v[16:19], v[178:181], v[202:205], v[16:19]
	v_mfma_f32_16x16x32_bf16 v[4:7], v[170:173], v[210:213], v[4:7]
	v_mfma_f32_16x16x32_bf16 v[0:3], v[178:181], v[210:213], v[0:3]
	v_mfma_f32_16x16x32_bf16 v[52:55], v[174:177], v[190:193], v[52:55]
	v_mfma_f32_16x16x32_bf16 v[48:51], v[182:185], v[190:193], v[48:51]
	v_mfma_f32_16x16x32_bf16 v[36:39], v[174:177], v[198:201], v[36:39]
	v_mfma_f32_16x16x32_bf16 v[32:35], v[182:185], v[198:201], v[32:35]
	v_mfma_f32_16x16x32_bf16 v[20:23], v[174:177], v[206:209], v[20:23]
	v_mfma_f32_16x16x32_bf16 v[16:19], v[182:185], v[206:209], v[16:19]
	v_mfma_f32_16x16x32_bf16 v[4:7], v[174:177], v[214:217], v[4:7]
	v_mfma_f32_16x16x32_bf16 v[0:3], v[182:185], v[214:217], v[0:3]
	s_setprio 0
	s_barrier
	s_add_i32 s18, s18, 2
	s_add_u32 s66, s66, 0x100
	s_addc_u32 s67, s67, 0
	s_add_u32 s16, s16, 0x100
	s_addc_u32 s17, s17, 0
	s_cmp_gt_u32 s18, 13
	s_cbranch_scc0 .LBB0_745
	s_branch .Lpeel_exit_in1

;     __device__ __forceinline__ void operator()(const f32x4 (&acc)[2][2][4][2], const Unit& u, int wr, int wc, int fr, int fq) const {
;     ...
;         const int row0 = u.pm * BM + wr * 64 + fr + (u.qa > 0 ? HALF : 0), col0 = u.pn * BM + wc * 32 + 8 * fq + (u.qb > 0 ? HALF : 0);
;         float rsv[2][4];
; #pragma unroll
;         for (int ai = 0; ai < 2; ++ai)
; #pragma unroll
;             for (int m = 0; m < 4; ++m) rsv[ai][m] = ss[row0 + ai * HALF + m * 16];
; #pragma unroll
;         for (int ai = 0; ai < 2; ++ai)
; #pragma unroll
;             for (int m = 0; m < 4; ++m) rsv[ai][m] = __builtin_amdgcn_rsqf(rsv[ai][m] * (1.0f / 1024.0f) + RMS_EPS);
; #pragma unroll
;         for (int ai = 0; ai < 2; ++ai)
; #pragma unroll
;             for (int m = 0; m < 4; ++m) {
;                 if (ai == 1 && !whole) continue;
;                 const int row = row0 + ai * HALF + m * 16;
;                 const float rs = rsv[ai][m];
;                 float s1 = 0.f, s2 = 0.f;
;                 bf16_t* rowp = BLK ? O + ((size_t)u.pm * (ldc >> 6) + (size_t)(col0 >> 6)) * 16384 + (size_t)((col0 >> 5) & 1) * 8192 + (size_t)(row - u.pm * BM) * 32 + (col0 & 31) : O + (size_t)row * ldc + col0;
; #pragma unroll
;                 for (int bj = 0; bj < 2; ++bj) {
;                     if (bj == 1 && !whole) continue;
;                     f32x4 v0 = acc[ai][bj][m][0] * rs, v1 = acc[ai][bj][m][1] * rs;
;                     if (ACT == 1) {
; #pragma unroll
;                         for (int j = 0; j < 4; ++j) { const float a = fmaxf(v0[j], 0.f), b = fmaxf(v1[j], 0.f); v0[j] = a * a; v1[j] = b * b; }
;                     }
;                     u32x4 w; w.x = cvt_pk_bf16(v0[0], v0[1]); w.y = cvt_pk_bf16(v0[2], v0[3]); w.z = cvt_pk_bf16(v1[0], v1[1]); w.w = cvt_pk_bf16(v1[2], v1[3]);
;                     *(u32x4*)(rowp + (BLK ? bj * 2 * 16384 : bj * HALF)) = w;
;                     if (STATS) { s1 += (v0[0] + v0[1]) + (v0[2] + v0[3]) + (v1[0] + v1[1]) + (v1[2] + v1[3]);
;                         s2 += (v0[0] * v0[0] + v0[1] * v0[1]) + (v0[2] * v0[2] + v0[3] * v0[3]) + (v1[0] * v1[0] + v1[1] * v1[1]) + (v1[2] * v1[2] + v1[3] * v1[3]); }
;                 }
;                 if (STATS && u.pn >= stat_pn0) {
;                     s1 += __shfl_xor(s1, 16); s1 += __shfl_xor(s1, 32); s2 += __shfl_xor(s2, 16); s2 += __shfl_xor(s2, 32);
.LBB0_748:
	v_lshl_add_u32 v160, s64, 8, v162
	v_ashrrev_i32_e32 v161, 31, v160
	v_or_b32_e32 v158, 16, v160
	v_lshl_add_u64 v[144:145], v[160:161], 2, s[38:39]
	v_or_b32_e32 v156, 32, v160
	v_or_b32_e32 v154, 48, v160
	v_ashrrev_i32_e32 v159, 31, v158
	global_load_dword v177, v[144:145], off
	v_ashrrev_i32_e32 v157, 31, v156
	v_ashrrev_i32_e32 v155, 31, v154
	v_add_u32_e32 v152, 0x80, v160
	v_add_u32_e32 v150, 0x90, v160
	v_add_u32_e32 v146, 0xa0, v160
	v_add_u32_e32 v144, 0xb0, v160
	v_lshl_add_u64 v[148:149], v[158:159], 2, s[38:39]
	v_lshl_add_u64 v[170:171], v[156:157], 2, s[38:39]
	v_lshl_add_u64 v[172:173], v[154:155], 2, s[38:39]
	v_ashrrev_i32_e32 v153, 31, v152
	v_ashrrev_i32_e32 v151, 31, v150
	v_ashrrev_i32_e32 v147, 31, v146
	v_ashrrev_i32_e32 v145, 31, v144
	v_lshl_add_u64 v[178:179], v[152:153], 2, s[38:39]
	v_lshl_add_u64 v[180:181], v[150:151], 2, s[38:39]
	v_lshl_add_u64 v[182:183], v[146:147], 2, s[38:39]
	v_lshl_add_u64 v[184:185], v[144:145], 2, s[38:39]
	global_load_dword v176, v[148:149], off
	global_load_dword v175, v[170:171], off
	global_load_dword v174, v[172:173], off
	s_nop 0
	global_load_dword v173, v[178:179], off
	global_load_dword v172, v[180:181], off
	global_load_dword v171, v[182:183], off
	global_load_dword v170, v[184:185], off
	v_lshl_or_b32 v148, s0, 8, v164
	v_mov_b64_e32 v[178:179], s[34:35]
	s_cmp_gt_i32 s0, 3
	v_ashrrev_i32_e32 v149, 31, v148
	v_mad_i64_i32 v[178:179], s[6:7], v160, s93, v[178:179]
	s_cselect_b64 s[6:7], -1, 0
	v_lshl_add_u64 v[182:183], v[148:149], 1, v[178:179]
	s_cmp_lt_i32 s0, 4
	s_waitcnt vmcnt(0)
	v_fmamk_f32 v177, v177, 0x3a800000, v168
	v_rsq_f32_e32 v180, v177
	s_nop 0
	v_pk_mul_f32 v[126:127], v[126:127], v[180:181] op_sel_hi:[1,0]
	v_pk_mul_f32 v[124:125], v[124:125], v[180:181] op_sel_hi:[1,0]
	v_pk_mul_f32 v[122:123], v[122:123], v[180:181] op_sel_hi:[1,0]
	v_pk_mul_f32 v[120:121], v[120:121], v[180:181] op_sel_hi:[1,0]
	v_pk_mul_f32 v[118:119], v[118:119], v[180:181] op_sel_hi:[1,0]
	v_pk_mul_f32 v[116:117], v[116:117], v[180:181] op_sel_hi:[1,0]
	v_pk_mul_f32 v[114:115], v[114:115], v[180:181] op_sel_hi:[1,0]
	v_pk_mul_f32 v[112:113], v[112:113], v[180:181] op_sel_hi:[1,0]
	v_cvt_pk_bf16_f32 v178, v124, v125
	v_cvt_pk_bf16_f32 v179, v126, v127
	v_cvt_pk_bf16_f32 v180, v120, v121
	v_cvt_pk_bf16_f32 v181, v122, v123
	global_store_dwordx4 v[182:183], v[178:181], off sc1
	s_nop 1
	v_cvt_pk_bf16_f32 v178, v116, v117
	v_cvt_pk_bf16_f32 v179, v118, v119
	v_cvt_pk_bf16_f32 v180, v112, v113
	v_cvt_pk_bf16_f32 v181, v114, v115
	global_store_dwordx4 v[182:183], v[178:181], off offset:256 sc1
	s_cbranch_scc1 .LBB0_752
	s_nop 0
	v_mul_f32_e32 v178, v125, v125
	v_mul_f32_e32 v179, v127, v127
	v_fmac_f32_e32 v178, v124, v124
	v_fmac_f32_e32 v179, v126, v126
	v_add_f32_e32 v178, v178, v179
	v_mul_f32_e32 v179, v121, v121
	v_mul_f32_e32 v177, v123, v123
	v_fmac_f32_e32 v179, v120, v120
	v_fmac_f32_e32 v177, v122, v122
	v_add_f32_e32 v178, v179, v178
	v_add_f32_e32 v177, v177, v178
	v_mul_f32_e32 v178, v115, v115
	v_mul_f32_e32 v179, v117, v117
	v_mul_f32_e32 v180, v119, v119
	v_fmac_f32_e32 v178, v114, v114
	v_fmac_f32_e32 v179, v116, v116
	v_fmac_f32_e32 v180, v118, v118
	v_add_f32_e32 v114, v114, v115
	v_add_f32_e32 v115, v116, v117
	v_add_f32_e32 v116, v118, v119
	v_add_f32_e32 v179, v179, v180
	v_mul_f32_e32 v180, v113, v113
	v_add_f32_e32 v122, v122, v123
	v_add_f32_e32 v123, v124, v125
	v_add_f32_e32 v124, v126, v127
	v_add_f32_e32 v115, v115, v116
	v_add_f32_e32 v113, v112, v113
	v_add_f32_e32 v123, v123, v124
	v_add_f32_e32 v120, v120, v121
	v_add_f32_e32 v113, v113, v115
	v_and_b32_e32 v115, 64, v169
	v_add_f32_e32 v120, v120, v123
	v_add_f32_e32 v113, v114, v113
	v_xor_b32_e32 v114, 16, v169
	v_add_u32_e32 v115, 64, v115
	v_add_f32_e32 v120, v122, v120
	v_cmp_lt_i32_e32 vcc, v114, v115
	v_add_f32_e32 v120, 0, v120
	v_add_f32_e32 v113, v113, v120
	v_cndmask_b32_e32 v114, v169, v114, vcc
	v_lshlrev_b32_e32 v114, 2, v114
	v_fmac_f32_e32 v180, v112, v112
	ds_bpermute_b32 v116, v114, v113
	v_add_f32_e32 v112, v180, v179
	v_add_f32_e32 v112, v178, v112
	v_add_f32_e32 v117, v177, v112
	ds_bpermute_b32 v114, v114, v117
	s_waitcnt lgkmcnt(1)
	v_add_f32_e32 v112, v113, v116
	v_xor_b32_e32 v113, 32, v169
	v_cmp_lt_i32_e32 vcc, v113, v115
	s_waitcnt lgkmcnt(0)
	v_add_f32_e32 v114, v117, v114
	v_cndmask_b32_e32 v113, v169, v113, vcc
	v_lshlrev_b32_e32 v115, 2, v113
	ds_bpermute_b32 v113, v115, v112
	ds_bpermute_b32 v115, v115, v114
	s_and_saveexec_b64 s[0:1], s[2:3]
	s_cbranch_execz .LBB0_751
	s_waitcnt lgkmcnt(1)
	v_add_f32_e32 v117, v112, v113
	v_lshlrev_b64 v[112:113], 2, v[160:161]
	s_waitcnt lgkmcnt(0)
	v_add_f32_e32 v116, v114, v115
	v_lshl_add_u64 v[114:115], s[46:47], 0, v[112:113]
	v_lshl_add_u64 v[112:113], s[50:51], 0, v[112:113]
	global_atomic_add_f32 v[114:115], v117, off
	global_atomic_add_f32 v[112:113], v116, off

; __device__ __forceinline__ unsigned cvt_pk_bf16(float lo, float hi) { unsigned r; asm volatile("v_cvt_pk_bf16_f32 %0, %1, %2" : "=v"(r) : "v"(lo), "v"(hi)); return r; }
;     __device__ __forceinline__ void operator()(const f32x4 (&acc)[2][2][4][2], const Unit& u, int wr, int wc, int fr, int fq) const {
;     ...
;             for (int m = 0; m < 4; ++m) {
;                 if (ai == 1 && !whole) continue;
;                 const int row = row0 + ai * HALF + m * 16;
;                 const float rs = rsv[ai][m];
;                 float s1 = 0.f, s2 = 0.f;
;                 bf16_t* rowp = BLK ? O + ((size_t)u.pm * (ldc >> 6) + (size_t)(col0 >> 6)) * 16384 + (size_t)((col0 >> 5) & 1) * 8192 + (size_t)(row - u.pm * BM) * 32 + (col0 & 31) : O + (size_t)row * ldc + col0;
; #pragma unroll
;                 for (int bj = 0; bj < 2; ++bj) {
;                     if (bj == 1 && !whole) continue;
;                     f32x4 v0 = acc[ai][bj][m][0] * rs, v1 = acc[ai][bj][m][1] * rs;
;                     if (ACT == 1) {
; #pragma unroll
;                         for (int j = 0; j < 4; ++j) { const float a = fmaxf(v0[j], 0.f), b = fmaxf(v1[j], 0.f); v0[j] = a * a; v1[j] = b * b; }
;                     }
;                     u32x4 w; w.x = cvt_pk_bf16(v0[0], v0[1]); w.y = cvt_pk_bf16(v0[2], v0[3]); w.z = cvt_pk_bf16(v1[0], v1[1]); w.w = cvt_pk_bf16(v1[2], v1[3]);
;                     *(u32x4*)(rowp + (BLK ? bj * 2 * 16384 : bj * HALF)) = w;
;                     if (STATS) { s1 += (v0[0] + v0[1]) + (v0[2] + v0[3]) + (v1[0] + v1[1]) + (v1[2] + v1[3]);
;                         s2 += (v0[0] * v0[0] + v0[1] * v0[1]) + (v0[2] * v0[2] + v0[3] * v0[3]) + (v1[0] * v1[0] + v1[1] * v1[1]) + (v1[2] * v1[2] + v1[3] * v1[3]); }
;                 }
;                 if (STATS && u.pn >= stat_pn0) {
;                     s1 += __shfl_xor(s1, 16); s1 += __shfl_xor(s1, 32); s2 += __shfl_xor(s2, 16); s2 += __shfl_xor(s2, 32);
;                     if (fq == 0) { atomicAdd(st1 + row, s1); atomicAdd(st2 + row, s2); }
;                 }
.LBB0_752:
	v_fmamk_f32 v112, v176, 0x3a800000, v168
	v_rsq_f32_e32 v116, v112
	s_waitcnt lgkmcnt(1)
	v_mov_b64_e32 v[112:113], s[34:35]
	v_mad_i64_i32 v[112:113], s[0:1], v158, s93, v[112:113]
	v_pk_mul_f32 v[110:111], v[110:111], v[116:117] op_sel_hi:[1,0]
	v_pk_mul_f32 v[108:109], v[108:109], v[116:117] op_sel_hi:[1,0]
	v_pk_mul_f32 v[106:107], v[106:107], v[116:117] op_sel_hi:[1,0]
	v_pk_mul_f32 v[104:105], v[104:105], v[116:117] op_sel_hi:[1,0]
	v_pk_mul_f32 v[102:103], v[102:103], v[116:117] op_sel_hi:[1,0]
	v_pk_mul_f32 v[100:101], v[100:101], v[116:117] op_sel_hi:[1,0]
	v_pk_mul_f32 v[98:99], v[98:99], v[116:117] op_sel_hi:[1,0]
	v_pk_mul_f32 v[96:97], v[96:97], v[116:117] op_sel_hi:[1,0]
	v_cndmask_b32_e64 v116, 0, 1, s[6:7]
	v_lshl_add_u64 v[118:119], v[148:149], 1, v[112:113]
	v_cvt_pk_bf16_f32 v112, v108, v109
	v_cvt_pk_bf16_f32 v113, v110, v111
	v_cvt_pk_bf16_f32 v114, v104, v105
	s_waitcnt lgkmcnt(0)
	v_cvt_pk_bf16_f32 v115, v106, v107
	v_cmp_ne_u32_e64 s[0:1], 1, v116
	s_andn2_b64 vcc, exec, s[6:7]
	global_store_dwordx4 v[118:119], v[112:115], off sc1
	s_nop 1
	v_cvt_pk_bf16_f32 v112, v100, v101
	v_cvt_pk_bf16_f32 v113, v102, v103
	v_cvt_pk_bf16_f32 v114, v96, v97
	v_cvt_pk_bf16_f32 v115, v98, v99
	global_store_dwordx4 v[118:119], v[112:115], off offset:256 sc1
	s_cbranch_vccnz .LBB0_756
	s_nop 0
	v_mul_f32_e32 v113, v109, v109
	v_mul_f32_e32 v114, v111, v111
	v_fmac_f32_e32 v113, v108, v108
	v_fmac_f32_e32 v114, v110, v110
	v_add_f32_e32 v113, v113, v114
	v_mul_f32_e32 v114, v105, v105
	v_mul_f32_e32 v112, v107, v107
	v_fmac_f32_e32 v114, v104, v104
	v_fmac_f32_e32 v112, v106, v106
	v_add_f32_e32 v113, v114, v113
	v_add_f32_e32 v112, v112, v113
	v_mul_f32_e32 v113, v99, v99
	v_mul_f32_e32 v114, v101, v101
	v_mul_f32_e32 v115, v103, v103
	v_fmac_f32_e32 v113, v98, v98
	v_fmac_f32_e32 v114, v100, v100
	v_fmac_f32_e32 v115, v102, v102
	v_add_f32_e32 v98, v98, v99
	v_add_f32_e32 v99, v100, v101
	v_add_f32_e32 v100, v102, v103
	v_add_f32_e32 v114, v114, v115
	v_mul_f32_e32 v115, v97, v97
	v_add_f32_e32 v106, v106, v107
	v_add_f32_e32 v107, v108, v109
	v_add_f32_e32 v108, v110, v111
	v_add_f32_e32 v99, v99, v100
	v_add_f32_e32 v97, v96, v97
	v_add_f32_e32 v107, v107, v108
	v_add_f32_e32 v104, v104, v105
	v_add_f32_e32 v97, v97, v99
	v_and_b32_e32 v99, 64, v169
	v_add_f32_e32 v104, v104, v107
	v_add_f32_e32 v97, v98, v97
	v_xor_b32_e32 v98, 16, v169
	v_add_u32_e32 v99, 64, v99
	v_add_f32_e32 v104, v106, v104
	v_cmp_lt_i32_e32 vcc, v98, v99
	v_add_f32_e32 v104, 0, v104
	v_add_f32_e32 v97, v97, v104
	v_cndmask_b32_e32 v98, v169, v98, vcc
	v_lshlrev_b32_e32 v98, 2, v98
	v_fmac_f32_e32 v115, v96, v96
	ds_bpermute_b32 v100, v98, v97
	v_add_f32_e32 v96, v115, v114
	v_add_f32_e32 v96, v113, v96
	v_add_f32_e32 v101, v112, v96
	ds_bpermute_b32 v98, v98, v101
	s_waitcnt lgkmcnt(1)
	v_add_f32_e32 v96, v97, v100
	v_xor_b32_e32 v97, 32, v169
	v_cmp_lt_i32_e32 vcc, v97, v99
	s_waitcnt lgkmcnt(0)
	v_add_f32_e32 v98, v101, v98
	v_cndmask_b32_e32 v97, v169, v97, vcc
	v_lshlrev_b32_e32 v99, 2, v97
	ds_bpermute_b32 v97, v99, v96
	ds_bpermute_b32 v99, v99, v98
	s_and_saveexec_b64 s[6:7], s[2:3]
	s_cbranch_execz .LBB0_755
	s_waitcnt lgkmcnt(1)
	v_add_f32_e32 v101, v96, v97
	v_lshlrev_b64 v[96:97], 2, v[158:159]
	s_waitcnt lgkmcnt(0)
	v_add_f32_e32 v100, v98, v99
	v_lshl_add_u64 v[98:99], s[46:47], 0, v[96:97]
	v_lshl_add_u64 v[96:97], s[50:51], 0, v[96:97]
	global_atomic_add_f32 v[98:99], v101, off
	global_atomic_add_f32 v[96:97], v100, off

; __device__ __forceinline__ unsigned cvt_pk_bf16(float lo, float hi) { unsigned r; asm volatile("v_cvt_pk_bf16_f32 %0, %1, %2" : "=v"(r) : "v"(lo), "v"(hi)); return r; }
;     __device__ __forceinline__ void operator()(const f32x4 (&acc)[2][2][4][2], const Unit& u, int wr, int wc, int fr, int fq) const {
;     ...
;             for (int m = 0; m < 4; ++m) {
;                 if (ai == 1 && !whole) continue;
;                 const int row = row0 + ai * HALF + m * 16;
;                 const float rs = rsv[ai][m];
;                 float s1 = 0.f, s2 = 0.f;
;                 bf16_t* rowp = BLK ? O + ((size_t)u.pm * (ldc >> 6) + (size_t)(col0 >> 6)) * 16384 + (size_t)((col0 >> 5) & 1) * 8192 + (size_t)(row - u.pm * BM) * 32 + (col0 & 31) : O + (size_t)row * ldc + col0;
; #pragma unroll
;                 for (int bj = 0; bj < 2; ++bj) {
;                     if (bj == 1 && !whole) continue;
;                     f32x4 v0 = acc[ai][bj][m][0] * rs, v1 = acc[ai][bj][m][1] * rs;
;                     if (ACT == 1) {
; #pragma unroll
;                         for (int j = 0; j < 4; ++j) { const float a = fmaxf(v0[j], 0.f), b = fmaxf(v1[j], 0.f); v0[j] = a * a; v1[j] = b * b; }
;                     }
;                     u32x4 w; w.x = cvt_pk_bf16(v0[0], v0[1]); w.y = cvt_pk_bf16(v0[2], v0[3]); w.z = cvt_pk_bf16(v1[0], v1[1]); w.w = cvt_pk_bf16(v1[2], v1[3]);
;                     *(u32x4*)(rowp + (BLK ? bj * 2 * 16384 : bj * HALF)) = w;
;                     if (STATS) { s1 += (v0[0] + v0[1]) + (v0[2] + v0[3]) + (v1[0] + v1[1]) + (v1[2] + v1[3]);
;                         s2 += (v0[0] * v0[0] + v0[1] * v0[1]) + (v0[2] * v0[2] + v0[3] * v0[3]) + (v1[0] * v1[0] + v1[1] * v1[1]) + (v1[2] * v1[2] + v1[3] * v1[3]); }
;                 }
;                 if (STATS && u.pn >= stat_pn0) {
;                     s1 += __shfl_xor(s1, 16); s1 += __shfl_xor(s1, 32); s2 += __shfl_xor(s2, 16); s2 += __shfl_xor(s2, 32);
;                     if (fq == 0) { atomicAdd(st1 + row, s1); atomicAdd(st2 + row, s2); }
;                 }
.LBB0_756:
	v_fmamk_f32 v96, v175, 0x3a800000, v168
	v_rsq_f32_e32 v100, v96
	s_waitcnt lgkmcnt(1)
	v_mov_b64_e32 v[96:97], s[34:35]
	v_mad_i64_i32 v[96:97], s[6:7], v156, s93, v[96:97]
	v_lshl_add_u64 v[102:103], v[148:149], 1, v[96:97]
	v_pk_mul_f32 v[94:95], v[94:95], v[100:101] op_sel_hi:[1,0]
	v_pk_mul_f32 v[92:93], v[92:93], v[100:101] op_sel_hi:[1,0]
	v_pk_mul_f32 v[90:91], v[90:91], v[100:101] op_sel_hi:[1,0]
	v_pk_mul_f32 v[88:89], v[88:89], v[100:101] op_sel_hi:[1,0]
	v_cvt_pk_bf16_f32 v96, v92, v93
	v_cvt_pk_bf16_f32 v97, v94, v95
	v_pk_mul_f32 v[86:87], v[86:87], v[100:101] op_sel_hi:[1,0]
	v_cvt_pk_bf16_f32 v98, v88, v89
	s_waitcnt lgkmcnt(0)
	v_cvt_pk_bf16_f32 v99, v90, v91
	v_pk_mul_f32 v[84:85], v[84:85], v[100:101] op_sel_hi:[1,0]
	v_pk_mul_f32 v[82:83], v[82:83], v[100:101] op_sel_hi:[1,0]
	v_pk_mul_f32 v[80:81], v[80:81], v[100:101] op_sel_hi:[1,0]
	s_and_b64 vcc, exec, s[0:1]
	global_store_dwordx4 v[102:103], v[96:99], off sc1
	s_nop 1
	v_cvt_pk_bf16_f32 v96, v84, v85
	v_cvt_pk_bf16_f32 v97, v86, v87
	v_cvt_pk_bf16_f32 v98, v80, v81
	v_cvt_pk_bf16_f32 v99, v82, v83
	global_store_dwordx4 v[102:103], v[96:99], off offset:256 sc1
	s_cbranch_vccnz .LBB0_760
	s_nop 0
	v_mul_f32_e32 v97, v93, v93
	v_mul_f32_e32 v98, v95, v95
	v_fmac_f32_e32 v97, v92, v92
	v_fmac_f32_e32 v98, v94, v94
	v_add_f32_e32 v97, v97, v98
	v_mul_f32_e32 v98, v89, v89
	v_mul_f32_e32 v96, v91, v91
	v_fmac_f32_e32 v98, v88, v88
	v_fmac_f32_e32 v96, v90, v90
	v_add_f32_e32 v97, v98, v97
	v_add_f32_e32 v96, v96, v97
	v_mul_f32_e32 v97, v83, v83
	v_mul_f32_e32 v98, v85, v85
	v_mul_f32_e32 v99, v87, v87
	v_fmac_f32_e32 v97, v82, v82
	v_fmac_f32_e32 v98, v84, v84
	v_fmac_f32_e32 v99, v86, v86
	v_add_f32_e32 v82, v82, v83
	v_add_f32_e32 v83, v84, v85
	v_add_f32_e32 v84, v86, v87
	v_add_f32_e32 v98, v98, v99
	v_mul_f32_e32 v99, v81, v81
	v_add_f32_e32 v90, v90, v91
	v_add_f32_e32 v91, v92, v93
	v_add_f32_e32 v92, v94, v95
	v_add_f32_e32 v83, v83, v84
	v_add_f32_e32 v81, v80, v81
	v_add_f32_e32 v91, v91, v92
	v_add_f32_e32 v88, v88, v89
	v_add_f32_e32 v81, v81, v83
	v_and_b32_e32 v83, 64, v169
	v_add_f32_e32 v88, v88, v91
	v_add_f32_e32 v81, v82, v81
	v_xor_b32_e32 v82, 16, v169
	v_add_u32_e32 v83, 64, v83
	v_add_f32_e32 v88, v90, v88
	v_cmp_lt_i32_e32 vcc, v82, v83
	v_add_f32_e32 v88, 0, v88
	v_add_f32_e32 v81, v81, v88
	v_cndmask_b32_e32 v82, v169, v82, vcc
	v_lshlrev_b32_e32 v82, 2, v82
	v_fmac_f32_e32 v99, v80, v80
	ds_bpermute_b32 v84, v82, v81
	v_add_f32_e32 v80, v99, v98
	v_add_f32_e32 v80, v97, v80
	v_add_f32_e32 v85, v96, v80
	ds_bpermute_b32 v82, v82, v85
	s_waitcnt lgkmcnt(1)
	v_add_f32_e32 v80, v81, v84
	v_xor_b32_e32 v81, 32, v169
	v_cmp_lt_i32_e32 vcc, v81, v83
	s_waitcnt lgkmcnt(0)
	v_add_f32_e32 v82, v85, v82
	v_cndmask_b32_e32 v81, v169, v81, vcc
	v_lshlrev_b32_e32 v83, 2, v81
	ds_bpermute_b32 v81, v83, v80
	ds_bpermute_b32 v83, v83, v82
	s_and_saveexec_b64 s[6:7], s[2:3]
	s_cbranch_execz .LBB0_759
	s_waitcnt lgkmcnt(1)
	v_add_f32_e32 v85, v80, v81
	v_lshlrev_b64 v[80:81], 2, v[156:157]
	s_waitcnt lgkmcnt(0)
	v_add_f32_e32 v84, v82, v83
	v_lshl_add_u64 v[82:83], s[46:47], 0, v[80:81]
	v_lshl_add_u64 v[80:81], s[50:51], 0, v[80:81]
	global_atomic_add_f32 v[82:83], v85, off
	global_atomic_add_f32 v[80:81], v84, off

; __device__ __forceinline__ unsigned cvt_pk_bf16(float lo, float hi) { unsigned r; asm volatile("v_cvt_pk_bf16_f32 %0, %1, %2" : "=v"(r) : "v"(lo), "v"(hi)); return r; }
;     __device__ __forceinline__ void operator()(const f32x4 (&acc)[2][2][4][2], const Unit& u, int wr, int wc, int fr, int fq) const {
;     ...
;             for (int m = 0; m < 4; ++m) {
;                 if (ai == 1 && !whole) continue;
;                 const int row = row0 + ai * HALF + m * 16;
;                 const float rs = rsv[ai][m];
;                 float s1 = 0.f, s2 = 0.f;
;                 bf16_t* rowp = BLK ? O + ((size_t)u.pm * (ldc >> 6) + (size_t)(col0 >> 6)) * 16384 + (size_t)((col0 >> 5) & 1) * 8192 + (size_t)(row - u.pm * BM) * 32 + (col0 & 31) : O + (size_t)row * ldc + col0;
; #pragma unroll
;                 for (int bj = 0; bj < 2; ++bj) {
;                     if (bj == 1 && !whole) continue;
;                     f32x4 v0 = acc[ai][bj][m][0] * rs, v1 = acc[ai][bj][m][1] * rs;
;                     if (ACT == 1) {
; #pragma unroll
;                         for (int j = 0; j < 4; ++j) { const float a = fmaxf(v0[j], 0.f), b = fmaxf(v1[j], 0.f); v0[j] = a * a; v1[j] = b * b; }
;                     }
;                     u32x4 w; w.x = cvt_pk_bf16(v0[0], v0[1]); w.y = cvt_pk_bf16(v0[2], v0[3]); w.z = cvt_pk_bf16(v1[0], v1[1]); w.w = cvt_pk_bf16(v1[2], v1[3]);
;                     *(u32x4*)(rowp + (BLK ? bj * 2 * 16384 : bj * HALF)) = w;
;                     if (STATS) { s1 += (v0[0] + v0[1]) + (v0[2] + v0[3]) + (v1[0] + v1[1]) + (v1[2] + v1[3]);
;                         s2 += (v0[0] * v0[0] + v0[1] * v0[1]) + (v0[2] * v0[2] + v0[3] * v0[3]) + (v1[0] * v1[0] + v1[1] * v1[1]) + (v1[2] * v1[2] + v1[3] * v1[3]); }
;                 }
;                 if (STATS && u.pn >= stat_pn0) {
;                     s1 += __shfl_xor(s1, 16); s1 += __shfl_xor(s1, 32); s2 += __shfl_xor(s2, 16); s2 += __shfl_xor(s2, 32);
;                     if (fq == 0) { atomicAdd(st1 + row, s1); atomicAdd(st2 + row, s2); }
;                 }
.LBB0_760:
	v_fmamk_f32 v80, v174, 0x3a800000, v168
	v_rsq_f32_e32 v84, v80
	s_waitcnt lgkmcnt(1)
	v_mov_b64_e32 v[80:81], s[34:35]
	v_mad_i64_i32 v[80:81], s[6:7], v154, s93, v[80:81]
	v_lshl_add_u64 v[86:87], v[148:149], 1, v[80:81]
	v_pk_mul_f32 v[78:79], v[78:79], v[84:85] op_sel_hi:[1,0]
	v_pk_mul_f32 v[76:77], v[76:77], v[84:85] op_sel_hi:[1,0]
	v_pk_mul_f32 v[74:75], v[74:75], v[84:85] op_sel_hi:[1,0]
	v_pk_mul_f32 v[72:73], v[72:73], v[84:85] op_sel_hi:[1,0]
	v_cvt_pk_bf16_f32 v80, v76, v77
	v_cvt_pk_bf16_f32 v81, v78, v79
	v_pk_mul_f32 v[70:71], v[70:71], v[84:85] op_sel_hi:[1,0]
	v_cvt_pk_bf16_f32 v82, v72, v73
	s_waitcnt lgkmcnt(0)
	v_cvt_pk_bf16_f32 v83, v74, v75
	v_pk_mul_f32 v[68:69], v[68:69], v[84:85] op_sel_hi:[1,0]
	v_pk_mul_f32 v[66:67], v[66:67], v[84:85] op_sel_hi:[1,0]
	v_pk_mul_f32 v[64:65], v[64:65], v[84:85] op_sel_hi:[1,0]
	s_and_b64 vcc, exec, s[0:1]
	global_store_dwordx4 v[86:87], v[80:83], off sc1
	s_nop 1
	v_cvt_pk_bf16_f32 v80, v68, v69
	v_cvt_pk_bf16_f32 v81, v70, v71
	v_cvt_pk_bf16_f32 v82, v64, v65
	v_cvt_pk_bf16_f32 v83, v66, v67
	global_store_dwordx4 v[86:87], v[80:83], off offset:256 sc1
	s_cbranch_vccnz .LBB0_764
	s_nop 0
	v_mul_f32_e32 v81, v77, v77
	v_mul_f32_e32 v82, v79, v79
	v_fmac_f32_e32 v81, v76, v76
	v_fmac_f32_e32 v82, v78, v78
	v_add_f32_e32 v81, v81, v82
	v_mul_f32_e32 v82, v73, v73
	v_mul_f32_e32 v80, v75, v75
	v_fmac_f32_e32 v82, v72, v72
	v_fmac_f32_e32 v80, v74, v74
	v_add_f32_e32 v81, v82, v81
	v_add_f32_e32 v80, v80, v81
	v_mul_f32_e32 v81, v67, v67
	v_mul_f32_e32 v82, v69, v69
	v_mul_f32_e32 v83, v71, v71
	v_fmac_f32_e32 v81, v66, v66
	v_fmac_f32_e32 v82, v68, v68
	v_fmac_f32_e32 v83, v70, v70
	v_add_f32_e32 v66, v66, v67
	v_add_f32_e32 v67, v68, v69
	v_add_f32_e32 v68, v70, v71
	v_add_f32_e32 v82, v82, v83
	v_mul_f32_e32 v83, v65, v65
	v_add_f32_e32 v74, v74, v75
	v_add_f32_e32 v75, v76, v77
	v_add_f32_e32 v76, v78, v79
	v_add_f32_e32 v67, v67, v68
	v_add_f32_e32 v65, v64, v65
	v_add_f32_e32 v75, v75, v76
	v_add_f32_e32 v72, v72, v73
	v_add_f32_e32 v65, v65, v67
	v_and_b32_e32 v67, 64, v169
	v_add_f32_e32 v72, v72, v75
	v_add_f32_e32 v65, v66, v65
	v_xor_b32_e32 v66, 16, v169
	v_add_u32_e32 v67, 64, v67
	v_add_f32_e32 v72, v74, v72
	v_cmp_lt_i32_e32 vcc, v66, v67
	v_add_f32_e32 v72, 0, v72
	v_add_f32_e32 v65, v65, v72
	v_cndmask_b32_e32 v66, v169, v66, vcc
	v_lshlrev_b32_e32 v66, 2, v66
	v_fmac_f32_e32 v83, v64, v64
	ds_bpermute_b32 v68, v66, v65
	v_add_f32_e32 v64, v83, v82
	v_add_f32_e32 v64, v81, v64
	v_add_f32_e32 v69, v80, v64
	ds_bpermute_b32 v66, v66, v69
	s_waitcnt lgkmcnt(1)
	v_add_f32_e32 v64, v65, v68
	v_xor_b32_e32 v65, 32, v169
	v_cmp_lt_i32_e32 vcc, v65, v67
	s_waitcnt lgkmcnt(0)
	v_add_f32_e32 v66, v69, v66
	v_cndmask_b32_e32 v65, v169, v65, vcc
	v_lshlrev_b32_e32 v67, 2, v65
	ds_bpermute_b32 v65, v67, v64
	ds_bpermute_b32 v67, v67, v66
	s_and_saveexec_b64 s[6:7], s[2:3]
	s_cbranch_execz .LBB0_763
	s_waitcnt lgkmcnt(1)
	v_add_f32_e32 v69, v64, v65
	v_lshlrev_b64 v[64:65], 2, v[154:155]
	s_waitcnt lgkmcnt(0)
	v_add_f32_e32 v68, v66, v67
	v_lshl_add_u64 v[66:67], s[46:47], 0, v[64:65]
	v_lshl_add_u64 v[64:65], s[50:51], 0, v[64:65]
	global_atomic_add_f32 v[66:67], v69, off
	global_atomic_add_f32 v[64:65], v68, off

; __device__ __forceinline__ unsigned cvt_pk_bf16(float lo, float hi) { unsigned r; asm volatile("v_cvt_pk_bf16_f32 %0, %1, %2" : "=v"(r) : "v"(lo), "v"(hi)); return r; }
;     __device__ __forceinline__ void operator()(const f32x4 (&acc)[2][2][4][2], const Unit& u, int wr, int wc, int fr, int fq) const {
;     ...
;             for (int m = 0; m < 4; ++m) {
;                 if (ai == 1 && !whole) continue;
;                 const int row = row0 + ai * HALF + m * 16;
;                 const float rs = rsv[ai][m];
;                 float s1 = 0.f, s2 = 0.f;
;                 bf16_t* rowp = BLK ? O + ((size_t)u.pm * (ldc >> 6) + (size_t)(col0 >> 6)) * 16384 + (size_t)((col0 >> 5) & 1) * 8192 + (size_t)(row - u.pm * BM) * 32 + (col0 & 31) : O + (size_t)row * ldc + col0;
; #pragma unroll
;                 for (int bj = 0; bj < 2; ++bj) {
;                     if (bj == 1 && !whole) continue;
;                     f32x4 v0 = acc[ai][bj][m][0] * rs, v1 = acc[ai][bj][m][1] * rs;
;                     if (ACT == 1) {
; #pragma unroll
;                         for (int j = 0; j < 4; ++j) { const float a = fmaxf(v0[j], 0.f), b = fmaxf(v1[j], 0.f); v0[j] = a * a; v1[j] = b * b; }
;                     }
;                     u32x4 w; w.x = cvt_pk_bf16(v0[0], v0[1]); w.y = cvt_pk_bf16(v0[2], v0[3]); w.z = cvt_pk_bf16(v1[0], v1[1]); w.w = cvt_pk_bf16(v1[2], v1[3]);
;                     *(u32x4*)(rowp + (BLK ? bj * 2 * 16384 : bj * HALF)) = w;
;                     if (STATS) { s1 += (v0[0] + v0[1]) + (v0[2] + v0[3]) + (v1[0] + v1[1]) + (v1[2] + v1[3]);
;                         s2 += (v0[0] * v0[0] + v0[1] * v0[1]) + (v0[2] * v0[2] + v0[3] * v0[3]) + (v1[0] * v1[0] + v1[1] * v1[1]) + (v1[2] * v1[2] + v1[3] * v1[3]); }
;                 }
;                 if (STATS && u.pn >= stat_pn0) {
;                     s1 += __shfl_xor(s1, 16); s1 += __shfl_xor(s1, 32); s2 += __shfl_xor(s2, 16); s2 += __shfl_xor(s2, 32);
;                     if (fq == 0) { atomicAdd(st1 + row, s1); atomicAdd(st2 + row, s2); }
;                 }
.LBB0_764:
	v_fmamk_f32 v64, v173, 0x3a800000, v168
	v_rsq_f32_e32 v68, v64
	s_waitcnt lgkmcnt(1)
	v_mov_b64_e32 v[64:65], s[34:35]
	v_mad_i64_i32 v[64:65], s[6:7], v152, s93, v[64:65]
	v_lshl_add_u64 v[70:71], v[148:149], 1, v[64:65]
	v_pk_mul_f32 v[62:63], v[62:63], v[68:69] op_sel_hi:[1,0]
	v_pk_mul_f32 v[60:61], v[60:61], v[68:69] op_sel_hi:[1,0]
	v_pk_mul_f32 v[58:59], v[58:59], v[68:69] op_sel_hi:[1,0]
	v_pk_mul_f32 v[56:57], v[56:57], v[68:69] op_sel_hi:[1,0]
	v_cvt_pk_bf16_f32 v64, v60, v61
	v_cvt_pk_bf16_f32 v65, v62, v63
	v_pk_mul_f32 v[54:55], v[54:55], v[68:69] op_sel_hi:[1,0]
	v_cvt_pk_bf16_f32 v66, v56, v57
	s_waitcnt lgkmcnt(0)
	v_cvt_pk_bf16_f32 v67, v58, v59
	v_pk_mul_f32 v[52:53], v[52:53], v[68:69] op_sel_hi:[1,0]
	v_pk_mul_f32 v[50:51], v[50:51], v[68:69] op_sel_hi:[1,0]
	v_pk_mul_f32 v[48:49], v[48:49], v[68:69] op_sel_hi:[1,0]
	s_and_b64 vcc, exec, s[0:1]
	global_store_dwordx4 v[70:71], v[64:67], off sc1
	s_nop 1
	v_cvt_pk_bf16_f32 v64, v52, v53
	v_cvt_pk_bf16_f32 v65, v54, v55
	v_cvt_pk_bf16_f32 v66, v48, v49
	v_cvt_pk_bf16_f32 v67, v50, v51
	global_store_dwordx4 v[70:71], v[64:67], off offset:256 sc1
	s_cbranch_vccnz .LBB0_768
	s_nop 0
	v_mul_f32_e32 v65, v61, v61
	v_mul_f32_e32 v66, v63, v63
	v_fmac_f32_e32 v65, v60, v60
	v_fmac_f32_e32 v66, v62, v62
	v_add_f32_e32 v65, v65, v66
	v_mul_f32_e32 v66, v57, v57
	v_mul_f32_e32 v64, v59, v59
	v_fmac_f32_e32 v66, v56, v56
	v_fmac_f32_e32 v64, v58, v58
	v_add_f32_e32 v65, v66, v65
	v_add_f32_e32 v64, v64, v65
	v_mul_f32_e32 v65, v51, v51
	v_mul_f32_e32 v66, v53, v53
	v_mul_f32_e32 v67, v55, v55
	v_fmac_f32_e32 v65, v50, v50
	v_fmac_f32_e32 v66, v52, v52
	v_fmac_f32_e32 v67, v54, v54
	v_add_f32_e32 v50, v50, v51
	v_add_f32_e32 v51, v52, v53
	v_add_f32_e32 v52, v54, v55
	v_add_f32_e32 v66, v66, v67
	v_mul_f32_e32 v67, v49, v49
	v_add_f32_e32 v58, v58, v59
	v_add_f32_e32 v59, v60, v61
	v_add_f32_e32 v60, v62, v63
	v_add_f32_e32 v51, v51, v52
	v_add_f32_e32 v49, v48, v49
	v_add_f32_e32 v59, v59, v60
	v_add_f32_e32 v56, v56, v57
	v_add_f32_e32 v49, v49, v51
	v_and_b32_e32 v51, 64, v169
	v_add_f32_e32 v56, v56, v59
	v_add_f32_e32 v49, v50, v49
	v_xor_b32_e32 v50, 16, v169
	v_add_u32_e32 v51, 64, v51
	v_add_f32_e32 v56, v58, v56
	v_cmp_lt_i32_e32 vcc, v50, v51
	v_add_f32_e32 v56, 0, v56
	v_add_f32_e32 v49, v49, v56
	v_cndmask_b32_e32 v50, v169, v50, vcc
	v_lshlrev_b32_e32 v50, 2, v50
	v_fmac_f32_e32 v67, v48, v48
	ds_bpermute_b32 v52, v50, v49
	v_add_f32_e32 v48, v67, v66
	v_add_f32_e32 v48, v65, v48
	v_add_f32_e32 v53, v64, v48
	ds_bpermute_b32 v50, v50, v53
	s_waitcnt lgkmcnt(1)
	v_add_f32_e32 v48, v49, v52
	v_xor_b32_e32 v49, 32, v169
	v_cmp_lt_i32_e32 vcc, v49, v51
	s_waitcnt lgkmcnt(0)
	v_add_f32_e32 v50, v53, v50
	v_cndmask_b32_e32 v49, v169, v49, vcc
	v_lshlrev_b32_e32 v51, 2, v49
	ds_bpermute_b32 v49, v51, v48
	ds_bpermute_b32 v51, v51, v50
	s_and_saveexec_b64 s[6:7], s[2:3]
	s_cbranch_execz .LBB0_767
	s_waitcnt lgkmcnt(1)
	v_add_f32_e32 v53, v48, v49
	v_lshlrev_b64 v[48:49], 2, v[152:153]
	s_waitcnt lgkmcnt(0)
	v_add_f32_e32 v52, v50, v51
	v_lshl_add_u64 v[50:51], s[46:47], 0, v[48:49]
	v_lshl_add_u64 v[48:49], s[50:51], 0, v[48:49]
	global_atomic_add_f32 v[50:51], v53, off
	global_atomic_add_f32 v[48:49], v52, off

; __device__ __forceinline__ unsigned cvt_pk_bf16(float lo, float hi) { unsigned r; asm volatile("v_cvt_pk_bf16_f32 %0, %1, %2" : "=v"(r) : "v"(lo), "v"(hi)); return r; }
;     __device__ __forceinline__ void operator()(const f32x4 (&acc)[2][2][4][2], const Unit& u, int wr, int wc, int fr, int fq) const {
;     ...
;             for (int m = 0; m < 4; ++m) {
;                 if (ai == 1 && !whole) continue;
;                 const int row = row0 + ai * HALF + m * 16;
;                 const float rs = rsv[ai][m];
;                 float s1 = 0.f, s2 = 0.f;
;                 bf16_t* rowp = BLK ? O + ((size_t)u.pm * (ldc >> 6) + (size_t)(col0 >> 6)) * 16384 + (size_t)((col0 >> 5) & 1) * 8192 + (size_t)(row - u.pm * BM) * 32 + (col0 & 31) : O + (size_t)row * ldc + col0;
; #pragma unroll
;                 for (int bj = 0; bj < 2; ++bj) {
;                     if (bj == 1 && !whole) continue;
;                     f32x4 v0 = acc[ai][bj][m][0] * rs, v1 = acc[ai][bj][m][1] * rs;
;                     if (ACT == 1) {
; #pragma unroll
;                         for (int j = 0; j < 4; ++j) { const float a = fmaxf(v0[j], 0.f), b = fmaxf(v1[j], 0.f); v0[j] = a * a; v1[j] = b * b; }
;                     }
;                     u32x4 w; w.x = cvt_pk_bf16(v0[0], v0[1]); w.y = cvt_pk_bf16(v0[2], v0[3]); w.z = cvt_pk_bf16(v1[0], v1[1]); w.w = cvt_pk_bf16(v1[2], v1[3]);
;                     *(u32x4*)(rowp + (BLK ? bj * 2 * 16384 : bj * HALF)) = w;
;                     if (STATS) { s1 += (v0[0] + v0[1]) + (v0[2] + v0[3]) + (v1[0] + v1[1]) + (v1[2] + v1[3]);
;                         s2 += (v0[0] * v0[0] + v0[1] * v0[1]) + (v0[2] * v0[2] + v0[3] * v0[3]) + (v1[0] * v1[0] + v1[1] * v1[1]) + (v1[2] * v1[2] + v1[3] * v1[3]); }
;                 }
;                 if (STATS && u.pn >= stat_pn0) {
;                     s1 += __shfl_xor(s1, 16); s1 += __shfl_xor(s1, 32); s2 += __shfl_xor(s2, 16); s2 += __shfl_xor(s2, 32);
;                     if (fq == 0) { atomicAdd(st1 + row, s1); atomicAdd(st2 + row, s2); }
;                 }
.LBB0_768:
	v_fmamk_f32 v48, v172, 0x3a800000, v168
	v_rsq_f32_e32 v52, v48
	s_waitcnt lgkmcnt(1)
	v_mov_b64_e32 v[48:49], s[34:35]
	v_mad_i64_i32 v[48:49], s[6:7], v150, s93, v[48:49]
	v_lshl_add_u64 v[54:55], v[148:149], 1, v[48:49]
	v_pk_mul_f32 v[46:47], v[46:47], v[52:53] op_sel_hi:[1,0]
	v_pk_mul_f32 v[44:45], v[44:45], v[52:53] op_sel_hi:[1,0]
	v_pk_mul_f32 v[42:43], v[42:43], v[52:53] op_sel_hi:[1,0]
	v_pk_mul_f32 v[40:41], v[40:41], v[52:53] op_sel_hi:[1,0]
	v_cvt_pk_bf16_f32 v48, v44, v45
	v_cvt_pk_bf16_f32 v49, v46, v47
	v_pk_mul_f32 v[38:39], v[38:39], v[52:53] op_sel_hi:[1,0]
	v_cvt_pk_bf16_f32 v50, v40, v41
	s_waitcnt lgkmcnt(0)
	v_cvt_pk_bf16_f32 v51, v42, v43
	v_pk_mul_f32 v[36:37], v[36:37], v[52:53] op_sel_hi:[1,0]
	v_pk_mul_f32 v[34:35], v[34:35], v[52:53] op_sel_hi:[1,0]
	v_pk_mul_f32 v[32:33], v[32:33], v[52:53] op_sel_hi:[1,0]
	s_and_b64 vcc, exec, s[0:1]
	global_store_dwordx4 v[54:55], v[48:51], off sc1
	s_nop 1
	v_cvt_pk_bf16_f32 v48, v36, v37
	v_cvt_pk_bf16_f32 v49, v38, v39
	v_cvt_pk_bf16_f32 v50, v32, v33
	v_cvt_pk_bf16_f32 v51, v34, v35
	global_store_dwordx4 v[54:55], v[48:51], off offset:256 sc1
	s_cbranch_vccnz .LBB0_772
	s_nop 0
	v_mul_f32_e32 v49, v45, v45
	v_mul_f32_e32 v50, v47, v47
	v_fmac_f32_e32 v49, v44, v44
	v_fmac_f32_e32 v50, v46, v46
	v_add_f32_e32 v49, v49, v50
	v_mul_f32_e32 v50, v41, v41
	v_mul_f32_e32 v48, v43, v43
	v_fmac_f32_e32 v50, v40, v40
	v_fmac_f32_e32 v48, v42, v42
	v_add_f32_e32 v49, v50, v49
	v_add_f32_e32 v48, v48, v49
	v_mul_f32_e32 v49, v35, v35
	v_mul_f32_e32 v50, v37, v37
	v_mul_f32_e32 v51, v39, v39
	v_fmac_f32_e32 v49, v34, v34
	v_fmac_f32_e32 v50, v36, v36
	v_fmac_f32_e32 v51, v38, v38
	v_add_f32_e32 v34, v34, v35
	v_add_f32_e32 v35, v36, v37
	v_add_f32_e32 v36, v38, v39
	v_add_f32_e32 v50, v50, v51
	v_mul_f32_e32 v51, v33, v33
	v_add_f32_e32 v42, v42, v43
	v_add_f32_e32 v43, v44, v45
	v_add_f32_e32 v44, v46, v47
	v_add_f32_e32 v35, v35, v36
	v_add_f32_e32 v33, v32, v33
	v_add_f32_e32 v43, v43, v44
	v_add_f32_e32 v40, v40, v41
	v_add_f32_e32 v33, v33, v35
	v_and_b32_e32 v35, 64, v169
	v_add_f32_e32 v40, v40, v43
	v_add_f32_e32 v33, v34, v33
	v_xor_b32_e32 v34, 16, v169
	v_add_u32_e32 v35, 64, v35
	v_add_f32_e32 v40, v42, v40
	v_cmp_lt_i32_e32 vcc, v34, v35
	v_add_f32_e32 v40, 0, v40
	v_add_f32_e32 v33, v33, v40
	v_cndmask_b32_e32 v34, v169, v34, vcc
	v_lshlrev_b32_e32 v34, 2, v34
	v_fmac_f32_e32 v51, v32, v32
	ds_bpermute_b32 v36, v34, v33
	v_add_f32_e32 v32, v51, v50
	v_add_f32_e32 v32, v49, v32
	v_add_f32_e32 v37, v48, v32
	ds_bpermute_b32 v34, v34, v37
	s_waitcnt lgkmcnt(1)
	v_add_f32_e32 v32, v33, v36
	v_xor_b32_e32 v33, 32, v169
	v_cmp_lt_i32_e32 vcc, v33, v35
	s_waitcnt lgkmcnt(0)
	v_add_f32_e32 v34, v37, v34
	v_cndmask_b32_e32 v33, v169, v33, vcc
	v_lshlrev_b32_e32 v35, 2, v33
	ds_bpermute_b32 v33, v35, v32
	ds_bpermute_b32 v35, v35, v34
	s_and_saveexec_b64 s[6:7], s[2:3]
	s_cbranch_execz .LBB0_771
	s_waitcnt lgkmcnt(1)
	v_add_f32_e32 v37, v32, v33
	v_lshlrev_b64 v[32:33], 2, v[150:151]
	s_waitcnt lgkmcnt(0)
	v_add_f32_e32 v36, v34, v35
	v_lshl_add_u64 v[34:35], s[46:47], 0, v[32:33]
	v_lshl_add_u64 v[32:33], s[50:51], 0, v[32:33]
	global_atomic_add_f32 v[34:35], v37, off
	global_atomic_add_f32 v[32:33], v36, off

; __device__ __forceinline__ unsigned cvt_pk_bf16(float lo, float hi) { unsigned r; asm volatile("v_cvt_pk_bf16_f32 %0, %1, %2" : "=v"(r) : "v"(lo), "v"(hi)); return r; }
;     __device__ __forceinline__ void operator()(const f32x4 (&acc)[2][2][4][2], const Unit& u, int wr, int wc, int fr, int fq) const {
;     ...
;             for (int m = 0; m < 4; ++m) {
;                 if (ai == 1 && !whole) continue;
;                 const int row = row0 + ai * HALF + m * 16;
;                 const float rs = rsv[ai][m];
;                 float s1 = 0.f, s2 = 0.f;
;                 bf16_t* rowp = BLK ? O + ((size_t)u.pm * (ldc >> 6) + (size_t)(col0 >> 6)) * 16384 + (size_t)((col0 >> 5) & 1) * 8192 + (size_t)(row - u.pm * BM) * 32 + (col0 & 31) : O + (size_t)row * ldc + col0;
; #pragma unroll
;                 for (int bj = 0; bj < 2; ++bj) {
;                     if (bj == 1 && !whole) continue;
;                     f32x4 v0 = acc[ai][bj][m][0] * rs, v1 = acc[ai][bj][m][1] * rs;
;                     if (ACT == 1) {
; #pragma unroll
;                         for (int j = 0; j < 4; ++j) { const float a = fmaxf(v0[j], 0.f), b = fmaxf(v1[j], 0.f); v0[j] = a * a; v1[j] = b * b; }
;                     }
;                     u32x4 w; w.x = cvt_pk_bf16(v0[0], v0[1]); w.y = cvt_pk_bf16(v0[2], v0[3]); w.z = cvt_pk_bf16(v1[0], v1[1]); w.w = cvt_pk_bf16(v1[2], v1[3]);
;                     *(u32x4*)(rowp + (BLK ? bj * 2 * 16384 : bj * HALF)) = w;
;                     if (STATS) { s1 += (v0[0] + v0[1]) + (v0[2] + v0[3]) + (v1[0] + v1[1]) + (v1[2] + v1[3]);
;                         s2 += (v0[0] * v0[0] + v0[1] * v0[1]) + (v0[2] * v0[2] + v0[3] * v0[3]) + (v1[0] * v1[0] + v1[1] * v1[1]) + (v1[2] * v1[2] + v1[3] * v1[3]); }
;                 }
;                 if (STATS && u.pn >= stat_pn0) {
;                     s1 += __shfl_xor(s1, 16); s1 += __shfl_xor(s1, 32); s2 += __shfl_xor(s2, 16); s2 += __shfl_xor(s2, 32);
;                     if (fq == 0) { atomicAdd(st1 + row, s1); atomicAdd(st2 + row, s2); }
;                 }
.LBB0_772:
	v_fmamk_f32 v32, v171, 0x3a800000, v168
	v_rsq_f32_e32 v36, v32
	s_waitcnt lgkmcnt(1)
	v_mov_b64_e32 v[32:33], s[34:35]
	v_mad_i64_i32 v[32:33], s[6:7], v146, s93, v[32:33]
	v_lshl_add_u64 v[38:39], v[148:149], 1, v[32:33]
	v_pk_mul_f32 v[30:31], v[30:31], v[36:37] op_sel_hi:[1,0]
	v_pk_mul_f32 v[28:29], v[28:29], v[36:37] op_sel_hi:[1,0]
	v_pk_mul_f32 v[26:27], v[26:27], v[36:37] op_sel_hi:[1,0]
	v_pk_mul_f32 v[24:25], v[24:25], v[36:37] op_sel_hi:[1,0]
	v_cvt_pk_bf16_f32 v32, v28, v29
	v_cvt_pk_bf16_f32 v33, v30, v31
	v_pk_mul_f32 v[22:23], v[22:23], v[36:37] op_sel_hi:[1,0]
	v_cvt_pk_bf16_f32 v34, v24, v25
	s_waitcnt lgkmcnt(0)
	v_cvt_pk_bf16_f32 v35, v26, v27
	v_pk_mul_f32 v[20:21], v[20:21], v[36:37] op_sel_hi:[1,0]
	v_pk_mul_f32 v[18:19], v[18:19], v[36:37] op_sel_hi:[1,0]
	v_pk_mul_f32 v[16:17], v[16:17], v[36:37] op_sel_hi:[1,0]
	s_and_b64 vcc, exec, s[0:1]
	global_store_dwordx4 v[38:39], v[32:35], off sc1
	s_nop 1
	v_cvt_pk_bf16_f32 v32, v20, v21
	v_cvt_pk_bf16_f32 v33, v22, v23
	v_cvt_pk_bf16_f32 v34, v16, v17
	v_cvt_pk_bf16_f32 v35, v18, v19
	global_store_dwordx4 v[38:39], v[32:35], off offset:256 sc1
	s_cbranch_vccnz .LBB0_776
	s_nop 0
	v_mul_f32_e32 v33, v29, v29
	v_mul_f32_e32 v34, v31, v31
	v_fmac_f32_e32 v33, v28, v28
	v_fmac_f32_e32 v34, v30, v30
	v_add_f32_e32 v33, v33, v34
	v_mul_f32_e32 v34, v25, v25
	v_mul_f32_e32 v32, v27, v27
	v_fmac_f32_e32 v34, v24, v24
	v_fmac_f32_e32 v32, v26, v26
	v_add_f32_e32 v33, v34, v33
	v_add_f32_e32 v32, v32, v33
	v_mul_f32_e32 v33, v19, v19
	v_mul_f32_e32 v34, v21, v21
	v_mul_f32_e32 v35, v23, v23
	v_fmac_f32_e32 v33, v18, v18
	v_fmac_f32_e32 v34, v20, v20
	v_fmac_f32_e32 v35, v22, v22
	v_add_f32_e32 v18, v18, v19
	v_add_f32_e32 v19, v20, v21
	v_add_f32_e32 v20, v22, v23
	v_add_f32_e32 v34, v34, v35
	v_mul_f32_e32 v35, v17, v17
	v_add_f32_e32 v26, v26, v27
	v_add_f32_e32 v27, v28, v29
	v_add_f32_e32 v28, v30, v31
	v_add_f32_e32 v19, v19, v20
	v_add_f32_e32 v17, v16, v17
	v_add_f32_e32 v27, v27, v28
	v_add_f32_e32 v24, v24, v25
	v_add_f32_e32 v17, v17, v19
	v_and_b32_e32 v19, 64, v169
	v_add_f32_e32 v24, v24, v27
	v_add_f32_e32 v17, v18, v17
	v_xor_b32_e32 v18, 16, v169
	v_add_u32_e32 v19, 64, v19
	v_add_f32_e32 v24, v26, v24
	v_cmp_lt_i32_e32 vcc, v18, v19
	v_add_f32_e32 v24, 0, v24
	v_add_f32_e32 v17, v17, v24
	v_cndmask_b32_e32 v18, v169, v18, vcc
	v_lshlrev_b32_e32 v18, 2, v18
	v_fmac_f32_e32 v35, v16, v16
	ds_bpermute_b32 v20, v18, v17
	v_add_f32_e32 v16, v35, v34
	v_add_f32_e32 v16, v33, v16
	v_add_f32_e32 v21, v32, v16
	ds_bpermute_b32 v18, v18, v21
	s_waitcnt lgkmcnt(1)
	v_add_f32_e32 v16, v17, v20
	v_xor_b32_e32 v17, 32, v169
	v_cmp_lt_i32_e32 vcc, v17, v19
	s_waitcnt lgkmcnt(0)
	v_add_f32_e32 v18, v21, v18
	v_cndmask_b32_e32 v17, v169, v17, vcc
	v_lshlrev_b32_e32 v19, 2, v17
	ds_bpermute_b32 v17, v19, v16
	ds_bpermute_b32 v19, v19, v18
	s_and_saveexec_b64 s[6:7], s[2:3]
	s_cbranch_execz .LBB0_775
	s_waitcnt lgkmcnt(1)
	v_add_f32_e32 v21, v16, v17
	v_lshlrev_b64 v[16:17], 2, v[146:147]
	s_waitcnt lgkmcnt(0)
	v_add_f32_e32 v20, v18, v19
	v_lshl_add_u64 v[18:19], s[46:47], 0, v[16:17]
	v_lshl_add_u64 v[16:17], s[50:51], 0, v[16:17]
	global_atomic_add_f32 v[18:19], v21, off
	global_atomic_add_f32 v[16:17], v20, off

; __device__ __forceinline__ unsigned cvt_pk_bf16(float lo, float hi) { unsigned r; asm volatile("v_cvt_pk_bf16_f32 %0, %1, %2" : "=v"(r) : "v"(lo), "v"(hi)); return r; }
;     __device__ __forceinline__ void operator()(const f32x4 (&acc)[2][2][4][2], const Unit& u, int wr, int wc, int fr, int fq) const {
;     ...
;             for (int m = 0; m < 4; ++m) {
;                 if (ai == 1 && !whole) continue;
;                 const int row = row0 + ai * HALF + m * 16;
;                 const float rs = rsv[ai][m];
;                 float s1 = 0.f, s2 = 0.f;
;                 bf16_t* rowp = BLK ? O + ((size_t)u.pm * (ldc >> 6) + (size_t)(col0 >> 6)) * 16384 + (size_t)((col0 >> 5) & 1) * 8192 + (size_t)(row - u.pm * BM) * 32 + (col0 & 31) : O + (size_t)row * ldc + col0;
; #pragma unroll
;                 for (int bj = 0; bj < 2; ++bj) {
;                     if (bj == 1 && !whole) continue;
;                     f32x4 v0 = acc[ai][bj][m][0] * rs, v1 = acc[ai][bj][m][1] * rs;
;                     if (ACT == 1) {
; #pragma unroll
;                         for (int j = 0; j < 4; ++j) { const float a = fmaxf(v0[j], 0.f), b = fmaxf(v1[j], 0.f); v0[j] = a * a; v1[j] = b * b; }
;                     }
;                     u32x4 w; w.x = cvt_pk_bf16(v0[0], v0[1]); w.y = cvt_pk_bf16(v0[2], v0[3]); w.z = cvt_pk_bf16(v1[0], v1[1]); w.w = cvt_pk_bf16(v1[2], v1[3]);
;                     *(u32x4*)(rowp + (BLK ? bj * 2 * 16384 : bj * HALF)) = w;
;                     if (STATS) { s1 += (v0[0] + v0[1]) + (v0[2] + v0[3]) + (v1[0] + v1[1]) + (v1[2] + v1[3]);
;                         s2 += (v0[0] * v0[0] + v0[1] * v0[1]) + (v0[2] * v0[2] + v0[3] * v0[3]) + (v1[0] * v1[0] + v1[1] * v1[1]) + (v1[2] * v1[2] + v1[3] * v1[3]); }
;                 }
;                 if (STATS && u.pn >= stat_pn0) {
;                     s1 += __shfl_xor(s1, 16); s1 += __shfl_xor(s1, 32); s2 += __shfl_xor(s2, 16); s2 += __shfl_xor(s2, 32);
;                     if (fq == 0) { atomicAdd(st1 + row, s1); atomicAdd(st2 + row, s2); }
;                 }
.LBB0_776:
	v_fmamk_f32 v16, v170, 0x3a800000, v168
	v_rsq_f32_e32 v20, v16
	s_waitcnt lgkmcnt(1)
	v_mov_b64_e32 v[16:17], s[34:35]
	v_mad_i64_i32 v[16:17], s[6:7], v144, s93, v[16:17]
	v_lshl_add_u64 v[22:23], v[148:149], 1, v[16:17]
	v_pk_mul_f32 v[14:15], v[14:15], v[20:21] op_sel_hi:[1,0]
	v_pk_mul_f32 v[12:13], v[12:13], v[20:21] op_sel_hi:[1,0]
	v_pk_mul_f32 v[10:11], v[10:11], v[20:21] op_sel_hi:[1,0]
	v_pk_mul_f32 v[8:9], v[8:9], v[20:21] op_sel_hi:[1,0]
	v_cvt_pk_bf16_f32 v16, v12, v13
	v_cvt_pk_bf16_f32 v17, v14, v15
	v_pk_mul_f32 v[6:7], v[6:7], v[20:21] op_sel_hi:[1,0]
	v_cvt_pk_bf16_f32 v18, v8, v9
	s_waitcnt lgkmcnt(0)
	v_cvt_pk_bf16_f32 v19, v10, v11
	v_pk_mul_f32 v[4:5], v[4:5], v[20:21] op_sel_hi:[1,0]
	v_pk_mul_f32 v[2:3], v[2:3], v[20:21] op_sel_hi:[1,0]
	v_pk_mul_f32 v[0:1], v[0:1], v[20:21] op_sel_hi:[1,0]
	s_and_b64 vcc, exec, s[0:1]
	global_store_dwordx4 v[22:23], v[16:19], off sc1
	s_nop 1
	v_cvt_pk_bf16_f32 v16, v4, v5
	v_cvt_pk_bf16_f32 v17, v6, v7
	v_cvt_pk_bf16_f32 v18, v0, v1
	v_cvt_pk_bf16_f32 v19, v2, v3
	global_store_dwordx4 v[22:23], v[16:19], off offset:256 sc1
	s_cbranch_vccnz .LBB0_780
	s_nop 0
	v_mul_f32_e32 v17, v13, v13
	v_mul_f32_e32 v18, v15, v15
	v_fmac_f32_e32 v17, v12, v12
	v_fmac_f32_e32 v18, v14, v14
	v_add_f32_e32 v17, v17, v18
	v_mul_f32_e32 v18, v9, v9
	v_mul_f32_e32 v16, v11, v11
	v_fmac_f32_e32 v18, v8, v8
	v_fmac_f32_e32 v16, v10, v10
	v_add_f32_e32 v17, v18, v17
	v_add_f32_e32 v16, v16, v17
	v_mul_f32_e32 v17, v3, v3
	v_mul_f32_e32 v18, v5, v5
	v_mul_f32_e32 v19, v7, v7
	v_fmac_f32_e32 v17, v2, v2
	v_fmac_f32_e32 v18, v4, v4
	v_fmac_f32_e32 v19, v6, v6
	v_add_f32_e32 v2, v2, v3
	v_add_f32_e32 v3, v4, v5
	v_add_f32_e32 v4, v6, v7
	v_add_f32_e32 v18, v18, v19
	v_mul_f32_e32 v19, v1, v1
	v_add_f32_e32 v10, v10, v11
	v_add_f32_e32 v11, v12, v13
	v_add_f32_e32 v12, v14, v15
	v_add_f32_e32 v3, v3, v4
	v_add_f32_e32 v1, v0, v1
	v_add_f32_e32 v11, v11, v12
	v_add_f32_e32 v8, v8, v9
	v_add_f32_e32 v1, v1, v3
	v_and_b32_e32 v3, 64, v169
	v_add_f32_e32 v8, v8, v11
	v_add_f32_e32 v1, v2, v1
	v_xor_b32_e32 v2, 16, v169
	v_add_u32_e32 v3, 64, v3
	v_add_f32_e32 v8, v10, v8
	v_cmp_lt_i32_e32 vcc, v2, v3
	v_add_f32_e32 v8, 0, v8
	v_add_f32_e32 v1, v1, v8
	v_cndmask_b32_e32 v2, v169, v2, vcc
	v_lshlrev_b32_e32 v2, 2, v2
	v_fmac_f32_e32 v19, v0, v0
	ds_bpermute_b32 v4, v2, v1
	v_add_f32_e32 v0, v19, v18
	v_add_f32_e32 v0, v17, v0
	v_add_f32_e32 v5, v16, v0
	ds_bpermute_b32 v2, v2, v5
	s_waitcnt lgkmcnt(1)
	v_add_f32_e32 v0, v1, v4
	v_xor_b32_e32 v1, 32, v169
	v_cmp_lt_i32_e32 vcc, v1, v3
	s_waitcnt lgkmcnt(0)
	v_add_f32_e32 v2, v5, v2
	v_cndmask_b32_e32 v1, v169, v1, vcc
	v_lshlrev_b32_e32 v3, 2, v1
	ds_bpermute_b32 v1, v3, v0
	ds_bpermute_b32 v3, v3, v2
	s_and_saveexec_b64 s[0:1], s[2:3]
	s_cbranch_execz .LBB0_779
	s_waitcnt lgkmcnt(1)
	v_add_f32_e32 v5, v0, v1
	v_lshlrev_b64 v[0:1], 2, v[144:145]
	s_waitcnt lgkmcnt(0)
	v_add_f32_e32 v4, v2, v3
	v_lshl_add_u64 v[2:3], s[46:47], 0, v[0:1]
	v_lshl_add_u64 v[0:1], s[50:51], 0, v[0:1]
	global_atomic_add_f32 v[2:3], v5, off
	global_atomic_add_f32 v[0:1], v4, off

; #define LAS __attribute__((address_space(3)))
; __device__ __forceinline__ unsigned pk2(float lo, float hi) { return pg8::cvt_pk_bf16(lo, hi); }
; __host__ __device__ __forceinline__ int gate_row(int n) { if (n < 512) return n; const int base = n < 1536 ? 512 : 1536, q = n - base, h = q >> 9, t = (q & 511) >> 7, r = q & 127; return base + t * 256 + h * 128 + r; }
; template <bool GATEMAP = false>
; __device__ __forceinline__ void p0_transpose_item(const float* W, int N, bf16* WT, int ldwt, int koff, const float* gain, LAS float* scr, int item, int lane) {
;     const int nblk = N / 64, kb = item / nblk, nb = item % nblk, k0 = 64 * kb, n0 = 64 * nb; const int nd0 = GATEMAP ? gate_row(n0) : n0;
;     const int ks = lane >> 4, n4 = (lane & 15) * 4;
;     f32x4 v[16];
; #pragma unroll
;     for (int i = 0; i < 16; ++i) v[i] = *(const f32x4*)(W + (size_t)(k0 + 4 * i + ks) * N + n0 + n4);
;     if (gain) {
; #pragma unroll
;         for (int i = 0; i < 16; ++i) v[i] = v[i] * gain[k0 + 4 * i + ks];
;     }
; #pragma unroll
;     for (int i = 0; i < 16; ++i) { LAS float* d = scr + (4 * i + ks) * 65 + n4; d[0] = v[i][0]; d[1] = v[i][1]; d[2] = v[i][2]; d[3] = v[i][3]; }
;     asm volatile("s_waitcnt lgkmcnt(0)" ::: "memory");
;     const int c = lane & 7;
; #pragma unroll
;     for (int j = 0; j < 8; ++j) { const int n = (lane >> 3) + 8 * j; const LAS float* q = scr + (8 * c) * 65 + n;
;         v4u o; o.x = pk2(q[0 * 65], q[1 * 65]); o.y = pk2(q[2 * 65], q[3 * 65]); o.z = pk2(q[4 * 65], q[5 * 65]); o.w = pk2(q[6 * 65], q[7 * 65]);
;         *(v4u*)(WT + (size_t)(nd0 + n) * ldwt + koff + k0 + 8 * c) = o; }
;     asm volatile("s_waitcnt lgkmcnt(0)" ::: "memory");
.LBB0_788:
	s_cmpk_gt_i32 s6, 0x3ff
	s_mov_b64 s[4:5], -1
	s_cbranch_scc0 .LBB0_790
	s_and_b32 s5, s14, 0x3ffc0
	s_and_b32 s4, s8, 0x3c0
	v_or_b32_e32 v0, s5, v10
	s_lshl_b32 s0, s4, 2
	v_lshl_add_u64 v[52:53], v[6:7], 0, s[0:1]
	v_lshlrev_b32_e32 v0, 12, v0
	v_lshl_add_u64 v[112:113], v[52:53], 0, v[0:1]
	v_add_co_u32_e32 v56, vcc, 0x4000, v112
	s_lshl_b32 s0, s5, 1
	s_nop 0
	v_addc_co_u32_e32 v57, vcc, 0, v113, vcc
	v_add_co_u32_e32 v60, vcc, 0x8000, v112
	global_load_dwordx4 v[52:55], v[112:113], off
	s_nop 0
	global_load_dwordx4 v[56:59], v[56:57], off
	v_addc_co_u32_e32 v61, vcc, 0, v113, vcc
	v_add_co_u32_e32 v64, vcc, 0xc000, v112
	v_or_b32_e32 v0, s4, v11
	s_nop 0
	v_addc_co_u32_e32 v65, vcc, 0, v113, vcc
	v_add_co_u32_e32 v68, vcc, 0x10000, v112
	global_load_dwordx4 v[60:63], v[60:61], off
	s_nop 0
	global_load_dwordx4 v[64:67], v[64:65], off
	v_addc_co_u32_e32 v69, vcc, 0, v113, vcc
	v_add_co_u32_e32 v72, vcc, 0x14000, v112
	v_lshlrev_b32_e32 v0, 13, v0
	s_nop 0
	v_addc_co_u32_e32 v73, vcc, 0, v113, vcc
	v_add_co_u32_e32 v76, vcc, 0x18000, v112
	global_load_dwordx4 v[68:71], v[68:69], off
	s_nop 0
	global_load_dwordx4 v[72:75], v[72:73], off
	v_addc_co_u32_e32 v77, vcc, 0, v113, vcc
	v_add_co_u32_e32 v80, vcc, 0x1c000, v112
	s_nop 1
	v_addc_co_u32_e32 v81, vcc, 0, v113, vcc
	v_add_co_u32_e32 v84, vcc, 0x20000, v112
	global_load_dwordx4 v[76:79], v[76:77], off
	s_nop 0
	global_load_dwordx4 v[80:83], v[80:81], off
	v_addc_co_u32_e32 v85, vcc, 0, v113, vcc
	v_add_co_u32_e32 v88, vcc, 0x24000, v112
	s_nop 1
	v_addc_co_u32_e32 v89, vcc, 0, v113, vcc
	v_add_co_u32_e32 v92, vcc, 0x28000, v112
	global_load_dwordx4 v[84:87], v[84:85], off
	s_nop 0
	global_load_dwordx4 v[88:91], v[88:89], off
	v_addc_co_u32_e32 v93, vcc, 0, v113, vcc
	v_add_co_u32_e32 v96, vcc, 0x2c000, v112
	s_nop 1
	v_addc_co_u32_e32 v97, vcc, 0, v113, vcc
	v_add_co_u32_e32 v100, vcc, 0x30000, v112
	global_load_dwordx4 v[92:95], v[92:93], off
	s_nop 0
	global_load_dwordx4 v[96:99], v[96:97], off
	v_addc_co_u32_e32 v101, vcc, 0, v113, vcc
	v_add_co_u32_e32 v104, vcc, 0x34000, v112
	s_nop 1
	v_addc_co_u32_e32 v105, vcc, 0, v113, vcc
	global_load_dwordx4 v[100:103], v[100:101], off
	s_nop 0
	global_load_dwordx4 v[104:107], v[104:105], off
	v_add_co_u32_e32 v108, vcc, 0x38000, v112
	s_nop 1
	v_addc_co_u32_e32 v109, vcc, 0, v113, vcc
	global_load_dwordx4 v[108:111], v[108:109], off
	v_add_co_u32_e32 v112, vcc, 0x3c000, v112
	s_nop 1
	v_addc_co_u32_e32 v113, vcc, 0, v113, vcc
	global_load_dwordx4 v[112:115], v[112:113], off
	s_waitcnt vmcnt(15)
	ds_write2_b32 v20, v52, v53 offset1:1
	ds_write2_b32 v20, v54, v55 offset0:2 offset1:3
	s_waitcnt vmcnt(14)
	ds_write2_b32 v21, v56, v57 offset1:1
	ds_write2_b32 v22, v58, v59 offset1:1
	s_waitcnt vmcnt(13)
	ds_write2_b32 v23, v60, v61 offset1:1
	ds_write2_b32 v24, v62, v63 offset1:1
	s_waitcnt vmcnt(12)
	ds_write2_b32 v25, v64, v65 offset1:1
	ds_write2_b32 v26, v66, v67 offset1:1
	s_waitcnt vmcnt(11)
	ds_write2_b32 v27, v68, v69 offset1:1
	ds_write2_b32 v28, v70, v71 offset1:1
	s_waitcnt vmcnt(10)
	ds_write2_b32 v29, v72, v73 offset1:1
	ds_write2_b32 v30, v74, v75 offset1:1
	s_waitcnt vmcnt(9)
	ds_write2_b32 v31, v76, v77 offset1:1
	ds_write2_b32 v32, v78, v79 offset1:1
	s_waitcnt vmcnt(8)
	ds_write2_b32 v33, v80, v81 offset1:1
	ds_write2_b32 v34, v82, v83 offset1:1
	s_waitcnt vmcnt(7)
	ds_write2_b32 v35, v84, v85 offset1:1
	ds_write2_b32 v36, v86, v87 offset1:1
	s_waitcnt vmcnt(6)
	ds_write2_b32 v37, v88, v89 offset1:1
	ds_write2_b32 v38, v90, v91 offset1:1
	s_waitcnt vmcnt(5)
	ds_write2_b32 v39, v92, v93 offset1:1
	ds_write2_b32 v40, v94, v95 offset1:1
	s_waitcnt vmcnt(4)
	ds_write2_b32 v41, v96, v97 offset1:1
	ds_write2_b32 v42, v98, v99 offset1:1
	s_waitcnt vmcnt(3)
	ds_write2_b32 v43, v100, v101 offset1:1
	ds_write2_b32 v44, v102, v103 offset1:1
	s_waitcnt vmcnt(2)
	ds_write2_b32 v45, v104, v105 offset1:1
	ds_write2_b32 v46, v106, v107 offset1:1
	s_waitcnt vmcnt(1)
	ds_write2_b32 v47, v108, v109 offset1:1
	ds_write2_b32 v48, v110, v111 offset1:1
	s_waitcnt vmcnt(0)
	ds_write2_b32 v49, v112, v113 offset1:1
	ds_write2_b32 v50, v114, v115 offset1:1
	s_waitcnt lgkmcnt(0)
	ds_read2_b32 v[52:53], v12 offset1:65
	s_waitcnt lgkmcnt(0)
	v_cvt_pk_bf16_f32 v52, v52, v53
	ds_read2_b32 v[54:55], v12 offset0:130 offset1:195
	s_waitcnt lgkmcnt(0)
	v_cvt_pk_bf16_f32 v53, v54, v55
	ds_read2_b32 v[54:55], v51 offset0:4 offset1:69
	v_lshl_add_u64 v[58:59], v[2:3], 0, s[0:1]
	s_waitcnt lgkmcnt(0)
	v_cvt_pk_bf16_f32 v54, v54, v55
	ds_read2_b32 v[56:57], v51 offset0:134 offset1:199
	s_waitcnt lgkmcnt(0)
	v_cvt_pk_bf16_f32 v55, v56, v57
	v_lshl_add_u64 v[60:61], v[58:59], 0, v[0:1]
	ds_read2_b32 v[56:57], v12 offset0:8 offset1:73
	global_store_dwordx4 v[60:61], v[52:55], off sc1
	v_or_b32_e32 v0, s4, v13
	v_lshlrev_b32_e32 v0, 13, v0
	s_waitcnt lgkmcnt(0)
	v_cvt_pk_bf16_f32 v52, v56, v57
	ds_read2_b32 v[54:55], v12 offset0:138 offset1:203
	s_waitcnt lgkmcnt(0)
	v_cvt_pk_bf16_f32 v53, v54, v55
	ds_read2_b32 v[54:55], v51 offset0:12 offset1:77
	s_waitcnt lgkmcnt(0)
	v_cvt_pk_bf16_f32 v54, v54, v55
	ds_read2_b32 v[56:57], v51 offset0:142 offset1:207
	s_waitcnt lgkmcnt(0)
	v_cvt_pk_bf16_f32 v55, v56, v57
	v_lshl_add_u64 v[60:61], v[58:59], 0, v[0:1]
	ds_read2_b32 v[56:57], v12 offset0:16 offset1:81
	global_store_dwordx4 v[60:61], v[52:55], off sc1
	v_or_b32_e32 v0, s4, v14
	v_lshlrev_b32_e32 v0, 13, v0
	s_waitcnt lgkmcnt(0)
	v_cvt_pk_bf16_f32 v52, v56, v57
	ds_read2_b32 v[54:55], v12 offset0:146 offset1:211
	s_waitcnt lgkmcnt(0)
	v_cvt_pk_bf16_f32 v53, v54, v55
	ds_read2_b32 v[54:55], v51 offset0:20 offset1:85
	s_waitcnt lgkmcnt(0)
; #define LAS __attribute__((address_space(3)))
; __device__ __forceinline__ unsigned pk2(float lo, float hi) { return pg8::cvt_pk_bf16(lo, hi); }
; __host__ __device__ __forceinline__ int gate_row(int n) { if (n < 512) return n; const int base = n < 1536 ? 512 : 1536, q = n - base, h = q >> 9, t = (q & 511) >> 7, r = q & 127; return base + t * 256 + h * 128 + r; }
; template <bool GATEMAP = false>
; __device__ __forceinline__ void p0_transpose_item(const float* W, int N, bf16* WT, int ldwt, int koff, const float* gain, LAS float* scr, int item, int lane) {
;     const int nblk = N / 64, kb = item / nblk, nb = item % nblk, k0 = 64 * kb, n0 = 64 * nb; const int nd0 = GATEMAP ? gate_row(n0) : n0;
;     const int ks = lane >> 4, n4 = (lane & 15) * 4;
;     f32x4 v[16];
; #pragma unroll
;     for (int i = 0; i < 16; ++i) v[i] = *(const f32x4*)(W + (size_t)(k0 + 4 * i + ks) * N + n0 + n4);
;     ...
;     const int c = lane & 7;
; #pragma unroll
;     for (int j = 0; j < 8; ++j) { const int n = (lane >> 3) + 8 * j; const LAS float* q = scr + (8 * c) * 65 + n;
;         v4u o; o.x = pk2(q[0 * 65], q[1 * 65]); o.y = pk2(q[2 * 65], q[3 * 65]); o.z = pk2(q[4 * 65], q[5 * 65]); o.w = pk2(q[6 * 65], q[7 * 65]);
;         *(v4u*)(WT + (size_t)(nd0 + n) * ldwt + koff + k0 + 8 * c) = o; }
;     asm volatile("s_waitcnt lgkmcnt(0)" ::: "memory");
	v_cvt_pk_bf16_f32 v54, v54, v55
	ds_read2_b32 v[56:57], v51 offset0:150 offset1:215
	s_waitcnt lgkmcnt(0)
	v_cvt_pk_bf16_f32 v55, v56, v57
	v_lshl_add_u64 v[60:61], v[58:59], 0, v[0:1]
	ds_read2_b32 v[56:57], v12 offset0:24 offset1:89
	global_store_dwordx4 v[60:61], v[52:55], off sc1
	v_or_b32_e32 v0, s4, v15
	v_lshlrev_b32_e32 v0, 13, v0
	s_waitcnt lgkmcnt(0)
	v_cvt_pk_bf16_f32 v52, v56, v57
	ds_read2_b32 v[54:55], v12 offset0:154 offset1:219
	s_waitcnt lgkmcnt(0)
	v_cvt_pk_bf16_f32 v53, v54, v55
	ds_read2_b32 v[54:55], v51 offset0:28 offset1:93
	s_waitcnt lgkmcnt(0)
	v_cvt_pk_bf16_f32 v54, v54, v55
	ds_read2_b32 v[56:57], v51 offset0:158 offset1:223
	s_waitcnt lgkmcnt(0)
	v_cvt_pk_bf16_f32 v55, v56, v57
	v_lshl_add_u64 v[60:61], v[58:59], 0, v[0:1]
	ds_read2_b32 v[56:57], v12 offset0:32 offset1:97
	global_store_dwordx4 v[60:61], v[52:55], off sc1
	v_or_b32_e32 v0, s4, v16
	v_lshlrev_b32_e32 v0, 13, v0
	s_waitcnt lgkmcnt(0)
	v_cvt_pk_bf16_f32 v52, v56, v57
	ds_read2_b32 v[54:55], v12 offset0:162 offset1:227
	s_waitcnt lgkmcnt(0)
	v_cvt_pk_bf16_f32 v53, v54, v55
	ds_read2_b32 v[54:55], v51 offset0:36 offset1:101
	s_waitcnt lgkmcnt(0)
	v_cvt_pk_bf16_f32 v54, v54, v55
	ds_read2_b32 v[56:57], v51 offset0:166 offset1:231
	s_waitcnt lgkmcnt(0)
	v_cvt_pk_bf16_f32 v55, v56, v57
	v_lshl_add_u64 v[60:61], v[58:59], 0, v[0:1]
	ds_read2_b32 v[56:57], v12 offset0:40 offset1:105
	global_store_dwordx4 v[60:61], v[52:55], off sc1
	v_or_b32_e32 v0, s4, v17
	v_lshlrev_b32_e32 v0, 13, v0
	s_waitcnt lgkmcnt(0)
	v_cvt_pk_bf16_f32 v52, v56, v57
	ds_read2_b32 v[54:55], v12 offset0:170 offset1:235
	s_waitcnt lgkmcnt(0)
	v_cvt_pk_bf16_f32 v53, v54, v55
	ds_read2_b32 v[54:55], v51 offset0:44 offset1:109
	s_waitcnt lgkmcnt(0)
	v_cvt_pk_bf16_f32 v54, v54, v55
	ds_read2_b32 v[56:57], v51 offset0:174 offset1:239
	s_waitcnt lgkmcnt(0)
	v_cvt_pk_bf16_f32 v55, v56, v57
	v_lshl_add_u64 v[60:61], v[58:59], 0, v[0:1]
	ds_read2_b32 v[56:57], v12 offset0:48 offset1:113
	global_store_dwordx4 v[60:61], v[52:55], off sc1
	v_or_b32_e32 v0, s4, v18
	v_lshlrev_b32_e32 v0, 13, v0
	s_waitcnt lgkmcnt(0)
	v_cvt_pk_bf16_f32 v52, v56, v57
	ds_read2_b32 v[54:55], v12 offset0:178 offset1:243
	s_waitcnt lgkmcnt(0)
	v_cvt_pk_bf16_f32 v53, v54, v55
	ds_read2_b32 v[54:55], v51 offset0:52 offset1:117
	s_waitcnt lgkmcnt(0)
	v_cvt_pk_bf16_f32 v54, v54, v55
	ds_read2_b32 v[56:57], v51 offset0:182 offset1:247
	s_waitcnt lgkmcnt(0)
	v_cvt_pk_bf16_f32 v55, v56, v57
	v_lshl_add_u64 v[60:61], v[58:59], 0, v[0:1]
	ds_read2_b32 v[56:57], v12 offset0:56 offset1:121
	global_store_dwordx4 v[60:61], v[52:55], off sc1
	v_or_b32_e32 v0, s4, v19
	v_lshlrev_b32_e32 v0, 13, v0
	s_waitcnt lgkmcnt(0)
	v_cvt_pk_bf16_f32 v52, v56, v57
	ds_read2_b32 v[54:55], v12 offset0:186 offset1:251
	s_waitcnt lgkmcnt(0)
	v_cvt_pk_bf16_f32 v53, v54, v55
	ds_read2_b32 v[54:55], v51 offset0:60 offset1:125
	s_waitcnt lgkmcnt(0)
	v_cvt_pk_bf16_f32 v54, v54, v55
	ds_read2_b32 v[56:57], v51 offset0:190 offset1:255
	s_waitcnt lgkmcnt(0)
	v_cvt_pk_bf16_f32 v55, v56, v57
	v_lshl_add_u64 v[56:57], v[58:59], 0, v[0:1]
	global_store_dwordx4 v[56:57], v[52:55], off sc1
	s_waitcnt lgkmcnt(0)
	s_mov_b64 s[4:5], 0
.LBB0_790:
	s_andn2_b64 vcc, exec, s[4:5]
	s_cbranch_vccnz .LBB0_787
	s_ashr_i32 s0, s6, 31
	s_lshr_b32 s0, s0, 26
	s_add_i32 s0, s6, s0
	s_and_b32 s24, s0, 0xffffffc0
	s_lshl_b32 s0, s0, 6
	s_and_b32 s0, s0, 0xfffff000
	v_or_b32_e32 v116, s24, v10
	s_sub_i32 s4, s8, s0
	v_or_b32_e32 v118, 4, v116
	v_or_b32_e32 v120, 8, v116
	v_or_b32_e32 v122, 12, v116
	v_or_b32_e32 v124, 16, v116
	v_or_b32_e32 v126, 20, v116
	v_or_b32_e32 v128, 24, v116
	v_or_b32_e32 v130, 28, v116
	v_or_b32_e32 v132, 32, v116
	v_or_b32_e32 v134, 36, v116
	v_or_b32_e32 v136, 40, v116
	v_or_b32_e32 v138, 44, v116
	v_or_b32_e32 v140, 48, v116
	v_or_b32_e32 v142, 52, v116
	v_or_b32_e32 v144, 56, v116
	v_or_b32_e32 v146, 60, v116
	s_ashr_i32 s5, s4, 31
	v_ashrrev_i32_e32 v117, 31, v116
	v_ashrrev_i32_e32 v119, 31, v118
	v_ashrrev_i32_e32 v121, 31, v120
	v_ashrrev_i32_e32 v123, 31, v122
	v_ashrrev_i32_e32 v125, 31, v124
	v_ashrrev_i32_e32 v127, 31, v126
	v_ashrrev_i32_e32 v129, 31, v128
	v_ashrrev_i32_e32 v131, 31, v130
	v_ashrrev_i32_e32 v133, 31, v132
	v_ashrrev_i32_e32 v135, 31, v134
	v_ashrrev_i32_e32 v137, 31, v136
	v_ashrrev_i32_e32 v139, 31, v138
	v_ashrrev_i32_e32 v141, 31, v140
	v_ashrrev_i32_e32 v143, 31, v142
	v_ashrrev_i32_e32 v145, 31, v144
	v_ashrrev_i32_e32 v147, 31, v146
	v_lshl_add_u64 v[108:109], s[4:5], 2, v[8:9]
	v_lshlrev_b64 v[52:53], 14, v[116:117]
	v_lshlrev_b64 v[54:55], 14, v[118:119]
	v_lshlrev_b64 v[60:61], 14, v[120:121]
	v_lshlrev_b64 v[62:63], 14, v[122:123]
	v_lshlrev_b64 v[68:69], 14, v[124:125]
	v_lshlrev_b64 v[70:71], 14, v[126:127]
	v_lshlrev_b64 v[76:77], 14, v[128:129]
	v_lshlrev_b64 v[78:79], 14, v[130:131]
	v_lshlrev_b64 v[84:85], 14, v[132:133]
	v_lshlrev_b64 v[86:87], 14, v[134:135]
	v_lshlrev_b64 v[92:93], 14, v[136:137]
	v_lshlrev_b64 v[94:95], 14, v[138:139]
	v_lshlrev_b64 v[100:101], 14, v[140:141]
	v_lshlrev_b64 v[102:103], 14, v[142:143]
	v_lshlrev_b64 v[110:111], 14, v[144:145]
	v_lshlrev_b64 v[112:113], 14, v[146:147]
	v_lshl_add_u64 v[52:53], v[108:109], 0, v[52:53]
	v_lshl_add_u64 v[56:57], v[108:109], 0, v[54:55]
	v_lshl_add_u64 v[60:61], v[108:109], 0, v[60:61]
	v_lshl_add_u64 v[64:65], v[108:109], 0, v[62:63]
	v_lshl_add_u64 v[68:69], v[108:109], 0, v[68:69]
	v_lshl_add_u64 v[72:73], v[108:109], 0, v[70:71]
	v_lshl_add_u64 v[76:77], v[108:109], 0, v[76:77]
	v_lshl_add_u64 v[80:81], v[108:109], 0, v[78:79]
	v_lshl_add_u64 v[84:85], v[108:109], 0, v[84:85]
	v_lshl_add_u64 v[88:89], v[108:109], 0, v[86:87]
; #define LAS __attribute__((address_space(3)))
; template <bool GATEMAP = false>
; __device__ __forceinline__ void p0_transpose_item(const float* W, int N, bf16* WT, int ldwt, int koff, const float* gain, LAS float* scr, int item, int lane) {
;     ...
;     for (int i = 0; i < 16; ++i) v[i] = *(const f32x4*)(W + (size_t)(k0 + 4 * i + ks) * N + n0 + n4);
;     if (gain) {
; #pragma unroll
;         for (int i = 0; i < 16; ++i) v[i] = v[i] * gain[k0 + 4 * i + ks];
;     }
; #pragma unroll
;     for (int i = 0; i < 16; ++i) { LAS float* d = scr + (4 * i + ks) * 65 + n4; d[0] = v[i][0]; d[1] = v[i][1]; d[2] = v[i][2]; d[3] = v[i][3]; }
	v_lshl_add_u64 v[92:93], v[108:109], 0, v[92:93]
	v_lshl_add_u64 v[96:97], v[108:109], 0, v[94:95]
	v_lshl_add_u64 v[100:101], v[108:109], 0, v[100:101]
	v_lshl_add_u64 v[104:105], v[108:109], 0, v[102:103]
	v_lshl_add_u64 v[110:111], v[108:109], 0, v[110:111]
	v_lshl_add_u64 v[112:113], v[108:109], 0, v[112:113]
	v_lshl_add_u64 v[116:117], v[116:117], 2, s[2:3]
	global_load_dwordx4 v[52:55], v[52:53], off
	s_nop 0
	global_load_dwordx4 v[56:59], v[56:57], off
	s_nop 0
	global_load_dwordx4 v[60:63], v[60:61], off
	s_nop 0
	global_load_dwordx4 v[64:67], v[64:65], off
	s_nop 0
	global_load_dwordx4 v[68:71], v[68:69], off
	s_nop 0
	global_load_dwordx4 v[72:75], v[72:73], off
	s_nop 0
	global_load_dwordx4 v[76:79], v[76:77], off
	s_nop 0
	global_load_dwordx4 v[80:83], v[80:81], off
	s_nop 0
	global_load_dwordx4 v[84:87], v[84:85], off
	s_nop 0
	global_load_dwordx4 v[88:91], v[88:89], off
	s_nop 0
	global_load_dwordx4 v[92:95], v[92:93], off
	s_nop 0
	global_load_dwordx4 v[96:99], v[96:97], off
	s_nop 0
	global_load_dwordx4 v[100:103], v[100:101], off
	s_nop 0
	global_load_dwordx4 v[104:107], v[104:105], off
	s_nop 0
	global_load_dwordx4 v[108:111], v[110:111], off
	s_nop 0
	global_load_dwordx4 v[112:115], v[112:113], off
	s_ashr_i32 s25, s24, 31
	global_load_dword v0, v[116:117], off
	v_lshl_add_u64 v[116:117], v[118:119], 2, s[2:3]
	v_lshl_add_u64 v[118:119], v[120:121], 2, s[2:3]
	v_lshl_add_u64 v[120:121], v[122:123], 2, s[2:3]
	v_lshl_add_u64 v[122:123], v[124:125], 2, s[2:3]
	v_lshl_add_u64 v[124:125], v[126:127], 2, s[2:3]
	v_lshl_add_u64 v[126:127], v[128:129], 2, s[2:3]
	v_lshl_add_u64 v[128:129], v[130:131], 2, s[2:3]
	v_lshl_add_u64 v[130:131], v[132:133], 2, s[2:3]
	v_lshl_add_u64 v[132:133], v[134:135], 2, s[2:3]
	v_lshl_add_u64 v[134:135], v[136:137], 2, s[2:3]
	v_lshl_add_u64 v[136:137], v[138:139], 2, s[2:3]
	v_lshl_add_u64 v[138:139], v[140:141], 2, s[2:3]
	v_lshl_add_u64 v[140:141], v[142:143], 2, s[2:3]
	v_lshl_add_u64 v[142:143], v[144:145], 2, s[2:3]
	v_lshl_add_u64 v[144:145], v[146:147], 2, s[2:3]
	global_load_dword v116, v[116:117], off
	s_waitcnt vmcnt(1)
	v_pk_mul_f32 v[52:53], v[52:53], v[0:1] op_sel_hi:[1,0]
	global_load_dword v118, v[118:119], off
	v_pk_mul_f32 v[54:55], v[54:55], v[0:1] op_sel_hi:[1,0]
	global_load_dword v120, v[120:121], off
	s_nop 0
	global_load_dword v122, v[122:123], off
	s_nop 0
	global_load_dword v124, v[124:125], off
	s_nop 0
	global_load_dword v126, v[126:127], off
	s_nop 0
	global_load_dword v128, v[128:129], off
	s_nop 0
	global_load_dword v130, v[130:131], off
	s_waitcnt vmcnt(7)
	v_pk_mul_f32 v[58:59], v[58:59], v[116:117] op_sel_hi:[1,0]
	global_load_dword v132, v[132:133], off
	v_pk_mul_f32 v[56:57], v[56:57], v[116:117] op_sel_hi:[1,0]
	global_load_dword v134, v[134:135], off
	s_waitcnt vmcnt(8)
	v_pk_mul_f32 v[62:63], v[62:63], v[118:119] op_sel_hi:[1,0]
	global_load_dword v136, v[136:137], off
	v_pk_mul_f32 v[60:61], v[60:61], v[118:119] op_sel_hi:[1,0]
	global_load_dword v138, v[138:139], off
	s_waitcnt vmcnt(9)
	v_pk_mul_f32 v[66:67], v[66:67], v[120:121] op_sel_hi:[1,0]
	global_load_dword v140, v[140:141], off
	v_pk_mul_f32 v[64:65], v[64:65], v[120:121] op_sel_hi:[1,0]
	global_load_dword v142, v[142:143], off
	s_waitcnt vmcnt(10)
	v_pk_mul_f32 v[70:71], v[70:71], v[122:123] op_sel_hi:[1,0]
	global_load_dword v144, v[144:145], off
	v_pk_mul_f32 v[68:69], v[68:69], v[122:123] op_sel_hi:[1,0]
	s_waitcnt vmcnt(10)
	v_pk_mul_f32 v[74:75], v[74:75], v[124:125] op_sel_hi:[1,0]
	v_pk_mul_f32 v[72:73], v[72:73], v[124:125] op_sel_hi:[1,0]
	s_waitcnt vmcnt(9)
	v_pk_mul_f32 v[78:79], v[78:79], v[126:127] op_sel_hi:[1,0]
	v_pk_mul_f32 v[76:77], v[76:77], v[126:127] op_sel_hi:[1,0]
	s_waitcnt vmcnt(8)
	v_pk_mul_f32 v[82:83], v[82:83], v[128:129] op_sel_hi:[1,0]
	v_pk_mul_f32 v[80:81], v[80:81], v[128:129] op_sel_hi:[1,0]
	s_waitcnt vmcnt(7)
	v_pk_mul_f32 v[86:87], v[86:87], v[130:131] op_sel_hi:[1,0]
	v_pk_mul_f32 v[84:85], v[84:85], v[130:131] op_sel_hi:[1,0]
	s_waitcnt vmcnt(6)
	v_pk_mul_f32 v[90:91], v[90:91], v[132:133] op_sel_hi:[1,0]
	v_pk_mul_f32 v[88:89], v[88:89], v[132:133] op_sel_hi:[1,0]
	s_waitcnt vmcnt(5)
	v_pk_mul_f32 v[94:95], v[94:95], v[134:135] op_sel_hi:[1,0]
	v_pk_mul_f32 v[92:93], v[92:93], v[134:135] op_sel_hi:[1,0]
	s_waitcnt vmcnt(4)
	v_pk_mul_f32 v[98:99], v[98:99], v[136:137] op_sel_hi:[1,0]
	v_pk_mul_f32 v[96:97], v[96:97], v[136:137] op_sel_hi:[1,0]
	s_waitcnt vmcnt(3)
	v_pk_mul_f32 v[102:103], v[102:103], v[138:139] op_sel_hi:[1,0]
	v_pk_mul_f32 v[100:101], v[100:101], v[138:139] op_sel_hi:[1,0]
	s_waitcnt vmcnt(2)
	v_pk_mul_f32 v[106:107], v[106:107], v[140:141] op_sel_hi:[1,0]
	v_pk_mul_f32 v[104:105], v[104:105], v[140:141] op_sel_hi:[1,0]
	s_waitcnt vmcnt(1)
	v_pk_mul_f32 v[110:111], v[110:111], v[142:143] op_sel_hi:[1,0]
	v_pk_mul_f32 v[108:109], v[108:109], v[142:143] op_sel_hi:[1,0]
	s_waitcnt vmcnt(0)
	v_pk_mul_f32 v[114:115], v[114:115], v[144:145] op_sel_hi:[1,0]
	v_pk_mul_f32 v[112:113], v[112:113], v[144:145] op_sel_hi:[1,0]
	ds_write2_b32 v20, v52, v53 offset1:1
	ds_write2_b32 v20, v54, v55 offset0:2 offset1:3
	ds_write2_b32 v21, v56, v57 offset1:1
	ds_write2_b32 v22, v58, v59 offset1:1
	ds_write2_b32 v23, v60, v61 offset1:1
	ds_write2_b32 v24, v62, v63 offset1:1
	ds_write2_b32 v25, v64, v65 offset1:1
	ds_write2_b32 v26, v66, v67 offset1:1
	ds_write2_b32 v27, v68, v69 offset1:1
	ds_write2_b32 v28, v70, v71 offset1:1
	ds_write2_b32 v29, v72, v73 offset1:1
	ds_write2_b32 v30, v74, v75 offset1:1
	ds_write2_b32 v31, v76, v77 offset1:1
	ds_write2_b32 v32, v78, v79 offset1:1
	ds_write2_b32 v33, v80, v81 offset1:1
	ds_write2_b32 v34, v82, v83 offset1:1
	ds_write2_b32 v35, v84, v85 offset1:1
	ds_write2_b32 v36, v86, v87 offset1:1
	ds_write2_b32 v37, v88, v89 offset1:1
	ds_write2_b32 v38, v90, v91 offset1:1
	ds_write2_b32 v39, v92, v93 offset1:1
	ds_write2_b32 v40, v94, v95 offset1:1
	ds_write2_b32 v41, v96, v97 offset1:1
	ds_write2_b32 v42, v98, v99 offset1:1
	ds_write2_b32 v43, v100, v101 offset1:1
	ds_write2_b32 v44, v102, v103 offset1:1
	ds_write2_b32 v45, v104, v105 offset1:1
	ds_write2_b32 v46, v106, v107 offset1:1
	ds_write2_b32 v47, v108, v109 offset1:1
	ds_write2_b32 v48, v110, v111 offset1:1
	ds_write2_b32 v49, v112, v113 offset1:1
	ds_write2_b32 v50, v114, v115 offset1:1
	s_waitcnt lgkmcnt(0)
; #define LAS __attribute__((address_space(3)))
; __device__ __forceinline__ unsigned pk2(float lo, float hi) { return pg8::cvt_pk_bf16(lo, hi); }
; template <bool GATEMAP = false>
; __device__ __forceinline__ void p0_transpose_item(const float* W, int N, bf16* WT, int ldwt, int koff, const float* gain, LAS float* scr, int item, int lane) {
;     ...
;     const int c = lane & 7;
; #pragma unroll
;     for (int j = 0; j < 8; ++j) { const int n = (lane >> 3) + 8 * j; const LAS float* q = scr + (8 * c) * 65 + n;
;         v4u o; o.x = pk2(q[0 * 65], q[1 * 65]); o.y = pk2(q[2 * 65], q[3 * 65]); o.z = pk2(q[4 * 65], q[5 * 65]); o.w = pk2(q[6 * 65], q[7 * 65]);
;         *(v4u*)(WT + (size_t)(nd0 + n) * ldwt + koff + k0 + 8 * c) = o; }
;     asm volatile("s_waitcnt lgkmcnt(0)" ::: "memory");
	ds_read2_b32 v[52:53], v12 offset1:65
	s_waitcnt lgkmcnt(0)
	v_cvt_pk_bf16_f32 v52, v52, v53
	ds_read2_b32 v[54:55], v12 offset0:130 offset1:195
	s_waitcnt lgkmcnt(0)
	v_cvt_pk_bf16_f32 v53, v54, v55
	ds_read2_b32 v[54:55], v51 offset0:4 offset1:69
	s_waitcnt lgkmcnt(0)
	v_cvt_pk_bf16_f32 v54, v54, v55
	ds_read2_b32 v[56:57], v51 offset0:134 offset1:199
	s_waitcnt lgkmcnt(0)
	v_cvt_pk_bf16_f32 v55, v56, v57
	v_add_u32_e32 v56, s4, v11
	v_ashrrev_i32_e32 v57, 31, v56
	v_lshl_add_u64 v[58:59], s[24:25], 1, v[4:5]
	v_lshlrev_b64 v[62:63], 11, v[56:57]
	v_lshl_add_u64 v[62:63], v[58:59], 0, v[62:63]
	ds_read2_b32 v[60:61], v12 offset0:8 offset1:73
	global_store_dwordx4 v[62:63], v[52:55], off sc1
	s_waitcnt lgkmcnt(0)
	s_nop 0
	v_cvt_pk_bf16_f32 v52, v60, v61
	ds_read2_b32 v[54:55], v12 offset0:138 offset1:203
	s_waitcnt lgkmcnt(0)
	v_cvt_pk_bf16_f32 v53, v54, v55
	ds_read2_b32 v[54:55], v51 offset0:12 offset1:77
	s_waitcnt lgkmcnt(0)
	v_cvt_pk_bf16_f32 v54, v54, v55
	ds_read2_b32 v[60:61], v51 offset0:142 offset1:207
	s_waitcnt lgkmcnt(0)
	v_cvt_pk_bf16_f32 v55, v60, v61
	v_add_u32_e32 v60, 8, v56
	v_ashrrev_i32_e32 v61, 31, v60
	v_lshlrev_b64 v[60:61], 11, v[60:61]
	v_lshl_add_u64 v[60:61], v[58:59], 0, v[60:61]
	ds_read2_b32 v[62:63], v12 offset0:16 offset1:81
	global_store_dwordx4 v[60:61], v[52:55], off sc1
	s_waitcnt lgkmcnt(0)
	s_nop 0
	v_cvt_pk_bf16_f32 v52, v62, v63
	ds_read2_b32 v[54:55], v12 offset0:146 offset1:211
	s_waitcnt lgkmcnt(0)
	v_cvt_pk_bf16_f32 v53, v54, v55
	ds_read2_b32 v[54:55], v51 offset0:20 offset1:85
	s_waitcnt lgkmcnt(0)
	v_cvt_pk_bf16_f32 v54, v54, v55
	ds_read2_b32 v[60:61], v51 offset0:150 offset1:215
	s_waitcnt lgkmcnt(0)
	v_cvt_pk_bf16_f32 v55, v60, v61
	v_add_u32_e32 v60, 16, v56
	v_ashrrev_i32_e32 v61, 31, v60
	v_lshlrev_b64 v[60:61], 11, v[60:61]
	v_lshl_add_u64 v[60:61], v[58:59], 0, v[60:61]
	ds_read2_b32 v[62:63], v12 offset0:24 offset1:89
	global_store_dwordx4 v[60:61], v[52:55], off sc1
	s_waitcnt lgkmcnt(0)
	s_nop 0
	v_cvt_pk_bf16_f32 v52, v62, v63
	ds_read2_b32 v[54:55], v12 offset0:154 offset1:219
	s_waitcnt lgkmcnt(0)
	v_cvt_pk_bf16_f32 v53, v54, v55
	ds_read2_b32 v[54:55], v51 offset0:28 offset1:93
	s_waitcnt lgkmcnt(0)
	v_cvt_pk_bf16_f32 v54, v54, v55
	ds_read2_b32 v[60:61], v51 offset0:158 offset1:223
	s_waitcnt lgkmcnt(0)
	v_cvt_pk_bf16_f32 v55, v60, v61
	v_add_u32_e32 v60, 24, v56
	v_ashrrev_i32_e32 v61, 31, v60
	v_lshlrev_b64 v[60:61], 11, v[60:61]
	v_lshl_add_u64 v[60:61], v[58:59], 0, v[60:61]
	ds_read2_b32 v[62:63], v12 offset0:32 offset1:97
	global_store_dwordx4 v[60:61], v[52:55], off sc1
	s_waitcnt lgkmcnt(0)
	s_nop 0
	v_cvt_pk_bf16_f32 v52, v62, v63
	ds_read2_b32 v[54:55], v12 offset0:162 offset1:227
	s_waitcnt lgkmcnt(0)
	v_cvt_pk_bf16_f32 v53, v54, v55
	ds_read2_b32 v[54:55], v51 offset0:36 offset1:101
	s_waitcnt lgkmcnt(0)
	v_cvt_pk_bf16_f32 v54, v54, v55
	ds_read2_b32 v[60:61], v51 offset0:166 offset1:231
	s_waitcnt lgkmcnt(0)
	v_cvt_pk_bf16_f32 v55, v60, v61
	v_add_u32_e32 v60, 32, v56
	v_ashrrev_i32_e32 v61, 31, v60
	v_lshlrev_b64 v[60:61], 11, v[60:61]
	v_lshl_add_u64 v[60:61], v[58:59], 0, v[60:61]
	ds_read2_b32 v[62:63], v12 offset0:40 offset1:105
	global_store_dwordx4 v[60:61], v[52:55], off sc1
	s_waitcnt lgkmcnt(0)
	s_nop 0
	v_cvt_pk_bf16_f32 v52, v62, v63
	ds_read2_b32 v[54:55], v12 offset0:170 offset1:235
	s_waitcnt lgkmcnt(0)
	v_cvt_pk_bf16_f32 v53, v54, v55
	ds_read2_b32 v[54:55], v51 offset0:44 offset1:109
	s_waitcnt lgkmcnt(0)
	v_cvt_pk_bf16_f32 v54, v54, v55
	ds_read2_b32 v[60:61], v51 offset0:174 offset1:239
	s_waitcnt lgkmcnt(0)
	v_cvt_pk_bf16_f32 v55, v60, v61
	v_add_u32_e32 v60, 40, v56
	v_ashrrev_i32_e32 v61, 31, v60
	v_lshlrev_b64 v[60:61], 11, v[60:61]
	v_lshl_add_u64 v[60:61], v[58:59], 0, v[60:61]
	ds_read2_b32 v[62:63], v12 offset0:48 offset1:113
	global_store_dwordx4 v[60:61], v[52:55], off sc1
	s_waitcnt lgkmcnt(0)
	s_nop 0
	v_cvt_pk_bf16_f32 v52, v62, v63
	ds_read2_b32 v[54:55], v12 offset0:178 offset1:243
	s_waitcnt lgkmcnt(0)
	v_cvt_pk_bf16_f32 v53, v54, v55
	ds_read2_b32 v[54:55], v51 offset0:52 offset1:117
	s_waitcnt lgkmcnt(0)
	v_cvt_pk_bf16_f32 v54, v54, v55
	ds_read2_b32 v[60:61], v51 offset0:182 offset1:247
	s_waitcnt lgkmcnt(0)
	v_cvt_pk_bf16_f32 v55, v60, v61
	v_add_u32_e32 v60, 48, v56
	v_ashrrev_i32_e32 v61, 31, v60
	v_lshlrev_b64 v[60:61], 11, v[60:61]
	v_add_u32_e32 v56, 56, v56
	v_lshl_add_u64 v[60:61], v[58:59], 0, v[60:61]
	v_ashrrev_i32_e32 v57, 31, v56
	ds_read2_b32 v[62:63], v12 offset0:56 offset1:121
	global_store_dwordx4 v[60:61], v[52:55], off sc1
	v_lshlrev_b64 v[56:57], 11, v[56:57]
	v_lshl_add_u64 v[56:57], v[58:59], 0, v[56:57]
	s_waitcnt lgkmcnt(0)
	v_cvt_pk_bf16_f32 v52, v62, v63
	ds_read2_b32 v[54:55], v12 offset0:186 offset1:251
	s_waitcnt lgkmcnt(0)
	v_cvt_pk_bf16_f32 v53, v54, v55
	ds_read2_b32 v[54:55], v51 offset0:60 offset1:125
	s_waitcnt lgkmcnt(0)
	v_cvt_pk_bf16_f32 v54, v54, v55
	ds_read2_b32 v[60:61], v51 offset0:190 offset1:255
	s_waitcnt lgkmcnt(0)
	v_cvt_pk_bf16_f32 v55, v60, v61
	global_store_dwordx4 v[56:57], v[52:55], off sc1
	s_waitcnt lgkmcnt(0)
	s_branch .LBB0_787

; #define PG8_STAGE(bufoff, gbase, voff) do { _Pragma("unroll") for (int _i = 0; _i < 2; ++_i) \
;         __builtin_amdgcn_global_load_lds((const unsigned*)((const char*)(gbase) + (voff)[_i]), (PG8_LAS unsigned*)(lds + (bufoff) + ldsw + _i * 8192), 16, 0, 0); } while (0)
; #define PG8_WAIT_V(n) asm volatile("s_waitcnt vmcnt(" #n ")" ::: "memory")
; #define PG8_BAR __builtin_amdgcn_s_barrier()
; template <class Epi, class Sched, bool ALIGN_EPI = false, bool SP2 = false>
; __device__ __forceinline__ void gemm_phase(PG8_LAS unsigned char* lds, const Gemm g, const Sched& S, const Epi& E) {
;     ...
;     const int tid = tid_, wid = __builtin_amdgcn_readfirstlane(tid >> 6), lane = tid & 63, wr = wid >> 2, wc = wid & 3, fr = lane & 15, fq = lane >> 4;
;     const int K = g.K;
;     unsigned voffA[2], voffB[2];
; #pragma unroll
;     for (int i = 0; i < 2; ++i) { int R, C; stage_rc(tid * 16 + i * 8192, R, C); const int Rb = Epi::PERM ? ((R & ~31) + perm32(R & 31)) : R;
;         voffA[i] = g.asub ? (unsigned)((C >> 5) * 16384 + (R * 32 + (C & 31)) * 2) : (unsigned)(R * g.lda + C) * 2u; voffB[i] = (unsigned)(Rb * K + C) * 2u; }
;     const size_t kstep = (size_t)(BK * 2);
;     const size_t hstepB = (size_t)HALF * K * 2, hstepA = (size_t)HALF * g.lda * 2;
;     const size_t tstepB = 2 * hstepB, tstepA = g.tstepA; const size_t kstepA = g.kstepA;
;     const unsigned ldsw = (unsigned)wid * 1024u;
;     const int aoff = lds_byte(wr * 64 + fr, fq * 8), boff = lds_byte(wc * 32 + fr, fq * 8);
;     ...
;     if constexpr (SP2) {
;         PG8_STAGE(PG8_SB(0, 0), cB, voffB); PG8_STAGE(PG8_SB(0, 1), cB + hstepB, voffB); PG8_STAGE(PG8_SA(0, 0), cA, voffA); PG8_STAGE(PG8_SA(0, 1), cA + hstepA, voffA);
;         if (wr == 1) PG8_BAR;
;         PG8_WAIT_V(2); PG8_BAR;
;         PG8_STAGE(PG8_SB(1, 0), cB + kstep, voffB); PG8_STAGE(PG8_SA(1, 0), cA + kstepA, voffA); PG8_STAGE(PG8_SB(1, 1), cB + hstepB + kstep, voffB);
;         PG8_WAIT_V(6); PG8_BAR;
.LBB0_1072:
	s_and_b64 s[2:3], s[2:3], exec
	s_cselect_b32 s18, -1, s7
	s_cselect_b32 s9, 16, 4
	s_lshl_b32 s2, s19, 5
	s_mov_b64 s[20:21], 0x80
	s_and_b32 s26, s2, 0x60
	s_add_i32 m0, s49, 0x18000
	v_lshl_add_u64 v[6:7], v[6:7], 0, s[20:21]
	s_lshl_b32 s7, s6, 13
	s_lshl_b32 s19, s26, 7
	s_waitcnt vmcnt(2)
	s_barrier
	global_load_lds_dwordx4 v[6:7], off
	v_lshl_add_u64 v[4:5], v[4:5], 0, s[20:21]
	s_add_i32 m0, s49, 0x1a000
	s_add_i32 s58, s49, 0x8000
	s_add_i32 s59, s49, 0xa000
	global_load_lds_dwordx4 v[4:5], off
	v_lshl_add_u64 v[0:1], v[0:1], 0, s[20:21]
	s_mov_b32 m0, s58
	s_add_u32 s2, s54, 0x40080
	global_load_lds_dwordx4 v[0:1], off
	v_lshl_add_u64 v[0:1], v[2:3], 0, s[20:21]
	s_mov_b32 m0, s59
	s_addc_u32 s3, s55, 0
	global_load_lds_dwordx4 v[0:1], off
	s_add_i32 m0, s49, 0x1c000
	v_lshl_add_u64 v[0:1], s[2:3], 0, v[194:195]
	global_load_lds_dwordx4 v[0:1], off
	v_lshl_add_u64 v[0:1], s[2:3], 0, v[198:199]
	s_add_i32 m0, s49, 0x1e000
	s_cmpk_lt_u32 s24, 0x100
	global_load_lds_dwordx4 v[0:1], off
	v_bfe_u32 v1, v8, 4, 2
	v_and_b32_e32 v0, 15, v8
	v_lshlrev_b32_e32 v2, 4, v1
	v_lshl_or_b32 v239, s6, 6, v0
	v_lshl_or_b32 v0, v0, 6, v2
	v_lshlrev_b32_e32 v2, 2, v8
	v_and_b32_e32 v2, 32, v2
	v_bitop3_b32 v3, v0, s7, v2 bitop3:0xde
	v_bitop3_b32 v240, v0, s19, v2 bitop3:0xde
	v_lshlrev_b32_e32 v0, 14, v9
	v_and_b32_e32 v0, 0xffff8000, v0
	v_cmp_eq_u32_e64 s[2:3], 0, v1
	v_lshl_or_b32 v241, v1, 3, s26
	v_lshl_add_u32 v0, v10, 11, v0
	v_and_b32_e32 v1, 1, v9
	v_lshl_or_b32 v0, v1, 6, v0
	v_lshl_add_u32 v200, v11, 1, v0
	v_lshlrev_b32_e32 v0, 14, v12
	v_and_b32_e32 v0, 0xffff8000, v0
	v_lshl_add_u32 v0, v13, 11, v0
	v_and_b32_e32 v1, 1, v12
	s_waitcnt vmcnt(0)
	v_lshl_or_b32 v0, v1, 6, v0
	s_mov_b32 s19, 0
	s_cselect_b64 s[24:25], -1, 0
	v_lshl_add_u32 v202, v14, 1, v0
	s_add_i32 s60, 0, 0x10000
	s_add_i32 s61, 0, 0x14000
	v_mbcnt_lo_u32_b32 v0, -1, 0
	v_mov_b32_e32 v201, v195
	v_mov_b32_e32 v203, v195
	v_add_u32_e32 v242, s60, v240
	v_add_u32_e32 v243, s61, v240
	v_add_u32_e32 v244, 0, v3
	s_mov_b32 s62, 0xfe000000
	s_mov_b32 s63, 0xfe008000
	s_mov_b32 s64, 0xfe009000
	s_mov_b32 s65, 0xfe010000
	s_mov_b32 s66, 0xfe011000
	s_mov_b32 s67, 0xfe018000
	s_mov_b32 s76, 0xfe019000
	s_mov_b32 s77, 0xfe040000
	s_mov_b32 s78, 0xfe041000
	s_mov_b32 s79, 0xfe048000
	s_mov_b32 s80, 0xfe049000
	s_mov_b32 s81, 0xfe050000
	s_mov_b32 s82, 0xfe051000
	s_mov_b32 s83, 0xfe058000
	v_mbcnt_hi_u32_b32 v245, -1, v0
	s_mov_b32 s84, s19
	s_barrier
	s_branch .LBB0_1075

;     __host__ __device__ __forceinline__ bool next(int i, Unit& u) const { const long L = (long)i * G + c; if (L >= nwg) return false; map((int)L, u); return true; }
; #define PG8_STAGE(bufoff, gbase, voff) do { _Pragma("unroll") for (int _i = 0; _i < 2; ++_i) \
;         __builtin_amdgcn_global_load_lds((const unsigned*)((const char*)(gbase) + (voff)[_i]), (PG8_LAS unsigned*)(lds + (bufoff) + ldsw + _i * 8192), 16, 0, 0); } while (0)
; #define PG8_WAIT_V(n) asm volatile("s_waitcnt vmcnt(" #n ")" ::: "memory")
; #define PG8_WAIT_L(n) asm volatile("s_waitcnt lgkmcnt(" #n ")" ::: "memory")
; #define PG8_BAR __builtin_amdgcn_s_barrier()
;     __host__ __device__ __forceinline__ bool next(int i, Unit& u) const {
;         const int ii = (so.c < 16 * S && so.G >= so.nwg && i < 2) ? 1 - i : i;
;         const int L = ii * so.G + so.c; const bool isp = L < so.nwg; const int j = isp ? 0 : L - so.nwg;
;         Unit a; so.map(isp ? L : 0, a);
;         const int q = j / S, sp = j - q * S;
;         u.pm = isp ? a.pm : 64 + (q >> 2); u.pn = isp ? a.pn : (q & 3); u.sp = isp ? -1 : sp; u.nt = isp ? a.nt : ntS; u.k0 = isp ? 0 : sp * ntS * BK; u.qa = -1; u.qb = -1;
;         return isp || j < 16 * S;
; template <class Epi, class Sched, bool ALIGN_EPI = false, bool SP2 = false>
; __device__ __forceinline__ void gemm_phase(PG8_LAS unsigned char* lds, const Gemm g, const Sched& S, const Epi& E) {
;     ...
;         for (int t = 0; t < nt; t += 2) {
;             const bool last = (t == nt - 2);
;             const char* a1 = cA + (size_t)(t + 1) * kstepA;
;             const char* a2 = last ? nA : cA + (size_t)(t + 2) * kstepA; const char* b2 = last ? nB : cB + (size_t)(t + 2) * kstep;
;             const char* a3 = a2 + kstepA; const char* b3 = b2 + kstep;
;             if (last && has_next) S.a_ready(nxt);
;             if constexpr (SP2) {
;             PG8_LDB(B0, 0, 0); PG8_LDB(B1, 0, 1); PG8_SCHED; PG8_LDA(At, 0, 0); PG8_STAGE(PG8_SA(1, 1), a1 + hstepA, voffA);
;             PG8_WAIT_V(8); PG8_WAIT_L(0); PG8_BAR; PG8_MMA(0, 0, At, B0); if (whole) PG8_MMA(0, 1, At, B1); PG8_BAR; PG8_SCHED;
;             PG8_LDA(At, 0, 1); PG8_STAGE(PG8_SB(0, 0), b2, voffB); PG8_STAGE(PG8_SB(0, 1), b2 + hstepB, voffB); PG8_STAGE(PG8_SA(0, 0), a2, voffA);
;             PG8_WAIT_V(8); PG8_WAIT_L(0); PG8_BAR; if (whole) { PG8_MMA(1, 0, At, B0); PG8_MMA(1, 1, At, B1); } PG8_BAR; PG8_SCHED;
.LBB0_1079:
	s_add_i32 s7, s38, s6
	s_ashr_i32 s6, s7, 31
	s_lshr_b32 s6, s6, 28
	s_add_i32 s38, s7, s6
	s_ashr_i32 s6, s38, 4
	s_lshl_b32 s39, s6, 2
	s_sub_i32 s6, 64, s39
	s_min_i32 s40, s6, 4
	s_abs_i32 s41, s40
	v_cvt_f32_u32_e32 v0, s41
	s_sub_i32 s45, 0, s41
	s_and_b32 s38, s38, -16
	s_sub_i32 s7, s7, s38
	v_rcp_iflag_f32_e32 v0, v0
	s_abs_i32 s38, s7
	s_max_i32 s42, s46, 0x100
	s_xor_b32 s44, s7, s40
	v_mul_f32_e32 v0, 0x4f7ffffe, v0
	v_cvt_u32_f32_e32 v0, v0
	s_add_i32 s43, s42, 0xffffff00
	s_ashr_i32 s44, s44, 31
	s_mov_b32 s6, 0
	v_readfirstlane_b32 s47, v0
	s_mul_i32 s45, s45, s47
	s_mul_hi_u32 s45, s47, s45
	s_add_i32 s47, s47, s45
	s_mul_hi_u32 s45, s38, s47
	s_mul_i32 s47, s45, s41
	s_sub_i32 s38, s38, s47
	s_add_i32 s47, s45, 1
	s_sub_i32 s85, s38, s41
	s_cmp_ge_u32 s38, s41
	s_cselect_b32 s45, s47, s45
	s_cselect_b32 s38, s85, s38
	s_add_i32 s47, s45, 1
	s_cmp_ge_u32 s38, s41
	s_cselect_b32 s38, s47, s45
	s_xor_b32 s38, s38, s44
	s_sub_i32 s44, s38, s44
	s_mul_i32 s38, s44, s40
	s_sub_i32 s7, s7, s38
	s_lshr_b32 s38, s43, 4
	s_add_i32 s7, s39, s7
	s_and_b32 s85, s42, 3
	s_add_i32 s40, s38, 64
	s_and_b64 s[38:39], s[26:27], exec
	s_cselect_b32 s38, s7, s40
	s_bfe_u32 s7, s42, 0x20002
	s_and_b64 s[40:41], s[26:27], exec
	s_cselect_b32 s40, s44, s7
	s_lshl_b32 s7, s85, 9
	s_and_b64 s[42:43], s[26:27], exec
	s_cselect_b32 s7, 0, s7
	s_ashr_i32 s39, s38, 31
	s_lshl_b64 s[42:43], s[38:39], 19
	s_add_u32 s39, s36, s42
	s_addc_u32 s41, s37, s43
	s_add_u32 s42, s39, s7
	s_addc_u32 s43, s41, 0
	s_ashr_i32 s41, s40, 31
	s_lshl_b64 s[44:45], s[40:41], 19
	s_add_u32 s39, s28, s44
	s_addc_u32 s41, s29, s45
	s_add_u32 s44, s39, s7
	s_addc_u32 s45, s41, 0
	s_cmpk_lt_i32 s46, 0x140
	s_cselect_b64 s[46:47], -1, 0
	s_and_b64 s[86:87], s[46:47], exec
	s_cselect_b32 s39, s43, s53
	s_cselect_b32 s41, s42, s52
	s_cselect_b32 s86, s45, s55
	s_cselect_b32 s87, s44, s54
	s_add_i32 s90, s9, -2
	s_add_u32 s52, s52, 0x40080
	s_addc_u32 s53, s53, 0
	s_add_u32 s91, s54, 0x100
	s_addc_u32 s92, s55, 0
	s_waitcnt lgkmcnt(0)
	ds_read_b128 v[128:131], v242
	ds_read_b128 v[132:135], v242 offset:1024
	ds_read_b128 v[136:139], v242 offset:2048
	ds_read_b128 v[140:143], v242 offset:3072
	ds_read_b128 v[144:147], v243
	ds_read_b128 v[148:151], v243 offset:1024
	ds_read_b128 v[152:155], v243 offset:2048
	ds_read_b128 v[156:159], v243 offset:3072
	s_add_i32 s93, s6, 2
	s_add_u32 s7, s52, 0xfffc0080
	s_addc_u32 s54, s53, -1
	s_cmp_eq_u32 s90, s6
	s_cselect_b32 s6, s87, s91
	s_cselect_b32 s55, s39, s54
	s_cselect_b32 s54, s41, s7
	s_cselect_b32 s7, s86, s92
	v_lshl_add_u64 v[204:205], s[52:53], 0, v[200:201]
	s_add_i32 m0, s49, 0xc000
	ds_read_b128 v[160:163], v244
	ds_read_b128 v[164:167], v244 offset:1024
	ds_read_b128 v[168:171], v244 offset:2048
	ds_read_b128 v[172:175], v244 offset:3072
	ds_read_b128 v[176:179], v244 offset:4096
	ds_read_b128 v[180:183], v244 offset:5120
	ds_read_b128 v[184:187], v244 offset:6144
	ds_read_b128 v[188:191], v244 offset:7168
	global_load_lds_dwordx4 v[204:205], off
	v_lshl_add_u64 v[204:205], s[52:53], 0, v[202:203]
	s_add_i32 m0, s49, 0xe000
	s_nop 0
	global_load_lds_dwordx4 v[204:205], off
	s_waitcnt vmcnt(16)
	s_waitcnt lgkmcnt(0)
	s_barrier
	s_setprio 1
	s_waitcnt lgkmcnt(0)
	v_mfma_f32_16x16x32_bf16 v[124:127], v[128:131], v[160:163], 0
	v_mfma_f32_16x16x32_bf16 v[120:123], v[136:139], v[160:163], 0
	v_mfma_f32_16x16x32_bf16 v[116:119], v[128:131], v[168:171], 0
	v_mfma_f32_16x16x32_bf16 v[108:111], v[136:139], v[168:171], 0
	v_mfma_f32_16x16x32_bf16 v[100:103], v[128:131], v[176:179], 0
	v_mfma_f32_16x16x32_bf16 v[92:95], v[136:139], v[176:179], 0
	v_mfma_f32_16x16x32_bf16 v[84:87], v[128:131], v[184:187], 0
	v_mfma_f32_16x16x32_bf16 v[76:79], v[136:139], v[184:187], 0
	v_mfma_f32_16x16x32_bf16 v[124:127], v[132:135], v[164:167], v[124:127]
	v_mfma_f32_16x16x32_bf16 v[120:123], v[140:143], v[164:167], v[120:123]
	v_mfma_f32_16x16x32_bf16 v[116:119], v[132:135], v[172:175], v[116:119]
	v_mfma_f32_16x16x32_bf16 v[108:111], v[140:143], v[172:175], v[108:111]
	v_mfma_f32_16x16x32_bf16 v[100:103], v[132:135], v[180:183], v[100:103]
	v_mfma_f32_16x16x32_bf16 v[92:95], v[140:143], v[180:183], v[92:95]
	v_mfma_f32_16x16x32_bf16 v[84:87], v[132:135], v[188:191], v[84:87]
	v_mfma_f32_16x16x32_bf16 v[76:79], v[140:143], v[188:191], v[76:79]
	s_setprio 0
	s_setprio 1
	v_mfma_f32_16x16x32_bf16 v[112:115], v[144:147], v[160:163], 0
	v_mfma_f32_16x16x32_bf16 v[104:107], v[152:155], v[160:163], 0
	v_mfma_f32_16x16x32_bf16 v[96:99], v[144:147], v[168:171], 0
	v_mfma_f32_16x16x32_bf16 v[88:91], v[152:155], v[168:171], 0
	v_mfma_f32_16x16x32_bf16 v[80:83], v[144:147], v[176:179], 0
	v_mfma_f32_16x16x32_bf16 v[72:75], v[152:155], v[176:179], 0
	v_mfma_f32_16x16x32_bf16 v[68:71], v[144:147], v[184:187], 0
	v_mfma_f32_16x16x32_bf16 v[64:67], v[152:155], v[184:187], 0
	v_mfma_f32_16x16x32_bf16 v[112:115], v[148:151], v[164:167], v[112:115]
	v_mfma_f32_16x16x32_bf16 v[104:107], v[156:159], v[164:167], v[104:107]
	v_mfma_f32_16x16x32_bf16 v[96:99], v[148:151], v[172:175], v[96:99]
	v_mfma_f32_16x16x32_bf16 v[88:91], v[156:159], v[172:175], v[88:91]
	v_mfma_f32_16x16x32_bf16 v[80:83], v[148:151], v[180:183], v[80:83]
	v_mfma_f32_16x16x32_bf16 v[72:75], v[156:159], v[180:183], v[72:75]
	v_mfma_f32_16x16x32_bf16 v[68:71], v[148:151], v[188:191], v[68:71]
	v_mfma_f32_16x16x32_bf16 v[64:67], v[156:159], v[188:191], v[64:67]
	s_setprio 0
	s_barrier
; #define PG8_STAGE(bufoff, gbase, voff) do { _Pragma("unroll") for (int _i = 0; _i < 2; ++_i) \
;         __builtin_amdgcn_global_load_lds((const unsigned*)((const char*)(gbase) + (voff)[_i]), (PG8_LAS unsigned*)(lds + (bufoff) + ldsw + _i * 8192), 16, 0, 0); } while (0)
; #define PG8_LDA(dst, b, h) do { _Pragma("unroll") for (int m = 0; m < 4; ++m) _Pragma("unroll") for (int k = 0; k < 2; ++k) dst[m][k] = *(const PG8_LAS bf16x8*)(lds + PG8_SA(b, h) + aoff + m * 2048 + k * 1024); } while (0)
; #define PG8_LDB(dst, b, h) do { _Pragma("unroll") for (int n = 0; n < 2; ++n) _Pragma("unroll") for (int k = 0; k < 2; ++k) dst[n][k] = *(const PG8_LAS bf16x8*)(lds + PG8_SB(b, h) + boff + n * 2048 + k * 1024); } while (0)
; #define PG8_MMA(ai, bj, At, Bt) do { __builtin_amdgcn_s_setprio(1); _Pragma("unroll") for (int m = 0; m < 4; ++m) _Pragma("unroll") for (int n = 0; n < 2; ++n) _Pragma("unroll") for (int k = 0; k < 2; ++k) \
;         acc[ai][bj][m][n] = __builtin_amdgcn_mfma_f32_16x16x32_bf16(Bt[n][k], At[m][k], acc[ai][bj][m][n], 0, 0, 0); __builtin_amdgcn_s_setprio(0); } while (0)
; #define PG8_WAIT_V(n) asm volatile("s_waitcnt vmcnt(" #n ")" ::: "memory")
; #define PG8_WAIT_L(n) asm volatile("s_waitcnt lgkmcnt(" #n ")" ::: "memory")
; #define PG8_BAR __builtin_amdgcn_s_barrier()
; #define PG8_SCHED __builtin_amdgcn_sched_barrier(0)
; template <class Epi, class Sched, bool ALIGN_EPI = false, bool SP2 = false>
; __device__ __forceinline__ void gemm_phase(PG8_LAS unsigned char* lds, const Gemm g, const Sched& S, const Epi& E) {
;     ...
;             PG8_WAIT_V(8); PG8_WAIT_L(0); PG8_BAR; PG8_MMA(0, 0, At, B0); if (whole) PG8_MMA(0, 1, At, B1); PG8_BAR; PG8_SCHED;
;             PG8_LDA(At, 0, 1); PG8_STAGE(PG8_SB(0, 0), b2, voffB); PG8_STAGE(PG8_SB(0, 1), b2 + hstepB, voffB); PG8_STAGE(PG8_SA(0, 0), a2, voffA);
;             PG8_WAIT_V(8); PG8_WAIT_L(0); PG8_BAR; if (whole) { PG8_MMA(1, 0, At, B0); PG8_MMA(1, 1, At, B1); } PG8_BAR; PG8_SCHED;
;             PG8_LDB(B0, 1, 0); PG8_LDB(B1, 1, 1); PG8_SCHED; PG8_LDA(At, 1, 0); PG8_STAGE(PG8_SA(0, 1), a2 + hstepA, voffA);
;             PG8_WAIT_V(8); PG8_WAIT_L(0); PG8_BAR; PG8_MMA(0, 0, At, B0); if (whole) PG8_MMA(0, 1, At, B1); PG8_BAR; PG8_SCHED;
	s_add_i32 s94, s60, s8
	v_lshl_add_u64 v[204:205], s[6:7], 0, v[194:195]
	s_mov_b32 m0, s94
	ds_read_b128 v[160:163], v244 offset:16384
	ds_read_b128 v[164:167], v244 offset:17408
	ds_read_b128 v[168:171], v244 offset:18432
	ds_read_b128 v[172:175], v244 offset:19456
	ds_read_b128 v[176:179], v244 offset:20480
	ds_read_b128 v[180:183], v244 offset:21504
	ds_read_b128 v[184:187], v244 offset:22528
	ds_read_b128 v[188:191], v244 offset:23552
	global_load_lds_dwordx4 v[204:205], off
	s_add_i32 m0, s94, 0x2000
	s_add_u32 s94, s6, 0x40000
	v_lshl_add_u64 v[206:207], s[6:7], 0, v[198:199]
	s_addc_u32 s95, s7, 0
	s_add_i32 s96, s61, s8
	global_load_lds_dwordx4 v[206:207], off
	v_lshl_add_u64 v[208:209], s[94:95], 0, v[194:195]
	s_mov_b32 m0, s96
	v_lshl_add_u64 v[210:211], s[54:55], 0, v[196:197]
	global_load_lds_dwordx4 v[208:209], off
	v_lshl_add_u64 v[208:209], s[94:95], 0, v[198:199]
	s_add_i32 m0, s96, 0x2000
	s_nop 0
	global_load_lds_dwordx4 v[208:209], off
	v_lshl_add_u64 v[208:209], s[54:55], 0, v[192:193]
	s_mov_b32 m0, s49
	s_nop 0
	global_load_lds_dwordx4 v[208:209], off
	s_mov_b32 m0, s51
	s_nop 0
	global_load_lds_dwordx4 v[210:211], off
	s_waitcnt vmcnt(16)
	s_waitcnt lgkmcnt(0)
	s_barrier
	s_setprio 1
	s_waitcnt lgkmcnt(0)
	v_mfma_f32_16x16x32_bf16 v[60:63], v[128:131], v[160:163], 0
	v_mfma_f32_16x16x32_bf16 v[56:59], v[136:139], v[160:163], 0
	v_mfma_f32_16x16x32_bf16 v[52:55], v[128:131], v[168:171], 0
	v_mfma_f32_16x16x32_bf16 v[44:47], v[136:139], v[168:171], 0
	v_mfma_f32_16x16x32_bf16 v[36:39], v[128:131], v[176:179], 0
	v_mfma_f32_16x16x32_bf16 v[28:31], v[136:139], v[176:179], 0
	v_mfma_f32_16x16x32_bf16 v[20:23], v[128:131], v[184:187], 0
	v_mfma_f32_16x16x32_bf16 v[12:15], v[136:139], v[184:187], 0
	v_mfma_f32_16x16x32_bf16 v[60:63], v[132:135], v[164:167], v[60:63]
	v_mfma_f32_16x16x32_bf16 v[56:59], v[140:143], v[164:167], v[56:59]
	v_mfma_f32_16x16x32_bf16 v[52:55], v[132:135], v[172:175], v[52:55]
	v_mfma_f32_16x16x32_bf16 v[44:47], v[140:143], v[172:175], v[44:47]
	v_mfma_f32_16x16x32_bf16 v[36:39], v[132:135], v[180:183], v[36:39]
	v_mfma_f32_16x16x32_bf16 v[28:31], v[140:143], v[180:183], v[28:31]
	v_mfma_f32_16x16x32_bf16 v[20:23], v[132:135], v[188:191], v[20:23]
	v_mfma_f32_16x16x32_bf16 v[12:15], v[140:143], v[188:191], v[12:15]
	s_setprio 0
	s_setprio 1
	v_mfma_f32_16x16x32_bf16 v[48:51], v[144:147], v[160:163], 0
	v_mfma_f32_16x16x32_bf16 v[40:43], v[152:155], v[160:163], 0
	v_mfma_f32_16x16x32_bf16 v[32:35], v[144:147], v[168:171], 0
	v_mfma_f32_16x16x32_bf16 v[24:27], v[152:155], v[168:171], 0
	v_mfma_f32_16x16x32_bf16 v[16:19], v[144:147], v[176:179], 0
	v_mfma_f32_16x16x32_bf16 v[8:11], v[152:155], v[176:179], 0
	v_mfma_f32_16x16x32_bf16 v[4:7], v[144:147], v[184:187], 0
	v_mfma_f32_16x16x32_bf16 v[0:3], v[152:155], v[184:187], 0
	v_mfma_f32_16x16x32_bf16 v[48:51], v[148:151], v[164:167], v[48:51]
	v_mfma_f32_16x16x32_bf16 v[40:43], v[156:159], v[164:167], v[40:43]
	v_mfma_f32_16x16x32_bf16 v[32:35], v[148:151], v[172:175], v[32:35]
	v_mfma_f32_16x16x32_bf16 v[24:27], v[156:159], v[172:175], v[24:27]
	v_mfma_f32_16x16x32_bf16 v[16:19], v[148:151], v[180:183], v[16:19]
	v_mfma_f32_16x16x32_bf16 v[8:11], v[156:159], v[180:183], v[8:11]
	v_mfma_f32_16x16x32_bf16 v[4:7], v[148:151], v[188:191], v[4:7]
	v_mfma_f32_16x16x32_bf16 v[0:3], v[156:159], v[188:191], v[0:3]
	s_setprio 0
	s_barrier
	s_add_i32 s94, 0, 0x18000
	s_add_i32 s95, 0, 0x1c000
	v_add_u32_e32 v140, s94, v240
	v_add_u32_e32 v156, s95, v240
	ds_read_b128 v[128:131], v140
	ds_read_b128 v[132:135], v140 offset:1024
	ds_read_b128 v[136:139], v140 offset:2048
	ds_read_b128 v[140:143], v140 offset:3072
	ds_read_b128 v[144:147], v156
	ds_read_b128 v[148:151], v156 offset:1024
	ds_read_b128 v[152:155], v156 offset:2048
	ds_read_b128 v[156:159], v156 offset:3072
	s_add_u32 s54, s54, 0x40000
	s_addc_u32 s55, s55, 0
	s_mov_b32 m0, s56
	v_lshl_add_u64 v[212:213], s[54:55], 0, v[192:193]
	ds_read_b128 v[160:163], v244 offset:32768
	ds_read_b128 v[164:167], v244 offset:33792
	ds_read_b128 v[168:171], v244 offset:34816
	ds_read_b128 v[172:175], v244 offset:35840
	ds_read_b128 v[176:179], v244 offset:36864
	ds_read_b128 v[180:183], v244 offset:37888
	ds_read_b128 v[184:187], v244 offset:38912
	ds_read_b128 v[188:191], v244 offset:39936
	global_load_lds_dwordx4 v[212:213], off
	v_lshl_add_u64 v[212:213], s[54:55], 0, v[196:197]
	s_mov_b32 m0, s57
	s_nop 0
	global_load_lds_dwordx4 v[212:213], off
	s_waitcnt vmcnt(8)
	s_waitcnt lgkmcnt(0)
	s_barrier
; #define PG8_STAGE(bufoff, gbase, voff) do { _Pragma("unroll") for (int _i = 0; _i < 2; ++_i) \
;         __builtin_amdgcn_global_load_lds((const unsigned*)((const char*)(gbase) + (voff)[_i]), (PG8_LAS unsigned*)(lds + (bufoff) + ldsw + _i * 8192), 16, 0, 0); } while (0)
; #define PG8_LDA(dst, b, h) do { _Pragma("unroll") for (int m = 0; m < 4; ++m) _Pragma("unroll") for (int k = 0; k < 2; ++k) dst[m][k] = *(const PG8_LAS bf16x8*)(lds + PG8_SA(b, h) + aoff + m * 2048 + k * 1024); } while (0)
; #define PG8_MMA(ai, bj, At, Bt) do { __builtin_amdgcn_s_setprio(1); _Pragma("unroll") for (int m = 0; m < 4; ++m) _Pragma("unroll") for (int n = 0; n < 2; ++n) _Pragma("unroll") for (int k = 0; k < 2; ++k) \
;         acc[ai][bj][m][n] = __builtin_amdgcn_mfma_f32_16x16x32_bf16(Bt[n][k], At[m][k], acc[ai][bj][m][n], 0, 0, 0); __builtin_amdgcn_s_setprio(0); } while (0)
; #define PG8_WAIT_V(n) asm volatile("s_waitcnt vmcnt(" #n ")" ::: "memory")
; #define PG8_WAIT_L(n) asm volatile("s_waitcnt lgkmcnt(" #n ")" ::: "memory")
; #define PG8_BAR __builtin_amdgcn_s_barrier()
; #define PG8_SCHED __builtin_amdgcn_sched_barrier(0)
; template <class Epi, class Sched, bool ALIGN_EPI = false, bool SP2 = false>
; __device__ __forceinline__ void gemm_phase(PG8_LAS unsigned char* lds, const Gemm g, const Sched& S, const Epi& E) {
;     ...
;             PG8_WAIT_V(8); PG8_WAIT_L(0); PG8_BAR; PG8_MMA(0, 0, At, B0); if (whole) PG8_MMA(0, 1, At, B1); PG8_BAR; PG8_SCHED;
;             PG8_LDA(At, 1, 1); PG8_STAGE(PG8_SB(1, 0), b3, voffB); PG8_STAGE(PG8_SB(1, 1), b3 + hstepB, voffB); PG8_STAGE(PG8_SA(1, 0), a3, voffA);
;             PG8_WAIT_V(8); PG8_WAIT_L(0); PG8_BAR; if (whole) { PG8_MMA(1, 0, At, B0); PG8_MMA(1, 1, At, B1); } PG8_BAR; PG8_SCHED;
	s_setprio 1
	s_waitcnt lgkmcnt(0)
	v_mfma_f32_16x16x32_bf16 v[124:127], v[128:131], v[160:163], v[124:127]
	v_mfma_f32_16x16x32_bf16 v[120:123], v[136:139], v[160:163], v[120:123]
	v_mfma_f32_16x16x32_bf16 v[116:119], v[128:131], v[168:171], v[116:119]
	v_mfma_f32_16x16x32_bf16 v[108:111], v[136:139], v[168:171], v[108:111]
	v_mfma_f32_16x16x32_bf16 v[100:103], v[128:131], v[176:179], v[100:103]
	v_mfma_f32_16x16x32_bf16 v[92:95], v[136:139], v[176:179], v[92:95]
	v_mfma_f32_16x16x32_bf16 v[84:87], v[128:131], v[184:187], v[84:87]
	v_mfma_f32_16x16x32_bf16 v[76:79], v[136:139], v[184:187], v[76:79]
	v_mfma_f32_16x16x32_bf16 v[124:127], v[132:135], v[164:167], v[124:127]
	v_mfma_f32_16x16x32_bf16 v[120:123], v[140:143], v[164:167], v[120:123]
	v_mfma_f32_16x16x32_bf16 v[116:119], v[132:135], v[172:175], v[116:119]
	v_mfma_f32_16x16x32_bf16 v[108:111], v[140:143], v[172:175], v[108:111]
	v_mfma_f32_16x16x32_bf16 v[100:103], v[132:135], v[180:183], v[100:103]
	v_mfma_f32_16x16x32_bf16 v[92:95], v[140:143], v[180:183], v[92:95]
	v_mfma_f32_16x16x32_bf16 v[84:87], v[132:135], v[188:191], v[84:87]
	v_mfma_f32_16x16x32_bf16 v[76:79], v[140:143], v[188:191], v[76:79]
	s_setprio 0
	s_setprio 1
	v_mfma_f32_16x16x32_bf16 v[112:115], v[144:147], v[160:163], v[112:115]
	v_mfma_f32_16x16x32_bf16 v[104:107], v[152:155], v[160:163], v[104:107]
	v_mfma_f32_16x16x32_bf16 v[96:99], v[144:147], v[168:171], v[96:99]
	v_mfma_f32_16x16x32_bf16 v[88:91], v[152:155], v[168:171], v[88:91]
	v_mfma_f32_16x16x32_bf16 v[80:83], v[144:147], v[176:179], v[80:83]
	v_mfma_f32_16x16x32_bf16 v[72:75], v[152:155], v[176:179], v[72:75]
	v_mfma_f32_16x16x32_bf16 v[68:71], v[144:147], v[184:187], v[68:71]
	v_mfma_f32_16x16x32_bf16 v[64:67], v[152:155], v[184:187], v[64:67]
	v_mfma_f32_16x16x32_bf16 v[112:115], v[148:151], v[164:167], v[112:115]
	v_mfma_f32_16x16x32_bf16 v[104:107], v[156:159], v[164:167], v[104:107]
	v_mfma_f32_16x16x32_bf16 v[96:99], v[148:151], v[172:175], v[96:99]
	v_mfma_f32_16x16x32_bf16 v[88:91], v[156:159], v[172:175], v[88:91]
	v_mfma_f32_16x16x32_bf16 v[80:83], v[148:151], v[180:183], v[80:83]
	v_mfma_f32_16x16x32_bf16 v[72:75], v[156:159], v[180:183], v[72:75]
	v_mfma_f32_16x16x32_bf16 v[68:71], v[148:151], v[188:191], v[68:71]
	v_mfma_f32_16x16x32_bf16 v[64:67], v[156:159], v[188:191], v[64:67]
	s_setprio 0
	s_barrier
	s_add_i32 s54, s94, s8
	v_lshl_add_u64 v[204:205], v[204:205], 0, s[20:21]
	s_mov_b32 m0, s54
	ds_read_b128 v[160:163], v244 offset:49152
	ds_read_b128 v[164:167], v244 offset:50176
	ds_read_b128 v[168:171], v244 offset:51200
	ds_read_b128 v[172:175], v244 offset:52224
	ds_read_b128 v[176:179], v244 offset:53248
	ds_read_b128 v[180:183], v244 offset:54272
	ds_read_b128 v[184:187], v244 offset:55296
	ds_read_b128 v[188:191], v244 offset:56320
	global_load_lds_dwordx4 v[204:205], off
	s_add_i32 m0, s54, 0x2000
	s_add_u32 s6, s6, 0x40080
	v_lshl_add_u64 v[204:205], v[206:207], 0, s[20:21]
	s_addc_u32 s7, s7, 0
	s_add_i32 s54, s95, s8
	global_load_lds_dwordx4 v[204:205], off
	v_lshl_add_u64 v[204:205], s[6:7], 0, v[194:195]
	s_mov_b32 m0, s54
	s_nop 0
	global_load_lds_dwordx4 v[204:205], off
	v_lshl_add_u64 v[204:205], s[6:7], 0, v[198:199]
	s_add_i32 m0, s54, 0x2000
	s_nop 0
	global_load_lds_dwordx4 v[204:205], off
	v_lshl_add_u64 v[204:205], v[208:209], 0, s[20:21]
	s_mov_b32 m0, s58
	s_nop 0
	global_load_lds_dwordx4 v[204:205], off
	v_lshl_add_u64 v[204:205], v[210:211], 0, s[20:21]
	s_mov_b32 m0, s59
	s_nop 0
	global_load_lds_dwordx4 v[204:205], off
	s_waitcnt vmcnt(8)
	s_waitcnt lgkmcnt(0)
	s_barrier
	s_setprio 1
	s_waitcnt lgkmcnt(0)
	v_mfma_f32_16x16x32_bf16 v[60:63], v[128:131], v[160:163], v[60:63]
	v_mfma_f32_16x16x32_bf16 v[56:59], v[136:139], v[160:163], v[56:59]
	v_mfma_f32_16x16x32_bf16 v[52:55], v[128:131], v[168:171], v[52:55]
	v_mfma_f32_16x16x32_bf16 v[44:47], v[136:139], v[168:171], v[44:47]
	v_mfma_f32_16x16x32_bf16 v[36:39], v[128:131], v[176:179], v[36:39]
	v_mfma_f32_16x16x32_bf16 v[28:31], v[136:139], v[176:179], v[28:31]
	v_mfma_f32_16x16x32_bf16 v[20:23], v[128:131], v[184:187], v[20:23]
	v_mfma_f32_16x16x32_bf16 v[12:15], v[136:139], v[184:187], v[12:15]
	v_mfma_f32_16x16x32_bf16 v[60:63], v[132:135], v[164:167], v[60:63]
	v_mfma_f32_16x16x32_bf16 v[56:59], v[140:143], v[164:167], v[56:59]
	v_mfma_f32_16x16x32_bf16 v[52:55], v[132:135], v[172:175], v[52:55]
	v_mfma_f32_16x16x32_bf16 v[44:47], v[140:143], v[172:175], v[44:47]
	v_mfma_f32_16x16x32_bf16 v[36:39], v[132:135], v[180:183], v[36:39]
	v_mfma_f32_16x16x32_bf16 v[28:31], v[140:143], v[180:183], v[28:31]
	v_mfma_f32_16x16x32_bf16 v[20:23], v[132:135], v[188:191], v[20:23]
	v_mfma_f32_16x16x32_bf16 v[12:15], v[140:143], v[188:191], v[12:15]
	s_setprio 0
	s_setprio 1
	v_mfma_f32_16x16x32_bf16 v[48:51], v[144:147], v[160:163], v[48:51]
	v_mfma_f32_16x16x32_bf16 v[40:43], v[152:155], v[160:163], v[40:43]
	v_mfma_f32_16x16x32_bf16 v[32:35], v[144:147], v[168:171], v[32:35]
	v_mfma_f32_16x16x32_bf16 v[24:27], v[152:155], v[168:171], v[24:27]
	v_mfma_f32_16x16x32_bf16 v[16:19], v[144:147], v[176:179], v[16:19]
	v_mfma_f32_16x16x32_bf16 v[8:11], v[152:155], v[176:179], v[8:11]
	v_mfma_f32_16x16x32_bf16 v[4:7], v[144:147], v[184:187], v[4:7]
	v_mfma_f32_16x16x32_bf16 v[0:3], v[152:155], v[184:187], v[0:3]
	v_mfma_f32_16x16x32_bf16 v[48:51], v[148:151], v[164:167], v[48:51]
	v_mfma_f32_16x16x32_bf16 v[40:43], v[156:159], v[164:167], v[40:43]
	v_mfma_f32_16x16x32_bf16 v[32:35], v[148:151], v[172:175], v[32:35]
	v_mfma_f32_16x16x32_bf16 v[24:27], v[156:159], v[172:175], v[24:27]
	v_mfma_f32_16x16x32_bf16 v[16:19], v[148:151], v[180:183], v[16:19]
	v_mfma_f32_16x16x32_bf16 v[8:11], v[156:159], v[180:183], v[8:11]
	v_mfma_f32_16x16x32_bf16 v[4:7], v[148:151], v[188:191], v[4:7]
	v_mfma_f32_16x16x32_bf16 v[0:3], v[156:159], v[188:191], v[0:3]
	s_setprio 0
	s_barrier
	s_add_u32 s52, s52, 0x100
	s_addc_u32 s53, s53, 0
	s_add_u32 s91, s91, 0x100
	s_addc_u32 s92, s92, 0
	s_cmp_ge_u32 s93, s9
	s_mov_b32 s6, s93
	s_cbranch_scc0 .LBB0_1080
	s_branch .Lpeel_exit_out1

; #define PG8_BAR __builtin_amdgcn_s_barrier()
;     __device__ __forceinline__ void operator()(const f32x4 (&acc)[2][2][4][2], const Unit& u, int wr, int wc, int fr, int fq) const {
;     ...
;         u32x4 xo[2][4][2];
; #pragma unroll
;         for (int ai = 0; ai < 2; ++ai)
; #pragma unroll
;             for (int m = 0; m < 4; ++m)
; #pragma unroll
;                 for (int bj = 0; bj < 2; ++bj) xo[ai][m][bj] = *(const u32x4*)(xb + (size_t)(row0 + ai * HALF + m * 16) * 1024 + col0 + bj * HALF);
; #pragma unroll
;         for (int ai = 0; ai < 2; ++ai)
; #pragma unroll
;             for (int m = 0; m < 4; ++m) {
;                 const int row = row0 + ai * HALF + m * 16;
;                 bf16_t* xr = xb + (size_t)row * 1024 + col0;
;                 float part_ss = 0.f;
; #pragma unroll
;                 for (int bj = 0; bj < 2; ++bj) {
;                     const u32x4 o = xo[ai][m][bj];
;                     f32x4 v0 = acc[ai][bj][m][0], v1 = acc[ai][bj][m][1];
;                     v0[0] += __uint_as_float(o.x << 16); v0[1] += __uint_as_float(o.x & 0xffff0000u); v0[2] += __uint_as_float(o.y << 16); v0[3] += __uint_as_float(o.y & 0xffff0000u);
;                     v1[0] += __uint_as_float(o.z << 16); v1[1] += __uint_as_float(o.z & 0xffff0000u); v1[2] += __uint_as_float(o.w << 16); v1[3] += __uint_as_float(o.w & 0xffff0000u);
;                     if (xout) { float* xo = xout + (size_t)row * 1024 + col0 + bj * HALF; *(f32x4*)xo = v0; *(f32x4*)(xo + 4) = v1; }
;                     else { u32x4 w; w.x = cvt_pk_bf16(v0[0], v0[1]); w.y = cvt_pk_bf16(v0[2], v0[3]); w.z = cvt_pk_bf16(v1[0], v1[1]); w.w = cvt_pk_bf16(v1[2], v1[3]); *(u32x4*)(xr + bj * HALF) = w; }
;                     part_ss += (v0[0] * v0[0] + v0[1] * v0[1]) + (v0[2] * v0[2] + v0[3] * v0[3]) + (v1[0] * v1[0] + v1[1] * v1[1]) + (v1[2] * v1[2] + v1[3] * v1[3]);
;                 }
;                 part_ss += __shfl_xor(part_ss, 16); part_ss += __shfl_xor(part_ss, 32);
;                 if (fq == 0) atomicAdd(ss + row, part_ss);
;             }
; template <class Epi, class Sched, bool ALIGN_EPI = false, bool SP2 = false>
; __device__ __forceinline__ void gemm_phase(PG8_LAS unsigned char* lds, const Gemm g, const Sched& S, const Epi& E) {
;     ...
;         if constexpr (ALIGN_EPI) { if (wr == 0) PG8_BAR; }
.Lpeel_exit_out1:
	s_and_b64 vcc, exec, s[24:25]
	s_cbranch_vccz .LBB0_1083
	s_barrier
.LBB0_1083:
	v_lshl_add_u32 v206, s48, 8, v239
	v_lshl_or_b32 v204, s50, 8, v241
	s_mov_b64 s[6:7], -1
	s_cmp_lt_i32 s18, 0
	v_ashrrev_i32_e32 v205, 31, v204
	v_ashrrev_i32_e32 v207, 31, v206
	s_cbranch_scc0 .LBB0_1102
	v_lshlrev_b64 v[236:237], 1, v[204:205]
	v_lshl_add_u64 v[128:129], s[30:31], 0, v[236:237]
	v_lshlrev_b64 v[246:247], 11, v[206:207]
	v_lshl_add_u64 v[130:131], v[128:129], 0, v[246:247]
	global_load_dwordx4 v[188:191], v[130:131], off
	global_load_dwordx4 v[184:187], v[130:131], off offset:256
	v_or_b32_e32 v230, 16, v206
	v_ashrrev_i32_e32 v231, 31, v230
	v_or_b32_e32 v226, 32, v206
	v_lshlrev_b64 v[234:235], 11, v[230:231]
	v_ashrrev_i32_e32 v227, 31, v226
	v_or_b32_e32 v222, 48, v206
	v_lshl_add_u64 v[130:131], v[128:129], 0, v[234:235]
	v_lshlrev_b64 v[232:233], 11, v[226:227]
	v_ashrrev_i32_e32 v223, 31, v222
	v_add_u32_e32 v218, 0x80, v206
	global_load_dwordx4 v[180:183], v[130:131], off
	global_load_dwordx4 v[176:179], v[130:131], off offset:256
	v_lshl_add_u64 v[130:131], v[128:129], 0, v[232:233]
	v_lshlrev_b64 v[228:229], 11, v[222:223]
	v_ashrrev_i32_e32 v219, 31, v218
	v_add_u32_e32 v214, 0x90, v206
	global_load_dwordx4 v[172:175], v[130:131], off
	global_load_dwordx4 v[168:171], v[130:131], off offset:256
	v_lshl_add_u64 v[130:131], v[128:129], 0, v[228:229]
	v_lshlrev_b64 v[224:225], 11, v[218:219]
	v_ashrrev_i32_e32 v215, 31, v214
	v_add_u32_e32 v210, 0xa0, v206
	v_add_u32_e32 v208, 0xb0, v206
	global_load_dwordx4 v[164:167], v[130:131], off
	global_load_dwordx4 v[160:163], v[130:131], off offset:256
	v_lshl_add_u64 v[130:131], v[128:129], 0, v[224:225]
	v_lshlrev_b64 v[220:221], 11, v[214:215]
	v_ashrrev_i32_e32 v211, 31, v210
	v_ashrrev_i32_e32 v209, 31, v208
	global_load_dwordx4 v[156:159], v[130:131], off
	global_load_dwordx4 v[152:155], v[130:131], off offset:256
	v_lshl_add_u64 v[130:131], v[128:129], 0, v[220:221]
	v_lshlrev_b64 v[216:217], 11, v[210:211]
	v_lshlrev_b64 v[212:213], 11, v[208:209]
	global_load_dwordx4 v[148:151], v[130:131], off
	global_load_dwordx4 v[144:147], v[130:131], off offset:256
	v_lshl_add_u64 v[130:131], v[128:129], 0, v[216:217]
	v_lshl_add_u64 v[128:129], v[128:129], 0, v[212:213]
	global_load_dwordx4 v[140:143], v[130:131], off
	global_load_dwordx4 v[136:139], v[130:131], off offset:256
	global_load_dwordx4 v[132:135], v[128:129], off
	s_nop 0
	global_load_dwordx4 v[128:131], v[128:129], off offset:256
	v_lshl_add_u64 v[246:247], s[30:31], 0, v[246:247]
	v_lshl_add_u64 v[236:237], v[246:247], 0, v[236:237]
	s_waitcnt vmcnt(0)
	v_lshlrev_b32_e32 v246, 16, v188
	v_and_b32_e32 v188, 0xffff0000, v188
	v_add_f32_e32 v247, v125, v188
	v_lshlrev_b32_e32 v188, 16, v189
	v_add_f32_e32 v248, v126, v188
	v_and_b32_e32 v188, 0xffff0000, v189
	v_add_f32_e32 v249, v127, v188
	v_lshlrev_b32_e32 v188, 16, v190
	v_add_f32_e32 v250, v120, v188
	v_and_b32_e32 v188, 0xffff0000, v190
	v_add_f32_e32 v251, v121, v188
	v_lshlrev_b32_e32 v188, 16, v191
	v_add_f32_e32 v252, v122, v188
	v_and_b32_e32 v188, 0xffff0000, v191
	v_add_f32_e32 v246, v124, v246
	v_add_f32_e32 v253, v123, v188
	v_cvt_pk_bf16_f32 v188, v246, v247
	v_cvt_pk_bf16_f32 v189, v248, v249
	v_cvt_pk_bf16_f32 v190, v250, v251
	v_cvt_pk_bf16_f32 v191, v252, v253
	global_store_dwordx4 v[236:237], v[188:191], off sc1
	s_nop 1
	v_mul_f32_e32 v188, v247, v247
	v_mul_f32_e32 v189, v249, v249
	v_fmac_f32_e32 v188, v246, v246
	v_fmac_f32_e32 v189, v248, v248
	v_add_f32_e32 v188, v188, v189
	v_mul_f32_e32 v189, v251, v251
	v_fmac_f32_e32 v189, v250, v250
	v_add_f32_e32 v188, v189, v188
	v_mul_f32_e32 v189, v253, v253
	v_fmac_f32_e32 v189, v252, v252
	v_add_f32_e32 v188, v189, v188
	v_lshlrev_b32_e32 v189, 16, v184
	v_and_b32_e32 v184, 0xffff0000, v184
	v_add_f32_e32 v190, v113, v184
	v_lshlrev_b32_e32 v184, 16, v185
	v_add_f32_e32 v191, v114, v184
	v_and_b32_e32 v184, 0xffff0000, v185
	v_add_f32_e32 v246, v115, v184
	v_lshlrev_b32_e32 v184, 16, v186
	v_add_f32_e32 v247, v104, v184
	v_and_b32_e32 v184, 0xffff0000, v186
	v_add_f32_e32 v248, v105, v184
	v_lshlrev_b32_e32 v184, 16, v187
	v_add_f32_e32 v249, v106, v184
	v_and_b32_e32 v184, 0xffff0000, v187
	v_add_f32_e32 v189, v112, v189
	v_add_f32_e32 v250, v107, v184
	v_cvt_pk_bf16_f32 v184, v189, v190
	v_cvt_pk_bf16_f32 v185, v191, v246
	v_cvt_pk_bf16_f32 v186, v247, v248
	v_cvt_pk_bf16_f32 v187, v249, v250
	global_store_dwordx4 v[236:237], v[184:187], off offset:256 sc1
	s_nop 1
	v_mul_f32_e32 v184, v190, v190
	v_mul_f32_e32 v185, v246, v246
	v_fmac_f32_e32 v184, v189, v189
	v_fmac_f32_e32 v185, v191, v191
	v_add_f32_e32 v184, v184, v185
	v_mul_f32_e32 v185, v248, v248
	v_fmac_f32_e32 v185, v247, v247
	v_add_f32_e32 v184, v185, v184
	v_mul_f32_e32 v185, v250, v250
	v_fmac_f32_e32 v185, v249, v249
	v_add_f32_e32 v184, v185, v184
	v_and_b32_e32 v186, 64, v245
	v_add_f32_e32 v185, v188, v184
	v_xor_b32_e32 v184, 16, v245
	v_add_u32_e32 v187, 64, v186
	v_cmp_lt_i32_e32 vcc, v184, v187
	s_nop 1
	v_cndmask_b32_e32 v184, v245, v184, vcc
	v_lshlrev_b32_e32 v184, 2, v184
	ds_bpermute_b32 v186, v184, v185
	s_waitcnt lgkmcnt(0)
	v_add_f32_e32 v186, v185, v186
	v_xor_b32_e32 v185, 32, v245
	v_cmp_lt_i32_e32 vcc, v185, v187
	s_nop 1
	v_cndmask_b32_e32 v185, v245, v185, vcc
	v_lshlrev_b32_e32 v185, 2, v185
	ds_bpermute_b32 v187, v185, v186
	s_and_saveexec_b64 s[6:7], s[2:3]
	s_cbranch_execz .LBB0_1086
	s_waitcnt lgkmcnt(0)
	v_add_f32_e32 v188, v186, v187
	v_lshl_add_u64 v[186:187], v[206:207], 2, s[4:5]
	global_atomic_add_f32 v[186:187], v188, off
; __device__ __forceinline__ unsigned cvt_pk_bf16(float lo, float hi) { unsigned r; asm volatile("v_cvt_pk_bf16_f32 %0, %1, %2" : "=v"(r) : "v"(lo), "v"(hi)); return r; }
;     __device__ __forceinline__ void operator()(const f32x4 (&acc)[2][2][4][2], const Unit& u, int wr, int wc, int fr, int fq) const {
;     ...
;         for (int ai = 0; ai < 2; ++ai)
; #pragma unroll
;             for (int m = 0; m < 4; ++m) {
;                 const int row = row0 + ai * HALF + m * 16;
;                 bf16_t* xr = xb + (size_t)row * 1024 + col0;
;                 float part_ss = 0.f;
; #pragma unroll
;                 for (int bj = 0; bj < 2; ++bj) {
;                     const u32x4 o = xo[ai][m][bj];
;                     f32x4 v0 = acc[ai][bj][m][0], v1 = acc[ai][bj][m][1];
;                     v0[0] += __uint_as_float(o.x << 16); v0[1] += __uint_as_float(o.x & 0xffff0000u); v0[2] += __uint_as_float(o.y << 16); v0[3] += __uint_as_float(o.y & 0xffff0000u);
;                     v1[0] += __uint_as_float(o.z << 16); v1[1] += __uint_as_float(o.z & 0xffff0000u); v1[2] += __uint_as_float(o.w << 16); v1[3] += __uint_as_float(o.w & 0xffff0000u);
;                     if (xout) { float* xo = xout + (size_t)row * 1024 + col0 + bj * HALF; *(f32x4*)xo = v0; *(f32x4*)(xo + 4) = v1; }
;                     else { u32x4 w; w.x = cvt_pk_bf16(v0[0], v0[1]); w.y = cvt_pk_bf16(v0[2], v0[3]); w.z = cvt_pk_bf16(v1[0], v1[1]); w.w = cvt_pk_bf16(v1[2], v1[3]); *(u32x4*)(xr + bj * HALF) = w; }
;                     part_ss += (v0[0] * v0[0] + v0[1] * v0[1]) + (v0[2] * v0[2] + v0[3] * v0[3]) + (v1[0] * v1[0] + v1[1] * v1[1]) + (v1[2] * v1[2] + v1[3] * v1[3]);
;                 }
;                 part_ss += __shfl_xor(part_ss, 16); part_ss += __shfl_xor(part_ss, 32);
;                 if (fq == 0) atomicAdd(ss + row, part_ss);
.LBB0_1086:
	s_or_b64 exec, exec, s[6:7]
	v_lshlrev_b32_e32 v188, 16, v180
	v_and_b32_e32 v180, 0xffff0000, v180
	v_add_f32_e32 v189, v117, v180
	v_lshlrev_b32_e32 v180, 16, v181
	v_add_f32_e32 v190, v118, v180
	v_and_b32_e32 v180, 0xffff0000, v181
	v_add_f32_e32 v191, v119, v180
	v_lshlrev_b32_e32 v180, 16, v182
	s_waitcnt lgkmcnt(0)
	v_lshl_add_u64 v[186:187], s[30:31], 0, v[234:235]
	v_add_f32_e32 v234, v108, v180
	v_and_b32_e32 v180, 0xffff0000, v182
	v_add_f32_e32 v182, v109, v180
	v_lshlrev_b32_e32 v180, 16, v183
	v_add_f32_e32 v235, v110, v180
	v_and_b32_e32 v180, 0xffff0000, v183
	v_add_f32_e32 v188, v116, v188
	v_add_f32_e32 v183, v111, v180
	v_cvt_pk_bf16_f32 v180, v188, v189
	v_mul_f32_e32 v189, v189, v189
	v_fmac_f32_e32 v189, v188, v188
	v_mul_f32_e32 v188, v191, v191
	v_fmac_f32_e32 v188, v190, v190
	v_add_f32_e32 v188, v189, v188
	v_mul_f32_e32 v189, v182, v182
	v_cvt_pk_bf16_f32 v181, v190, v191
	v_fmac_f32_e32 v189, v234, v234
	v_lshlrev_b32_e32 v190, 16, v177
	v_and_b32_e32 v177, 0xffff0000, v177
	v_add_f32_e32 v188, v189, v188
	v_mul_f32_e32 v189, v183, v183
	v_add_f32_e32 v191, v99, v177
	v_lshlrev_b32_e32 v177, 16, v178
	v_fmac_f32_e32 v189, v235, v235
	v_add_f32_e32 v236, v88, v177
	v_and_b32_e32 v177, 0xffff0000, v178
	v_add_f32_e32 v188, v189, v188
	v_lshlrev_b32_e32 v189, 16, v176
	v_and_b32_e32 v176, 0xffff0000, v176
	v_add_f32_e32 v237, v89, v177
	v_lshlrev_b32_e32 v177, 16, v179
	v_add_f32_e32 v176, v97, v176
	v_add_f32_e32 v246, v90, v177
	v_and_b32_e32 v177, 0xffff0000, v179
	v_add_f32_e32 v189, v96, v189
	v_add_f32_e32 v190, v98, v190
	v_add_f32_e32 v247, v91, v177
	v_mul_f32_e32 v177, v176, v176
	v_mul_f32_e32 v178, v191, v191
	v_fmac_f32_e32 v177, v189, v189
	v_fmac_f32_e32 v178, v190, v190
	v_add_f32_e32 v177, v177, v178
	v_mul_f32_e32 v178, v237, v237
	v_fmac_f32_e32 v178, v236, v236
	v_add_f32_e32 v177, v178, v177
	v_mul_f32_e32 v178, v247, v247
	v_fmac_f32_e32 v178, v246, v246
	v_add_f32_e32 v177, v178, v177
	v_add_f32_e32 v177, v188, v177
	ds_bpermute_b32 v179, v184, v177
	v_lshl_add_u64 v[186:187], v[204:205], 1, v[186:187]
	v_cvt_pk_bf16_f32 v182, v234, v182
	v_cvt_pk_bf16_f32 v183, v235, v183
	global_store_dwordx4 v[186:187], v[180:183], off sc1
	v_cvt_pk_bf16_f32 v178, v189, v176
	s_waitcnt lgkmcnt(0)
	v_add_f32_e32 v176, v177, v179
	ds_bpermute_b32 v177, v185, v176
	v_cvt_pk_bf16_f32 v179, v190, v191
	v_cvt_pk_bf16_f32 v180, v236, v237
	v_cvt_pk_bf16_f32 v181, v246, v247
	global_store_dwordx4 v[186:187], v[178:181], off offset:256 sc1
	s_and_saveexec_b64 s[6:7], s[2:3]
	s_cbranch_execz .LBB0_1088
	s_waitcnt lgkmcnt(0)
	v_add_f32_e32 v178, v176, v177
	v_lshl_add_u64 v[176:177], v[230:231], 2, s[4:5]
	global_atomic_add_f32 v[176:177], v178, off
.LBB0_1088:
	s_or_b64 exec, exec, s[6:7]
	v_lshlrev_b32_e32 v178, 16, v172
	v_and_b32_e32 v172, 0xffff0000, v172
	v_add_f32_e32 v179, v101, v172
	v_lshlrev_b32_e32 v172, 16, v173
	v_add_f32_e32 v180, v102, v172
	v_and_b32_e32 v172, 0xffff0000, v173
	v_add_f32_e32 v181, v103, v172
	v_lshlrev_b32_e32 v172, 16, v174
	v_add_f32_e32 v182, v92, v172
	v_and_b32_e32 v172, 0xffff0000, v174
	v_add_f32_e32 v174, v93, v172
	v_lshlrev_b32_e32 v172, 16, v175
	v_add_f32_e32 v183, v94, v172
	v_and_b32_e32 v172, 0xffff0000, v175
	v_add_f32_e32 v178, v100, v178
	v_add_f32_e32 v175, v95, v172
	v_cvt_pk_bf16_f32 v172, v178, v179
	v_mul_f32_e32 v179, v179, v179
	v_fmac_f32_e32 v179, v178, v178
	v_mul_f32_e32 v178, v181, v181
	v_fmac_f32_e32 v178, v180, v180
	v_add_f32_e32 v178, v179, v178
	v_mul_f32_e32 v179, v174, v174
	v_cvt_pk_bf16_f32 v173, v180, v181
	v_fmac_f32_e32 v179, v182, v182
	v_lshlrev_b32_e32 v180, 16, v169
	v_and_b32_e32 v169, 0xffff0000, v169
	v_add_f32_e32 v178, v179, v178
	v_mul_f32_e32 v179, v175, v175
	v_add_f32_e32 v181, v83, v169
	v_lshlrev_b32_e32 v169, 16, v170
	v_fmac_f32_e32 v179, v183, v183
	v_add_f32_e32 v186, v72, v169
	v_and_b32_e32 v169, 0xffff0000, v170
	v_add_f32_e32 v178, v179, v178
	v_lshlrev_b32_e32 v179, 16, v168
	v_and_b32_e32 v168, 0xffff0000, v168
	v_add_f32_e32 v187, v73, v169
	v_lshlrev_b32_e32 v169, 16, v171
	v_add_f32_e32 v168, v81, v168
	v_add_f32_e32 v188, v74, v169
	v_and_b32_e32 v169, 0xffff0000, v171
	v_add_f32_e32 v179, v80, v179
	v_add_f32_e32 v180, v82, v180
	v_add_f32_e32 v189, v75, v169
	v_mul_f32_e32 v169, v168, v168
	v_mul_f32_e32 v170, v181, v181
	v_fmac_f32_e32 v169, v179, v179
	v_fmac_f32_e32 v170, v180, v180
	v_add_f32_e32 v169, v169, v170
	v_mul_f32_e32 v170, v187, v187
	v_fmac_f32_e32 v170, v186, v186
	v_add_f32_e32 v169, v170, v169
	v_mul_f32_e32 v170, v189, v189
	v_fmac_f32_e32 v170, v188, v188
	v_add_f32_e32 v169, v170, v169
	v_add_f32_e32 v169, v178, v169
	ds_bpermute_b32 v171, v184, v169
	s_waitcnt lgkmcnt(1)
	v_lshl_add_u64 v[176:177], s[30:31], 0, v[232:233]
	v_lshl_add_u64 v[176:177], v[204:205], 1, v[176:177]
	v_cvt_pk_bf16_f32 v174, v182, v174
	v_cvt_pk_bf16_f32 v175, v183, v175
	global_store_dwordx4 v[176:177], v[172:175], off sc1
	v_cvt_pk_bf16_f32 v170, v179, v168
	s_waitcnt lgkmcnt(0)
	v_add_f32_e32 v168, v169, v171
	ds_bpermute_b32 v169, v185, v168
	v_cvt_pk_bf16_f32 v171, v180, v181
	v_cvt_pk_bf16_f32 v172, v186, v187
	v_cvt_pk_bf16_f32 v173, v188, v189
	global_store_dwordx4 v[176:177], v[170:173], off offset:256 sc1
	s_and_saveexec_b64 s[6:7], s[2:3]
	s_cbranch_execz .LBB0_1090
	s_waitcnt lgkmcnt(0)
	v_add_f32_e32 v170, v168, v169
	v_lshl_add_u64 v[168:169], v[226:227], 2, s[4:5]
	global_atomic_add_f32 v[168:169], v170, off
; __device__ __forceinline__ unsigned cvt_pk_bf16(float lo, float hi) { unsigned r; asm volatile("v_cvt_pk_bf16_f32 %0, %1, %2" : "=v"(r) : "v"(lo), "v"(hi)); return r; }
;     __device__ __forceinline__ void operator()(const f32x4 (&acc)[2][2][4][2], const Unit& u, int wr, int wc, int fr, int fq) const {
;     ...
;         for (int ai = 0; ai < 2; ++ai)
; #pragma unroll
;             for (int m = 0; m < 4; ++m) {
;                 const int row = row0 + ai * HALF + m * 16;
;                 bf16_t* xr = xb + (size_t)row * 1024 + col0;
;                 float part_ss = 0.f;
; #pragma unroll
;                 for (int bj = 0; bj < 2; ++bj) {
;                     const u32x4 o = xo[ai][m][bj];
;                     f32x4 v0 = acc[ai][bj][m][0], v1 = acc[ai][bj][m][1];
;                     v0[0] += __uint_as_float(o.x << 16); v0[1] += __uint_as_float(o.x & 0xffff0000u); v0[2] += __uint_as_float(o.y << 16); v0[3] += __uint_as_float(o.y & 0xffff0000u);
;                     v1[0] += __uint_as_float(o.z << 16); v1[1] += __uint_as_float(o.z & 0xffff0000u); v1[2] += __uint_as_float(o.w << 16); v1[3] += __uint_as_float(o.w & 0xffff0000u);
;                     if (xout) { float* xo = xout + (size_t)row * 1024 + col0 + bj * HALF; *(f32x4*)xo = v0; *(f32x4*)(xo + 4) = v1; }
;                     else { u32x4 w; w.x = cvt_pk_bf16(v0[0], v0[1]); w.y = cvt_pk_bf16(v0[2], v0[3]); w.z = cvt_pk_bf16(v1[0], v1[1]); w.w = cvt_pk_bf16(v1[2], v1[3]); *(u32x4*)(xr + bj * HALF) = w; }
;                     part_ss += (v0[0] * v0[0] + v0[1] * v0[1]) + (v0[2] * v0[2] + v0[3] * v0[3]) + (v1[0] * v1[0] + v1[1] * v1[1]) + (v1[2] * v1[2] + v1[3] * v1[3]);
;                 }
;                 part_ss += __shfl_xor(part_ss, 16); part_ss += __shfl_xor(part_ss, 32);
;                 if (fq == 0) atomicAdd(ss + row, part_ss);
.LBB0_1090:
	s_or_b64 exec, exec, s[6:7]
	v_lshlrev_b32_e32 v170, 16, v164
	v_and_b32_e32 v164, 0xffff0000, v164
	v_add_f32_e32 v171, v85, v164
	v_lshlrev_b32_e32 v164, 16, v165
	v_add_f32_e32 v172, v86, v164
	v_and_b32_e32 v164, 0xffff0000, v165
	v_add_f32_e32 v173, v87, v164
	v_lshlrev_b32_e32 v164, 16, v166
	v_add_f32_e32 v174, v76, v164
	v_and_b32_e32 v164, 0xffff0000, v166
	v_add_f32_e32 v166, v77, v164
	v_lshlrev_b32_e32 v164, 16, v167
	v_add_f32_e32 v175, v78, v164
	v_and_b32_e32 v164, 0xffff0000, v167
	v_add_f32_e32 v170, v84, v170
	v_add_f32_e32 v167, v79, v164
	v_cvt_pk_bf16_f32 v164, v170, v171
	v_mul_f32_e32 v171, v171, v171
	v_fmac_f32_e32 v171, v170, v170
	v_mul_f32_e32 v170, v173, v173
	v_fmac_f32_e32 v170, v172, v172
	v_add_f32_e32 v170, v171, v170
	v_mul_f32_e32 v171, v166, v166
	v_cvt_pk_bf16_f32 v165, v172, v173
	v_fmac_f32_e32 v171, v174, v174
	v_lshlrev_b32_e32 v172, 16, v161
	v_and_b32_e32 v161, 0xffff0000, v161
	v_add_f32_e32 v170, v171, v170
	v_mul_f32_e32 v171, v167, v167
	v_add_f32_e32 v173, v71, v161
	v_lshlrev_b32_e32 v161, 16, v162
	v_fmac_f32_e32 v171, v175, v175
	v_add_f32_e32 v176, v64, v161
	v_and_b32_e32 v161, 0xffff0000, v162
	v_add_f32_e32 v170, v171, v170
	v_lshlrev_b32_e32 v171, 16, v160
	v_and_b32_e32 v160, 0xffff0000, v160
	v_add_f32_e32 v177, v65, v161
	v_lshlrev_b32_e32 v161, 16, v163
	v_add_f32_e32 v160, v69, v160
	v_add_f32_e32 v178, v66, v161
	v_and_b32_e32 v161, 0xffff0000, v163
	v_add_f32_e32 v171, v68, v171
	v_add_f32_e32 v172, v70, v172
	v_add_f32_e32 v179, v67, v161
	v_mul_f32_e32 v161, v160, v160
	v_mul_f32_e32 v162, v173, v173
	v_fmac_f32_e32 v161, v171, v171
	v_fmac_f32_e32 v162, v172, v172
	v_add_f32_e32 v161, v161, v162
	v_mul_f32_e32 v162, v177, v177
	v_fmac_f32_e32 v162, v176, v176
	v_add_f32_e32 v161, v162, v161
	v_mul_f32_e32 v162, v179, v179
	v_fmac_f32_e32 v162, v178, v178
	v_add_f32_e32 v161, v162, v161
	v_add_f32_e32 v161, v170, v161
	ds_bpermute_b32 v163, v184, v161
	s_waitcnt lgkmcnt(1)
	v_lshl_add_u64 v[168:169], s[30:31], 0, v[228:229]
	v_lshl_add_u64 v[168:169], v[204:205], 1, v[168:169]
	v_cvt_pk_bf16_f32 v166, v174, v166
	v_cvt_pk_bf16_f32 v167, v175, v167
	global_store_dwordx4 v[168:169], v[164:167], off sc1
	v_cvt_pk_bf16_f32 v162, v171, v160
	s_waitcnt lgkmcnt(0)
	v_add_f32_e32 v160, v161, v163
	ds_bpermute_b32 v161, v185, v160
	v_cvt_pk_bf16_f32 v163, v172, v173
	v_cvt_pk_bf16_f32 v164, v176, v177
	v_cvt_pk_bf16_f32 v165, v178, v179
	global_store_dwordx4 v[168:169], v[162:165], off offset:256 sc1
	s_and_saveexec_b64 s[6:7], s[2:3]
	s_cbranch_execz .LBB0_1092
	s_waitcnt lgkmcnt(0)
	v_add_f32_e32 v162, v160, v161
	v_lshl_add_u64 v[160:161], v[222:223], 2, s[4:5]
	global_atomic_add_f32 v[160:161], v162, off
.LBB0_1092:
	s_or_b64 exec, exec, s[6:7]
	v_lshlrev_b32_e32 v162, 16, v156
	v_and_b32_e32 v156, 0xffff0000, v156
	v_add_f32_e32 v163, v61, v156
	v_lshlrev_b32_e32 v156, 16, v157
	v_add_f32_e32 v164, v62, v156
	v_and_b32_e32 v156, 0xffff0000, v157
	v_add_f32_e32 v165, v63, v156
	v_lshlrev_b32_e32 v156, 16, v158
	v_add_f32_e32 v166, v56, v156
	v_and_b32_e32 v156, 0xffff0000, v158
	v_add_f32_e32 v158, v57, v156
	v_lshlrev_b32_e32 v156, 16, v159
	v_add_f32_e32 v167, v58, v156
	v_and_b32_e32 v156, 0xffff0000, v159
	v_add_f32_e32 v162, v60, v162
	v_add_f32_e32 v159, v59, v156
	v_cvt_pk_bf16_f32 v156, v162, v163
	v_mul_f32_e32 v163, v163, v163
	v_fmac_f32_e32 v163, v162, v162
	v_mul_f32_e32 v162, v165, v165
	v_fmac_f32_e32 v162, v164, v164
	v_add_f32_e32 v162, v163, v162
	v_mul_f32_e32 v163, v158, v158
	v_cvt_pk_bf16_f32 v157, v164, v165
	v_fmac_f32_e32 v163, v166, v166
	v_lshlrev_b32_e32 v164, 16, v153
	v_and_b32_e32 v153, 0xffff0000, v153
	v_add_f32_e32 v162, v163, v162
	v_mul_f32_e32 v163, v159, v159
	v_add_f32_e32 v165, v51, v153
	v_lshlrev_b32_e32 v153, 16, v154
	v_fmac_f32_e32 v163, v167, v167
	v_add_f32_e32 v168, v40, v153
	v_and_b32_e32 v153, 0xffff0000, v154
	v_add_f32_e32 v162, v163, v162
	v_lshlrev_b32_e32 v163, 16, v152
	v_and_b32_e32 v152, 0xffff0000, v152
	v_add_f32_e32 v169, v41, v153
	v_lshlrev_b32_e32 v153, 16, v155
	v_add_f32_e32 v152, v49, v152
	v_add_f32_e32 v170, v42, v153
	v_and_b32_e32 v153, 0xffff0000, v155
	v_add_f32_e32 v163, v48, v163
	v_add_f32_e32 v164, v50, v164
	v_add_f32_e32 v171, v43, v153
	v_mul_f32_e32 v153, v152, v152
	v_mul_f32_e32 v154, v165, v165
	v_fmac_f32_e32 v153, v163, v163
	v_fmac_f32_e32 v154, v164, v164
	v_add_f32_e32 v153, v153, v154
	v_mul_f32_e32 v154, v169, v169
	v_fmac_f32_e32 v154, v168, v168
	v_add_f32_e32 v153, v154, v153
	v_mul_f32_e32 v154, v171, v171
	v_fmac_f32_e32 v154, v170, v170
	v_add_f32_e32 v153, v154, v153
	v_add_f32_e32 v153, v162, v153
	ds_bpermute_b32 v155, v184, v153
	s_waitcnt lgkmcnt(1)
	v_lshl_add_u64 v[160:161], s[30:31], 0, v[224:225]
	v_lshl_add_u64 v[160:161], v[204:205], 1, v[160:161]
	v_cvt_pk_bf16_f32 v158, v166, v158
	v_cvt_pk_bf16_f32 v159, v167, v159
	global_store_dwordx4 v[160:161], v[156:159], off sc1
	v_cvt_pk_bf16_f32 v154, v163, v152
	s_waitcnt lgkmcnt(0)
	v_add_f32_e32 v152, v153, v155
	ds_bpermute_b32 v153, v185, v152
	v_cvt_pk_bf16_f32 v155, v164, v165
	v_cvt_pk_bf16_f32 v156, v168, v169
	v_cvt_pk_bf16_f32 v157, v170, v171
	global_store_dwordx4 v[160:161], v[154:157], off offset:256 sc1
	s_and_saveexec_b64 s[6:7], s[2:3]
	s_cbranch_execz .LBB0_1094
	s_waitcnt lgkmcnt(0)
	v_add_f32_e32 v154, v152, v153
	v_lshl_add_u64 v[152:153], v[218:219], 2, s[4:5]
	global_atomic_add_f32 v[152:153], v154, off
; __device__ __forceinline__ unsigned cvt_pk_bf16(float lo, float hi) { unsigned r; asm volatile("v_cvt_pk_bf16_f32 %0, %1, %2" : "=v"(r) : "v"(lo), "v"(hi)); return r; }
;     __device__ __forceinline__ void operator()(const f32x4 (&acc)[2][2][4][2], const Unit& u, int wr, int wc, int fr, int fq) const {
;     ...
;         for (int ai = 0; ai < 2; ++ai)
; #pragma unroll
;             for (int m = 0; m < 4; ++m) {
;                 const int row = row0 + ai * HALF + m * 16;
;                 bf16_t* xr = xb + (size_t)row * 1024 + col0;
;                 float part_ss = 0.f;
; #pragma unroll
;                 for (int bj = 0; bj < 2; ++bj) {
;                     const u32x4 o = xo[ai][m][bj];
;                     f32x4 v0 = acc[ai][bj][m][0], v1 = acc[ai][bj][m][1];
;                     v0[0] += __uint_as_float(o.x << 16); v0[1] += __uint_as_float(o.x & 0xffff0000u); v0[2] += __uint_as_float(o.y << 16); v0[3] += __uint_as_float(o.y & 0xffff0000u);
;                     v1[0] += __uint_as_float(o.z << 16); v1[1] += __uint_as_float(o.z & 0xffff0000u); v1[2] += __uint_as_float(o.w << 16); v1[3] += __uint_as_float(o.w & 0xffff0000u);
;                     if (xout) { float* xo = xout + (size_t)row * 1024 + col0 + bj * HALF; *(f32x4*)xo = v0; *(f32x4*)(xo + 4) = v1; }
;                     else { u32x4 w; w.x = cvt_pk_bf16(v0[0], v0[1]); w.y = cvt_pk_bf16(v0[2], v0[3]); w.z = cvt_pk_bf16(v1[0], v1[1]); w.w = cvt_pk_bf16(v1[2], v1[3]); *(u32x4*)(xr + bj * HALF) = w; }
;                     part_ss += (v0[0] * v0[0] + v0[1] * v0[1]) + (v0[2] * v0[2] + v0[3] * v0[3]) + (v1[0] * v1[0] + v1[1] * v1[1]) + (v1[2] * v1[2] + v1[3] * v1[3]);
;                 }
;                 part_ss += __shfl_xor(part_ss, 16); part_ss += __shfl_xor(part_ss, 32);
;                 if (fq == 0) atomicAdd(ss + row, part_ss);
.LBB0_1094:
	s_or_b64 exec, exec, s[6:7]
	v_lshlrev_b32_e32 v154, 16, v148
	v_and_b32_e32 v148, 0xffff0000, v148
	v_add_f32_e32 v155, v53, v148
	v_lshlrev_b32_e32 v148, 16, v149
	v_add_f32_e32 v156, v54, v148
	v_and_b32_e32 v148, 0xffff0000, v149
	v_add_f32_e32 v157, v55, v148
	v_lshlrev_b32_e32 v148, 16, v150
	v_add_f32_e32 v158, v44, v148
	v_and_b32_e32 v148, 0xffff0000, v150
	v_add_f32_e32 v150, v45, v148
	v_lshlrev_b32_e32 v148, 16, v151
	v_add_f32_e32 v159, v46, v148
	v_and_b32_e32 v148, 0xffff0000, v151
	v_add_f32_e32 v154, v52, v154
	v_add_f32_e32 v151, v47, v148
	v_cvt_pk_bf16_f32 v148, v154, v155
	v_mul_f32_e32 v155, v155, v155
	v_fmac_f32_e32 v155, v154, v154
	v_mul_f32_e32 v154, v157, v157
	v_fmac_f32_e32 v154, v156, v156
	v_add_f32_e32 v154, v155, v154
	v_mul_f32_e32 v155, v150, v150
	v_cvt_pk_bf16_f32 v149, v156, v157
	v_fmac_f32_e32 v155, v158, v158
	v_lshlrev_b32_e32 v156, 16, v145
	v_and_b32_e32 v145, 0xffff0000, v145
	v_add_f32_e32 v154, v155, v154
	v_mul_f32_e32 v155, v151, v151
	v_add_f32_e32 v157, v35, v145
	v_lshlrev_b32_e32 v145, 16, v146
	v_fmac_f32_e32 v155, v159, v159
	v_add_f32_e32 v160, v24, v145
	v_and_b32_e32 v145, 0xffff0000, v146
	v_add_f32_e32 v154, v155, v154
	v_lshlrev_b32_e32 v155, 16, v144
	v_and_b32_e32 v144, 0xffff0000, v144
	v_add_f32_e32 v161, v25, v145
	v_lshlrev_b32_e32 v145, 16, v147
	v_add_f32_e32 v144, v33, v144
	v_add_f32_e32 v162, v26, v145
	v_and_b32_e32 v145, 0xffff0000, v147
	v_add_f32_e32 v155, v32, v155
	v_add_f32_e32 v156, v34, v156
	v_add_f32_e32 v163, v27, v145
	v_mul_f32_e32 v145, v144, v144
	v_mul_f32_e32 v146, v157, v157
	v_fmac_f32_e32 v145, v155, v155
	v_fmac_f32_e32 v146, v156, v156
	v_add_f32_e32 v145, v145, v146
	v_mul_f32_e32 v146, v161, v161
	v_fmac_f32_e32 v146, v160, v160
	v_add_f32_e32 v145, v146, v145
	v_mul_f32_e32 v146, v163, v163
	v_fmac_f32_e32 v146, v162, v162
	v_add_f32_e32 v145, v146, v145
	v_add_f32_e32 v145, v154, v145
	ds_bpermute_b32 v147, v184, v145
	s_waitcnt lgkmcnt(1)
	v_lshl_add_u64 v[152:153], s[30:31], 0, v[220:221]
	v_lshl_add_u64 v[152:153], v[204:205], 1, v[152:153]
	v_cvt_pk_bf16_f32 v150, v158, v150
	v_cvt_pk_bf16_f32 v151, v159, v151
	global_store_dwordx4 v[152:153], v[148:151], off sc1
	v_cvt_pk_bf16_f32 v146, v155, v144
	s_waitcnt lgkmcnt(0)
	v_add_f32_e32 v144, v145, v147
	ds_bpermute_b32 v145, v185, v144
	v_cvt_pk_bf16_f32 v147, v156, v157
	v_cvt_pk_bf16_f32 v148, v160, v161
	v_cvt_pk_bf16_f32 v149, v162, v163
	global_store_dwordx4 v[152:153], v[146:149], off offset:256 sc1
	s_and_saveexec_b64 s[6:7], s[2:3]
	s_cbranch_execz .LBB0_1096
	s_waitcnt lgkmcnt(0)
	v_add_f32_e32 v146, v144, v145
	v_lshl_add_u64 v[144:145], v[214:215], 2, s[4:5]
	global_atomic_add_f32 v[144:145], v146, off
; __device__ __forceinline__ unsigned cvt_pk_bf16(float lo, float hi) { unsigned r; asm volatile("v_cvt_pk_bf16_f32 %0, %1, %2" : "=v"(r) : "v"(lo), "v"(hi)); return r; }
;     __device__ __forceinline__ void operator()(const f32x4 (&acc)[2][2][4][2], const Unit& u, int wr, int wc, int fr, int fq) const {
;     ...
;         for (int ai = 0; ai < 2; ++ai)
; #pragma unroll
;             for (int m = 0; m < 4; ++m) {
;                 const int row = row0 + ai * HALF + m * 16;
;                 bf16_t* xr = xb + (size_t)row * 1024 + col0;
;                 float part_ss = 0.f;
; #pragma unroll
;                 for (int bj = 0; bj < 2; ++bj) {
;                     const u32x4 o = xo[ai][m][bj];
;                     f32x4 v0 = acc[ai][bj][m][0], v1 = acc[ai][bj][m][1];
;                     v0[0] += __uint_as_float(o.x << 16); v0[1] += __uint_as_float(o.x & 0xffff0000u); v0[2] += __uint_as_float(o.y << 16); v0[3] += __uint_as_float(o.y & 0xffff0000u);
;                     v1[0] += __uint_as_float(o.z << 16); v1[1] += __uint_as_float(o.z & 0xffff0000u); v1[2] += __uint_as_float(o.w << 16); v1[3] += __uint_as_float(o.w & 0xffff0000u);
;                     if (xout) { float* xo = xout + (size_t)row * 1024 + col0 + bj * HALF; *(f32x4*)xo = v0; *(f32x4*)(xo + 4) = v1; }
;                     else { u32x4 w; w.x = cvt_pk_bf16(v0[0], v0[1]); w.y = cvt_pk_bf16(v0[2], v0[3]); w.z = cvt_pk_bf16(v1[0], v1[1]); w.w = cvt_pk_bf16(v1[2], v1[3]); *(u32x4*)(xr + bj * HALF) = w; }
;                     part_ss += (v0[0] * v0[0] + v0[1] * v0[1]) + (v0[2] * v0[2] + v0[3] * v0[3]) + (v1[0] * v1[0] + v1[1] * v1[1]) + (v1[2] * v1[2] + v1[3] * v1[3]);
;                 }
;                 part_ss += __shfl_xor(part_ss, 16); part_ss += __shfl_xor(part_ss, 32);
;                 if (fq == 0) atomicAdd(ss + row, part_ss);
.LBB0_1096:
	s_or_b64 exec, exec, s[6:7]
	v_lshlrev_b32_e32 v146, 16, v140
	v_and_b32_e32 v140, 0xffff0000, v140
	v_add_f32_e32 v147, v37, v140
	v_lshlrev_b32_e32 v140, 16, v141
	v_add_f32_e32 v148, v38, v140
	v_and_b32_e32 v140, 0xffff0000, v141
	v_add_f32_e32 v149, v39, v140
	v_lshlrev_b32_e32 v140, 16, v142
	v_add_f32_e32 v150, v28, v140
	v_and_b32_e32 v140, 0xffff0000, v142
	v_add_f32_e32 v142, v29, v140
	v_lshlrev_b32_e32 v140, 16, v143
	v_add_f32_e32 v151, v30, v140
	v_and_b32_e32 v140, 0xffff0000, v143
	v_add_f32_e32 v146, v36, v146
	v_add_f32_e32 v143, v31, v140
	v_cvt_pk_bf16_f32 v140, v146, v147
	v_mul_f32_e32 v147, v147, v147
	v_fmac_f32_e32 v147, v146, v146
	v_mul_f32_e32 v146, v149, v149
	v_fmac_f32_e32 v146, v148, v148
	v_add_f32_e32 v146, v147, v146
	v_mul_f32_e32 v147, v142, v142
	v_cvt_pk_bf16_f32 v141, v148, v149
	v_fmac_f32_e32 v147, v150, v150
	v_lshlrev_b32_e32 v148, 16, v137
	v_and_b32_e32 v137, 0xffff0000, v137
	v_add_f32_e32 v146, v147, v146
	v_mul_f32_e32 v147, v143, v143
	v_add_f32_e32 v149, v19, v137
	v_lshlrev_b32_e32 v137, 16, v138
	v_fmac_f32_e32 v147, v151, v151
	v_add_f32_e32 v152, v8, v137
	v_and_b32_e32 v137, 0xffff0000, v138
	v_add_f32_e32 v146, v147, v146
	v_lshlrev_b32_e32 v147, 16, v136
	v_and_b32_e32 v136, 0xffff0000, v136
	v_add_f32_e32 v153, v9, v137
	v_lshlrev_b32_e32 v137, 16, v139
	v_add_f32_e32 v136, v17, v136
	v_add_f32_e32 v154, v10, v137
	v_and_b32_e32 v137, 0xffff0000, v139
	v_add_f32_e32 v147, v16, v147
	v_add_f32_e32 v148, v18, v148
	v_add_f32_e32 v155, v11, v137
	v_mul_f32_e32 v137, v136, v136
	v_mul_f32_e32 v138, v149, v149
	v_fmac_f32_e32 v137, v147, v147
	v_fmac_f32_e32 v138, v148, v148
	v_add_f32_e32 v137, v137, v138
	v_mul_f32_e32 v138, v153, v153
	v_fmac_f32_e32 v138, v152, v152
	v_add_f32_e32 v137, v138, v137
	v_mul_f32_e32 v138, v155, v155
	v_fmac_f32_e32 v138, v154, v154
	v_add_f32_e32 v137, v138, v137
	v_add_f32_e32 v137, v146, v137
	ds_bpermute_b32 v139, v184, v137
	s_waitcnt lgkmcnt(1)
	v_lshl_add_u64 v[144:145], s[30:31], 0, v[216:217]
	v_lshl_add_u64 v[144:145], v[204:205], 1, v[144:145]
	v_cvt_pk_bf16_f32 v142, v150, v142
	v_cvt_pk_bf16_f32 v143, v151, v143
	global_store_dwordx4 v[144:145], v[140:143], off sc1
	v_cvt_pk_bf16_f32 v138, v147, v136
	s_waitcnt lgkmcnt(0)
	v_add_f32_e32 v136, v137, v139
	ds_bpermute_b32 v137, v185, v136
	v_cvt_pk_bf16_f32 v139, v148, v149
	v_cvt_pk_bf16_f32 v140, v152, v153
	v_cvt_pk_bf16_f32 v141, v154, v155
	global_store_dwordx4 v[144:145], v[138:141], off offset:256 sc1
	s_and_saveexec_b64 s[6:7], s[2:3]
	s_cbranch_execz .LBB0_1098
	s_waitcnt lgkmcnt(0)
	v_add_f32_e32 v138, v136, v137
	v_lshl_add_u64 v[136:137], v[210:211], 2, s[4:5]
	global_atomic_add_f32 v[136:137], v138, off
.LBB0_1098:
	s_or_b64 exec, exec, s[6:7]
	v_lshlrev_b32_e32 v138, 16, v132
	v_and_b32_e32 v132, 0xffff0000, v132
	v_add_f32_e32 v139, v21, v132
	v_lshlrev_b32_e32 v132, 16, v133
	v_add_f32_e32 v140, v22, v132
	v_and_b32_e32 v132, 0xffff0000, v133
	v_add_f32_e32 v141, v23, v132
	v_lshlrev_b32_e32 v132, 16, v134
	v_add_f32_e32 v142, v12, v132
	v_and_b32_e32 v132, 0xffff0000, v134
	v_add_f32_e32 v134, v13, v132
	v_lshlrev_b32_e32 v132, 16, v135
	v_add_f32_e32 v143, v14, v132
	v_and_b32_e32 v132, 0xffff0000, v135
	v_add_f32_e32 v138, v20, v138
	v_add_f32_e32 v135, v15, v132
	v_cvt_pk_bf16_f32 v132, v138, v139
	v_mul_f32_e32 v139, v139, v139
	v_fmac_f32_e32 v139, v138, v138
	v_mul_f32_e32 v138, v141, v141
	v_fmac_f32_e32 v138, v140, v140
	v_add_f32_e32 v138, v139, v138
	v_mul_f32_e32 v139, v134, v134
	v_cvt_pk_bf16_f32 v133, v140, v141
	v_fmac_f32_e32 v139, v142, v142
	v_lshlrev_b32_e32 v140, 16, v129
	v_and_b32_e32 v129, 0xffff0000, v129
	v_add_f32_e32 v138, v139, v138
	v_mul_f32_e32 v139, v135, v135
	v_add_f32_e32 v141, v7, v129
	v_lshlrev_b32_e32 v129, 16, v130
	v_fmac_f32_e32 v139, v143, v143
	v_add_f32_e32 v144, v0, v129
	v_and_b32_e32 v129, 0xffff0000, v130
	v_add_f32_e32 v138, v139, v138
	v_lshlrev_b32_e32 v139, 16, v128
	v_and_b32_e32 v128, 0xffff0000, v128
	v_add_f32_e32 v145, v1, v129
	v_lshlrev_b32_e32 v129, 16, v131
	v_add_f32_e32 v128, v5, v128
	v_add_f32_e32 v146, v2, v129
	v_and_b32_e32 v129, 0xffff0000, v131
	v_add_f32_e32 v139, v4, v139
	v_add_f32_e32 v140, v6, v140
	v_add_f32_e32 v147, v3, v129
	v_mul_f32_e32 v129, v128, v128
	v_mul_f32_e32 v130, v141, v141
	v_fmac_f32_e32 v129, v139, v139
	v_fmac_f32_e32 v130, v140, v140
	v_add_f32_e32 v129, v129, v130
	v_mul_f32_e32 v130, v145, v145
	v_fmac_f32_e32 v130, v144, v144
	v_add_f32_e32 v129, v130, v129
	v_mul_f32_e32 v130, v147, v147
	v_fmac_f32_e32 v130, v146, v146
	v_add_f32_e32 v129, v130, v129
	v_add_f32_e32 v129, v138, v129
	ds_bpermute_b32 v131, v184, v129
	s_waitcnt lgkmcnt(1)
	v_lshl_add_u64 v[136:137], s[30:31], 0, v[212:213]
	v_lshl_add_u64 v[136:137], v[204:205], 1, v[136:137]
	v_cvt_pk_bf16_f32 v134, v142, v134
	v_cvt_pk_bf16_f32 v135, v143, v135
	global_store_dwordx4 v[136:137], v[132:135], off sc1
	v_cvt_pk_bf16_f32 v130, v139, v128
	s_waitcnt lgkmcnt(0)
	v_add_f32_e32 v128, v129, v131
	ds_bpermute_b32 v129, v185, v128
	v_cvt_pk_bf16_f32 v131, v140, v141
	v_cvt_pk_bf16_f32 v132, v144, v145
	v_cvt_pk_bf16_f32 v133, v146, v147
	global_store_dwordx4 v[136:137], v[130:133], off offset:256 sc1
	s_and_saveexec_b64 s[6:7], s[2:3]
	s_cbranch_execz .LBB0_1100
	s_waitcnt lgkmcnt(0)
	v_add_f32_e32 v130, v128, v129
	v_lshl_add_u64 v[128:129], v[208:209], 2, s[4:5]
	global_atomic_add_f32 v[128:129], v130, off

; __device__ __forceinline__ unsigned cvt_pk_bf16(float lo, float hi) { unsigned r; asm volatile("v_cvt_pk_bf16_f32 %0, %1, %2" : "=v"(r) : "v"(lo), "v"(hi)); return r; }
;     __device__ __forceinline__ void operator()(const f32x4 (&acc)[2][2][4][2], const Unit& u, int wr, int wc, int fr, int fq) const {
;     ...
;         if (u.sp >= 0) {
;             bf16_t* pb = (bf16_t*)part + ((size_t)u.sp * 1024 + (row0 - 16384)) * 1024 + col0;
; #pragma unroll
;             for (int ai = 0; ai < 2; ++ai)
; #pragma unroll
;                 for (int m = 0; m < 4; ++m)
; #pragma unroll
;                     for (int bj = 0; bj < 2; ++bj) { const f32x4 v0 = acc[ai][bj][m][0], v1 = acc[ai][bj][m][1];
;                         u32x4 w; w.x = cvt_pk_bf16(v0[0], v0[1]); w.y = cvt_pk_bf16(v0[2], v0[3]); w.z = cvt_pk_bf16(v1[0], v1[1]); w.w = cvt_pk_bf16(v1[2], v1[3]);
;                         *(u32x4*)(pb + (size_t)(ai * HALF + m * 16) * 1024 + bj * HALF) = w; }
;             return;
.LBB0_1102:
	s_and_b64 vcc, exec, s[6:7]
	s_cbranch_vccz .LBB0_1101
	s_lshl_b64 s[6:7], s[18:19], 21
	s_add_u32 s6, s88, s6
	s_waitcnt lgkmcnt(0)
	v_lshlrev_b64 v[128:129], 11, v[206:207]
	s_addc_u32 s7, s89, s7
	v_lshl_add_u64 v[128:129], s[6:7], 0, v[128:129]
	v_lshl_add_u64 v[128:129], v[204:205], 1, v[128:129]
	s_mov_b32 s6, 0xfe000000
	s_mov_b32 s7, -1
	v_cvt_pk_bf16_f32 v124, v124, v125
	v_cvt_pk_bf16_f32 v125, v126, v127
	v_cvt_pk_bf16_f32 v126, v120, v121
	v_add_co_u32_e32 v120, vcc, s62, v128
	v_lshl_add_u64 v[130:131], v[128:129], 0, s[6:7]
	s_nop 0
	v_addc_co_u32_e32 v121, vcc, -1, v129, vcc
	v_cvt_pk_bf16_f32 v127, v122, v123
	global_store_dwordx4 v[120:121], v[124:127], off sc1
	v_cvt_pk_bf16_f32 v112, v112, v113
	v_cvt_pk_bf16_f32 v113, v114, v115
	v_cvt_pk_bf16_f32 v114, v104, v105
	v_cvt_pk_bf16_f32 v115, v106, v107
	global_store_dwordx4 v[130:131], v[112:115], off offset:256 sc1
	v_cvt_pk_bf16_f32 v104, v116, v117
	v_cvt_pk_bf16_f32 v105, v118, v119
	v_cvt_pk_bf16_f32 v106, v108, v109
	v_add_co_u32_e32 v108, vcc, s63, v128
	v_cvt_pk_bf16_f32 v107, v110, v111
	s_nop 1
	v_addc_co_u32_e32 v109, vcc, -1, v129, vcc
	global_store_dwordx4 v[108:109], v[104:107], off sc1
	v_cvt_pk_bf16_f32 v96, v96, v97
	v_cvt_pk_bf16_f32 v97, v98, v99
	v_cvt_pk_bf16_f32 v98, v88, v89
	v_add_co_u32_e32 v88, vcc, s64, v128
	v_cvt_pk_bf16_f32 v99, v90, v91
	s_nop 1
	v_addc_co_u32_e32 v89, vcc, -1, v129, vcc
	global_store_dwordx4 v[88:89], v[96:99], off offset:-3840 sc1
	v_cvt_pk_bf16_f32 v88, v100, v101
	v_cvt_pk_bf16_f32 v89, v102, v103
	v_cvt_pk_bf16_f32 v90, v92, v93
	v_add_co_u32_e32 v92, vcc, s65, v128
	v_cvt_pk_bf16_f32 v91, v94, v95
	s_nop 1
	v_addc_co_u32_e32 v93, vcc, -1, v129, vcc
	global_store_dwordx4 v[92:93], v[88:91], off sc1
	v_cvt_pk_bf16_f32 v80, v80, v81
	v_cvt_pk_bf16_f32 v81, v82, v83
	v_cvt_pk_bf16_f32 v82, v72, v73
	v_add_co_u32_e32 v72, vcc, s66, v128
	v_cvt_pk_bf16_f32 v83, v74, v75
	s_nop 1
	v_addc_co_u32_e32 v73, vcc, -1, v129, vcc
	global_store_dwordx4 v[72:73], v[80:83], off offset:-3840 sc1
	v_cvt_pk_bf16_f32 v72, v84, v85
	v_cvt_pk_bf16_f32 v73, v86, v87
	v_cvt_pk_bf16_f32 v74, v76, v77
	v_add_co_u32_e32 v76, vcc, s67, v128
	v_cvt_pk_bf16_f32 v75, v78, v79
	s_nop 1
	v_addc_co_u32_e32 v77, vcc, -1, v129, vcc
	global_store_dwordx4 v[76:77], v[72:75], off sc1
	v_cvt_pk_bf16_f32 v68, v68, v69
	v_cvt_pk_bf16_f32 v69, v70, v71
	v_cvt_pk_bf16_f32 v70, v64, v65
	v_add_co_u32_e32 v64, vcc, s76, v128
	v_cvt_pk_bf16_f32 v71, v66, v67
	s_nop 1
	v_addc_co_u32_e32 v65, vcc, -1, v129, vcc
	global_store_dwordx4 v[64:65], v[68:71], off offset:-3840 sc1
	v_cvt_pk_bf16_f32 v60, v60, v61
	v_cvt_pk_bf16_f32 v61, v62, v63
	v_cvt_pk_bf16_f32 v62, v56, v57
	v_add_co_u32_e32 v56, vcc, s77, v128
	v_cvt_pk_bf16_f32 v63, v58, v59
	s_nop 1
	v_addc_co_u32_e32 v57, vcc, -1, v129, vcc
	global_store_dwordx4 v[56:57], v[60:63], off sc1
	v_cvt_pk_bf16_f32 v48, v48, v49
	v_cvt_pk_bf16_f32 v49, v50, v51
	v_cvt_pk_bf16_f32 v50, v40, v41
	v_add_co_u32_e32 v40, vcc, s78, v128
	v_cvt_pk_bf16_f32 v51, v42, v43
	s_nop 1
	v_addc_co_u32_e32 v41, vcc, -1, v129, vcc
	global_store_dwordx4 v[40:41], v[48:51], off offset:-3840 sc1
	v_cvt_pk_bf16_f32 v40, v52, v53
	v_cvt_pk_bf16_f32 v41, v54, v55
	v_cvt_pk_bf16_f32 v42, v44, v45
	v_add_co_u32_e32 v44, vcc, s79, v128
	v_cvt_pk_bf16_f32 v43, v46, v47
	s_nop 1
	v_addc_co_u32_e32 v45, vcc, -1, v129, vcc
	global_store_dwordx4 v[44:45], v[40:43], off sc1
	v_cvt_pk_bf16_f32 v32, v32, v33
	v_cvt_pk_bf16_f32 v33, v34, v35
	v_cvt_pk_bf16_f32 v34, v24, v25
	v_add_co_u32_e32 v24, vcc, s80, v128
	v_cvt_pk_bf16_f32 v35, v26, v27
	s_nop 1
	v_addc_co_u32_e32 v25, vcc, -1, v129, vcc
	global_store_dwordx4 v[24:25], v[32:35], off offset:-3840 sc1
	v_cvt_pk_bf16_f32 v24, v36, v37
	v_cvt_pk_bf16_f32 v25, v38, v39
	v_cvt_pk_bf16_f32 v26, v28, v29
	v_add_co_u32_e32 v28, vcc, s81, v128
	v_cvt_pk_bf16_f32 v27, v30, v31
	s_nop 1
	v_addc_co_u32_e32 v29, vcc, -1, v129, vcc
	global_store_dwordx4 v[28:29], v[24:27], off sc1
	v_cvt_pk_bf16_f32 v16, v16, v17
	v_cvt_pk_bf16_f32 v17, v18, v19
	v_cvt_pk_bf16_f32 v18, v8, v9
	v_add_co_u32_e32 v8, vcc, s82, v128
	v_cvt_pk_bf16_f32 v19, v10, v11
	s_nop 1
	v_addc_co_u32_e32 v9, vcc, -1, v129, vcc
	global_store_dwordx4 v[8:9], v[16:19], off offset:-3840 sc1
	v_cvt_pk_bf16_f32 v8, v20, v21
	v_cvt_pk_bf16_f32 v9, v22, v23
	v_cvt_pk_bf16_f32 v10, v12, v13
	v_add_co_u32_e32 v12, vcc, s83, v128
	v_cvt_pk_bf16_f32 v11, v14, v15
	s_nop 1
	v_addc_co_u32_e32 v13, vcc, -1, v129, vcc
	global_store_dwordx4 v[12:13], v[8:11], off sc1
	v_cvt_pk_bf16_f32 v4, v4, v5
	v_cvt_pk_bf16_f32 v5, v6, v7
	v_cvt_pk_bf16_f32 v6, v0, v1
	v_add_co_u32_e32 v0, vcc, 0xfe059000, v128
	v_cvt_pk_bf16_f32 v7, v2, v3
	s_nop 1
	v_addc_co_u32_e32 v1, vcc, -1, v129, vcc
	global_store_dwordx4 v[0:1], v[4:7], off offset:-3840 sc1
	s_andn2_b64 vcc, exec, s[46:47]
	s_mov_b64 s[6:7], -1
	s_cbranch_vccnz .LBB0_1074

; #define PG8_STAGE(bufoff, gbase, voff) do { _Pragma("unroll") for (int _i = 0; _i < 2; ++_i) \
;         __builtin_amdgcn_global_load_lds((const unsigned*)((const char*)(gbase) + (voff)[_i]), (PG8_LAS unsigned*)(lds + (bufoff) + ldsw + _i * 8192), 16, 0, 0); } while (0)
; #define PG8_WAIT_V(n) asm volatile("s_waitcnt vmcnt(" #n ")" ::: "memory")
; #define PG8_BAR __builtin_amdgcn_s_barrier()
; template <class Epi, class Sched, bool ALIGN_EPI = false, bool SP2 = false>
; __device__ __forceinline__ void gemm_phase(PG8_LAS unsigned char* lds, const Gemm g, const Sched& S, const Epi& E) {
;     ...
;     for (int i = 0; i < 2; ++i) { int R, C; stage_rc(tid * 16 + i * 8192, R, C); const int Rb = Epi::PERM ? ((R & ~31) + perm32(R & 31)) : R;
;         voffA[i] = g.asub ? (unsigned)((C >> 5) * 16384 + (R * 32 + (C & 31)) * 2) : (unsigned)(R * g.lda + C) * 2u; voffB[i] = (unsigned)(Rb * K + C) * 2u; }
;     const size_t kstep = (size_t)(BK * 2);
;     const size_t hstepB = (size_t)HALF * K * 2, hstepA = (size_t)HALF * g.lda * 2;
;     const size_t tstepB = 2 * hstepB, tstepA = g.tstepA; const size_t kstepA = g.kstepA;
;     const unsigned ldsw = (unsigned)wid * 1024u;
;     const int aoff = lds_byte(wr * 64 + fr, fq * 8), boff = lds_byte(wc * 32 + fr, fq * 8);
;     ...
;     if constexpr (SP2) {
;         PG8_STAGE(PG8_SB(0, 0), cB, voffB); PG8_STAGE(PG8_SB(0, 1), cB + hstepB, voffB); PG8_STAGE(PG8_SA(0, 0), cA, voffA); PG8_STAGE(PG8_SA(0, 1), cA + hstepA, voffA);
;         if (wr == 1) PG8_BAR;
;         PG8_WAIT_V(2); PG8_BAR;
;         PG8_STAGE(PG8_SB(1, 0), cB + kstep, voffB); PG8_STAGE(PG8_SA(1, 0), cA + kstepA, voffA); PG8_STAGE(PG8_SB(1, 1), cB + hstepB + kstep, voffB);
;         PG8_WAIT_V(6); PG8_BAR;
.LBB0_1295:
	s_and_b64 s[2:3], s[2:3], exec
	s_cselect_b32 s16, -1, s7
	s_cselect_b32 s9, 64, 8
	s_lshl_b32 s2, s17, 5
	s_and_b32 s24, s2, 0x60
	s_lshl_b32 s7, s6, 13
	s_lshl_b32 s17, s24, 7
	s_add_u32 s18, s72, 0x44000
	s_mov_b64 s[20:21], 0x80
	s_addc_u32 s19, s73, 0
	s_add_i32 m0, s28, 0x18000
	v_lshl_add_u64 v[2:3], v[2:3], 0, s[20:21]
	s_waitcnt vmcnt(2)
	s_barrier
	global_load_lds_dwordx4 v[2:3], off
	s_add_i32 m0, s28, 0x1a000
	s_add_u32 s2, s50, 0x8000
	v_lshl_add_u64 v[0:1], v[0:1], 0, s[20:21]
	s_addc_u32 s3, s51, 0
	s_add_i32 s58, s28, 0x8000
	global_load_lds_dwordx4 v[0:1], off
	v_lshl_add_u64 v[0:1], s[2:3], 0, v[192:193]
	s_mov_b32 m0, s58
	s_add_i32 s59, s28, 0xa000
	global_load_lds_dwordx4 v[0:1], off
	v_lshl_add_u64 v[0:1], s[2:3], 0, v[196:197]
	s_add_u32 s2, s52, 0x100080
	s_mov_b32 m0, s59
	s_addc_u32 s3, s53, 0
	global_load_lds_dwordx4 v[0:1], off
	s_add_i32 m0, s28, 0x1c000
	v_lshl_add_u64 v[0:1], s[2:3], 0, v[194:195]
	global_load_lds_dwordx4 v[0:1], off
	v_lshl_add_u64 v[0:1], s[2:3], 0, v[198:199]
	s_add_i32 m0, s28, 0x1e000
	s_cmpk_lt_u32 s22, 0x100
	global_load_lds_dwordx4 v[0:1], off
	v_bfe_u32 v1, v4, 4, 2
	v_and_b32_e32 v0, 15, v4
	v_lshlrev_b32_e32 v2, 4, v1
	v_lshl_or_b32 v239, s6, 6, v0
	v_lshl_or_b32 v0, v0, 6, v2
	v_lshlrev_b32_e32 v2, 2, v4
	v_and_b32_e32 v2, 32, v2
	v_bitop3_b32 v3, v0, s7, v2 bitop3:0xde
	v_bitop3_b32 v240, v0, s17, v2 bitop3:0xde
	v_lshlrev_b32_e32 v0, 9, v5
	v_and_b32_e32 v0, 0xfffffc00, v0
	v_add_u32_e32 v0, v7, v0
	v_cmp_eq_u32_e64 s[2:3], 0, v1
	v_lshl_or_b32 v241, v1, 3, s24
	v_add3_u32 v0, v0, v6, v8
	v_mov_b32_e32 v1, v195
	s_mov_b64 s[6:7], 0xa000
	v_lshl_add_u64 v[200:201], v[0:1], 0, s[6:7]
	v_lshlrev_b32_e32 v0, 9, v9
	v_and_b32_e32 v0, 0xfffffc00, v0
	v_add_u32_e32 v0, v11, v0
	s_waitcnt vmcnt(0)
	v_add3_u32 v0, v0, v10, v12
	s_mov_b32 s17, 0
	s_cselect_b64 s[22:23], -1, 0
	v_lshl_add_u64 v[202:203], v[0:1], 0, s[6:7]
	s_add_i32 s60, 0, 0x10000
	s_add_i32 s61, 0, 0x14000
	s_mov_b32 s24, 0xfe000000
	v_mbcnt_lo_u32_b32 v0, -1, 0
	v_add_u32_e32 v242, s60, v240
	v_add_u32_e32 v243, s61, v240
	v_add_u32_e32 v244, 0, v3
	s_mov_b32 s25, -1
	s_mov_b32 s62, 0xfe000000
	s_mov_b32 s63, 0xfe008000
	s_mov_b32 s64, 0xfe009000
	s_mov_b32 s65, 0xfe010000
	s_mov_b32 s66, 0xfe011000
	s_mov_b32 s67, 0xfe018000
	s_mov_b32 s76, 0xfe019000
	s_mov_b32 s77, 0xfe040000
	s_mov_b32 s78, 0xfe041000
	s_mov_b32 s79, 0xfe048000
	s_mov_b32 s80, 0xfe049000
	s_mov_b32 s81, 0xfe050000
	s_mov_b32 s82, 0xfe051000
	s_mov_b32 s83, 0xfe058000
	v_mbcnt_hi_u32_b32 v245, -1, v0
	s_mov_b32 s84, s17
	s_barrier
	s_branch .LBB0_1298

;     __host__ __device__ __forceinline__ bool next(int i, Unit& u) const { const long L = (long)i * G + c; if (L >= nwg) return false; map((int)L, u); return true; }
; #define PG8_STAGE(bufoff, gbase, voff) do { _Pragma("unroll") for (int _i = 0; _i < 2; ++_i) \
;         __builtin_amdgcn_global_load_lds((const unsigned*)((const char*)(gbase) + (voff)[_i]), (PG8_LAS unsigned*)(lds + (bufoff) + ldsw + _i * 8192), 16, 0, 0); } while (0)
; #define PG8_WAIT_V(n) asm volatile("s_waitcnt vmcnt(" #n ")" ::: "memory")
;     __host__ __device__ __forceinline__ bool next(int i, Unit& u) const {
;         const int ii = (so.c < 16 * S && so.G >= so.nwg && i < 2) ? 1 - i : i;
;         const int L = ii * so.G + so.c; const bool isp = L < so.nwg; const int j = isp ? 0 : L - so.nwg;
;         Unit a; so.map(isp ? L : 0, a);
;         const int q = j / S, sp = j - q * S;
;         u.pm = isp ? a.pm : 64 + (q >> 2); u.pn = isp ? a.pn : (q & 3); u.sp = isp ? -1 : sp; u.nt = isp ? a.nt : ntS; u.k0 = isp ? 0 : sp * ntS * BK; u.qa = -1; u.qb = -1;
;         return isp || j < 16 * S;
; template <class Epi, class Sched, bool ALIGN_EPI = false, bool SP2 = false>
; __device__ __forceinline__ void gemm_phase(PG8_LAS unsigned char* lds, const Gemm g, const Sched& S, const Epi& E) {
;     ...
;         const bool has_next = S.next(ui + 1, nxt);
;         const char* nA = has_next ? (const char*)g.A + (size_t)nxt.pm * tstepA + (size_t)(nxt.k0 >> 6) * kstepA + (nxt.qa > 0 ? hstepA : (size_t)0) : cA; const char* nB = has_next ? (const char*)g.Bt + (size_t)nxt.pn * tstepB + (size_t)nxt.k0 * 2 + (nxt.qb > 0 ? hstepB : (size_t)0) : cB;
;         const bool whole = cur.qa < 0;
;         const int nt = cur.nt;
;         for (int t = 0; t < nt; t += 2) {
;             const bool last = (t == nt - 2);
;             const char* a1 = cA + (size_t)(t + 1) * kstepA;
;             const char* a2 = last ? nA : cA + (size_t)(t + 2) * kstepA; const char* b2 = last ? nB : cB + (size_t)(t + 2) * kstep;
;             const char* a3 = a2 + kstepA; const char* b3 = b2 + kstep;
;             if (last && has_next) S.a_ready(nxt);
;             if constexpr (SP2) {
;             PG8_LDB(B0, 0, 0); PG8_LDB(B1, 0, 1); PG8_SCHED; PG8_LDA(At, 0, 0); PG8_STAGE(PG8_SA(1, 1), a1 + hstepA, voffA);
;             PG8_WAIT_V(8); PG8_WAIT_L(0); PG8_BAR; PG8_MMA(0, 0, At, B0); if (whole) PG8_MMA(0, 1, At, B1); PG8_BAR; PG8_SCHED;
.LBB0_1302:
	s_add_i32 s7, s36, s6
	s_ashr_i32 s6, s7, 31
	s_lshr_b32 s6, s6, 28
	s_add_i32 s36, s7, s6
	s_ashr_i32 s6, s36, 4
	s_lshl_b32 s37, s6, 2
	s_sub_i32 s6, 64, s37
	s_min_i32 s38, s6, 4
	s_abs_i32 s39, s38
	v_cvt_f32_u32_e32 v0, s39
	s_sub_i32 s43, 0, s39
	s_and_b32 s36, s36, -16
	s_sub_i32 s7, s7, s36
	v_rcp_iflag_f32_e32 v0, v0
	s_abs_i32 s36, s7
	s_max_i32 s40, s44, 0x100
	s_xor_b32 s42, s7, s38
	v_mul_f32_e32 v0, 0x4f7ffffe, v0
	v_cvt_u32_f32_e32 v0, v0
	s_add_i32 s41, s40, 0xffffff00
	s_ashr_i32 s42, s42, 31
	s_mov_b32 s6, 0
	v_readfirstlane_b32 s45, v0
	s_mul_i32 s43, s43, s45
	s_mul_hi_u32 s43, s45, s43
	s_add_i32 s45, s45, s43
	s_mul_hi_u32 s43, s36, s45
	s_mul_i32 s45, s43, s39
	s_sub_i32 s36, s36, s45
	s_add_i32 s45, s43, 1
	s_sub_i32 s54, s36, s39
	s_cmp_ge_u32 s36, s39
	s_cselect_b32 s43, s45, s43
	s_cselect_b32 s36, s54, s36
	s_add_i32 s45, s43, 1
	s_cmp_ge_u32 s36, s39
	s_cselect_b32 s36, s45, s43
	s_xor_b32 s36, s36, s42
	s_sub_i32 s42, s36, s42
	s_mul_i32 s36, s42, s38
	s_sub_i32 s7, s7, s36
	s_lshr_b32 s36, s41, 5
	s_add_i32 s7, s37, s7
	s_and_b32 s85, s40, 7
	s_add_i32 s38, s36, 64
	s_and_b64 s[36:37], s[26:27], exec
	s_cselect_b32 s36, s7, s38
	s_bfe_u32 s7, s40, 0x20003
	s_and_b64 s[38:39], s[26:27], exec
	s_cselect_b32 s38, s42, s7
	s_lshl_b32 s7, s85, 9
	s_and_b64 s[40:41], s[26:27], exec
	s_cselect_b32 s7, 0, s7
	s_ashr_i32 s37, s36, 31
	s_lshl_b64 s[40:41], s[36:37], 21
	s_add_u32 s37, s34, s40
	s_addc_u32 s39, s35, s41
	s_lshl_b32 s40, s7, 9
	s_add_u32 s40, s37, s40
	s_addc_u32 s41, s39, 0
	s_ashr_i32 s39, s38, 31
	s_lshl_b64 s[42:43], s[38:39], 21
	s_add_u32 s37, s12, s42
	s_addc_u32 s39, s13, s43
	s_lshl_b32 s7, s7, 1
	s_add_u32 s42, s37, s7
	s_addc_u32 s43, s39, 0
	s_cmpk_lt_i32 s44, 0x180
	s_cselect_b64 s[44:45], -1, 0
	s_and_b64 s[54:55], s[44:45], exec
	s_cselect_b32 s37, s41, s51
	s_cselect_b32 s39, s40, s50
	s_cselect_b32 s86, s43, s53
	s_cselect_b32 s87, s42, s52
	s_add_i32 s90, s9, -2
	s_add_u32 s91, s52, 0x100
	s_addc_u32 s92, s53, 0
	s_waitcnt lgkmcnt(0)
	ds_read_b128 v[128:131], v242
	ds_read_b128 v[132:135], v242 offset:1024
	ds_read_b128 v[136:139], v242 offset:2048
	ds_read_b128 v[140:143], v242 offset:3072
	ds_read_b128 v[144:147], v243
	ds_read_b128 v[148:151], v243 offset:1024
	ds_read_b128 v[152:155], v243 offset:2048
	ds_read_b128 v[156:159], v243 offset:3072
	s_add_i32 s93, s6, 2
	s_add_u32 s52, s50, 0x10000
	s_addc_u32 s53, s51, 0
	s_cmp_eq_u32 s90, s6
	s_cselect_b32 s56, s39, s52
	s_cselect_b32 s57, s37, s53
	s_cselect_b32 s54, s87, s91
	s_cselect_b32 s55, s86, s92
	s_add_u32 s6, s56, 0x8000
	s_addc_u32 s7, s57, 0
	v_lshl_add_u64 v[204:205], s[50:51], 0, v[200:201]
	s_add_i32 m0, s28, 0xc000
	ds_read_b128 v[160:163], v244
	ds_read_b128 v[164:167], v244 offset:1024
	ds_read_b128 v[168:171], v244 offset:2048
	ds_read_b128 v[172:175], v244 offset:3072
	ds_read_b128 v[176:179], v244 offset:4096
	ds_read_b128 v[180:183], v244 offset:5120
	ds_read_b128 v[184:187], v244 offset:6144
	ds_read_b128 v[188:191], v244 offset:7168
	global_load_lds_dwordx4 v[204:205], off
	v_lshl_add_u64 v[204:205], s[50:51], 0, v[202:203]
	s_add_i32 m0, s28, 0xe000
	s_nop 0
	global_load_lds_dwordx4 v[204:205], off
	s_waitcnt vmcnt(16)
	s_waitcnt lgkmcnt(0)
	s_barrier
	s_setprio 1
	s_waitcnt lgkmcnt(0)
	v_mfma_f32_16x16x32_bf16 v[124:127], v[128:131], v[160:163], 0
	v_mfma_f32_16x16x32_bf16 v[120:123], v[136:139], v[160:163], 0
	v_mfma_f32_16x16x32_bf16 v[116:119], v[128:131], v[168:171], 0
	v_mfma_f32_16x16x32_bf16 v[108:111], v[136:139], v[168:171], 0
	v_mfma_f32_16x16x32_bf16 v[100:103], v[128:131], v[176:179], 0
	v_mfma_f32_16x16x32_bf16 v[92:95], v[136:139], v[176:179], 0
	v_mfma_f32_16x16x32_bf16 v[84:87], v[128:131], v[184:187], 0
	v_mfma_f32_16x16x32_bf16 v[76:79], v[136:139], v[184:187], 0
	v_mfma_f32_16x16x32_bf16 v[124:127], v[132:135], v[164:167], v[124:127]
	v_mfma_f32_16x16x32_bf16 v[120:123], v[140:143], v[164:167], v[120:123]
	v_mfma_f32_16x16x32_bf16 v[116:119], v[132:135], v[172:175], v[116:119]
	v_mfma_f32_16x16x32_bf16 v[108:111], v[140:143], v[172:175], v[108:111]
	v_mfma_f32_16x16x32_bf16 v[100:103], v[132:135], v[180:183], v[100:103]
	v_mfma_f32_16x16x32_bf16 v[92:95], v[140:143], v[180:183], v[92:95]
	v_mfma_f32_16x16x32_bf16 v[84:87], v[132:135], v[188:191], v[84:87]
	v_mfma_f32_16x16x32_bf16 v[76:79], v[140:143], v[188:191], v[76:79]
	s_setprio 0
	s_setprio 1
	v_mfma_f32_16x16x32_bf16 v[112:115], v[144:147], v[160:163], 0
	v_mfma_f32_16x16x32_bf16 v[104:107], v[152:155], v[160:163], 0
	v_mfma_f32_16x16x32_bf16 v[96:99], v[144:147], v[168:171], 0
	v_mfma_f32_16x16x32_bf16 v[88:91], v[152:155], v[168:171], 0
	v_mfma_f32_16x16x32_bf16 v[80:83], v[144:147], v[176:179], 0
	v_mfma_f32_16x16x32_bf16 v[72:75], v[152:155], v[176:179], 0
	v_mfma_f32_16x16x32_bf16 v[68:71], v[144:147], v[184:187], 0
	v_mfma_f32_16x16x32_bf16 v[64:67], v[152:155], v[184:187], 0
	v_mfma_f32_16x16x32_bf16 v[112:115], v[148:151], v[164:167], v[112:115]
	v_mfma_f32_16x16x32_bf16 v[104:107], v[156:159], v[164:167], v[104:107]
	v_mfma_f32_16x16x32_bf16 v[96:99], v[148:151], v[172:175], v[96:99]
	v_mfma_f32_16x16x32_bf16 v[88:91], v[156:159], v[172:175], v[88:91]
	v_mfma_f32_16x16x32_bf16 v[80:83], v[148:151], v[180:183], v[80:83]
	v_mfma_f32_16x16x32_bf16 v[72:75], v[156:159], v[180:183], v[72:75]
	v_mfma_f32_16x16x32_bf16 v[68:71], v[148:151], v[188:191], v[68:71]
	v_mfma_f32_16x16x32_bf16 v[64:67], v[156:159], v[188:191], v[64:67]
	s_setprio 0
	s_barrier
; #define PG8_STAGE(bufoff, gbase, voff) do { _Pragma("unroll") for (int _i = 0; _i < 2; ++_i) \
;         __builtin_amdgcn_global_load_lds((const unsigned*)((const char*)(gbase) + (voff)[_i]), (PG8_LAS unsigned*)(lds + (bufoff) + ldsw + _i * 8192), 16, 0, 0); } while (0)
; #define PG8_LDA(dst, b, h) do { _Pragma("unroll") for (int m = 0; m < 4; ++m) _Pragma("unroll") for (int k = 0; k < 2; ++k) dst[m][k] = *(const PG8_LAS bf16x8*)(lds + PG8_SA(b, h) + aoff + m * 2048 + k * 1024); } while (0)
; #define PG8_LDB(dst, b, h) do { _Pragma("unroll") for (int n = 0; n < 2; ++n) _Pragma("unroll") for (int k = 0; k < 2; ++k) dst[n][k] = *(const PG8_LAS bf16x8*)(lds + PG8_SB(b, h) + boff + n * 2048 + k * 1024); } while (0)
; #define PG8_MMA(ai, bj, At, Bt) do { __builtin_amdgcn_s_setprio(1); _Pragma("unroll") for (int m = 0; m < 4; ++m) _Pragma("unroll") for (int n = 0; n < 2; ++n) _Pragma("unroll") for (int k = 0; k < 2; ++k) \
;         acc[ai][bj][m][n] = __builtin_amdgcn_mfma_f32_16x16x32_bf16(Bt[n][k], At[m][k], acc[ai][bj][m][n], 0, 0, 0); __builtin_amdgcn_s_setprio(0); } while (0)
; #define PG8_WAIT_V(n) asm volatile("s_waitcnt vmcnt(" #n ")" ::: "memory")
; #define PG8_WAIT_L(n) asm volatile("s_waitcnt lgkmcnt(" #n ")" ::: "memory")
; #define PG8_BAR __builtin_amdgcn_s_barrier()
; #define PG8_SCHED __builtin_amdgcn_sched_barrier(0)
; template <class Epi, class Sched, bool ALIGN_EPI = false, bool SP2 = false>
; __device__ __forceinline__ void gemm_phase(PG8_LAS unsigned char* lds, const Gemm g, const Sched& S, const Epi& E) {
;     ...
;             PG8_LDA(At, 0, 1); PG8_STAGE(PG8_SB(0, 0), b2, voffB); PG8_STAGE(PG8_SB(0, 1), b2 + hstepB, voffB); PG8_STAGE(PG8_SA(0, 0), a2, voffA);
;             PG8_WAIT_V(8); PG8_WAIT_L(0); PG8_BAR; if (whole) { PG8_MMA(1, 0, At, B0); PG8_MMA(1, 1, At, B1); } PG8_BAR; PG8_SCHED;
;             PG8_LDB(B0, 1, 0); PG8_LDB(B1, 1, 1); PG8_SCHED; PG8_LDA(At, 1, 0); PG8_STAGE(PG8_SA(0, 1), a2 + hstepA, voffA);
;             PG8_WAIT_V(8); PG8_WAIT_L(0); PG8_BAR; PG8_MMA(0, 0, At, B0); if (whole) PG8_MMA(0, 1, At, B1); PG8_BAR; PG8_SCHED;
	s_add_i32 s50, s60, s8
	v_lshl_add_u64 v[204:205], s[54:55], 0, v[194:195]
	s_mov_b32 m0, s50
	ds_read_b128 v[160:163], v244 offset:16384
	ds_read_b128 v[164:167], v244 offset:17408
	ds_read_b128 v[168:171], v244 offset:18432
	ds_read_b128 v[172:175], v244 offset:19456
	ds_read_b128 v[176:179], v244 offset:20480
	ds_read_b128 v[180:183], v244 offset:21504
	ds_read_b128 v[184:187], v244 offset:22528
	ds_read_b128 v[188:191], v244 offset:23552
	global_load_lds_dwordx4 v[204:205], off
	s_add_i32 m0, s50, 0x2000
	s_add_u32 s50, s54, 0x100000
	v_lshl_add_u64 v[206:207], s[54:55], 0, v[198:199]
	s_addc_u32 s51, s55, 0
	s_add_i32 s94, s61, s8
	global_load_lds_dwordx4 v[206:207], off
	v_lshl_add_u64 v[208:209], s[50:51], 0, v[194:195]
	s_mov_b32 m0, s94
	s_nop 0
	global_load_lds_dwordx4 v[208:209], off
	v_lshl_add_u64 v[208:209], s[50:51], 0, v[198:199]
	s_add_i32 m0, s94, 0x2000
	s_nop 0
	global_load_lds_dwordx4 v[208:209], off
	v_lshl_add_u64 v[208:209], s[56:57], 0, v[192:193]
	s_mov_b32 m0, s28
	s_nop 0
	global_load_lds_dwordx4 v[208:209], off
	v_lshl_add_u64 v[208:209], s[56:57], 0, v[196:197]
	s_mov_b32 m0, s29
	s_nop 0
	global_load_lds_dwordx4 v[208:209], off
	s_waitcnt vmcnt(16)
	s_waitcnt lgkmcnt(0)
	s_barrier
	s_setprio 1
	s_waitcnt lgkmcnt(0)
	v_mfma_f32_16x16x32_bf16 v[60:63], v[128:131], v[160:163], 0
	v_mfma_f32_16x16x32_bf16 v[56:59], v[136:139], v[160:163], 0
	v_mfma_f32_16x16x32_bf16 v[52:55], v[128:131], v[168:171], 0
	v_mfma_f32_16x16x32_bf16 v[44:47], v[136:139], v[168:171], 0
	v_mfma_f32_16x16x32_bf16 v[36:39], v[128:131], v[176:179], 0
	v_mfma_f32_16x16x32_bf16 v[28:31], v[136:139], v[176:179], 0
	v_mfma_f32_16x16x32_bf16 v[20:23], v[128:131], v[184:187], 0
	v_mfma_f32_16x16x32_bf16 v[12:15], v[136:139], v[184:187], 0
	v_mfma_f32_16x16x32_bf16 v[60:63], v[132:135], v[164:167], v[60:63]
	v_mfma_f32_16x16x32_bf16 v[56:59], v[140:143], v[164:167], v[56:59]
	v_mfma_f32_16x16x32_bf16 v[52:55], v[132:135], v[172:175], v[52:55]
	v_mfma_f32_16x16x32_bf16 v[44:47], v[140:143], v[172:175], v[44:47]
	v_mfma_f32_16x16x32_bf16 v[36:39], v[132:135], v[180:183], v[36:39]
	v_mfma_f32_16x16x32_bf16 v[28:31], v[140:143], v[180:183], v[28:31]
	v_mfma_f32_16x16x32_bf16 v[20:23], v[132:135], v[188:191], v[20:23]
	v_mfma_f32_16x16x32_bf16 v[12:15], v[140:143], v[188:191], v[12:15]
	s_setprio 0
	s_setprio 1
	v_mfma_f32_16x16x32_bf16 v[48:51], v[144:147], v[160:163], 0
	v_mfma_f32_16x16x32_bf16 v[40:43], v[152:155], v[160:163], 0
	v_mfma_f32_16x16x32_bf16 v[32:35], v[144:147], v[168:171], 0
	v_mfma_f32_16x16x32_bf16 v[24:27], v[152:155], v[168:171], 0
	v_mfma_f32_16x16x32_bf16 v[16:19], v[144:147], v[176:179], 0
	v_mfma_f32_16x16x32_bf16 v[8:11], v[152:155], v[176:179], 0
	v_mfma_f32_16x16x32_bf16 v[4:7], v[144:147], v[184:187], 0
	v_mfma_f32_16x16x32_bf16 v[0:3], v[152:155], v[184:187], 0
	v_mfma_f32_16x16x32_bf16 v[48:51], v[148:151], v[164:167], v[48:51]
	v_mfma_f32_16x16x32_bf16 v[40:43], v[156:159], v[164:167], v[40:43]
	v_mfma_f32_16x16x32_bf16 v[32:35], v[148:151], v[172:175], v[32:35]
	v_mfma_f32_16x16x32_bf16 v[24:27], v[156:159], v[172:175], v[24:27]
	v_mfma_f32_16x16x32_bf16 v[16:19], v[148:151], v[180:183], v[16:19]
	v_mfma_f32_16x16x32_bf16 v[8:11], v[156:159], v[180:183], v[8:11]
	v_mfma_f32_16x16x32_bf16 v[4:7], v[148:151], v[188:191], v[4:7]
	v_mfma_f32_16x16x32_bf16 v[0:3], v[156:159], v[188:191], v[0:3]
	s_setprio 0
	s_barrier
	s_add_i32 s94, 0, 0x18000
	s_add_i32 s95, 0, 0x1c000
	v_add_u32_e32 v140, s94, v240
	v_add_u32_e32 v156, s95, v240
	ds_read_b128 v[128:131], v140
	ds_read_b128 v[132:135], v140 offset:1024
	ds_read_b128 v[136:139], v140 offset:2048
	ds_read_b128 v[140:143], v140 offset:3072
	ds_read_b128 v[144:147], v156
	ds_read_b128 v[148:151], v156 offset:1024
	ds_read_b128 v[152:155], v156 offset:2048
	ds_read_b128 v[156:159], v156 offset:3072
	s_add_u32 s50, s56, 0x2000
	s_addc_u32 s51, s57, 0
	s_mov_b32 m0, s47
	v_lshl_add_u64 v[208:209], s[50:51], 0, v[192:193]
	ds_read_b128 v[160:163], v244 offset:32768
	ds_read_b128 v[164:167], v244 offset:33792
	ds_read_b128 v[168:171], v244 offset:34816
	ds_read_b128 v[172:175], v244 offset:35840
	ds_read_b128 v[176:179], v244 offset:36864
	ds_read_b128 v[180:183], v244 offset:37888
	ds_read_b128 v[184:187], v244 offset:38912
	ds_read_b128 v[188:191], v244 offset:39936
	global_load_lds_dwordx4 v[208:209], off
	v_lshl_add_u64 v[208:209], s[50:51], 0, v[196:197]
	s_mov_b32 m0, s49
	s_nop 0
	global_load_lds_dwordx4 v[208:209], off
	s_waitcnt vmcnt(8)
	s_waitcnt lgkmcnt(0)
	s_barrier
; #define PG8_STAGE(bufoff, gbase, voff) do { _Pragma("unroll") for (int _i = 0; _i < 2; ++_i) \
;         __builtin_amdgcn_global_load_lds((const unsigned*)((const char*)(gbase) + (voff)[_i]), (PG8_LAS unsigned*)(lds + (bufoff) + ldsw + _i * 8192), 16, 0, 0); } while (0)
; #define PG8_LDA(dst, b, h) do { _Pragma("unroll") for (int m = 0; m < 4; ++m) _Pragma("unroll") for (int k = 0; k < 2; ++k) dst[m][k] = *(const PG8_LAS bf16x8*)(lds + PG8_SA(b, h) + aoff + m * 2048 + k * 1024); } while (0)
; #define PG8_MMA(ai, bj, At, Bt) do { __builtin_amdgcn_s_setprio(1); _Pragma("unroll") for (int m = 0; m < 4; ++m) _Pragma("unroll") for (int n = 0; n < 2; ++n) _Pragma("unroll") for (int k = 0; k < 2; ++k) \
;         acc[ai][bj][m][n] = __builtin_amdgcn_mfma_f32_16x16x32_bf16(Bt[n][k], At[m][k], acc[ai][bj][m][n], 0, 0, 0); __builtin_amdgcn_s_setprio(0); } while (0)
; #define PG8_WAIT_V(n) asm volatile("s_waitcnt vmcnt(" #n ")" ::: "memory")
; #define PG8_WAIT_L(n) asm volatile("s_waitcnt lgkmcnt(" #n ")" ::: "memory")
; #define PG8_BAR __builtin_amdgcn_s_barrier()
; #define PG8_SCHED __builtin_amdgcn_sched_barrier(0)
; template <class Epi, class Sched, bool ALIGN_EPI = false, bool SP2 = false>
; __device__ __forceinline__ void gemm_phase(PG8_LAS unsigned char* lds, const Gemm g, const Sched& S, const Epi& E) {
;     ...
;         for (int t = 0; t < nt; t += 2) {
;     ...
;             PG8_WAIT_V(8); PG8_WAIT_L(0); PG8_BAR; PG8_MMA(0, 0, At, B0); if (whole) PG8_MMA(0, 1, At, B1); PG8_BAR; PG8_SCHED;
;             PG8_LDA(At, 1, 1); PG8_STAGE(PG8_SB(1, 0), b3, voffB); PG8_STAGE(PG8_SB(1, 1), b3 + hstepB, voffB); PG8_STAGE(PG8_SA(1, 0), a3, voffA);
;             PG8_WAIT_V(8); PG8_WAIT_L(0); PG8_BAR; if (whole) { PG8_MMA(1, 0, At, B0); PG8_MMA(1, 1, At, B1); } PG8_BAR; PG8_SCHED;
	s_setprio 1
	s_waitcnt lgkmcnt(0)
	v_mfma_f32_16x16x32_bf16 v[124:127], v[128:131], v[160:163], v[124:127]
	v_mfma_f32_16x16x32_bf16 v[120:123], v[136:139], v[160:163], v[120:123]
	v_mfma_f32_16x16x32_bf16 v[116:119], v[128:131], v[168:171], v[116:119]
	v_mfma_f32_16x16x32_bf16 v[108:111], v[136:139], v[168:171], v[108:111]
	v_mfma_f32_16x16x32_bf16 v[100:103], v[128:131], v[176:179], v[100:103]
	v_mfma_f32_16x16x32_bf16 v[92:95], v[136:139], v[176:179], v[92:95]
	v_mfma_f32_16x16x32_bf16 v[84:87], v[128:131], v[184:187], v[84:87]
	v_mfma_f32_16x16x32_bf16 v[76:79], v[136:139], v[184:187], v[76:79]
	v_mfma_f32_16x16x32_bf16 v[124:127], v[132:135], v[164:167], v[124:127]
	v_mfma_f32_16x16x32_bf16 v[120:123], v[140:143], v[164:167], v[120:123]
	v_mfma_f32_16x16x32_bf16 v[116:119], v[132:135], v[172:175], v[116:119]
	v_mfma_f32_16x16x32_bf16 v[108:111], v[140:143], v[172:175], v[108:111]
	v_mfma_f32_16x16x32_bf16 v[100:103], v[132:135], v[180:183], v[100:103]
	v_mfma_f32_16x16x32_bf16 v[92:95], v[140:143], v[180:183], v[92:95]
	v_mfma_f32_16x16x32_bf16 v[84:87], v[132:135], v[188:191], v[84:87]
	v_mfma_f32_16x16x32_bf16 v[76:79], v[140:143], v[188:191], v[76:79]
	s_setprio 0
	s_setprio 1
	v_mfma_f32_16x16x32_bf16 v[112:115], v[144:147], v[160:163], v[112:115]
	v_mfma_f32_16x16x32_bf16 v[104:107], v[152:155], v[160:163], v[104:107]
	v_mfma_f32_16x16x32_bf16 v[96:99], v[144:147], v[168:171], v[96:99]
	v_mfma_f32_16x16x32_bf16 v[88:91], v[152:155], v[168:171], v[88:91]
	v_mfma_f32_16x16x32_bf16 v[80:83], v[144:147], v[176:179], v[80:83]
	v_mfma_f32_16x16x32_bf16 v[72:75], v[152:155], v[176:179], v[72:75]
	v_mfma_f32_16x16x32_bf16 v[68:71], v[144:147], v[184:187], v[68:71]
	v_mfma_f32_16x16x32_bf16 v[64:67], v[152:155], v[184:187], v[64:67]
	v_mfma_f32_16x16x32_bf16 v[112:115], v[148:151], v[164:167], v[112:115]
	v_mfma_f32_16x16x32_bf16 v[104:107], v[156:159], v[164:167], v[104:107]
	v_mfma_f32_16x16x32_bf16 v[96:99], v[148:151], v[172:175], v[96:99]
	v_mfma_f32_16x16x32_bf16 v[88:91], v[156:159], v[172:175], v[88:91]
	v_mfma_f32_16x16x32_bf16 v[80:83], v[148:151], v[180:183], v[80:83]
	v_mfma_f32_16x16x32_bf16 v[72:75], v[156:159], v[180:183], v[72:75]
	v_mfma_f32_16x16x32_bf16 v[68:71], v[148:151], v[188:191], v[68:71]
	v_mfma_f32_16x16x32_bf16 v[64:67], v[156:159], v[188:191], v[64:67]
	s_setprio 0
	s_barrier
	s_add_i32 s50, s94, s8
	v_lshl_add_u64 v[204:205], v[204:205], 0, s[20:21]
	s_mov_b32 m0, s50
	ds_read_b128 v[160:163], v244 offset:49152
	ds_read_b128 v[164:167], v244 offset:50176
	ds_read_b128 v[168:171], v244 offset:51200
	ds_read_b128 v[172:175], v244 offset:52224
	ds_read_b128 v[176:179], v244 offset:53248
	ds_read_b128 v[180:183], v244 offset:54272
	ds_read_b128 v[184:187], v244 offset:55296
	ds_read_b128 v[188:191], v244 offset:56320
	global_load_lds_dwordx4 v[204:205], off
	s_add_i32 m0, s50, 0x2000
	s_add_u32 s50, s54, 0x100080
	v_lshl_add_u64 v[204:205], v[206:207], 0, s[20:21]
	s_addc_u32 s51, s55, 0
	s_add_i32 s54, s95, s8
	global_load_lds_dwordx4 v[204:205], off
	v_lshl_add_u64 v[204:205], s[50:51], 0, v[194:195]
	s_mov_b32 m0, s54
	s_nop 0
	global_load_lds_dwordx4 v[204:205], off
	v_lshl_add_u64 v[204:205], s[50:51], 0, v[198:199]
	s_add_i32 m0, s54, 0x2000
	s_nop 0
	global_load_lds_dwordx4 v[204:205], off
	v_lshl_add_u64 v[204:205], s[6:7], 0, v[192:193]
	s_mov_b32 m0, s58
	s_nop 0
	global_load_lds_dwordx4 v[204:205], off
	v_lshl_add_u64 v[204:205], s[6:7], 0, v[196:197]
	s_mov_b32 m0, s59
	s_nop 0
	global_load_lds_dwordx4 v[204:205], off
	s_waitcnt vmcnt(8)
	s_waitcnt lgkmcnt(0)
	s_barrier
	s_setprio 1
	s_waitcnt lgkmcnt(0)
	v_mfma_f32_16x16x32_bf16 v[60:63], v[128:131], v[160:163], v[60:63]
	v_mfma_f32_16x16x32_bf16 v[56:59], v[136:139], v[160:163], v[56:59]
	v_mfma_f32_16x16x32_bf16 v[52:55], v[128:131], v[168:171], v[52:55]
	v_mfma_f32_16x16x32_bf16 v[44:47], v[136:139], v[168:171], v[44:47]
	v_mfma_f32_16x16x32_bf16 v[36:39], v[128:131], v[176:179], v[36:39]
	v_mfma_f32_16x16x32_bf16 v[28:31], v[136:139], v[176:179], v[28:31]
	v_mfma_f32_16x16x32_bf16 v[20:23], v[128:131], v[184:187], v[20:23]
	v_mfma_f32_16x16x32_bf16 v[12:15], v[136:139], v[184:187], v[12:15]
	v_mfma_f32_16x16x32_bf16 v[60:63], v[132:135], v[164:167], v[60:63]
	v_mfma_f32_16x16x32_bf16 v[56:59], v[140:143], v[164:167], v[56:59]
	v_mfma_f32_16x16x32_bf16 v[52:55], v[132:135], v[172:175], v[52:55]
	v_mfma_f32_16x16x32_bf16 v[44:47], v[140:143], v[172:175], v[44:47]
	v_mfma_f32_16x16x32_bf16 v[36:39], v[132:135], v[180:183], v[36:39]
	v_mfma_f32_16x16x32_bf16 v[28:31], v[140:143], v[180:183], v[28:31]
	v_mfma_f32_16x16x32_bf16 v[20:23], v[132:135], v[188:191], v[20:23]
	v_mfma_f32_16x16x32_bf16 v[12:15], v[140:143], v[188:191], v[12:15]
	s_setprio 0
	s_setprio 1
	v_mfma_f32_16x16x32_bf16 v[48:51], v[144:147], v[160:163], v[48:51]
	v_mfma_f32_16x16x32_bf16 v[40:43], v[152:155], v[160:163], v[40:43]
	v_mfma_f32_16x16x32_bf16 v[32:35], v[144:147], v[168:171], v[32:35]
	v_mfma_f32_16x16x32_bf16 v[24:27], v[152:155], v[168:171], v[24:27]
	v_mfma_f32_16x16x32_bf16 v[16:19], v[144:147], v[176:179], v[16:19]
	v_mfma_f32_16x16x32_bf16 v[8:11], v[152:155], v[176:179], v[8:11]
	v_mfma_f32_16x16x32_bf16 v[4:7], v[144:147], v[184:187], v[4:7]
	v_mfma_f32_16x16x32_bf16 v[0:3], v[152:155], v[184:187], v[0:3]
	v_mfma_f32_16x16x32_bf16 v[48:51], v[148:151], v[164:167], v[48:51]
	v_mfma_f32_16x16x32_bf16 v[40:43], v[156:159], v[164:167], v[40:43]
	v_mfma_f32_16x16x32_bf16 v[32:35], v[148:151], v[172:175], v[32:35]
	v_mfma_f32_16x16x32_bf16 v[24:27], v[156:159], v[172:175], v[24:27]
	v_mfma_f32_16x16x32_bf16 v[16:19], v[148:151], v[180:183], v[16:19]
	v_mfma_f32_16x16x32_bf16 v[8:11], v[156:159], v[180:183], v[8:11]
	v_mfma_f32_16x16x32_bf16 v[4:7], v[148:151], v[188:191], v[4:7]
	v_mfma_f32_16x16x32_bf16 v[0:3], v[156:159], v[188:191], v[0:3]
	s_setprio 0
	s_barrier
	s_add_u32 s91, s91, 0x100
	s_addc_u32 s92, s92, 0
	s_cmp_ge_u32 s93, s9
	s_mov_b64 s[50:51], s[52:53]
	s_mov_b32 s6, s93
	s_cbranch_scc0 .LBB0_1303
	s_branch .Lpeel_exit_down1

; #define PG8_BAR __builtin_amdgcn_s_barrier()
;     __device__ __forceinline__ void operator()(const f32x4 (&acc)[2][2][4][2], const Unit& u, int wr, int wc, int fr, int fq) const {
;     ...
;         u32x4 xo[2][4][2];
; #pragma unroll
;         for (int ai = 0; ai < 2; ++ai)
; #pragma unroll
;             for (int m = 0; m < 4; ++m)
; #pragma unroll
;                 for (int bj = 0; bj < 2; ++bj) xo[ai][m][bj] = *(const u32x4*)(xb + (size_t)(row0 + ai * HALF + m * 16) * 1024 + col0 + bj * HALF);
; #pragma unroll
;         for (int ai = 0; ai < 2; ++ai)
; #pragma unroll
;             for (int m = 0; m < 4; ++m) {
;                 const int row = row0 + ai * HALF + m * 16;
;                 bf16_t* xr = xb + (size_t)row * 1024 + col0;
;                 float part_ss = 0.f;
; #pragma unroll
;                 for (int bj = 0; bj < 2; ++bj) {
;                     const u32x4 o = xo[ai][m][bj];
;                     f32x4 v0 = acc[ai][bj][m][0], v1 = acc[ai][bj][m][1];
;                     v0[0] += __uint_as_float(o.x << 16); v0[1] += __uint_as_float(o.x & 0xffff0000u); v0[2] += __uint_as_float(o.y << 16); v0[3] += __uint_as_float(o.y & 0xffff0000u);
;                     v1[0] += __uint_as_float(o.z << 16); v1[1] += __uint_as_float(o.z & 0xffff0000u); v1[2] += __uint_as_float(o.w << 16); v1[3] += __uint_as_float(o.w & 0xffff0000u);
;                     if (xout) { float* xo = xout + (size_t)row * 1024 + col0 + bj * HALF; *(f32x4*)xo = v0; *(f32x4*)(xo + 4) = v1; }
;                     else { u32x4 w; w.x = cvt_pk_bf16(v0[0], v0[1]); w.y = cvt_pk_bf16(v0[2], v0[3]); w.z = cvt_pk_bf16(v1[0], v1[1]); w.w = cvt_pk_bf16(v1[2], v1[3]); *(u32x4*)(xr + bj * HALF) = w; }
;                     part_ss += (v0[0] * v0[0] + v0[1] * v0[1]) + (v0[2] * v0[2] + v0[3] * v0[3]) + (v1[0] * v1[0] + v1[1] * v1[1]) + (v1[2] * v1[2] + v1[3] * v1[3]);
;                 }
;                 part_ss += __shfl_xor(part_ss, 16); part_ss += __shfl_xor(part_ss, 32);
;                 if (fq == 0) atomicAdd(ss + row, part_ss);
; template <class Epi, class Sched, bool ALIGN_EPI = false, bool SP2 = false>
; __device__ __forceinline__ void gemm_phase(PG8_LAS unsigned char* lds, const Gemm g, const Sched& S, const Epi& E) {
;     ...
;         if constexpr (ALIGN_EPI) { if (wr == 0) PG8_BAR; }
.Lpeel_exit_down1:
	s_and_b64 vcc, exec, s[22:23]
	s_cbranch_vccz .LBB0_1306
	s_barrier
.LBB0_1306:
	v_lshl_add_u32 v206, s46, 8, v239
	v_lshl_or_b32 v204, s48, 8, v241
	s_mov_b64 s[6:7], -1
	s_cmp_lt_i32 s16, 0
	v_ashrrev_i32_e32 v205, 31, v204
	v_ashrrev_i32_e32 v207, 31, v206
	s_cbranch_scc0 .LBB0_1325
	v_lshlrev_b64 v[236:237], 1, v[204:205]
	v_lshl_add_u64 v[128:129], s[30:31], 0, v[236:237]
	v_lshlrev_b64 v[246:247], 11, v[206:207]
	v_lshl_add_u64 v[130:131], v[128:129], 0, v[246:247]
	global_load_dwordx4 v[188:191], v[130:131], off
	global_load_dwordx4 v[184:187], v[130:131], off offset:256
	v_or_b32_e32 v230, 16, v206
	v_ashrrev_i32_e32 v231, 31, v230
	v_or_b32_e32 v226, 32, v206
	v_lshlrev_b64 v[234:235], 11, v[230:231]
	v_ashrrev_i32_e32 v227, 31, v226
	v_or_b32_e32 v222, 48, v206
	v_lshl_add_u64 v[130:131], v[128:129], 0, v[234:235]
	v_lshlrev_b64 v[232:233], 11, v[226:227]
	v_ashrrev_i32_e32 v223, 31, v222
	v_add_u32_e32 v218, 0x80, v206
	global_load_dwordx4 v[180:183], v[130:131], off
	global_load_dwordx4 v[176:179], v[130:131], off offset:256
	v_lshl_add_u64 v[130:131], v[128:129], 0, v[232:233]
	v_lshlrev_b64 v[228:229], 11, v[222:223]
	v_ashrrev_i32_e32 v219, 31, v218
	v_add_u32_e32 v214, 0x90, v206
	global_load_dwordx4 v[172:175], v[130:131], off
	global_load_dwordx4 v[168:171], v[130:131], off offset:256
	v_lshl_add_u64 v[130:131], v[128:129], 0, v[228:229]
	v_lshlrev_b64 v[224:225], 11, v[218:219]
	v_ashrrev_i32_e32 v215, 31, v214
	v_add_u32_e32 v210, 0xa0, v206
	v_add_u32_e32 v208, 0xb0, v206
	global_load_dwordx4 v[164:167], v[130:131], off
	global_load_dwordx4 v[160:163], v[130:131], off offset:256
	v_lshl_add_u64 v[130:131], v[128:129], 0, v[224:225]
	v_lshlrev_b64 v[220:221], 11, v[214:215]
	v_ashrrev_i32_e32 v211, 31, v210
	v_ashrrev_i32_e32 v209, 31, v208
	global_load_dwordx4 v[156:159], v[130:131], off
	global_load_dwordx4 v[152:155], v[130:131], off offset:256
	v_lshl_add_u64 v[130:131], v[128:129], 0, v[220:221]
	v_lshlrev_b64 v[216:217], 11, v[210:211]
	v_lshlrev_b64 v[212:213], 11, v[208:209]
	global_load_dwordx4 v[148:151], v[130:131], off
	global_load_dwordx4 v[144:147], v[130:131], off offset:256
	v_lshl_add_u64 v[130:131], v[128:129], 0, v[216:217]
	v_lshl_add_u64 v[128:129], v[128:129], 0, v[212:213]
	global_load_dwordx4 v[140:143], v[130:131], off
	global_load_dwordx4 v[136:139], v[130:131], off offset:256
	global_load_dwordx4 v[132:135], v[128:129], off
	s_nop 0
	global_load_dwordx4 v[128:131], v[128:129], off offset:256
	v_lshl_add_u64 v[246:247], s[30:31], 0, v[246:247]
	v_lshl_add_u64 v[236:237], v[246:247], 0, v[236:237]
	s_waitcnt vmcnt(0)
	v_lshlrev_b32_e32 v246, 16, v188
	v_and_b32_e32 v188, 0xffff0000, v188
	v_add_f32_e32 v247, v125, v188
	v_lshlrev_b32_e32 v188, 16, v189
	v_add_f32_e32 v248, v126, v188
	v_and_b32_e32 v188, 0xffff0000, v189
	v_add_f32_e32 v249, v127, v188
	v_lshlrev_b32_e32 v188, 16, v190
	v_add_f32_e32 v250, v120, v188
	v_and_b32_e32 v188, 0xffff0000, v190
	v_add_f32_e32 v251, v121, v188
	v_lshlrev_b32_e32 v188, 16, v191
	v_add_f32_e32 v252, v122, v188
	v_and_b32_e32 v188, 0xffff0000, v191
	v_add_f32_e32 v246, v124, v246
	v_add_f32_e32 v253, v123, v188
	v_cvt_pk_bf16_f32 v188, v246, v247
	v_cvt_pk_bf16_f32 v189, v248, v249
	v_cvt_pk_bf16_f32 v190, v250, v251
	v_cvt_pk_bf16_f32 v191, v252, v253
	global_store_dwordx4 v[236:237], v[188:191], off sc1
	s_nop 1
	v_mul_f32_e32 v188, v247, v247
	v_mul_f32_e32 v189, v249, v249
	v_fmac_f32_e32 v188, v246, v246
	v_fmac_f32_e32 v189, v248, v248
	v_add_f32_e32 v188, v188, v189
	v_mul_f32_e32 v189, v251, v251
	v_fmac_f32_e32 v189, v250, v250
	v_add_f32_e32 v188, v189, v188
	v_mul_f32_e32 v189, v253, v253
	v_fmac_f32_e32 v189, v252, v252
	v_add_f32_e32 v188, v189, v188
	v_lshlrev_b32_e32 v189, 16, v184
	v_and_b32_e32 v184, 0xffff0000, v184
	v_add_f32_e32 v190, v113, v184
	v_lshlrev_b32_e32 v184, 16, v185
	v_add_f32_e32 v191, v114, v184
	v_and_b32_e32 v184, 0xffff0000, v185
	v_add_f32_e32 v246, v115, v184
	v_lshlrev_b32_e32 v184, 16, v186
	v_add_f32_e32 v247, v104, v184
	v_and_b32_e32 v184, 0xffff0000, v186
	v_add_f32_e32 v248, v105, v184
	v_lshlrev_b32_e32 v184, 16, v187
	v_add_f32_e32 v249, v106, v184
	v_and_b32_e32 v184, 0xffff0000, v187
	v_add_f32_e32 v189, v112, v189
	v_add_f32_e32 v250, v107, v184
	v_cvt_pk_bf16_f32 v184, v189, v190
	v_cvt_pk_bf16_f32 v185, v191, v246
	v_cvt_pk_bf16_f32 v186, v247, v248
	v_cvt_pk_bf16_f32 v187, v249, v250
	global_store_dwordx4 v[236:237], v[184:187], off offset:256 sc1
	s_nop 1
	v_mul_f32_e32 v184, v190, v190
	v_mul_f32_e32 v185, v246, v246
	v_fmac_f32_e32 v184, v189, v189
	v_fmac_f32_e32 v185, v191, v191
	v_add_f32_e32 v184, v184, v185
	v_mul_f32_e32 v185, v248, v248
	v_fmac_f32_e32 v185, v247, v247
	v_add_f32_e32 v184, v185, v184
	v_mul_f32_e32 v185, v250, v250
	v_fmac_f32_e32 v185, v249, v249
	v_add_f32_e32 v184, v185, v184
	v_and_b32_e32 v186, 64, v245
	v_add_f32_e32 v185, v188, v184
	v_xor_b32_e32 v184, 16, v245
	v_add_u32_e32 v187, 64, v186
	v_cmp_lt_i32_e32 vcc, v184, v187
	s_nop 1
	v_cndmask_b32_e32 v184, v245, v184, vcc
	v_lshlrev_b32_e32 v184, 2, v184
	ds_bpermute_b32 v186, v184, v185
	s_waitcnt lgkmcnt(0)
	v_add_f32_e32 v186, v185, v186
	v_xor_b32_e32 v185, 32, v245
	v_cmp_lt_i32_e32 vcc, v185, v187
	s_nop 1
	v_cndmask_b32_e32 v185, v245, v185, vcc
	v_lshlrev_b32_e32 v185, 2, v185
	ds_bpermute_b32 v187, v185, v186
	s_and_saveexec_b64 s[6:7], s[2:3]
	s_cbranch_execz .LBB0_1309
	s_waitcnt lgkmcnt(0)
	v_add_f32_e32 v188, v186, v187
	v_lshl_add_u64 v[186:187], v[206:207], 2, s[18:19]
	global_atomic_add_f32 v[186:187], v188, off
; __device__ __forceinline__ unsigned cvt_pk_bf16(float lo, float hi) { unsigned r; asm volatile("v_cvt_pk_bf16_f32 %0, %1, %2" : "=v"(r) : "v"(lo), "v"(hi)); return r; }
;     __device__ __forceinline__ void operator()(const f32x4 (&acc)[2][2][4][2], const Unit& u, int wr, int wc, int fr, int fq) const {
;     ...
;         for (int ai = 0; ai < 2; ++ai)
; #pragma unroll
;             for (int m = 0; m < 4; ++m) {
;                 const int row = row0 + ai * HALF + m * 16;
;                 bf16_t* xr = xb + (size_t)row * 1024 + col0;
;                 float part_ss = 0.f;
; #pragma unroll
;                 for (int bj = 0; bj < 2; ++bj) {
;                     const u32x4 o = xo[ai][m][bj];
;                     f32x4 v0 = acc[ai][bj][m][0], v1 = acc[ai][bj][m][1];
;                     v0[0] += __uint_as_float(o.x << 16); v0[1] += __uint_as_float(o.x & 0xffff0000u); v0[2] += __uint_as_float(o.y << 16); v0[3] += __uint_as_float(o.y & 0xffff0000u);
;                     v1[0] += __uint_as_float(o.z << 16); v1[1] += __uint_as_float(o.z & 0xffff0000u); v1[2] += __uint_as_float(o.w << 16); v1[3] += __uint_as_float(o.w & 0xffff0000u);
;                     if (xout) { float* xo = xout + (size_t)row * 1024 + col0 + bj * HALF; *(f32x4*)xo = v0; *(f32x4*)(xo + 4) = v1; }
;                     else { u32x4 w; w.x = cvt_pk_bf16(v0[0], v0[1]); w.y = cvt_pk_bf16(v0[2], v0[3]); w.z = cvt_pk_bf16(v1[0], v1[1]); w.w = cvt_pk_bf16(v1[2], v1[3]); *(u32x4*)(xr + bj * HALF) = w; }
;                     part_ss += (v0[0] * v0[0] + v0[1] * v0[1]) + (v0[2] * v0[2] + v0[3] * v0[3]) + (v1[0] * v1[0] + v1[1] * v1[1]) + (v1[2] * v1[2] + v1[3] * v1[3]);
;                 }
;                 part_ss += __shfl_xor(part_ss, 16); part_ss += __shfl_xor(part_ss, 32);
;                 if (fq == 0) atomicAdd(ss + row, part_ss);
.LBB0_1309:
	s_or_b64 exec, exec, s[6:7]
	v_lshlrev_b32_e32 v188, 16, v180
	v_and_b32_e32 v180, 0xffff0000, v180
	v_add_f32_e32 v189, v117, v180
	v_lshlrev_b32_e32 v180, 16, v181
	v_add_f32_e32 v190, v118, v180
	v_and_b32_e32 v180, 0xffff0000, v181
	v_add_f32_e32 v191, v119, v180
	v_lshlrev_b32_e32 v180, 16, v182
	s_waitcnt lgkmcnt(0)
	v_lshl_add_u64 v[186:187], s[30:31], 0, v[234:235]
	v_add_f32_e32 v234, v108, v180
	v_and_b32_e32 v180, 0xffff0000, v182
	v_add_f32_e32 v182, v109, v180
	v_lshlrev_b32_e32 v180, 16, v183
	v_add_f32_e32 v235, v110, v180
	v_and_b32_e32 v180, 0xffff0000, v183
	v_add_f32_e32 v188, v116, v188
	v_add_f32_e32 v183, v111, v180
	v_cvt_pk_bf16_f32 v180, v188, v189
	v_mul_f32_e32 v189, v189, v189
	v_fmac_f32_e32 v189, v188, v188
	v_mul_f32_e32 v188, v191, v191
	v_fmac_f32_e32 v188, v190, v190
	v_add_f32_e32 v188, v189, v188
	v_mul_f32_e32 v189, v182, v182
	v_cvt_pk_bf16_f32 v181, v190, v191
	v_fmac_f32_e32 v189, v234, v234
	v_lshlrev_b32_e32 v190, 16, v177
	v_and_b32_e32 v177, 0xffff0000, v177
	v_add_f32_e32 v188, v189, v188
	v_mul_f32_e32 v189, v183, v183
	v_add_f32_e32 v191, v99, v177
	v_lshlrev_b32_e32 v177, 16, v178
	v_fmac_f32_e32 v189, v235, v235
	v_add_f32_e32 v236, v88, v177
	v_and_b32_e32 v177, 0xffff0000, v178
	v_add_f32_e32 v188, v189, v188
	v_lshlrev_b32_e32 v189, 16, v176
	v_and_b32_e32 v176, 0xffff0000, v176
	v_add_f32_e32 v237, v89, v177
	v_lshlrev_b32_e32 v177, 16, v179
	v_add_f32_e32 v176, v97, v176
	v_add_f32_e32 v246, v90, v177
	v_and_b32_e32 v177, 0xffff0000, v179
	v_add_f32_e32 v189, v96, v189
	v_add_f32_e32 v190, v98, v190
	v_add_f32_e32 v247, v91, v177
	v_mul_f32_e32 v177, v176, v176
	v_mul_f32_e32 v178, v191, v191
	v_fmac_f32_e32 v177, v189, v189
	v_fmac_f32_e32 v178, v190, v190
	v_add_f32_e32 v177, v177, v178
	v_mul_f32_e32 v178, v237, v237
	v_fmac_f32_e32 v178, v236, v236
	v_add_f32_e32 v177, v178, v177
	v_mul_f32_e32 v178, v247, v247
	v_fmac_f32_e32 v178, v246, v246
	v_add_f32_e32 v177, v178, v177
	v_add_f32_e32 v177, v188, v177
	ds_bpermute_b32 v179, v184, v177
	v_lshl_add_u64 v[186:187], v[204:205], 1, v[186:187]
	v_cvt_pk_bf16_f32 v182, v234, v182
	v_cvt_pk_bf16_f32 v183, v235, v183
	global_store_dwordx4 v[186:187], v[180:183], off sc1
	v_cvt_pk_bf16_f32 v178, v189, v176
	s_waitcnt lgkmcnt(0)
	v_add_f32_e32 v176, v177, v179
	ds_bpermute_b32 v177, v185, v176
	v_cvt_pk_bf16_f32 v179, v190, v191
	v_cvt_pk_bf16_f32 v180, v236, v237
	v_cvt_pk_bf16_f32 v181, v246, v247
	global_store_dwordx4 v[186:187], v[178:181], off offset:256 sc1
	s_and_saveexec_b64 s[6:7], s[2:3]
	s_cbranch_execz .LBB0_1311
	s_waitcnt lgkmcnt(0)
	v_add_f32_e32 v178, v176, v177
	v_lshl_add_u64 v[176:177], v[230:231], 2, s[18:19]
	global_atomic_add_f32 v[176:177], v178, off
.LBB0_1311:
	s_or_b64 exec, exec, s[6:7]
	v_lshlrev_b32_e32 v178, 16, v172
	v_and_b32_e32 v172, 0xffff0000, v172
	v_add_f32_e32 v179, v101, v172
	v_lshlrev_b32_e32 v172, 16, v173
	v_add_f32_e32 v180, v102, v172
	v_and_b32_e32 v172, 0xffff0000, v173
	v_add_f32_e32 v181, v103, v172
	v_lshlrev_b32_e32 v172, 16, v174
	v_add_f32_e32 v182, v92, v172
	v_and_b32_e32 v172, 0xffff0000, v174
	v_add_f32_e32 v174, v93, v172
	v_lshlrev_b32_e32 v172, 16, v175
	v_add_f32_e32 v183, v94, v172
	v_and_b32_e32 v172, 0xffff0000, v175
	v_add_f32_e32 v178, v100, v178
	v_add_f32_e32 v175, v95, v172
	v_cvt_pk_bf16_f32 v172, v178, v179
	v_mul_f32_e32 v179, v179, v179
	v_fmac_f32_e32 v179, v178, v178
	v_mul_f32_e32 v178, v181, v181
	v_fmac_f32_e32 v178, v180, v180
	v_add_f32_e32 v178, v179, v178
	v_mul_f32_e32 v179, v174, v174
	v_cvt_pk_bf16_f32 v173, v180, v181
	v_fmac_f32_e32 v179, v182, v182
	v_lshlrev_b32_e32 v180, 16, v169
	v_and_b32_e32 v169, 0xffff0000, v169
	v_add_f32_e32 v178, v179, v178
	v_mul_f32_e32 v179, v175, v175
	v_add_f32_e32 v181, v83, v169
	v_lshlrev_b32_e32 v169, 16, v170
	v_fmac_f32_e32 v179, v183, v183
	v_add_f32_e32 v186, v72, v169
	v_and_b32_e32 v169, 0xffff0000, v170
	v_add_f32_e32 v178, v179, v178
	v_lshlrev_b32_e32 v179, 16, v168
	v_and_b32_e32 v168, 0xffff0000, v168
	v_add_f32_e32 v187, v73, v169
	v_lshlrev_b32_e32 v169, 16, v171
	v_add_f32_e32 v168, v81, v168
	v_add_f32_e32 v188, v74, v169
	v_and_b32_e32 v169, 0xffff0000, v171
	v_add_f32_e32 v179, v80, v179
	v_add_f32_e32 v180, v82, v180
	v_add_f32_e32 v189, v75, v169
	v_mul_f32_e32 v169, v168, v168
	v_mul_f32_e32 v170, v181, v181
	v_fmac_f32_e32 v169, v179, v179
	v_fmac_f32_e32 v170, v180, v180
	v_add_f32_e32 v169, v169, v170
	v_mul_f32_e32 v170, v187, v187
	v_fmac_f32_e32 v170, v186, v186
	v_add_f32_e32 v169, v170, v169
	v_mul_f32_e32 v170, v189, v189
	v_fmac_f32_e32 v170, v188, v188
	v_add_f32_e32 v169, v170, v169
	v_add_f32_e32 v169, v178, v169
	ds_bpermute_b32 v171, v184, v169
	s_waitcnt lgkmcnt(1)
	v_lshl_add_u64 v[176:177], s[30:31], 0, v[232:233]
	v_lshl_add_u64 v[176:177], v[204:205], 1, v[176:177]
	v_cvt_pk_bf16_f32 v174, v182, v174
	v_cvt_pk_bf16_f32 v175, v183, v175
	global_store_dwordx4 v[176:177], v[172:175], off sc1
	v_cvt_pk_bf16_f32 v170, v179, v168
	s_waitcnt lgkmcnt(0)
	v_add_f32_e32 v168, v169, v171
	ds_bpermute_b32 v169, v185, v168
	v_cvt_pk_bf16_f32 v171, v180, v181
	v_cvt_pk_bf16_f32 v172, v186, v187
	v_cvt_pk_bf16_f32 v173, v188, v189
	global_store_dwordx4 v[176:177], v[170:173], off offset:256 sc1
	s_and_saveexec_b64 s[6:7], s[2:3]
	s_cbranch_execz .LBB0_1313
	s_waitcnt lgkmcnt(0)
	v_add_f32_e32 v170, v168, v169
	v_lshl_add_u64 v[168:169], v[226:227], 2, s[18:19]
	global_atomic_add_f32 v[168:169], v170, off
; __device__ __forceinline__ unsigned cvt_pk_bf16(float lo, float hi) { unsigned r; asm volatile("v_cvt_pk_bf16_f32 %0, %1, %2" : "=v"(r) : "v"(lo), "v"(hi)); return r; }
;     __device__ __forceinline__ void operator()(const f32x4 (&acc)[2][2][4][2], const Unit& u, int wr, int wc, int fr, int fq) const {
;     ...
;         for (int ai = 0; ai < 2; ++ai)
; #pragma unroll
;             for (int m = 0; m < 4; ++m) {
;                 const int row = row0 + ai * HALF + m * 16;
;                 bf16_t* xr = xb + (size_t)row * 1024 + col0;
;                 float part_ss = 0.f;
; #pragma unroll
;                 for (int bj = 0; bj < 2; ++bj) {
;                     const u32x4 o = xo[ai][m][bj];
;                     f32x4 v0 = acc[ai][bj][m][0], v1 = acc[ai][bj][m][1];
;                     v0[0] += __uint_as_float(o.x << 16); v0[1] += __uint_as_float(o.x & 0xffff0000u); v0[2] += __uint_as_float(o.y << 16); v0[3] += __uint_as_float(o.y & 0xffff0000u);
;                     v1[0] += __uint_as_float(o.z << 16); v1[1] += __uint_as_float(o.z & 0xffff0000u); v1[2] += __uint_as_float(o.w << 16); v1[3] += __uint_as_float(o.w & 0xffff0000u);
;                     if (xout) { float* xo = xout + (size_t)row * 1024 + col0 + bj * HALF; *(f32x4*)xo = v0; *(f32x4*)(xo + 4) = v1; }
;                     else { u32x4 w; w.x = cvt_pk_bf16(v0[0], v0[1]); w.y = cvt_pk_bf16(v0[2], v0[3]); w.z = cvt_pk_bf16(v1[0], v1[1]); w.w = cvt_pk_bf16(v1[2], v1[3]); *(u32x4*)(xr + bj * HALF) = w; }
;                     part_ss += (v0[0] * v0[0] + v0[1] * v0[1]) + (v0[2] * v0[2] + v0[3] * v0[3]) + (v1[0] * v1[0] + v1[1] * v1[1]) + (v1[2] * v1[2] + v1[3] * v1[3]);
;                 }
;                 part_ss += __shfl_xor(part_ss, 16); part_ss += __shfl_xor(part_ss, 32);
;                 if (fq == 0) atomicAdd(ss + row, part_ss);
.LBB0_1313:
	s_or_b64 exec, exec, s[6:7]
	v_lshlrev_b32_e32 v170, 16, v164
	v_and_b32_e32 v164, 0xffff0000, v164
	v_add_f32_e32 v171, v85, v164
	v_lshlrev_b32_e32 v164, 16, v165
	v_add_f32_e32 v172, v86, v164
	v_and_b32_e32 v164, 0xffff0000, v165
	v_add_f32_e32 v173, v87, v164
	v_lshlrev_b32_e32 v164, 16, v166
	v_add_f32_e32 v174, v76, v164
	v_and_b32_e32 v164, 0xffff0000, v166
	v_add_f32_e32 v166, v77, v164
	v_lshlrev_b32_e32 v164, 16, v167
	v_add_f32_e32 v175, v78, v164
	v_and_b32_e32 v164, 0xffff0000, v167
	v_add_f32_e32 v170, v84, v170
	v_add_f32_e32 v167, v79, v164
	v_cvt_pk_bf16_f32 v164, v170, v171
	v_mul_f32_e32 v171, v171, v171
	v_fmac_f32_e32 v171, v170, v170
	v_mul_f32_e32 v170, v173, v173
	v_fmac_f32_e32 v170, v172, v172
	v_add_f32_e32 v170, v171, v170
	v_mul_f32_e32 v171, v166, v166
	v_cvt_pk_bf16_f32 v165, v172, v173
	v_fmac_f32_e32 v171, v174, v174
	v_lshlrev_b32_e32 v172, 16, v161
	v_and_b32_e32 v161, 0xffff0000, v161
	v_add_f32_e32 v170, v171, v170
	v_mul_f32_e32 v171, v167, v167
	v_add_f32_e32 v173, v71, v161
	v_lshlrev_b32_e32 v161, 16, v162
	v_fmac_f32_e32 v171, v175, v175
	v_add_f32_e32 v176, v64, v161
	v_and_b32_e32 v161, 0xffff0000, v162
	v_add_f32_e32 v170, v171, v170
	v_lshlrev_b32_e32 v171, 16, v160
	v_and_b32_e32 v160, 0xffff0000, v160
	v_add_f32_e32 v177, v65, v161
	v_lshlrev_b32_e32 v161, 16, v163
	v_add_f32_e32 v160, v69, v160
	v_add_f32_e32 v178, v66, v161
	v_and_b32_e32 v161, 0xffff0000, v163
	v_add_f32_e32 v171, v68, v171
	v_add_f32_e32 v172, v70, v172
	v_add_f32_e32 v179, v67, v161
	v_mul_f32_e32 v161, v160, v160
	v_mul_f32_e32 v162, v173, v173
	v_fmac_f32_e32 v161, v171, v171
	v_fmac_f32_e32 v162, v172, v172
	v_add_f32_e32 v161, v161, v162
	v_mul_f32_e32 v162, v177, v177
	v_fmac_f32_e32 v162, v176, v176
	v_add_f32_e32 v161, v162, v161
	v_mul_f32_e32 v162, v179, v179
	v_fmac_f32_e32 v162, v178, v178
	v_add_f32_e32 v161, v162, v161
	v_add_f32_e32 v161, v170, v161
	ds_bpermute_b32 v163, v184, v161
	s_waitcnt lgkmcnt(1)
	v_lshl_add_u64 v[168:169], s[30:31], 0, v[228:229]
	v_lshl_add_u64 v[168:169], v[204:205], 1, v[168:169]
	v_cvt_pk_bf16_f32 v166, v174, v166
	v_cvt_pk_bf16_f32 v167, v175, v167
	global_store_dwordx4 v[168:169], v[164:167], off sc1
	v_cvt_pk_bf16_f32 v162, v171, v160
	s_waitcnt lgkmcnt(0)
	v_add_f32_e32 v160, v161, v163
	ds_bpermute_b32 v161, v185, v160
	v_cvt_pk_bf16_f32 v163, v172, v173
	v_cvt_pk_bf16_f32 v164, v176, v177
	v_cvt_pk_bf16_f32 v165, v178, v179
	global_store_dwordx4 v[168:169], v[162:165], off offset:256 sc1
	s_and_saveexec_b64 s[6:7], s[2:3]
	s_cbranch_execz .LBB0_1315
	s_waitcnt lgkmcnt(0)
	v_add_f32_e32 v162, v160, v161
	v_lshl_add_u64 v[160:161], v[222:223], 2, s[18:19]
	global_atomic_add_f32 v[160:161], v162, off
.LBB0_1315:
	s_or_b64 exec, exec, s[6:7]
	v_lshlrev_b32_e32 v162, 16, v156
	v_and_b32_e32 v156, 0xffff0000, v156
	v_add_f32_e32 v163, v61, v156
	v_lshlrev_b32_e32 v156, 16, v157
	v_add_f32_e32 v164, v62, v156
	v_and_b32_e32 v156, 0xffff0000, v157
	v_add_f32_e32 v165, v63, v156
	v_lshlrev_b32_e32 v156, 16, v158
	v_add_f32_e32 v166, v56, v156
	v_and_b32_e32 v156, 0xffff0000, v158
	v_add_f32_e32 v158, v57, v156
	v_lshlrev_b32_e32 v156, 16, v159
	v_add_f32_e32 v167, v58, v156
	v_and_b32_e32 v156, 0xffff0000, v159
	v_add_f32_e32 v162, v60, v162
	v_add_f32_e32 v159, v59, v156
	v_cvt_pk_bf16_f32 v156, v162, v163
	v_mul_f32_e32 v163, v163, v163
	v_fmac_f32_e32 v163, v162, v162
	v_mul_f32_e32 v162, v165, v165
	v_fmac_f32_e32 v162, v164, v164
	v_add_f32_e32 v162, v163, v162
	v_mul_f32_e32 v163, v158, v158
	v_cvt_pk_bf16_f32 v157, v164, v165
	v_fmac_f32_e32 v163, v166, v166
	v_lshlrev_b32_e32 v164, 16, v153
	v_and_b32_e32 v153, 0xffff0000, v153
	v_add_f32_e32 v162, v163, v162
	v_mul_f32_e32 v163, v159, v159
	v_add_f32_e32 v165, v51, v153
	v_lshlrev_b32_e32 v153, 16, v154
	v_fmac_f32_e32 v163, v167, v167
	v_add_f32_e32 v168, v40, v153
	v_and_b32_e32 v153, 0xffff0000, v154
	v_add_f32_e32 v162, v163, v162
	v_lshlrev_b32_e32 v163, 16, v152
	v_and_b32_e32 v152, 0xffff0000, v152
	v_add_f32_e32 v169, v41, v153
	v_lshlrev_b32_e32 v153, 16, v155
	v_add_f32_e32 v152, v49, v152
	v_add_f32_e32 v170, v42, v153
	v_and_b32_e32 v153, 0xffff0000, v155
	v_add_f32_e32 v163, v48, v163
	v_add_f32_e32 v164, v50, v164
	v_add_f32_e32 v171, v43, v153
	v_mul_f32_e32 v153, v152, v152
	v_mul_f32_e32 v154, v165, v165
	v_fmac_f32_e32 v153, v163, v163
	v_fmac_f32_e32 v154, v164, v164
	v_add_f32_e32 v153, v153, v154
	v_mul_f32_e32 v154, v169, v169
	v_fmac_f32_e32 v154, v168, v168
	v_add_f32_e32 v153, v154, v153
	v_mul_f32_e32 v154, v171, v171
	v_fmac_f32_e32 v154, v170, v170
	v_add_f32_e32 v153, v154, v153
	v_add_f32_e32 v153, v162, v153
	ds_bpermute_b32 v155, v184, v153
	s_waitcnt lgkmcnt(1)
	v_lshl_add_u64 v[160:161], s[30:31], 0, v[224:225]
	v_lshl_add_u64 v[160:161], v[204:205], 1, v[160:161]
	v_cvt_pk_bf16_f32 v158, v166, v158
	v_cvt_pk_bf16_f32 v159, v167, v159
	global_store_dwordx4 v[160:161], v[156:159], off sc1
	v_cvt_pk_bf16_f32 v154, v163, v152
	s_waitcnt lgkmcnt(0)
	v_add_f32_e32 v152, v153, v155
	ds_bpermute_b32 v153, v185, v152
	v_cvt_pk_bf16_f32 v155, v164, v165
	v_cvt_pk_bf16_f32 v156, v168, v169
	v_cvt_pk_bf16_f32 v157, v170, v171
	global_store_dwordx4 v[160:161], v[154:157], off offset:256 sc1
	s_and_saveexec_b64 s[6:7], s[2:3]
	s_cbranch_execz .LBB0_1317
	s_waitcnt lgkmcnt(0)
	v_add_f32_e32 v154, v152, v153
	v_lshl_add_u64 v[152:153], v[218:219], 2, s[18:19]
	global_atomic_add_f32 v[152:153], v154, off
; __device__ __forceinline__ unsigned cvt_pk_bf16(float lo, float hi) { unsigned r; asm volatile("v_cvt_pk_bf16_f32 %0, %1, %2" : "=v"(r) : "v"(lo), "v"(hi)); return r; }
;     __device__ __forceinline__ void operator()(const f32x4 (&acc)[2][2][4][2], const Unit& u, int wr, int wc, int fr, int fq) const {
;     ...
;         for (int ai = 0; ai < 2; ++ai)
; #pragma unroll
;             for (int m = 0; m < 4; ++m) {
;                 const int row = row0 + ai * HALF + m * 16;
;                 bf16_t* xr = xb + (size_t)row * 1024 + col0;
;                 float part_ss = 0.f;
; #pragma unroll
;                 for (int bj = 0; bj < 2; ++bj) {
;                     const u32x4 o = xo[ai][m][bj];
;                     f32x4 v0 = acc[ai][bj][m][0], v1 = acc[ai][bj][m][1];
;                     v0[0] += __uint_as_float(o.x << 16); v0[1] += __uint_as_float(o.x & 0xffff0000u); v0[2] += __uint_as_float(o.y << 16); v0[3] += __uint_as_float(o.y & 0xffff0000u);
;                     v1[0] += __uint_as_float(o.z << 16); v1[1] += __uint_as_float(o.z & 0xffff0000u); v1[2] += __uint_as_float(o.w << 16); v1[3] += __uint_as_float(o.w & 0xffff0000u);
;                     if (xout) { float* xo = xout + (size_t)row * 1024 + col0 + bj * HALF; *(f32x4*)xo = v0; *(f32x4*)(xo + 4) = v1; }
;                     else { u32x4 w; w.x = cvt_pk_bf16(v0[0], v0[1]); w.y = cvt_pk_bf16(v0[2], v0[3]); w.z = cvt_pk_bf16(v1[0], v1[1]); w.w = cvt_pk_bf16(v1[2], v1[3]); *(u32x4*)(xr + bj * HALF) = w; }
;                     part_ss += (v0[0] * v0[0] + v0[1] * v0[1]) + (v0[2] * v0[2] + v0[3] * v0[3]) + (v1[0] * v1[0] + v1[1] * v1[1]) + (v1[2] * v1[2] + v1[3] * v1[3]);
;                 }
;                 part_ss += __shfl_xor(part_ss, 16); part_ss += __shfl_xor(part_ss, 32);
;                 if (fq == 0) atomicAdd(ss + row, part_ss);
.LBB0_1317:
	s_or_b64 exec, exec, s[6:7]
	v_lshlrev_b32_e32 v154, 16, v148
	v_and_b32_e32 v148, 0xffff0000, v148
	v_add_f32_e32 v155, v53, v148
	v_lshlrev_b32_e32 v148, 16, v149
	v_add_f32_e32 v156, v54, v148
	v_and_b32_e32 v148, 0xffff0000, v149
	v_add_f32_e32 v157, v55, v148
	v_lshlrev_b32_e32 v148, 16, v150
	v_add_f32_e32 v158, v44, v148
	v_and_b32_e32 v148, 0xffff0000, v150
	v_add_f32_e32 v150, v45, v148
	v_lshlrev_b32_e32 v148, 16, v151
	v_add_f32_e32 v159, v46, v148
	v_and_b32_e32 v148, 0xffff0000, v151
	v_add_f32_e32 v154, v52, v154
	v_add_f32_e32 v151, v47, v148
	v_cvt_pk_bf16_f32 v148, v154, v155
	v_mul_f32_e32 v155, v155, v155
	v_fmac_f32_e32 v155, v154, v154
	v_mul_f32_e32 v154, v157, v157
	v_fmac_f32_e32 v154, v156, v156
	v_add_f32_e32 v154, v155, v154
	v_mul_f32_e32 v155, v150, v150
	v_cvt_pk_bf16_f32 v149, v156, v157
	v_fmac_f32_e32 v155, v158, v158
	v_lshlrev_b32_e32 v156, 16, v145
	v_and_b32_e32 v145, 0xffff0000, v145
	v_add_f32_e32 v154, v155, v154
	v_mul_f32_e32 v155, v151, v151
	v_add_f32_e32 v157, v35, v145
	v_lshlrev_b32_e32 v145, 16, v146
	v_fmac_f32_e32 v155, v159, v159
	v_add_f32_e32 v160, v24, v145
	v_and_b32_e32 v145, 0xffff0000, v146
	v_add_f32_e32 v154, v155, v154
	v_lshlrev_b32_e32 v155, 16, v144
	v_and_b32_e32 v144, 0xffff0000, v144
	v_add_f32_e32 v161, v25, v145
	v_lshlrev_b32_e32 v145, 16, v147
	v_add_f32_e32 v144, v33, v144
	v_add_f32_e32 v162, v26, v145
	v_and_b32_e32 v145, 0xffff0000, v147
	v_add_f32_e32 v155, v32, v155
	v_add_f32_e32 v156, v34, v156
	v_add_f32_e32 v163, v27, v145
	v_mul_f32_e32 v145, v144, v144
	v_mul_f32_e32 v146, v157, v157
	v_fmac_f32_e32 v145, v155, v155
	v_fmac_f32_e32 v146, v156, v156
	v_add_f32_e32 v145, v145, v146
	v_mul_f32_e32 v146, v161, v161
	v_fmac_f32_e32 v146, v160, v160
	v_add_f32_e32 v145, v146, v145
	v_mul_f32_e32 v146, v163, v163
	v_fmac_f32_e32 v146, v162, v162
	v_add_f32_e32 v145, v146, v145
	v_add_f32_e32 v145, v154, v145
	ds_bpermute_b32 v147, v184, v145
	s_waitcnt lgkmcnt(1)
	v_lshl_add_u64 v[152:153], s[30:31], 0, v[220:221]
	v_lshl_add_u64 v[152:153], v[204:205], 1, v[152:153]
	v_cvt_pk_bf16_f32 v150, v158, v150
	v_cvt_pk_bf16_f32 v151, v159, v151
	global_store_dwordx4 v[152:153], v[148:151], off sc1
	v_cvt_pk_bf16_f32 v146, v155, v144
	s_waitcnt lgkmcnt(0)
	v_add_f32_e32 v144, v145, v147
	ds_bpermute_b32 v145, v185, v144
	v_cvt_pk_bf16_f32 v147, v156, v157
	v_cvt_pk_bf16_f32 v148, v160, v161
	v_cvt_pk_bf16_f32 v149, v162, v163
	global_store_dwordx4 v[152:153], v[146:149], off offset:256 sc1
	s_and_saveexec_b64 s[6:7], s[2:3]
	s_cbranch_execz .LBB0_1319
	s_waitcnt lgkmcnt(0)
	v_add_f32_e32 v146, v144, v145
	v_lshl_add_u64 v[144:145], v[214:215], 2, s[18:19]
	global_atomic_add_f32 v[144:145], v146, off
; __device__ __forceinline__ unsigned cvt_pk_bf16(float lo, float hi) { unsigned r; asm volatile("v_cvt_pk_bf16_f32 %0, %1, %2" : "=v"(r) : "v"(lo), "v"(hi)); return r; }
;     __device__ __forceinline__ void operator()(const f32x4 (&acc)[2][2][4][2], const Unit& u, int wr, int wc, int fr, int fq) const {
;     ...
;         for (int ai = 0; ai < 2; ++ai)
; #pragma unroll
;             for (int m = 0; m < 4; ++m) {
;                 const int row = row0 + ai * HALF + m * 16;
;                 bf16_t* xr = xb + (size_t)row * 1024 + col0;
;                 float part_ss = 0.f;
; #pragma unroll
;                 for (int bj = 0; bj < 2; ++bj) {
;                     const u32x4 o = xo[ai][m][bj];
;                     f32x4 v0 = acc[ai][bj][m][0], v1 = acc[ai][bj][m][1];
;                     v0[0] += __uint_as_float(o.x << 16); v0[1] += __uint_as_float(o.x & 0xffff0000u); v0[2] += __uint_as_float(o.y << 16); v0[3] += __uint_as_float(o.y & 0xffff0000u);
;                     v1[0] += __uint_as_float(o.z << 16); v1[1] += __uint_as_float(o.z & 0xffff0000u); v1[2] += __uint_as_float(o.w << 16); v1[3] += __uint_as_float(o.w & 0xffff0000u);
;                     if (xout) { float* xo = xout + (size_t)row * 1024 + col0 + bj * HALF; *(f32x4*)xo = v0; *(f32x4*)(xo + 4) = v1; }
;                     else { u32x4 w; w.x = cvt_pk_bf16(v0[0], v0[1]); w.y = cvt_pk_bf16(v0[2], v0[3]); w.z = cvt_pk_bf16(v1[0], v1[1]); w.w = cvt_pk_bf16(v1[2], v1[3]); *(u32x4*)(xr + bj * HALF) = w; }
;                     part_ss += (v0[0] * v0[0] + v0[1] * v0[1]) + (v0[2] * v0[2] + v0[3] * v0[3]) + (v1[0] * v1[0] + v1[1] * v1[1]) + (v1[2] * v1[2] + v1[3] * v1[3]);
;                 }
;                 part_ss += __shfl_xor(part_ss, 16); part_ss += __shfl_xor(part_ss, 32);
;                 if (fq == 0) atomicAdd(ss + row, part_ss);
.LBB0_1319:
	s_or_b64 exec, exec, s[6:7]
	v_lshlrev_b32_e32 v146, 16, v140
	v_and_b32_e32 v140, 0xffff0000, v140
	v_add_f32_e32 v147, v37, v140
	v_lshlrev_b32_e32 v140, 16, v141
	v_add_f32_e32 v148, v38, v140
	v_and_b32_e32 v140, 0xffff0000, v141
	v_add_f32_e32 v149, v39, v140
	v_lshlrev_b32_e32 v140, 16, v142
	v_add_f32_e32 v150, v28, v140
	v_and_b32_e32 v140, 0xffff0000, v142
	v_add_f32_e32 v142, v29, v140
	v_lshlrev_b32_e32 v140, 16, v143
	v_add_f32_e32 v151, v30, v140
	v_and_b32_e32 v140, 0xffff0000, v143
	v_add_f32_e32 v146, v36, v146
	v_add_f32_e32 v143, v31, v140
	v_cvt_pk_bf16_f32 v140, v146, v147
	v_mul_f32_e32 v147, v147, v147
	v_fmac_f32_e32 v147, v146, v146
	v_mul_f32_e32 v146, v149, v149
	v_fmac_f32_e32 v146, v148, v148
	v_add_f32_e32 v146, v147, v146
	v_mul_f32_e32 v147, v142, v142
	v_cvt_pk_bf16_f32 v141, v148, v149
	v_fmac_f32_e32 v147, v150, v150
	v_lshlrev_b32_e32 v148, 16, v137
	v_and_b32_e32 v137, 0xffff0000, v137
	v_add_f32_e32 v146, v147, v146
	v_mul_f32_e32 v147, v143, v143
	v_add_f32_e32 v149, v19, v137
	v_lshlrev_b32_e32 v137, 16, v138
	v_fmac_f32_e32 v147, v151, v151
	v_add_f32_e32 v152, v8, v137
	v_and_b32_e32 v137, 0xffff0000, v138
	v_add_f32_e32 v146, v147, v146
	v_lshlrev_b32_e32 v147, 16, v136
	v_and_b32_e32 v136, 0xffff0000, v136
	v_add_f32_e32 v153, v9, v137
	v_lshlrev_b32_e32 v137, 16, v139
	v_add_f32_e32 v136, v17, v136
	v_add_f32_e32 v154, v10, v137
	v_and_b32_e32 v137, 0xffff0000, v139
	v_add_f32_e32 v147, v16, v147
	v_add_f32_e32 v148, v18, v148
	v_add_f32_e32 v155, v11, v137
	v_mul_f32_e32 v137, v136, v136
	v_mul_f32_e32 v138, v149, v149
	v_fmac_f32_e32 v137, v147, v147
	v_fmac_f32_e32 v138, v148, v148
	v_add_f32_e32 v137, v137, v138
	v_mul_f32_e32 v138, v153, v153
	v_fmac_f32_e32 v138, v152, v152
	v_add_f32_e32 v137, v138, v137
	v_mul_f32_e32 v138, v155, v155
	v_fmac_f32_e32 v138, v154, v154
	v_add_f32_e32 v137, v138, v137
	v_add_f32_e32 v137, v146, v137
	ds_bpermute_b32 v139, v184, v137
	s_waitcnt lgkmcnt(1)
	v_lshl_add_u64 v[144:145], s[30:31], 0, v[216:217]
	v_lshl_add_u64 v[144:145], v[204:205], 1, v[144:145]
	v_cvt_pk_bf16_f32 v142, v150, v142
	v_cvt_pk_bf16_f32 v143, v151, v143
	global_store_dwordx4 v[144:145], v[140:143], off sc1
	v_cvt_pk_bf16_f32 v138, v147, v136
	s_waitcnt lgkmcnt(0)
	v_add_f32_e32 v136, v137, v139
	ds_bpermute_b32 v137, v185, v136
	v_cvt_pk_bf16_f32 v139, v148, v149
	v_cvt_pk_bf16_f32 v140, v152, v153
	v_cvt_pk_bf16_f32 v141, v154, v155
	global_store_dwordx4 v[144:145], v[138:141], off offset:256 sc1
	s_and_saveexec_b64 s[6:7], s[2:3]
	s_cbranch_execz .LBB0_1321
	s_waitcnt lgkmcnt(0)
	v_add_f32_e32 v138, v136, v137
	v_lshl_add_u64 v[136:137], v[210:211], 2, s[18:19]
	global_atomic_add_f32 v[136:137], v138, off
.LBB0_1321:
	s_or_b64 exec, exec, s[6:7]
	v_lshlrev_b32_e32 v138, 16, v132
	v_and_b32_e32 v132, 0xffff0000, v132
	v_add_f32_e32 v139, v21, v132
	v_lshlrev_b32_e32 v132, 16, v133
	v_add_f32_e32 v140, v22, v132
	v_and_b32_e32 v132, 0xffff0000, v133
	v_add_f32_e32 v141, v23, v132
	v_lshlrev_b32_e32 v132, 16, v134
	v_add_f32_e32 v142, v12, v132
	v_and_b32_e32 v132, 0xffff0000, v134
	v_add_f32_e32 v134, v13, v132
	v_lshlrev_b32_e32 v132, 16, v135
	v_add_f32_e32 v143, v14, v132
	v_and_b32_e32 v132, 0xffff0000, v135
	v_add_f32_e32 v138, v20, v138
	v_add_f32_e32 v135, v15, v132
	v_cvt_pk_bf16_f32 v132, v138, v139
	v_mul_f32_e32 v139, v139, v139
	v_fmac_f32_e32 v139, v138, v138
	v_mul_f32_e32 v138, v141, v141
	v_fmac_f32_e32 v138, v140, v140
	v_add_f32_e32 v138, v139, v138
	v_mul_f32_e32 v139, v134, v134
	v_cvt_pk_bf16_f32 v133, v140, v141
	v_fmac_f32_e32 v139, v142, v142
	v_lshlrev_b32_e32 v140, 16, v129
	v_and_b32_e32 v129, 0xffff0000, v129
	v_add_f32_e32 v138, v139, v138
	v_mul_f32_e32 v139, v135, v135
	v_add_f32_e32 v141, v7, v129
	v_lshlrev_b32_e32 v129, 16, v130
	v_fmac_f32_e32 v139, v143, v143
	v_add_f32_e32 v144, v0, v129
	v_and_b32_e32 v129, 0xffff0000, v130
	v_add_f32_e32 v138, v139, v138
	v_lshlrev_b32_e32 v139, 16, v128
	v_and_b32_e32 v128, 0xffff0000, v128
	v_add_f32_e32 v145, v1, v129
	v_lshlrev_b32_e32 v129, 16, v131
	v_add_f32_e32 v128, v5, v128
	v_add_f32_e32 v146, v2, v129
	v_and_b32_e32 v129, 0xffff0000, v131
	v_add_f32_e32 v139, v4, v139
	v_add_f32_e32 v140, v6, v140
	v_add_f32_e32 v147, v3, v129
	v_mul_f32_e32 v129, v128, v128
	v_mul_f32_e32 v130, v141, v141
	v_fmac_f32_e32 v129, v139, v139
	v_fmac_f32_e32 v130, v140, v140
	v_add_f32_e32 v129, v129, v130
	v_mul_f32_e32 v130, v145, v145
	v_fmac_f32_e32 v130, v144, v144
	v_add_f32_e32 v129, v130, v129
	v_mul_f32_e32 v130, v147, v147
	v_fmac_f32_e32 v130, v146, v146
	v_add_f32_e32 v129, v130, v129
	v_add_f32_e32 v129, v138, v129
	ds_bpermute_b32 v131, v184, v129
	s_waitcnt lgkmcnt(1)
	v_lshl_add_u64 v[136:137], s[30:31], 0, v[212:213]
	v_lshl_add_u64 v[136:137], v[204:205], 1, v[136:137]
	v_cvt_pk_bf16_f32 v134, v142, v134
	v_cvt_pk_bf16_f32 v135, v143, v135
	global_store_dwordx4 v[136:137], v[132:135], off sc1
	v_cvt_pk_bf16_f32 v130, v139, v128
	s_waitcnt lgkmcnt(0)
	v_add_f32_e32 v128, v129, v131
	ds_bpermute_b32 v129, v185, v128
	v_cvt_pk_bf16_f32 v131, v140, v141
	v_cvt_pk_bf16_f32 v132, v144, v145
	v_cvt_pk_bf16_f32 v133, v146, v147
	global_store_dwordx4 v[136:137], v[130:133], off offset:256 sc1
	s_and_saveexec_b64 s[6:7], s[2:3]
	s_cbranch_execz .LBB0_1323
	s_waitcnt lgkmcnt(0)
	v_add_f32_e32 v130, v128, v129
	v_lshl_add_u64 v[128:129], v[208:209], 2, s[18:19]
	global_atomic_add_f32 v[128:129], v130, off

; __device__ __forceinline__ unsigned cvt_pk_bf16(float lo, float hi) { unsigned r; asm volatile("v_cvt_pk_bf16_f32 %0, %1, %2" : "=v"(r) : "v"(lo), "v"(hi)); return r; }
;     __device__ __forceinline__ void operator()(const f32x4 (&acc)[2][2][4][2], const Unit& u, int wr, int wc, int fr, int fq) const {
;     ...
;         if (u.sp >= 0) {
;             bf16_t* pb = (bf16_t*)part + ((size_t)u.sp * 1024 + (row0 - 16384)) * 1024 + col0;
; #pragma unroll
;             for (int ai = 0; ai < 2; ++ai)
; #pragma unroll
;                 for (int m = 0; m < 4; ++m)
; #pragma unroll
;                     for (int bj = 0; bj < 2; ++bj) { const f32x4 v0 = acc[ai][bj][m][0], v1 = acc[ai][bj][m][1];
;                         u32x4 w; w.x = cvt_pk_bf16(v0[0], v0[1]); w.y = cvt_pk_bf16(v0[2], v0[3]); w.z = cvt_pk_bf16(v1[0], v1[1]); w.w = cvt_pk_bf16(v1[2], v1[3]);
;                         *(u32x4*)(pb + (size_t)(ai * HALF + m * 16) * 1024 + bj * HALF) = w; }
;             return;
.LBB0_1325:
	s_and_b64 vcc, exec, s[6:7]
	s_cbranch_vccz .LBB0_1324
	s_lshl_b64 s[6:7], s[16:17], 21
	s_add_u32 s6, s88, s6
	s_waitcnt lgkmcnt(0)
	v_lshlrev_b64 v[128:129], 11, v[206:207]
	s_addc_u32 s7, s89, s7
	v_lshl_add_u64 v[128:129], s[6:7], 0, v[128:129]
	v_lshl_add_u64 v[128:129], v[204:205], 1, v[128:129]
	v_cvt_pk_bf16_f32 v124, v124, v125
	v_cvt_pk_bf16_f32 v125, v126, v127
	v_cvt_pk_bf16_f32 v126, v120, v121
	v_add_co_u32_e32 v120, vcc, s62, v128
	v_lshl_add_u64 v[130:131], v[128:129], 0, s[24:25]
	s_nop 0
	v_addc_co_u32_e32 v121, vcc, -1, v129, vcc
	v_cvt_pk_bf16_f32 v127, v122, v123
	global_store_dwordx4 v[120:121], v[124:127], off sc1
	v_cvt_pk_bf16_f32 v112, v112, v113
	v_cvt_pk_bf16_f32 v113, v114, v115
	v_cvt_pk_bf16_f32 v114, v104, v105
	v_cvt_pk_bf16_f32 v115, v106, v107
	global_store_dwordx4 v[130:131], v[112:115], off offset:256 sc1
	v_cvt_pk_bf16_f32 v104, v116, v117
	v_cvt_pk_bf16_f32 v105, v118, v119
	v_cvt_pk_bf16_f32 v106, v108, v109
	v_add_co_u32_e32 v108, vcc, s63, v128
	v_cvt_pk_bf16_f32 v107, v110, v111
	s_nop 1
	v_addc_co_u32_e32 v109, vcc, -1, v129, vcc
	global_store_dwordx4 v[108:109], v[104:107], off sc1
	v_cvt_pk_bf16_f32 v96, v96, v97
	v_cvt_pk_bf16_f32 v97, v98, v99
	v_cvt_pk_bf16_f32 v98, v88, v89
	v_add_co_u32_e32 v88, vcc, s64, v128
	v_cvt_pk_bf16_f32 v99, v90, v91
	s_nop 1
	v_addc_co_u32_e32 v89, vcc, -1, v129, vcc
	global_store_dwordx4 v[88:89], v[96:99], off offset:-3840 sc1
	v_cvt_pk_bf16_f32 v88, v100, v101
	v_cvt_pk_bf16_f32 v89, v102, v103
	v_cvt_pk_bf16_f32 v90, v92, v93
	v_add_co_u32_e32 v92, vcc, s65, v128
	v_cvt_pk_bf16_f32 v91, v94, v95
	s_nop 1
	v_addc_co_u32_e32 v93, vcc, -1, v129, vcc
	global_store_dwordx4 v[92:93], v[88:91], off sc1
	v_cvt_pk_bf16_f32 v80, v80, v81
	v_cvt_pk_bf16_f32 v81, v82, v83
	v_cvt_pk_bf16_f32 v82, v72, v73
	v_add_co_u32_e32 v72, vcc, s66, v128
	v_cvt_pk_bf16_f32 v83, v74, v75
	s_nop 1
	v_addc_co_u32_e32 v73, vcc, -1, v129, vcc
	global_store_dwordx4 v[72:73], v[80:83], off offset:-3840 sc1
	v_cvt_pk_bf16_f32 v72, v84, v85
	v_cvt_pk_bf16_f32 v73, v86, v87
	v_cvt_pk_bf16_f32 v74, v76, v77
	v_add_co_u32_e32 v76, vcc, s67, v128
	v_cvt_pk_bf16_f32 v75, v78, v79
	s_nop 1
	v_addc_co_u32_e32 v77, vcc, -1, v129, vcc
	global_store_dwordx4 v[76:77], v[72:75], off sc1
	v_cvt_pk_bf16_f32 v68, v68, v69
	v_cvt_pk_bf16_f32 v69, v70, v71
	v_cvt_pk_bf16_f32 v70, v64, v65
	v_add_co_u32_e32 v64, vcc, s76, v128
	v_cvt_pk_bf16_f32 v71, v66, v67
	s_nop 1
	v_addc_co_u32_e32 v65, vcc, -1, v129, vcc
	global_store_dwordx4 v[64:65], v[68:71], off offset:-3840 sc1
	v_cvt_pk_bf16_f32 v60, v60, v61
	v_cvt_pk_bf16_f32 v61, v62, v63
	v_cvt_pk_bf16_f32 v62, v56, v57
	v_add_co_u32_e32 v56, vcc, s77, v128
	v_cvt_pk_bf16_f32 v63, v58, v59
	s_nop 1
	v_addc_co_u32_e32 v57, vcc, -1, v129, vcc
	global_store_dwordx4 v[56:57], v[60:63], off sc1
	v_cvt_pk_bf16_f32 v48, v48, v49
	v_cvt_pk_bf16_f32 v49, v50, v51
	v_cvt_pk_bf16_f32 v50, v40, v41
	v_add_co_u32_e32 v40, vcc, s78, v128
	v_cvt_pk_bf16_f32 v51, v42, v43
	s_nop 1
	v_addc_co_u32_e32 v41, vcc, -1, v129, vcc
	global_store_dwordx4 v[40:41], v[48:51], off offset:-3840 sc1
	v_cvt_pk_bf16_f32 v40, v52, v53
	v_cvt_pk_bf16_f32 v41, v54, v55
	v_cvt_pk_bf16_f32 v42, v44, v45
	v_add_co_u32_e32 v44, vcc, s79, v128
	v_cvt_pk_bf16_f32 v43, v46, v47
	s_nop 1
	v_addc_co_u32_e32 v45, vcc, -1, v129, vcc
	global_store_dwordx4 v[44:45], v[40:43], off sc1
	v_cvt_pk_bf16_f32 v32, v32, v33
	v_cvt_pk_bf16_f32 v33, v34, v35
	v_cvt_pk_bf16_f32 v34, v24, v25
	v_add_co_u32_e32 v24, vcc, s80, v128
	v_cvt_pk_bf16_f32 v35, v26, v27
	s_nop 1
	v_addc_co_u32_e32 v25, vcc, -1, v129, vcc
	global_store_dwordx4 v[24:25], v[32:35], off offset:-3840 sc1
	v_cvt_pk_bf16_f32 v24, v36, v37
	v_cvt_pk_bf16_f32 v25, v38, v39
	v_cvt_pk_bf16_f32 v26, v28, v29
	v_add_co_u32_e32 v28, vcc, s81, v128
	v_cvt_pk_bf16_f32 v27, v30, v31
	s_nop 1
	v_addc_co_u32_e32 v29, vcc, -1, v129, vcc
	global_store_dwordx4 v[28:29], v[24:27], off sc1
	v_cvt_pk_bf16_f32 v16, v16, v17
	v_cvt_pk_bf16_f32 v17, v18, v19
	v_cvt_pk_bf16_f32 v18, v8, v9
	v_add_co_u32_e32 v8, vcc, s82, v128
	v_cvt_pk_bf16_f32 v19, v10, v11
	s_nop 1
	v_addc_co_u32_e32 v9, vcc, -1, v129, vcc
	global_store_dwordx4 v[8:9], v[16:19], off offset:-3840 sc1
	v_cvt_pk_bf16_f32 v8, v20, v21
	v_cvt_pk_bf16_f32 v9, v22, v23
	v_cvt_pk_bf16_f32 v10, v12, v13
	v_add_co_u32_e32 v12, vcc, s83, v128
	v_cvt_pk_bf16_f32 v11, v14, v15
	s_nop 1
	v_addc_co_u32_e32 v13, vcc, -1, v129, vcc
	global_store_dwordx4 v[12:13], v[8:11], off sc1
	v_cvt_pk_bf16_f32 v4, v4, v5
	v_cvt_pk_bf16_f32 v5, v6, v7
	v_cvt_pk_bf16_f32 v6, v0, v1
	v_add_co_u32_e32 v0, vcc, 0xfe059000, v128
	v_cvt_pk_bf16_f32 v7, v2, v3
	s_nop 1
	v_addc_co_u32_e32 v1, vcc, -1, v129, vcc
	global_store_dwordx4 v[0:1], v[4:7], off offset:-3840 sc1
	s_andn2_b64 vcc, exec, s[44:45]
	s_mov_b64 s[6:7], -1
	s_cbranch_vccnz .LBB0_1297
